# As[0][1] restaged one phase earlier (phase 4, with phase-3 reads waited before the barrier): phase-5 load segment has no LDS-DMA, phase 4 has four; vmcnt(8)
# baseline (speedup 1.0000x reference)
.LBB0_86:
	v_mov_b64_e32 v[0:1], 0x800
	s_ashr_i32 s7, s6, 31
	v_cmp_lt_i64_e32 vcc, s[8:9], v[0:1]
	s_lshl_b64 s[8:9], s[6:7], 20
	s_add_u32 s8, s23, s8
	s_addc_u32 s9, s24, s9
	s_and_b64 s[10:11], vcc, exec
	s_cselect_b32 s7, s9, s15
	s_cselect_b32 s38, s8, s14
	s_ashr_i32 s5, s4, 31
	s_lshl_b64 s[10:11], s[4:5], 20
	s_add_u32 s10, s25, s10
	s_addc_u32 s11, s26, s11
	s_and_b64 s[18:19], vcc, exec
	s_cselect_b32 s5, s11, s17
	s_cselect_b32 s39, s10, s16
	s_add_u32 s14, s14, 0x80080
	s_addc_u32 s15, s15, 0
	s_add_u32 s40, s16, 0x100
	s_addc_u32 s41, s17, 0
	s_mov_b32 s42, -2
	s_mov_b64 s[48:49], 0x80
	v_add_u32_e32 v220, 0x10000, v183
	s_add_u32 s16, s14, 0xfff80080
	s_addc_u32 s17, s15, -1
	s_add_i32 s43, 0, 0x10000
	ds_read_b128 v[128:131], v220 offset:0
	ds_read_b128 v[132:135], v220 offset:1024
	ds_read_b128 v[136:139], v220 offset:2048
	ds_read_b128 v[140:143], v220 offset:3072
	s_cmp_eq_u32 s42, 28
	s_cselect_b32 s19, s7, s17
	s_cselect_b32 s18, s38, s16
	s_cselect_b32 s17, s5, s41
	s_cselect_b32 s16, s39, s40
	s_add_i32 m0, s28, 0xc000
	ds_read_b128 v[144:147], v185
	ds_read_b128 v[148:151], v185 offset:1024
	ds_read_b128 v[152:155], v185 offset:2048
	ds_read_b128 v[156:159], v185 offset:3072
	ds_read_b128 v[170:173], v185 offset:4096
	ds_read_b128 v[174:177], v185 offset:5120
	ds_read_b128 v[178:181], v185 offset:6144
	ds_read_b128 v[186:189], v185 offset:7168
	global_load_lds_dwordx4 v166, s[14:15]
	s_add_i32 m0, s28, 0xe000
	s_nop 0
	global_load_lds_dwordx4 v168, s[14:15]
	s_waitcnt lgkmcnt(8)
	s_barrier
	s_waitcnt lgkmcnt(0)
	v_mfma_f32_16x16x32_bf16 v[124:127], v[128:131], v[144:147], 0
	v_mfma_f32_16x16x32_bf16 v[120:123], v[136:139], v[144:147], 0
	v_mfma_f32_16x16x32_bf16 v[108:111], v[128:131], v[152:155], 0
	v_mfma_f32_16x16x32_bf16 v[104:107], v[136:139], v[152:155], 0
	s_add_i32 s46, 0, 0x14000
	s_add_i32 s43, s43, s27
	v_mfma_f32_16x16x32_bf16 v[92:95], v[128:131], v[170:173], 0
	s_mov_b32 m0, s43
	v_mfma_f32_16x16x32_bf16 v[88:91], v[136:139], v[170:173], 0
	v_mfma_f32_16x16x32_bf16 v[76:79], v[128:131], v[178:181], 0
	v_mfma_f32_16x16x32_bf16 v[72:75], v[136:139], v[178:181], 0
	v_mfma_f32_16x16x32_bf16 v[124:127], v[132:135], v[148:151], v[124:127]
	v_mfma_f32_16x16x32_bf16 v[120:123], v[140:143], v[148:151], v[120:123]
	v_mfma_f32_16x16x32_bf16 v[108:111], v[132:135], v[156:159], v[108:111]
	v_mfma_f32_16x16x32_bf16 v[104:107], v[140:143], v[156:159], v[104:107]
	v_mfma_f32_16x16x32_bf16 v[92:95], v[132:135], v[174:177], v[92:95]
	v_mfma_f32_16x16x32_bf16 v[88:91], v[140:143], v[174:177], v[88:91]
	v_mfma_f32_16x16x32_bf16 v[76:79], v[132:135], v[186:189], v[76:79]
	v_mfma_f32_16x16x32_bf16 v[72:75], v[140:143], v[186:189], v[72:75]
	s_barrier
	ds_read_b128 v[196:199], v220 offset:16384
	ds_read_b128 v[204:207], v220 offset:17408
	ds_read_b128 v[208:211], v220 offset:18432
	ds_read_b128 v[214:217], v220 offset:19456
	global_load_lds_dwordx4 v192, s[16:17]
	s_add_i32 m0, s43, 0x2000
	s_nop 0
	global_load_lds_dwordx4 v164, s[16:17]
	s_barrier
	s_waitcnt lgkmcnt(0)
	v_mfma_f32_16x16x32_bf16 v[116:119], v[196:199], v[144:147], 0
	v_mfma_f32_16x16x32_bf16 v[112:115], v[208:211], v[144:147], 0
	v_mfma_f32_16x16x32_bf16 v[100:103], v[196:199], v[152:155], 0
	v_mfma_f32_16x16x32_bf16 v[96:99], v[208:211], v[152:155], 0
	s_mov_b32 m0, s28
	v_mfma_f32_16x16x32_bf16 v[84:87], v[196:199], v[170:173], 0
	s_add_u32 s48, s18, 0x80
	s_addc_u32 s49, s19, 0
	v_mfma_f32_16x16x32_bf16 v[80:83], v[208:211], v[170:173], 0
	v_mfma_f32_16x16x32_bf16 v[68:71], v[196:199], v[178:181], 0
	v_mfma_f32_16x16x32_bf16 v[64:67], v[208:211], v[178:181], 0
	v_mfma_f32_16x16x32_bf16 v[116:119], v[204:207], v[148:151], v[116:119]
	v_mfma_f32_16x16x32_bf16 v[112:115], v[214:217], v[148:151], v[112:115]
	v_mfma_f32_16x16x32_bf16 v[100:103], v[204:207], v[156:159], v[100:103]
	v_mfma_f32_16x16x32_bf16 v[96:99], v[214:217], v[156:159], v[96:99]
	v_mfma_f32_16x16x32_bf16 v[84:87], v[204:207], v[174:177], v[84:87]
	v_mfma_f32_16x16x32_bf16 v[80:83], v[214:217], v[174:177], v[80:83]
	v_mfma_f32_16x16x32_bf16 v[68:71], v[204:207], v[186:189], v[68:71]
	v_mfma_f32_16x16x32_bf16 v[64:67], v[214:217], v[186:189], v[64:67]
	s_barrier
	ds_read_b128 v[144:147], v185 offset:16384
	ds_read_b128 v[148:151], v185 offset:17408
	ds_read_b128 v[152:155], v185 offset:18432
	ds_read_b128 v[156:159], v185 offset:19456
	ds_read_b128 v[170:173], v185 offset:20480
	ds_read_b128 v[174:177], v185 offset:21504
	ds_read_b128 v[178:181], v185 offset:22528
	ds_read_b128 v[186:189], v185 offset:23552
	global_load_lds_dwordx4 v160, s[18:19]
	s_mov_b32 m0, s29
	s_nop 0
	global_load_lds_dwordx4 v162, s[18:19]
	s_waitcnt lgkmcnt(0)
	s_barrier
	v_mfma_f32_16x16x32_bf16 v[60:63], v[128:131], v[144:147], 0
	v_mfma_f32_16x16x32_bf16 v[56:59], v[136:139], v[144:147], 0
	v_mfma_f32_16x16x32_bf16 v[44:47], v[128:131], v[152:155], 0
	v_mfma_f32_16x16x32_bf16 v[40:43], v[136:139], v[152:155], 0
	s_add_u32 s44, s16, 0x80000
	s_addc_u32 s45, s17, 0
	v_mfma_f32_16x16x32_bf16 v[28:31], v[128:131], v[170:173], 0
	s_add_i32 s43, s46, s27
	s_mov_b32 m0, s43
	v_mfma_f32_16x16x32_bf16 v[24:27], v[136:139], v[170:173], 0
	v_mfma_f32_16x16x32_bf16 v[12:15], v[128:131], v[178:181], 0
	v_mfma_f32_16x16x32_bf16 v[8:11], v[136:139], v[178:181], 0
	v_mfma_f32_16x16x32_bf16 v[60:63], v[132:135], v[148:151], v[60:63]
	v_mfma_f32_16x16x32_bf16 v[56:59], v[140:143], v[148:151], v[56:59]
	v_mfma_f32_16x16x32_bf16 v[44:47], v[132:135], v[156:159], v[44:47]
	v_mfma_f32_16x16x32_bf16 v[40:43], v[140:143], v[156:159], v[40:43]
	v_mfma_f32_16x16x32_bf16 v[28:31], v[132:135], v[174:177], v[28:31]
	v_mfma_f32_16x16x32_bf16 v[24:27], v[140:143], v[174:177], v[24:27]
	v_mfma_f32_16x16x32_bf16 v[12:15], v[132:135], v[186:189], v[12:15]
	v_mfma_f32_16x16x32_bf16 v[8:11], v[140:143], v[186:189], v[8:11]
	s_barrier
	global_load_lds_dwordx4 v192, s[44:45]
	s_add_i32 m0, s43, 0x2000
	s_nop 0
	global_load_lds_dwordx4 v164, s[44:45]
	s_add_u32 s18, s18, 0x80000
	s_addc_u32 s19, s19, 0
	s_mov_b32 m0, s30
	s_nop 0
	global_load_lds_dwordx4 v160, s[18:19]
	s_mov_b32 m0, s31
	s_nop 0
	global_load_lds_dwordx4 v162, s[18:19]
	s_waitcnt vmcnt(8)
	s_barrier
	v_mfma_f32_16x16x32_bf16 v[52:55], v[196:199], v[144:147], 0
	v_mfma_f32_16x16x32_bf16 v[48:51], v[208:211], v[144:147], 0
	v_mfma_f32_16x16x32_bf16 v[36:39], v[196:199], v[152:155], 0
	v_mfma_f32_16x16x32_bf16 v[32:35], v[208:211], v[152:155], 0
	s_add_i32 s43, 0, 0x18000
	v_mfma_f32_16x16x32_bf16 v[20:23], v[196:199], v[170:173], 0
	v_mfma_f32_16x16x32_bf16 v[16:19], v[208:211], v[170:173], 0
	v_mfma_f32_16x16x32_bf16 v[4:7], v[196:199], v[178:181], 0
	v_mfma_f32_16x16x32_bf16 v[0:3], v[208:211], v[178:181], 0
	v_mfma_f32_16x16x32_bf16 v[52:55], v[204:207], v[148:151], v[52:55]
	v_mfma_f32_16x16x32_bf16 v[48:51], v[214:217], v[148:151], v[48:51]
	v_mfma_f32_16x16x32_bf16 v[36:39], v[204:207], v[156:159], v[36:39]
	v_mfma_f32_16x16x32_bf16 v[32:35], v[214:217], v[156:159], v[32:35]
	v_mfma_f32_16x16x32_bf16 v[20:23], v[204:207], v[174:177], v[20:23]
	v_mfma_f32_16x16x32_bf16 v[16:19], v[214:217], v[174:177], v[16:19]
	v_mfma_f32_16x16x32_bf16 v[4:7], v[204:207], v[186:189], v[4:7]
	v_mfma_f32_16x16x32_bf16 v[0:3], v[214:217], v[186:189], v[0:3]
	s_barrier
	ds_read_b128 v[128:131], v220 offset:32768
	ds_read_b128 v[132:135], v220 offset:33792
	ds_read_b128 v[136:139], v220 offset:34816
	ds_read_b128 v[140:143], v220 offset:35840
	ds_read_b128 v[144:147], v185 offset:32768
	ds_read_b128 v[148:151], v185 offset:33792
	ds_read_b128 v[152:155], v185 offset:34816
	ds_read_b128 v[156:159], v185 offset:35840
	ds_read_b128 v[170:173], v185 offset:36864
	ds_read_b128 v[174:177], v185 offset:37888
	ds_read_b128 v[178:181], v185 offset:38912
	ds_read_b128 v[186:189], v185 offset:39936
	s_waitcnt lgkmcnt(8)
	s_barrier
	s_waitcnt lgkmcnt(0)
	v_mfma_f32_16x16x32_bf16 v[124:127], v[128:131], v[144:147], v[124:127]
	v_mfma_f32_16x16x32_bf16 v[120:123], v[136:139], v[144:147], v[120:123]
	v_mfma_f32_16x16x32_bf16 v[108:111], v[128:131], v[152:155], v[108:111]
	v_mfma_f32_16x16x32_bf16 v[104:107], v[136:139], v[152:155], v[104:107]
	s_add_i32 s18, 0, 0x1c000
	s_add_i32 s19, s43, s27
	v_mfma_f32_16x16x32_bf16 v[92:95], v[128:131], v[170:173], v[92:95]
	s_add_i32 m0, s19, 0xffffff80
	v_mfma_f32_16x16x32_bf16 v[88:91], v[136:139], v[170:173], v[88:91]
	v_mfma_f32_16x16x32_bf16 v[76:79], v[128:131], v[178:181], v[76:79]
	v_mfma_f32_16x16x32_bf16 v[72:75], v[136:139], v[178:181], v[72:75]
	v_mfma_f32_16x16x32_bf16 v[124:127], v[132:135], v[148:151], v[124:127]
	v_mfma_f32_16x16x32_bf16 v[120:123], v[140:143], v[148:151], v[120:123]
	v_mfma_f32_16x16x32_bf16 v[108:111], v[132:135], v[156:159], v[108:111]
	v_mfma_f32_16x16x32_bf16 v[104:107], v[140:143], v[156:159], v[104:107]
	v_mfma_f32_16x16x32_bf16 v[92:95], v[132:135], v[174:177], v[92:95]
	v_mfma_f32_16x16x32_bf16 v[88:91], v[140:143], v[174:177], v[88:91]
	v_mfma_f32_16x16x32_bf16 v[76:79], v[132:135], v[186:189], v[76:79]
	v_mfma_f32_16x16x32_bf16 v[72:75], v[140:143], v[186:189], v[72:75]
	s_barrier
	ds_read_b128 v[196:199], v220 offset:49152
	ds_read_b128 v[204:207], v220 offset:50176
	ds_read_b128 v[208:211], v220 offset:51200
	ds_read_b128 v[214:217], v220 offset:52224
	global_load_lds_dwordx4 v192, s[16:17] offset:128
	s_add_i32 m0, s19, 0x1f80
	s_nop 0
	global_load_lds_dwordx4 v164, s[16:17] offset:128
	s_barrier
	s_waitcnt lgkmcnt(0)
	v_mfma_f32_16x16x32_bf16 v[116:119], v[196:199], v[144:147], v[116:119]
	v_mfma_f32_16x16x32_bf16 v[112:115], v[208:211], v[144:147], v[112:115]
	v_mfma_f32_16x16x32_bf16 v[100:103], v[196:199], v[152:155], v[100:103]
	v_mfma_f32_16x16x32_bf16 v[96:99], v[208:211], v[152:155], v[96:99]
	s_mov_b32 m0, s35
	v_mfma_f32_16x16x32_bf16 v[84:87], v[196:199], v[170:173], v[84:87]
	v_mfma_f32_16x16x32_bf16 v[80:83], v[208:211], v[170:173], v[80:83]
	v_mfma_f32_16x16x32_bf16 v[68:71], v[196:199], v[178:181], v[68:71]
	v_mfma_f32_16x16x32_bf16 v[64:67], v[208:211], v[178:181], v[64:67]
	v_mfma_f32_16x16x32_bf16 v[116:119], v[204:207], v[148:151], v[116:119]
	v_mfma_f32_16x16x32_bf16 v[112:115], v[214:217], v[148:151], v[112:115]
	v_mfma_f32_16x16x32_bf16 v[100:103], v[204:207], v[156:159], v[100:103]
	v_mfma_f32_16x16x32_bf16 v[96:99], v[214:217], v[156:159], v[96:99]
	v_mfma_f32_16x16x32_bf16 v[84:87], v[204:207], v[174:177], v[84:87]
	v_mfma_f32_16x16x32_bf16 v[80:83], v[214:217], v[174:177], v[80:83]
	v_mfma_f32_16x16x32_bf16 v[68:71], v[204:207], v[186:189], v[68:71]
	v_mfma_f32_16x16x32_bf16 v[64:67], v[214:217], v[186:189], v[64:67]
	s_barrier
	ds_read_b128 v[144:147], v185 offset:49152
	ds_read_b128 v[148:151], v185 offset:50176
	ds_read_b128 v[152:155], v185 offset:51200
	ds_read_b128 v[156:159], v185 offset:52224
	ds_read_b128 v[170:173], v185 offset:53248
	ds_read_b128 v[174:177], v185 offset:54272
	ds_read_b128 v[178:181], v185 offset:55296
	ds_read_b128 v[186:189], v185 offset:56320
	global_load_lds_dwordx4 v160, s[48:49]
	s_mov_b32 m0, s36
	s_nop 0
	global_load_lds_dwordx4 v162, s[48:49]
	s_barrier
	s_waitcnt lgkmcnt(0)
	v_mfma_f32_16x16x32_bf16 v[60:63], v[128:131], v[144:147], v[60:63]
	v_mfma_f32_16x16x32_bf16 v[56:59], v[136:139], v[144:147], v[56:59]
	v_mfma_f32_16x16x32_bf16 v[44:47], v[128:131], v[152:155], v[44:47]
	v_mfma_f32_16x16x32_bf16 v[40:43], v[136:139], v[152:155], v[40:43]
	s_add_u32 s16, s16, 0x80080
	s_addc_u32 s17, s17, 0
	v_mfma_f32_16x16x32_bf16 v[28:31], v[128:131], v[170:173], v[28:31]
	s_add_i32 s18, s18, s27
	s_mov_b32 m0, s18
	v_mfma_f32_16x16x32_bf16 v[24:27], v[136:139], v[170:173], v[24:27]
	v_mfma_f32_16x16x32_bf16 v[12:15], v[128:131], v[178:181], v[12:15]
	v_mfma_f32_16x16x32_bf16 v[8:11], v[136:139], v[178:181], v[8:11]
	v_mfma_f32_16x16x32_bf16 v[60:63], v[132:135], v[148:151], v[60:63]
	v_mfma_f32_16x16x32_bf16 v[56:59], v[140:143], v[148:151], v[56:59]
	v_mfma_f32_16x16x32_bf16 v[44:47], v[132:135], v[156:159], v[44:47]
	v_mfma_f32_16x16x32_bf16 v[40:43], v[140:143], v[156:159], v[40:43]
	v_mfma_f32_16x16x32_bf16 v[28:31], v[132:135], v[174:177], v[28:31]
	v_mfma_f32_16x16x32_bf16 v[24:27], v[140:143], v[174:177], v[24:27]
	v_mfma_f32_16x16x32_bf16 v[12:15], v[132:135], v[186:189], v[12:15]
	v_mfma_f32_16x16x32_bf16 v[8:11], v[140:143], v[186:189], v[8:11]
	s_barrier
	global_load_lds_dwordx4 v192, s[16:17]
	s_add_i32 m0, s18, 0x2000
	s_nop 0
	global_load_lds_dwordx4 v164, s[16:17]
	s_waitcnt vmcnt(6)
	s_barrier
	v_mfma_f32_16x16x32_bf16 v[52:55], v[196:199], v[144:147], v[52:55]
	v_mfma_f32_16x16x32_bf16 v[48:51], v[208:211], v[144:147], v[48:51]
	v_mfma_f32_16x16x32_bf16 v[36:39], v[196:199], v[152:155], v[36:39]
	v_mfma_f32_16x16x32_bf16 v[32:35], v[208:211], v[152:155], v[32:35]
	s_add_i32 s42, s42, 2
	v_mfma_f32_16x16x32_bf16 v[20:23], v[196:199], v[170:173], v[20:23]
	s_add_u32 s14, s14, 0x100
	s_addc_u32 s15, s15, 0
	v_mfma_f32_16x16x32_bf16 v[16:19], v[208:211], v[170:173], v[16:19]
	s_add_u32 s40, s40, 0x100
	s_addc_u32 s41, s41, 0
	v_mfma_f32_16x16x32_bf16 v[4:7], v[196:199], v[178:181], v[4:7]
	s_add_u32 s16, s14, 0xfff80080
	s_addc_u32 s17, s15, -1
	v_mfma_f32_16x16x32_bf16 v[0:3], v[208:211], v[178:181], v[0:3]
	s_add_i32 s43, 0, 0x10000
	s_cmp_eq_u32 s42, 28
	v_mfma_f32_16x16x32_bf16 v[52:55], v[204:207], v[148:151], v[52:55]
	s_cselect_b32 s19, s7, s17
	s_cselect_b32 s18, s38, s16
	v_mfma_f32_16x16x32_bf16 v[48:51], v[214:217], v[148:151], v[48:51]
	s_cselect_b32 s17, s5, s41
	s_cselect_b32 s16, s39, s40
	v_mfma_f32_16x16x32_bf16 v[36:39], v[204:207], v[156:159], v[36:39]
	s_add_i32 m0, s28, 0xc000
	v_mfma_f32_16x16x32_bf16 v[32:35], v[214:217], v[156:159], v[32:35]
	v_mfma_f32_16x16x32_bf16 v[20:23], v[204:207], v[174:177], v[20:23]
	v_mfma_f32_16x16x32_bf16 v[16:19], v[214:217], v[174:177], v[16:19]
	v_mfma_f32_16x16x32_bf16 v[4:7], v[204:207], v[186:189], v[4:7]
	v_mfma_f32_16x16x32_bf16 v[0:3], v[214:217], v[186:189], v[0:3]
	s_cmp_gt_u32 s42, 29
	s_barrier
.LBB0_87:
	ds_read_b128 v[128:131], v220 offset:0
	ds_read_b128 v[132:135], v220 offset:1024
	ds_read_b128 v[136:139], v220 offset:2048
	ds_read_b128 v[140:143], v220 offset:3072
	ds_read_b128 v[144:147], v185
	ds_read_b128 v[148:151], v185 offset:1024
	ds_read_b128 v[152:155], v185 offset:2048
	ds_read_b128 v[156:159], v185 offset:3072
	ds_read_b128 v[170:173], v185 offset:4096
	ds_read_b128 v[174:177], v185 offset:5120
	ds_read_b128 v[178:181], v185 offset:6144
	ds_read_b128 v[186:189], v185 offset:7168
	global_load_lds_dwordx4 v166, s[14:15]
	s_add_i32 m0, s28, 0xe000
	s_nop 0
	global_load_lds_dwordx4 v168, s[14:15]
	s_waitcnt lgkmcnt(8)
	s_barrier
	s_waitcnt lgkmcnt(0)
	v_mfma_f32_16x16x32_bf16 v[124:127], v[128:131], v[144:147], v[124:127]
	v_mfma_f32_16x16x32_bf16 v[120:123], v[136:139], v[144:147], v[120:123]
	v_mfma_f32_16x16x32_bf16 v[108:111], v[128:131], v[152:155], v[108:111]
	v_mfma_f32_16x16x32_bf16 v[104:107], v[136:139], v[152:155], v[104:107]
	s_add_i32 s46, 0, 0x14000
	s_add_i32 s43, s43, s27
	v_mfma_f32_16x16x32_bf16 v[92:95], v[128:131], v[170:173], v[92:95]
	s_mov_b32 m0, s43
	v_mfma_f32_16x16x32_bf16 v[88:91], v[136:139], v[170:173], v[88:91]
	v_mfma_f32_16x16x32_bf16 v[76:79], v[128:131], v[178:181], v[76:79]
	v_mfma_f32_16x16x32_bf16 v[72:75], v[136:139], v[178:181], v[72:75]
	v_mfma_f32_16x16x32_bf16 v[124:127], v[132:135], v[148:151], v[124:127]
	v_mfma_f32_16x16x32_bf16 v[120:123], v[140:143], v[148:151], v[120:123]
	v_mfma_f32_16x16x32_bf16 v[108:111], v[132:135], v[156:159], v[108:111]
	v_mfma_f32_16x16x32_bf16 v[104:107], v[140:143], v[156:159], v[104:107]
	v_mfma_f32_16x16x32_bf16 v[92:95], v[132:135], v[174:177], v[92:95]
	v_mfma_f32_16x16x32_bf16 v[88:91], v[140:143], v[174:177], v[88:91]
	v_mfma_f32_16x16x32_bf16 v[76:79], v[132:135], v[186:189], v[76:79]
	v_mfma_f32_16x16x32_bf16 v[72:75], v[140:143], v[186:189], v[72:75]
	s_barrier
	ds_read_b128 v[196:199], v220 offset:16384
	ds_read_b128 v[204:207], v220 offset:17408
	ds_read_b128 v[208:211], v220 offset:18432
	ds_read_b128 v[214:217], v220 offset:19456
	global_load_lds_dwordx4 v192, s[16:17]
	s_add_i32 m0, s43, 0x2000
	s_nop 0
	global_load_lds_dwordx4 v164, s[16:17]
	s_barrier
	s_waitcnt lgkmcnt(0)
	v_mfma_f32_16x16x32_bf16 v[116:119], v[196:199], v[144:147], v[116:119]
	v_mfma_f32_16x16x32_bf16 v[112:115], v[208:211], v[144:147], v[112:115]
	v_mfma_f32_16x16x32_bf16 v[100:103], v[196:199], v[152:155], v[100:103]
	v_mfma_f32_16x16x32_bf16 v[96:99], v[208:211], v[152:155], v[96:99]
	s_mov_b32 m0, s28
	v_mfma_f32_16x16x32_bf16 v[84:87], v[196:199], v[170:173], v[84:87]
	s_add_u32 s48, s18, 0x80
	s_addc_u32 s49, s19, 0
	v_mfma_f32_16x16x32_bf16 v[80:83], v[208:211], v[170:173], v[80:83]
	v_mfma_f32_16x16x32_bf16 v[68:71], v[196:199], v[178:181], v[68:71]
	v_mfma_f32_16x16x32_bf16 v[64:67], v[208:211], v[178:181], v[64:67]
	v_mfma_f32_16x16x32_bf16 v[116:119], v[204:207], v[148:151], v[116:119]
	v_mfma_f32_16x16x32_bf16 v[112:115], v[214:217], v[148:151], v[112:115]
	v_mfma_f32_16x16x32_bf16 v[100:103], v[204:207], v[156:159], v[100:103]
	v_mfma_f32_16x16x32_bf16 v[96:99], v[214:217], v[156:159], v[96:99]
	v_mfma_f32_16x16x32_bf16 v[84:87], v[204:207], v[174:177], v[84:87]
	v_mfma_f32_16x16x32_bf16 v[80:83], v[214:217], v[174:177], v[80:83]
	v_mfma_f32_16x16x32_bf16 v[68:71], v[204:207], v[186:189], v[68:71]
	v_mfma_f32_16x16x32_bf16 v[64:67], v[214:217], v[186:189], v[64:67]
	s_barrier
	ds_read_b128 v[144:147], v185 offset:16384
	ds_read_b128 v[148:151], v185 offset:17408
	ds_read_b128 v[152:155], v185 offset:18432
	ds_read_b128 v[156:159], v185 offset:19456
	ds_read_b128 v[170:173], v185 offset:20480
	ds_read_b128 v[174:177], v185 offset:21504
	ds_read_b128 v[178:181], v185 offset:22528
	ds_read_b128 v[186:189], v185 offset:23552
	global_load_lds_dwordx4 v160, s[18:19]
	s_mov_b32 m0, s29
	s_nop 0
	global_load_lds_dwordx4 v162, s[18:19]
	s_waitcnt lgkmcnt(0)
	s_barrier
	v_mfma_f32_16x16x32_bf16 v[60:63], v[128:131], v[144:147], v[60:63]
	v_mfma_f32_16x16x32_bf16 v[56:59], v[136:139], v[144:147], v[56:59]
	v_mfma_f32_16x16x32_bf16 v[44:47], v[128:131], v[152:155], v[44:47]
	v_mfma_f32_16x16x32_bf16 v[40:43], v[136:139], v[152:155], v[40:43]
	s_add_u32 s44, s16, 0x80000
	s_addc_u32 s45, s17, 0
	v_mfma_f32_16x16x32_bf16 v[28:31], v[128:131], v[170:173], v[28:31]
	s_add_i32 s43, s46, s27
	s_mov_b32 m0, s43
	v_mfma_f32_16x16x32_bf16 v[24:27], v[136:139], v[170:173], v[24:27]
	v_mfma_f32_16x16x32_bf16 v[12:15], v[128:131], v[178:181], v[12:15]
	v_mfma_f32_16x16x32_bf16 v[8:11], v[136:139], v[178:181], v[8:11]
	v_mfma_f32_16x16x32_bf16 v[60:63], v[132:135], v[148:151], v[60:63]
	v_mfma_f32_16x16x32_bf16 v[56:59], v[140:143], v[148:151], v[56:59]
	v_mfma_f32_16x16x32_bf16 v[44:47], v[132:135], v[156:159], v[44:47]
	v_mfma_f32_16x16x32_bf16 v[40:43], v[140:143], v[156:159], v[40:43]
	v_mfma_f32_16x16x32_bf16 v[28:31], v[132:135], v[174:177], v[28:31]
	v_mfma_f32_16x16x32_bf16 v[24:27], v[140:143], v[174:177], v[24:27]
	v_mfma_f32_16x16x32_bf16 v[12:15], v[132:135], v[186:189], v[12:15]
	v_mfma_f32_16x16x32_bf16 v[8:11], v[140:143], v[186:189], v[8:11]
	s_barrier
	global_load_lds_dwordx4 v192, s[44:45]
	s_add_i32 m0, s43, 0x2000
	s_nop 0
	global_load_lds_dwordx4 v164, s[44:45]
	s_add_u32 s18, s18, 0x80000
	s_addc_u32 s19, s19, 0
	s_mov_b32 m0, s30
	s_nop 0
	global_load_lds_dwordx4 v160, s[18:19]
	s_mov_b32 m0, s31
	s_nop 0
	global_load_lds_dwordx4 v162, s[18:19]
	s_waitcnt vmcnt(8)
	s_barrier
	v_mfma_f32_16x16x32_bf16 v[52:55], v[196:199], v[144:147], v[52:55]
	v_mfma_f32_16x16x32_bf16 v[48:51], v[208:211], v[144:147], v[48:51]
	v_mfma_f32_16x16x32_bf16 v[36:39], v[196:199], v[152:155], v[36:39]
	v_mfma_f32_16x16x32_bf16 v[32:35], v[208:211], v[152:155], v[32:35]
	s_add_i32 s43, 0, 0x18000
	v_mfma_f32_16x16x32_bf16 v[20:23], v[196:199], v[170:173], v[20:23]
	v_mfma_f32_16x16x32_bf16 v[16:19], v[208:211], v[170:173], v[16:19]
	v_mfma_f32_16x16x32_bf16 v[4:7], v[196:199], v[178:181], v[4:7]
	v_mfma_f32_16x16x32_bf16 v[0:3], v[208:211], v[178:181], v[0:3]
	v_mfma_f32_16x16x32_bf16 v[52:55], v[204:207], v[148:151], v[52:55]
	v_mfma_f32_16x16x32_bf16 v[48:51], v[214:217], v[148:151], v[48:51]
	v_mfma_f32_16x16x32_bf16 v[36:39], v[204:207], v[156:159], v[36:39]
	v_mfma_f32_16x16x32_bf16 v[32:35], v[214:217], v[156:159], v[32:35]
	v_mfma_f32_16x16x32_bf16 v[20:23], v[204:207], v[174:177], v[20:23]
	v_mfma_f32_16x16x32_bf16 v[16:19], v[214:217], v[174:177], v[16:19]
	v_mfma_f32_16x16x32_bf16 v[4:7], v[204:207], v[186:189], v[4:7]
	v_mfma_f32_16x16x32_bf16 v[0:3], v[214:217], v[186:189], v[0:3]
	s_barrier
	ds_read_b128 v[128:131], v220 offset:32768
	ds_read_b128 v[132:135], v220 offset:33792
	ds_read_b128 v[136:139], v220 offset:34816
	ds_read_b128 v[140:143], v220 offset:35840
	ds_read_b128 v[144:147], v185 offset:32768
	ds_read_b128 v[148:151], v185 offset:33792
	ds_read_b128 v[152:155], v185 offset:34816
	ds_read_b128 v[156:159], v185 offset:35840
	ds_read_b128 v[170:173], v185 offset:36864
	ds_read_b128 v[174:177], v185 offset:37888
	ds_read_b128 v[178:181], v185 offset:38912
	ds_read_b128 v[186:189], v185 offset:39936
	s_waitcnt lgkmcnt(8)
	s_barrier
	s_waitcnt lgkmcnt(0)
	v_mfma_f32_16x16x32_bf16 v[124:127], v[128:131], v[144:147], v[124:127]
	v_mfma_f32_16x16x32_bf16 v[120:123], v[136:139], v[144:147], v[120:123]
	v_mfma_f32_16x16x32_bf16 v[108:111], v[128:131], v[152:155], v[108:111]
	v_mfma_f32_16x16x32_bf16 v[104:107], v[136:139], v[152:155], v[104:107]
	s_add_i32 s18, 0, 0x1c000
	s_add_i32 s19, s43, s27
	v_mfma_f32_16x16x32_bf16 v[92:95], v[128:131], v[170:173], v[92:95]
	s_add_i32 m0, s19, 0xffffff80
	v_mfma_f32_16x16x32_bf16 v[88:91], v[136:139], v[170:173], v[88:91]
	v_mfma_f32_16x16x32_bf16 v[76:79], v[128:131], v[178:181], v[76:79]
	v_mfma_f32_16x16x32_bf16 v[72:75], v[136:139], v[178:181], v[72:75]
	v_mfma_f32_16x16x32_bf16 v[124:127], v[132:135], v[148:151], v[124:127]
	v_mfma_f32_16x16x32_bf16 v[120:123], v[140:143], v[148:151], v[120:123]
	v_mfma_f32_16x16x32_bf16 v[108:111], v[132:135], v[156:159], v[108:111]
	v_mfma_f32_16x16x32_bf16 v[104:107], v[140:143], v[156:159], v[104:107]
	v_mfma_f32_16x16x32_bf16 v[92:95], v[132:135], v[174:177], v[92:95]
	v_mfma_f32_16x16x32_bf16 v[88:91], v[140:143], v[174:177], v[88:91]
	v_mfma_f32_16x16x32_bf16 v[76:79], v[132:135], v[186:189], v[76:79]
	v_mfma_f32_16x16x32_bf16 v[72:75], v[140:143], v[186:189], v[72:75]
	s_barrier
	ds_read_b128 v[196:199], v220 offset:49152
	ds_read_b128 v[204:207], v220 offset:50176
	ds_read_b128 v[208:211], v220 offset:51200
	ds_read_b128 v[214:217], v220 offset:52224
	global_load_lds_dwordx4 v192, s[16:17] offset:128
	s_add_i32 m0, s19, 0x1f80
	s_nop 0
	global_load_lds_dwordx4 v164, s[16:17] offset:128
	s_barrier
	s_waitcnt lgkmcnt(0)
	v_mfma_f32_16x16x32_bf16 v[116:119], v[196:199], v[144:147], v[116:119]
	v_mfma_f32_16x16x32_bf16 v[112:115], v[208:211], v[144:147], v[112:115]
	v_mfma_f32_16x16x32_bf16 v[100:103], v[196:199], v[152:155], v[100:103]
	v_mfma_f32_16x16x32_bf16 v[96:99], v[208:211], v[152:155], v[96:99]
	s_mov_b32 m0, s35
	v_mfma_f32_16x16x32_bf16 v[84:87], v[196:199], v[170:173], v[84:87]
	v_mfma_f32_16x16x32_bf16 v[80:83], v[208:211], v[170:173], v[80:83]
	v_mfma_f32_16x16x32_bf16 v[68:71], v[196:199], v[178:181], v[68:71]
	v_mfma_f32_16x16x32_bf16 v[64:67], v[208:211], v[178:181], v[64:67]
	v_mfma_f32_16x16x32_bf16 v[116:119], v[204:207], v[148:151], v[116:119]
	v_mfma_f32_16x16x32_bf16 v[112:115], v[214:217], v[148:151], v[112:115]
	v_mfma_f32_16x16x32_bf16 v[100:103], v[204:207], v[156:159], v[100:103]
	v_mfma_f32_16x16x32_bf16 v[96:99], v[214:217], v[156:159], v[96:99]
	v_mfma_f32_16x16x32_bf16 v[84:87], v[204:207], v[174:177], v[84:87]
	v_mfma_f32_16x16x32_bf16 v[80:83], v[214:217], v[174:177], v[80:83]
	v_mfma_f32_16x16x32_bf16 v[68:71], v[204:207], v[186:189], v[68:71]
	v_mfma_f32_16x16x32_bf16 v[64:67], v[214:217], v[186:189], v[64:67]
	s_barrier
	ds_read_b128 v[144:147], v185 offset:49152
	ds_read_b128 v[148:151], v185 offset:50176
	ds_read_b128 v[152:155], v185 offset:51200
	ds_read_b128 v[156:159], v185 offset:52224
	ds_read_b128 v[170:173], v185 offset:53248
	ds_read_b128 v[174:177], v185 offset:54272
	ds_read_b128 v[178:181], v185 offset:55296
	ds_read_b128 v[186:189], v185 offset:56320
	global_load_lds_dwordx4 v160, s[48:49]
	s_mov_b32 m0, s36
	s_nop 0
	global_load_lds_dwordx4 v162, s[48:49]
	s_barrier
	s_waitcnt lgkmcnt(0)
	v_mfma_f32_16x16x32_bf16 v[60:63], v[128:131], v[144:147], v[60:63]
	v_mfma_f32_16x16x32_bf16 v[56:59], v[136:139], v[144:147], v[56:59]
	v_mfma_f32_16x16x32_bf16 v[44:47], v[128:131], v[152:155], v[44:47]
	v_mfma_f32_16x16x32_bf16 v[40:43], v[136:139], v[152:155], v[40:43]
	s_add_u32 s16, s16, 0x80080
	s_addc_u32 s17, s17, 0
	v_mfma_f32_16x16x32_bf16 v[28:31], v[128:131], v[170:173], v[28:31]
	s_add_i32 s18, s18, s27
	s_mov_b32 m0, s18
	v_mfma_f32_16x16x32_bf16 v[24:27], v[136:139], v[170:173], v[24:27]
	v_mfma_f32_16x16x32_bf16 v[12:15], v[128:131], v[178:181], v[12:15]
	v_mfma_f32_16x16x32_bf16 v[8:11], v[136:139], v[178:181], v[8:11]
	v_mfma_f32_16x16x32_bf16 v[60:63], v[132:135], v[148:151], v[60:63]
	v_mfma_f32_16x16x32_bf16 v[56:59], v[140:143], v[148:151], v[56:59]
	v_mfma_f32_16x16x32_bf16 v[44:47], v[132:135], v[156:159], v[44:47]
	v_mfma_f32_16x16x32_bf16 v[40:43], v[140:143], v[156:159], v[40:43]
	v_mfma_f32_16x16x32_bf16 v[28:31], v[132:135], v[174:177], v[28:31]
	v_mfma_f32_16x16x32_bf16 v[24:27], v[140:143], v[174:177], v[24:27]
	v_mfma_f32_16x16x32_bf16 v[12:15], v[132:135], v[186:189], v[12:15]
	v_mfma_f32_16x16x32_bf16 v[8:11], v[140:143], v[186:189], v[8:11]
	s_barrier
	global_load_lds_dwordx4 v192, s[16:17]
	s_add_i32 m0, s18, 0x2000
	s_nop 0
	global_load_lds_dwordx4 v164, s[16:17]
	s_waitcnt vmcnt(6)
	s_barrier
	v_mfma_f32_16x16x32_bf16 v[52:55], v[196:199], v[144:147], v[52:55]
	v_mfma_f32_16x16x32_bf16 v[48:51], v[208:211], v[144:147], v[48:51]
	v_mfma_f32_16x16x32_bf16 v[36:39], v[196:199], v[152:155], v[36:39]
	v_mfma_f32_16x16x32_bf16 v[32:35], v[208:211], v[152:155], v[32:35]
	s_add_i32 s42, s42, 2
	v_mfma_f32_16x16x32_bf16 v[20:23], v[196:199], v[170:173], v[20:23]
	s_add_u32 s14, s14, 0x100
	s_addc_u32 s15, s15, 0
	v_mfma_f32_16x16x32_bf16 v[16:19], v[208:211], v[170:173], v[16:19]
	s_add_u32 s40, s40, 0x100
	s_addc_u32 s41, s41, 0
	v_mfma_f32_16x16x32_bf16 v[4:7], v[196:199], v[178:181], v[4:7]
	s_add_u32 s16, s14, 0xfff80080
	s_addc_u32 s17, s15, -1
	v_mfma_f32_16x16x32_bf16 v[0:3], v[208:211], v[178:181], v[0:3]
	s_add_i32 s43, 0, 0x10000
	s_cmp_eq_u32 s42, 28
	v_mfma_f32_16x16x32_bf16 v[52:55], v[204:207], v[148:151], v[52:55]
	s_cselect_b32 s19, s7, s17
	s_cselect_b32 s18, s38, s16
	v_mfma_f32_16x16x32_bf16 v[48:51], v[214:217], v[148:151], v[48:51]
	s_cselect_b32 s17, s5, s41
	s_cselect_b32 s16, s39, s40
	v_mfma_f32_16x16x32_bf16 v[36:39], v[204:207], v[156:159], v[36:39]
	s_add_i32 m0, s28, 0xc000
	v_mfma_f32_16x16x32_bf16 v[32:35], v[214:217], v[156:159], v[32:35]
	v_mfma_f32_16x16x32_bf16 v[20:23], v[204:207], v[174:177], v[20:23]
	v_mfma_f32_16x16x32_bf16 v[16:19], v[214:217], v[174:177], v[16:19]
	v_mfma_f32_16x16x32_bf16 v[4:7], v[204:207], v[186:189], v[4:7]
	v_mfma_f32_16x16x32_bf16 v[0:3], v[214:217], v[186:189], v[0:3]
	s_cmp_gt_u32 s42, 29
	s_barrier
	s_cbranch_scc0 .LBB0_87
	v_lshl_or_b32 v128, s13, 8, v184
	v_lshl_add_u32 v172, s12, 8, v182
	v_ashrrev_i32_e32 v129, 31, v128
	v_lshlrev_b64 v[170:171], 1, v[128:129]
	v_ashrrev_i32_e32 v173, 31, v172
	v_lshl_add_u64 v[174:175], s[2:3], 0, v[170:171]
	v_lshlrev_b64 v[128:129], 13, v[172:173]
	v_lshl_add_u64 v[130:131], v[174:175], 0, v[128:129]
	global_load_dwordx4 v[186:189], v[130:131], off
	global_load_dwordx4 v[196:199], v[130:131], off offset:256
	s_lshl_b32 s5, s13, 1
	v_mul_f32_e32 v133, 0xbfb8aa3b, v124
	v_mul_f32_e32 v135, 0xbfb8aa3b, v125
	v_mul_f32_e32 v137, 0xbfb8aa3b, v126
	v_mul_f32_e32 v138, 0xbfb8aa3b, v127
	v_mul_f32_e32 v139, 0xbfb8aa3b, v120
	v_mul_f32_e32 v140, 0xbfb8aa3b, v121
	s_and_b32 s12, s5, -4
	v_or_b32_e32 v132, 16, v172
	v_or_b32_e32 v136, 48, v172
	v_exp_f32_e32 v148, v133
	v_exp_f32_e32 v149, v135
	v_exp_f32_e32 v150, v137
	v_exp_f32_e32 v151, v138
	v_exp_f32_e32 v204, v139
	v_exp_f32_e32 v205, v140
	s_ashr_i32 s13, s12, 31
	v_or_b32_e32 v134, 32, v172
	v_ashrrev_i32_e32 v133, 31, v132
	v_ashrrev_i32_e32 v137, 31, v136
	s_lshl_b64 s[12:13], s[12:13], 2
	v_mul_f32_e32 v141, 0xbfb8aa3b, v122
	v_ashrrev_i32_e32 v135, 31, v134
	v_lshlrev_b64 v[180:181], 13, v[132:133]
	v_lshlrev_b64 v[176:177], 13, v[136:137]
	s_add_u32 s12, s33, s12
	v_exp_f32_e32 v212, v141
	v_lshlrev_b64 v[138:139], 7, v[172:173]
	v_lshlrev_b64 v[140:141], 7, v[132:133]
	v_lshlrev_b64 v[142:143], 7, v[134:135]
	v_lshlrev_b64 v[178:179], 13, v[134:135]
	v_lshlrev_b64 v[144:145], 7, v[136:137]
	v_lshl_add_u64 v[128:129], s[2:3], 0, v[128:129]
	v_lshl_add_u64 v[130:131], v[174:175], 0, v[180:181]
	v_lshl_add_u64 v[136:137], v[174:175], 0, v[176:177]
	s_addc_u32 s13, s34, s13
	v_lshl_add_u64 v[146:147], v[174:175], 0, v[178:179]
	v_lshl_add_u64 v[190:191], v[128:129], 0, v[170:171]
	global_load_dwordx4 v[156:159], v[130:131], off
	global_load_dwordx4 v[152:155], v[130:131], off offset:256
	global_load_dwordx4 v[132:135], v[136:137], off
	s_nop 0
	global_load_dwordx4 v[128:131], v[136:137], off offset:256
	v_add_f32_e32 v148, 1.0, v148
	v_add_f32_e32 v149, 1.0, v149
	v_add_f32_e32 v150, 1.0, v150
	v_add_f32_e32 v151, 1.0, v151
	v_add_f32_e32 v173, 1.0, v204
	v_add_f32_e32 v204, 1.0, v205
	v_lshl_add_u64 v[136:137], s[12:13], 0, v[138:139]
	v_lshl_add_u64 v[138:139], s[12:13], 0, v[140:141]
	v_lshl_add_u64 v[140:141], s[12:13], 0, v[142:143]
	v_lshl_add_u64 v[144:145], s[12:13], 0, v[144:145]
	v_rcp_f32_e32 v214, v148
	v_rcp_f32_e32 v215, v149
	v_rcp_f32_e32 v216, v150
	v_rcp_f32_e32 v217, v151
	v_rcp_f32_e32 v218, v204
	global_load_dwordx4 v[204:207], v[136:137], off
	global_load_dwordx4 v[208:211], v[138:139], off
	s_nop 0
	global_load_dwordx4 v[136:139], v[140:141], off
	global_load_dwordx4 v[148:151], v[146:147], off
	s_nop 0
	global_load_dwordx4 v[140:143], v[146:147], off offset:256
	s_nop 0
	global_load_dwordx4 v[144:147], v[144:145], off
	v_rcp_f32_e32 v173, v173
	v_mul_f32_e32 v124, v124, v214
	v_mul_f32_e32 v125, v125, v215
	v_mul_f32_e32 v127, v127, v217
	v_mul_f32_e32 v120, v120, v173
	v_mul_f32_e32 v121, v121, v218
	s_mov_b32 s14, 0x358637bd
	s_mov_b32 s5, 0x800000
	v_mul_f32_e32 v126, v126, v216
	s_mov_b64 s[16:17], s[10:11]
	s_mov_b32 s11, 0xc000
	s_waitcnt vmcnt(0)
	v_lshlrev_b32_e32 v173, 16, v186
	v_and_b32_e32 v186, 0xffff0000, v186
	v_lshlrev_b32_e32 v214, 16, v187
	v_and_b32_e32 v187, 0xffff0000, v187
	v_mul_f32_e32 v125, v125, v186
	v_mul_f32_e32 v127, v127, v187
	v_add_f32_e32 v186, 1.0, v212
	v_mul_f32_e32 v187, 0xbfb8aa3b, v123
	v_rcp_f32_e32 v186, v186
	v_exp_f32_e32 v187, v187
	v_mul_f32_e32 v124, v124, v173
	v_and_b32_e32 v173, 0xffff0000, v188
	v_mul_f32_e32 v122, v122, v186
	v_add_f32_e32 v186, 1.0, v187
	v_mul_f32_e32 v187, 0xbfb8aa3b, v116
	v_rcp_f32_e32 v186, v186
	v_exp_f32_e32 v187, v187
	v_mul_f32_e32 v121, v121, v173
	v_lshlrev_b32_e32 v173, 16, v189
	v_mul_f32_e32 v123, v123, v186
	v_add_f32_e32 v186, 1.0, v187
	v_mul_f32_e32 v187, 0xbfb8aa3b, v117
	v_rcp_f32_e32 v186, v186
	v_exp_f32_e32 v187, v187
	v_mul_f32_e32 v122, v122, v173
	v_and_b32_e32 v173, 0xffff0000, v189
	v_mul_f32_e32 v116, v116, v186
	v_add_f32_e32 v186, 1.0, v187
	v_mul_f32_e32 v187, 0xbfb8aa3b, v118
	v_rcp_f32_e32 v186, v186
	v_exp_f32_e32 v187, v187
	v_mul_f32_e32 v123, v123, v173
	v_lshlrev_b32_e32 v173, 16, v196
	v_mul_f32_e32 v173, v116, v173
	v_mul_f32_e32 v116, v117, v186
	v_add_f32_e32 v186, 1.0, v187
	v_mul_f32_e32 v187, 0xbfb8aa3b, v119
	v_rcp_f32_e32 v186, v186
	v_exp_f32_e32 v187, v187
	v_and_b32_e32 v117, 0xffff0000, v196
	v_lshlrev_b32_e32 v215, 16, v188
	v_mul_f32_e32 v188, v116, v117
	v_mul_f32_e32 v116, v118, v186
	v_add_f32_e32 v118, 1.0, v187
	v_rcp_f32_e32 v118, v118
	v_mul_f32_e32 v186, 0xbfb8aa3b, v112
	v_exp_f32_e32 v186, v186
	v_lshlrev_b32_e32 v117, 16, v197
	v_mul_f32_e32 v187, v116, v117
	v_mul_f32_e32 v116, v119, v118
	v_mul_f32_e32 v119, 0xbfb8aa3b, v113
	v_add_f32_e32 v118, 1.0, v186
	v_exp_f32_e32 v119, v119
	v_rcp_f32_e32 v118, v118
	v_and_b32_e32 v117, 0xffff0000, v197
	v_mul_f32_e32 v186, v116, v117
	v_add_f32_e32 v117, 1.0, v119
	v_mul_f32_e32 v112, v112, v118
	v_rcp_f32_e32 v117, v117
	v_mul_f32_e32 v118, 0xbfb8aa3b, v114
	v_exp_f32_e32 v118, v118
	v_lshlrev_b32_e32 v116, 16, v198
	v_mul_f32_e32 v189, v112, v116
	v_mul_f32_e32 v112, v113, v117
	v_and_b32_e32 v113, 0xffff0000, v198
	v_add_f32_e32 v116, 1.0, v118
	v_mul_f32_e32 v196, v112, v113
	v_mul_f32_e32 v112, 0xbfb8aa3b, v115
	v_rcp_f32_e32 v116, v116
	v_exp_f32_e32 v112, v112
	v_mov_b32_e32 v117, v206
	v_mov_b32_e32 v206, v211
	v_mul_f32_e32 v113, v114, v116
	v_lshlrev_b32_e32 v114, 16, v199
	v_add_f32_e32 v112, 1.0, v112
	v_mul_f32_e32 v197, v113, v114
	v_rcp_f32_e32 v114, v112
	v_mov_b32_e32 v112, v208
	v_mov_b32_e32 v113, v204
	v_mov_b32_e32 v204, v209
	v_pk_add_f32 v[112:113], v[112:113], v[204:205]
	v_mov_b32_e32 v116, v210
	v_pk_add_f32 v[112:113], v[116:117], v[112:113]
	v_mul_f32_e32 v114, v115, v114
	v_pk_add_f32 v[116:117], v[206:207], v[112:113]
	v_mov_b64_e32 v[112:113], s[14:15]
	s_mov_b32 s14, 0x3b000000
	v_pk_fma_f32 v[118:119], v[116:117], s[14:15], v[112:113] op_sel_hi:[1,0,0]
	v_and_b32_e32 v115, 0xffff0000, v199
	v_mul_f32_e32 v116, 0x4b800000, v119
	v_cmp_gt_f32_e32 vcc, s5, v119
	v_mul_f32_e32 v126, v126, v214
	v_mul_f32_e32 v120, v120, v215
	v_cndmask_b32_e32 v116, v119, v116, vcc
	v_rsq_f32_e32 v116, v116
	v_mul_f32_e32 v119, v114, v115
	v_mul_f32_e32 v114, 0x45800000, v116
	v_cndmask_b32_e32 v198, v116, v114, vcc
	v_mul_f32_e32 v114, v124, v198
	v_mul_f32_e32 v115, v125, v198
	v_cvt_pk_bf16_f32 v114, v114, v115
	v_mul_f32_e32 v115, v126, v198
	v_mul_f32_e32 v116, v127, v198
	v_cvt_pk_bf16_f32 v115, v115, v116
	v_mul_f32_e32 v116, v120, v198
	v_mul_f32_e32 v117, v121, v198
	v_cvt_pk_bf16_f32 v116, v116, v117
	v_mul_f32_e32 v117, v122, v198
	v_mul_f32_e32 v120, v123, v198
	v_cvt_pk_bf16_f32 v117, v117, v120
	global_store_dwordx4 v[190:191], v[114:117], off
	v_mul_f32_e32 v119, v119, v198
	v_cmp_gt_f32_e32 vcc, s5, v118
	v_mul_f32_e32 v114, v173, v198
	v_mul_f32_e32 v115, v188, v198
	v_cvt_pk_bf16_f32 v114, v114, v115
	v_mul_f32_e32 v115, v187, v198
	v_mul_f32_e32 v116, v186, v198
	v_cvt_pk_bf16_f32 v115, v115, v116
	v_mul_f32_e32 v116, v189, v198
	v_mul_f32_e32 v117, v196, v198
	v_cvt_pk_bf16_f32 v116, v116, v117
	v_mul_f32_e32 v117, v197, v198
	v_cvt_pk_bf16_f32 v117, v117, v119
	v_mul_f32_e32 v119, 0x4b800000, v118
	v_cndmask_b32_e32 v118, v118, v119, vcc
	global_store_dwordx4 v[190:191], v[114:117], off offset:256
	v_rsq_f32_e32 v118, v118
	v_mul_f32_e32 v123, 0xbfb8aa3b, v61
	v_mul_f32_e32 v114, 0xbfb8aa3b, v108
	v_exp_f32_e32 v116, v114
	v_mul_f32_e32 v114, 0x45800000, v118
	v_cndmask_b32_e32 v117, v118, v114, vcc
	v_mul_f32_e32 v118, 0xbfb8aa3b, v109
	v_add_f32_e32 v116, 1.0, v116
	v_rcp_f32_e32 v116, v116
	v_exp_f32_e32 v118, v118
	v_lshl_add_u64 v[114:115], s[2:3], 0, v[180:181]
	v_lshl_add_u64 v[114:115], v[114:115], 0, v[170:171]
	v_mul_f32_e32 v108, v108, v116
	v_lshlrev_b32_e32 v116, 16, v156
	v_mul_f32_e32 v108, v108, v116
	v_add_f32_e32 v116, 1.0, v118
	v_rcp_f32_e32 v116, v116
	v_mul_f32_e32 v118, 0xbfb8aa3b, v110
	v_exp_f32_e32 v118, v118
	v_mul_f32_e32 v108, v108, v117
	v_mul_f32_e32 v109, v109, v116
	v_and_b32_e32 v116, 0xffff0000, v156
	v_mul_f32_e32 v109, v109, v116
	v_add_f32_e32 v116, 1.0, v118
	v_mul_f32_e32 v118, 0xbfb8aa3b, v111
	v_rcp_f32_e32 v116, v116
	v_exp_f32_e32 v118, v118
	v_mul_f32_e32 v109, v109, v117
	v_cvt_pk_bf16_f32 v108, v108, v109
	v_mul_f32_e32 v109, v110, v116
	v_add_f32_e32 v110, 1.0, v118
	v_rcp_f32_e32 v110, v110
	v_lshlrev_b32_e32 v116, 16, v157
	v_mul_f32_e32 v109, v109, v116
	v_and_b32_e32 v116, 0xffff0000, v157
	v_mul_f32_e32 v110, v111, v110
	v_mul_f32_e32 v111, 0xbfb8aa3b, v104
	v_exp_f32_e32 v111, v111
	v_mul_f32_e32 v110, v110, v116
	v_mul_f32_e32 v109, v109, v117
	v_mul_f32_e32 v110, v110, v117
	v_add_f32_e32 v111, 1.0, v111
	v_cvt_pk_bf16_f32 v109, v109, v110
	v_mul_f32_e32 v110, 0xbfb8aa3b, v105
	v_rcp_f32_e32 v111, v111
	v_exp_f32_e32 v110, v110
	v_exp_f32_e32 v123, v123
	v_mul_f32_e32 v124, 0xbfb8aa3b, v62
	v_mul_f32_e32 v104, v104, v111
	v_lshlrev_b32_e32 v111, 16, v158
	v_add_f32_e32 v110, 1.0, v110
	v_mul_f32_e32 v104, v104, v111
	v_rcp_f32_e32 v110, v110
	v_mul_f32_e32 v111, 0xbfb8aa3b, v106
	v_exp_f32_e32 v111, v111
	v_mul_f32_e32 v104, v104, v117
	v_mul_f32_e32 v105, v105, v110
	v_and_b32_e32 v110, 0xffff0000, v158
	v_mul_f32_e32 v105, v105, v110
	v_add_f32_e32 v110, 1.0, v111
	v_rcp_f32_e32 v111, v110
	v_mul_f32_e32 v110, 0xbfb8aa3b, v107
	v_exp_f32_e32 v116, v110
	v_mul_f32_e32 v105, v105, v117
	v_cvt_pk_bf16_f32 v110, v104, v105
	v_mul_f32_e32 v104, v106, v111
	v_add_f32_e32 v105, 1.0, v116
	v_rcp_f32_e32 v105, v105
	v_lshlrev_b32_e32 v106, 16, v159
	v_mul_f32_e32 v104, v104, v106
	v_and_b32_e32 v106, 0xffff0000, v159
	v_mul_f32_e32 v105, v107, v105
	v_mul_f32_e32 v107, 0xbfb8aa3b, v100
	v_exp_f32_e32 v107, v107
	v_mul_f32_e32 v104, v104, v117
	v_mul_f32_e32 v105, v105, v106
	v_mul_f32_e32 v105, v105, v117
	v_cvt_pk_bf16_f32 v111, v104, v105
	v_add_f32_e32 v104, 1.0, v107
	v_rcp_f32_e32 v104, v104
	v_mul_f32_e32 v105, 0xbfb8aa3b, v101
	v_exp_f32_e32 v105, v105
	global_store_dwordx4 v[114:115], v[108:111], off
	v_mul_f32_e32 v100, v100, v104
	v_lshlrev_b32_e32 v104, 16, v152
	v_mul_f32_e32 v100, v100, v104
	v_add_f32_e32 v104, 1.0, v105
	v_rcp_f32_e32 v104, v104
	v_mul_f32_e32 v105, 0xbfb8aa3b, v102
	v_exp_f32_e32 v105, v105
	v_mul_f32_e32 v100, v100, v117
	v_mul_f32_e32 v101, v101, v104
	v_and_b32_e32 v104, 0xffff0000, v152
	v_mul_f32_e32 v101, v101, v104
	v_add_f32_e32 v104, 1.0, v105
	v_mul_f32_e32 v105, 0xbfb8aa3b, v103
	v_rcp_f32_e32 v104, v104
	v_exp_f32_e32 v105, v105
	v_mul_f32_e32 v101, v101, v117
	v_cvt_pk_bf16_f32 v100, v100, v101
	v_mul_f32_e32 v101, v102, v104
	v_add_f32_e32 v102, 1.0, v105
	v_rcp_f32_e32 v102, v102
	v_lshlrev_b32_e32 v104, 16, v153
	v_mul_f32_e32 v101, v101, v104
	v_and_b32_e32 v104, 0xffff0000, v153
	v_mul_f32_e32 v102, v103, v102
	v_mul_f32_e32 v103, 0xbfb8aa3b, v96
	v_exp_f32_e32 v103, v103
	v_mul_f32_e32 v102, v102, v104
	v_mul_f32_e32 v101, v101, v117
	v_mul_f32_e32 v102, v102, v117
	v_add_f32_e32 v103, 1.0, v103
	v_cvt_pk_bf16_f32 v101, v101, v102
	v_mul_f32_e32 v102, 0xbfb8aa3b, v97
	v_rcp_f32_e32 v103, v103
	v_exp_f32_e32 v102, v102
	v_add_f32_e32 v123, 1.0, v123
	v_rcp_f32_e32 v123, v123
	v_mul_f32_e32 v96, v96, v103
	v_lshlrev_b32_e32 v103, 16, v154
	v_add_f32_e32 v102, 1.0, v102
	v_mul_f32_e32 v96, v96, v103
	v_rcp_f32_e32 v102, v102
	v_mul_f32_e32 v103, 0xbfb8aa3b, v98
	v_exp_f32_e32 v103, v103
	v_mul_f32_e32 v96, v96, v117
	v_mul_f32_e32 v97, v97, v102
	v_and_b32_e32 v102, 0xffff0000, v154
	v_mul_f32_e32 v97, v97, v102
	v_add_f32_e32 v102, 1.0, v103
	v_rcp_f32_e32 v103, v102
	v_mul_f32_e32 v102, 0xbfb8aa3b, v99
	v_exp_f32_e32 v104, v102
	v_mul_f32_e32 v97, v97, v117
	v_cvt_pk_bf16_f32 v102, v96, v97
	v_mul_f32_e32 v96, v98, v103
	v_add_f32_e32 v97, 1.0, v104
	v_rcp_f32_e32 v97, v97
	v_lshlrev_b32_e32 v98, 16, v155
	v_mul_f32_e32 v96, v96, v98
	v_and_b32_e32 v98, 0xffff0000, v155
	v_mul_f32_e32 v97, v99, v97
	v_mul_f32_e32 v99, 0xbfb8aa3b, v93
	v_exp_f32_e32 v99, v99
	v_mul_f32_e32 v97, v97, v98
	v_mul_f32_e32 v96, v96, v117
	v_mul_f32_e32 v97, v97, v117
	v_cvt_pk_bf16_f32 v103, v96, v97
	global_store_dwordx4 v[114:115], v[100:103], off offset:256
	v_add_f32_e32 v99, 1.0, v99
	v_rcp_f32_e32 v99, v99
	v_mul_f32_e32 v100, 0xbfb8aa3b, v94
	v_exp_f32_e32 v100, v100
	v_mul_f32_e32 v98, 0xbfb8aa3b, v92
	v_mul_f32_e32 v93, v93, v99
	v_exp_f32_e32 v98, v98
	v_add_f32_e32 v99, 1.0, v100
	v_mul_f32_e32 v100, 0xbfb8aa3b, v95
	v_rcp_f32_e32 v99, v99
	v_exp_f32_e32 v100, v100
	v_add_f32_e32 v98, 1.0, v98
	v_rcp_f32_e32 v98, v98
	v_mul_f32_e32 v94, v94, v99
	v_add_f32_e32 v99, 1.0, v100
	v_mul_f32_e32 v100, 0xbfb8aa3b, v88
	v_rcp_f32_e32 v99, v99
	v_exp_f32_e32 v100, v100
	v_mul_f32_e32 v92, v92, v98
	v_lshlrev_b32_e32 v98, 16, v148
	v_mul_f32_e32 v95, v95, v99
	v_add_f32_e32 v99, 1.0, v100
	v_mul_f32_e32 v100, 0xbfb8aa3b, v89
	v_rcp_f32_e32 v99, v99
	v_exp_f32_e32 v100, v100
	v_mul_f32_e32 v92, v92, v98
	v_and_b32_e32 v98, 0xffff0000, v148
	v_mul_f32_e32 v88, v88, v99
	v_add_f32_e32 v99, 1.0, v100
	v_mul_f32_e32 v100, 0xbfb8aa3b, v90
	v_rcp_f32_e32 v99, v99
	v_exp_f32_e32 v100, v100
	v_mul_f32_e32 v93, v93, v98
	v_lshlrev_b32_e32 v98, 16, v149
	v_mul_f32_e32 v89, v89, v99
	v_add_f32_e32 v99, 1.0, v100
	v_mul_f32_e32 v100, 0xbfb8aa3b, v91
	v_rcp_f32_e32 v99, v99
	v_exp_f32_e32 v100, v100
	v_mul_f32_e32 v94, v94, v98
	v_and_b32_e32 v98, 0xffff0000, v149
	v_mul_f32_e32 v90, v90, v99
	v_add_f32_e32 v99, 1.0, v100
	v_mul_f32_e32 v100, 0xbfb8aa3b, v84
	v_rcp_f32_e32 v99, v99
	v_exp_f32_e32 v100, v100
	v_mul_f32_e32 v95, v95, v98
	v_lshlrev_b32_e32 v98, 16, v150
	v_mul_f32_e32 v91, v91, v99
	v_add_f32_e32 v99, 1.0, v100
	v_mul_f32_e32 v100, 0xbfb8aa3b, v85
	v_rcp_f32_e32 v99, v99
	v_exp_f32_e32 v100, v100
	v_mul_f32_e32 v88, v88, v98
	v_and_b32_e32 v98, 0xffff0000, v150
	v_mul_f32_e32 v84, v84, v99
	v_add_f32_e32 v99, 1.0, v100
	v_mul_f32_e32 v100, 0xbfb8aa3b, v86
	v_rcp_f32_e32 v99, v99
	v_exp_f32_e32 v100, v100
	v_mul_f32_e32 v89, v89, v98
	v_lshlrev_b32_e32 v98, 16, v151
	v_mul_f32_e32 v90, v90, v98
	v_and_b32_e32 v98, 0xffff0000, v151
	v_mul_f32_e32 v91, v91, v98
	v_lshlrev_b32_e32 v98, 16, v140
	v_mul_f32_e32 v98, v84, v98
	v_mul_f32_e32 v84, v85, v99
	v_add_f32_e32 v99, 1.0, v100
	v_mul_f32_e32 v100, 0xbfb8aa3b, v87
	v_rcp_f32_e32 v99, v99
	v_exp_f32_e32 v100, v100
	v_and_b32_e32 v85, 0xffff0000, v140
	v_mul_f32_e32 v101, v84, v85
	v_mul_f32_e32 v84, v86, v99
	v_add_f32_e32 v86, 1.0, v100
	v_rcp_f32_e32 v86, v86
	v_mul_f32_e32 v99, 0xbfb8aa3b, v80
	v_exp_f32_e32 v99, v99
	v_lshlrev_b32_e32 v85, 16, v141
	v_mul_f32_e32 v100, v84, v85
	v_mul_f32_e32 v84, v87, v86
	v_mul_f32_e32 v87, 0xbfb8aa3b, v81
	v_add_f32_e32 v86, 1.0, v99
	v_exp_f32_e32 v87, v87
	v_rcp_f32_e32 v86, v86
	v_and_b32_e32 v85, 0xffff0000, v141
	v_mul_f32_e32 v99, v84, v85
	v_add_f32_e32 v85, 1.0, v87
	v_mul_f32_e32 v80, v80, v86
	v_rcp_f32_e32 v85, v85
	v_mul_f32_e32 v86, 0xbfb8aa3b, v82
	v_exp_f32_e32 v86, v86
	v_lshlrev_b32_e32 v84, 16, v142
	v_mul_f32_e32 v87, v80, v84
	v_mul_f32_e32 v80, v81, v85
	v_and_b32_e32 v81, 0xffff0000, v142
	v_add_f32_e32 v84, 1.0, v86
	v_mul_f32_e32 v86, v80, v81
	v_mul_f32_e32 v80, 0xbfb8aa3b, v83
	v_rcp_f32_e32 v84, v84
	v_exp_f32_e32 v80, v80
	v_mov_b32_e32 v85, v138
	v_mov_b32_e32 v138, v147
	v_mul_f32_e32 v81, v82, v84
	v_lshlrev_b32_e32 v82, 16, v143
	v_add_f32_e32 v80, 1.0, v80
	v_mul_f32_e32 v102, v81, v82
	v_rcp_f32_e32 v82, v80
	v_mov_b32_e32 v80, v144
	v_mov_b32_e32 v81, v136
	v_mov_b32_e32 v136, v145
	v_pk_add_f32 v[80:81], v[80:81], v[136:137]
	v_mov_b32_e32 v84, v146
	v_pk_add_f32 v[80:81], v[84:85], v[80:81]
	v_lshl_add_u64 v[96:97], s[2:3], 0, v[178:179]
	v_pk_add_f32 v[80:81], v[138:139], v[80:81]
	v_lshl_add_u64 v[96:97], v[96:97], 0, v[170:171]
	v_pk_fma_f32 v[84:85], v[80:81], s[14:15], v[112:113] op_sel_hi:[1,0,0]
	v_mul_f32_e32 v81, v83, v82
	v_mul_f32_e32 v80, 0x4b800000, v85
	v_cmp_gt_f32_e32 vcc, s5, v85
	v_and_b32_e32 v82, 0xffff0000, v143
	v_exp_f32_e32 v124, v124
	v_cndmask_b32_e32 v80, v85, v80, vcc
	v_rsq_f32_e32 v80, v80
	v_mul_f32_e32 v85, v81, v82
	v_mul_f32_e32 v61, v61, v123
	v_mul_f32_e32 v123, 0xbfb8aa3b, v63
	v_mul_f32_e32 v81, 0x45800000, v80
	v_cndmask_b32_e32 v103, v80, v81, vcc
	v_mul_f32_e32 v80, v92, v103
	v_mul_f32_e32 v81, v93, v103
	v_cvt_pk_bf16_f32 v80, v80, v81
	v_mul_f32_e32 v81, v94, v103
	v_mul_f32_e32 v82, v95, v103
	v_cvt_pk_bf16_f32 v81, v81, v82
	v_mul_f32_e32 v82, v88, v103
	v_mul_f32_e32 v83, v89, v103
	v_cvt_pk_bf16_f32 v82, v82, v83
	v_mul_f32_e32 v83, v90, v103
	v_mul_f32_e32 v88, v91, v103
	v_cvt_pk_bf16_f32 v83, v83, v88
	global_store_dwordx4 v[96:97], v[80:83], off
	v_mul_f32_e32 v85, v85, v103
	v_cmp_gt_f32_e32 vcc, s5, v84
	v_mul_f32_e32 v80, v98, v103
	v_mul_f32_e32 v81, v101, v103
	v_cvt_pk_bf16_f32 v80, v80, v81
	v_mul_f32_e32 v81, v100, v103
	v_mul_f32_e32 v82, v99, v103
	v_cvt_pk_bf16_f32 v81, v81, v82
	v_mul_f32_e32 v82, v87, v103
	v_mul_f32_e32 v83, v86, v103
	v_cvt_pk_bf16_f32 v82, v82, v83
	v_mul_f32_e32 v83, v102, v103
	v_cvt_pk_bf16_f32 v83, v83, v85
	v_mul_f32_e32 v85, 0x4b800000, v84
	v_cndmask_b32_e32 v84, v84, v85, vcc
	global_store_dwordx4 v[96:97], v[80:83], off offset:256
	v_rsq_f32_e32 v84, v84
	v_exp_f32_e32 v123, v123
	v_mul_f32_e32 v80, 0xbfb8aa3b, v76
	v_exp_f32_e32 v82, v80
	v_mul_f32_e32 v80, 0x45800000, v84
	v_cndmask_b32_e32 v83, v84, v80, vcc
	v_mul_f32_e32 v84, 0xbfb8aa3b, v77
	v_add_f32_e32 v82, 1.0, v82
	v_rcp_f32_e32 v82, v82
	v_exp_f32_e32 v84, v84
	v_lshl_add_u64 v[80:81], s[2:3], 0, v[176:177]
	v_lshl_add_u64 v[80:81], v[80:81], 0, v[170:171]
	v_mul_f32_e32 v76, v76, v82
	v_lshlrev_b32_e32 v82, 16, v132
	v_mul_f32_e32 v76, v76, v82
	v_add_f32_e32 v82, 1.0, v84
	v_rcp_f32_e32 v82, v82
	v_mul_f32_e32 v84, 0xbfb8aa3b, v78
	v_exp_f32_e32 v84, v84
	v_mul_f32_e32 v76, v76, v83
	v_mul_f32_e32 v77, v77, v82
	v_and_b32_e32 v82, 0xffff0000, v132
	v_mul_f32_e32 v77, v77, v82
	v_add_f32_e32 v82, 1.0, v84
	v_mul_f32_e32 v84, 0xbfb8aa3b, v79
	v_rcp_f32_e32 v82, v82
	v_exp_f32_e32 v84, v84
	v_mul_f32_e32 v77, v77, v83
	v_cvt_pk_bf16_f32 v76, v76, v77
	v_mul_f32_e32 v77, v78, v82
	v_add_f32_e32 v78, 1.0, v84
	v_rcp_f32_e32 v78, v78
	v_lshlrev_b32_e32 v82, 16, v133
	v_mul_f32_e32 v77, v77, v82
	v_and_b32_e32 v82, 0xffff0000, v133
	v_mul_f32_e32 v78, v79, v78
	v_mul_f32_e32 v79, 0xbfb8aa3b, v72
	v_exp_f32_e32 v79, v79
	v_mul_f32_e32 v78, v78, v82
	v_mul_f32_e32 v77, v77, v83
	v_mul_f32_e32 v78, v78, v83
	v_add_f32_e32 v79, 1.0, v79
	v_cvt_pk_bf16_f32 v77, v77, v78
	v_mul_f32_e32 v78, 0xbfb8aa3b, v73
	v_rcp_f32_e32 v79, v79
	v_exp_f32_e32 v78, v78
	v_mul_f32_e32 v72, v72, v79
	v_lshlrev_b32_e32 v79, 16, v134
	v_add_f32_e32 v78, 1.0, v78
	v_mul_f32_e32 v72, v72, v79
	v_rcp_f32_e32 v78, v78
	v_mul_f32_e32 v79, 0xbfb8aa3b, v74
	v_exp_f32_e32 v79, v79
	v_mul_f32_e32 v72, v72, v83
	v_mul_f32_e32 v73, v73, v78
	v_and_b32_e32 v78, 0xffff0000, v134
	v_mul_f32_e32 v73, v73, v78
	v_add_f32_e32 v78, 1.0, v79
	v_rcp_f32_e32 v79, v78
	v_mul_f32_e32 v78, 0xbfb8aa3b, v75
	v_exp_f32_e32 v82, v78
	v_mul_f32_e32 v73, v73, v83
	v_cvt_pk_bf16_f32 v78, v72, v73
	v_mul_f32_e32 v72, v74, v79
	v_add_f32_e32 v73, 1.0, v82
	v_rcp_f32_e32 v73, v73
	v_lshlrev_b32_e32 v74, 16, v135
	v_mul_f32_e32 v72, v72, v74
	v_and_b32_e32 v74, 0xffff0000, v135
	v_mul_f32_e32 v73, v75, v73
	v_mul_f32_e32 v75, 0xbfb8aa3b, v68
	v_exp_f32_e32 v75, v75
	v_mul_f32_e32 v72, v72, v83
	v_mul_f32_e32 v73, v73, v74
	v_mul_f32_e32 v73, v73, v83
	v_cvt_pk_bf16_f32 v79, v72, v73
	v_add_f32_e32 v72, 1.0, v75
	v_rcp_f32_e32 v72, v72
	v_mul_f32_e32 v73, 0xbfb8aa3b, v69
	v_exp_f32_e32 v73, v73
	global_store_dwordx4 v[80:81], v[76:79], off
	v_mul_f32_e32 v68, v68, v72
	v_lshlrev_b32_e32 v72, 16, v128
	v_mul_f32_e32 v68, v68, v72
	v_add_f32_e32 v72, 1.0, v73
	v_rcp_f32_e32 v72, v72
	v_mul_f32_e32 v73, 0xbfb8aa3b, v70
	v_exp_f32_e32 v73, v73
	v_mul_f32_e32 v68, v68, v83
	v_mul_f32_e32 v69, v69, v72
	v_and_b32_e32 v72, 0xffff0000, v128
	v_mul_f32_e32 v69, v69, v72
	v_add_f32_e32 v72, 1.0, v73
	v_mul_f32_e32 v73, 0xbfb8aa3b, v71
	v_rcp_f32_e32 v72, v72
	v_exp_f32_e32 v73, v73
	v_mul_f32_e32 v69, v69, v83
	v_cvt_pk_bf16_f32 v68, v68, v69
	v_mul_f32_e32 v69, v70, v72
	v_add_f32_e32 v70, 1.0, v73
	v_rcp_f32_e32 v70, v70
	v_lshlrev_b32_e32 v72, 16, v129
	v_mul_f32_e32 v69, v69, v72
	v_and_b32_e32 v72, 0xffff0000, v129
	v_mul_f32_e32 v70, v71, v70
	v_mul_f32_e32 v71, 0xbfb8aa3b, v64
	v_exp_f32_e32 v71, v71
	v_mul_f32_e32 v70, v70, v72
	v_mul_f32_e32 v69, v69, v83
	v_mul_f32_e32 v70, v70, v83
	v_add_f32_e32 v71, 1.0, v71
	v_cvt_pk_bf16_f32 v69, v69, v70
	v_mul_f32_e32 v70, 0xbfb8aa3b, v65
	v_rcp_f32_e32 v71, v71
	v_exp_f32_e32 v70, v70
	v_mul_f32_e32 v64, v64, v71
	v_lshlrev_b32_e32 v71, 16, v130
	v_add_f32_e32 v70, 1.0, v70
	v_mul_f32_e32 v64, v64, v71
	v_rcp_f32_e32 v70, v70
	v_mul_f32_e32 v71, 0xbfb8aa3b, v66
	v_exp_f32_e32 v71, v71
	v_mul_f32_e32 v64, v64, v83
	v_mul_f32_e32 v65, v65, v70
	v_and_b32_e32 v70, 0xffff0000, v130
	v_mul_f32_e32 v65, v65, v70
	v_add_f32_e32 v70, 1.0, v71
	v_rcp_f32_e32 v71, v70
	v_mul_f32_e32 v70, 0xbfb8aa3b, v67
	v_exp_f32_e32 v72, v70
	v_mul_f32_e32 v65, v65, v83
	v_cvt_pk_bf16_f32 v70, v64, v65
	v_mul_f32_e32 v64, v66, v71
	v_add_f32_e32 v65, 1.0, v72
	v_rcp_f32_e32 v65, v65
	v_lshlrev_b32_e32 v66, 16, v131
	v_mul_f32_e32 v64, v64, v66
	v_and_b32_e32 v66, 0xffff0000, v131
	v_mul_f32_e32 v65, v67, v65
	v_mul_f32_e32 v64, v64, v83
	v_mul_f32_e32 v65, v65, v66
	v_mul_f32_e32 v65, v65, v83
	v_cvt_pk_bf16_f32 v71, v64, v65
	v_add_u32_e32 v64, 0x80, v172
	v_ashrrev_i32_e32 v65, 31, v64
	v_lshlrev_b64 v[110:111], 13, v[64:65]
	v_lshl_add_u64 v[66:67], v[174:175], 0, v[110:111]
	global_load_dwordx4 v[102:105], v[66:67], off
	v_lshlrev_b64 v[64:65], 7, v[64:65]
	global_store_dwordx4 v[80:81], v[68:71], off offset:256
	v_lshl_add_u64 v[64:65], s[12:13], 0, v[64:65]
	global_load_dwordx4 v[106:109], v[64:65], off
	v_add_u32_e32 v64, 0x90, v172
	v_ashrrev_i32_e32 v65, 31, v64
	v_lshlrev_b64 v[68:69], 7, v[64:65]
	v_lshl_add_u64 v[68:69], s[12:13], 0, v[68:69]
	global_load_dwordx4 v[114:117], v[66:67], off offset:256
	global_load_dwordx4 v[118:121], v[68:69], off
	v_lshlrev_b64 v[100:101], 13, v[64:65]
	v_lshl_add_u64 v[64:65], v[174:175], 0, v[100:101]
	global_load_dwordx4 v[92:95], v[64:65], off
	global_load_dwordx4 v[88:91], v[64:65], off offset:256
	v_add_u32_e32 v64, 0xa0, v172
	v_ashrrev_i32_e32 v65, 31, v64
	v_lshlrev_b64 v[66:67], 7, v[64:65]
	v_lshl_add_u64 v[66:67], s[12:13], 0, v[66:67]
	v_lshlrev_b64 v[98:99], 13, v[64:65]
	v_lshl_add_u64 v[64:65], v[174:175], 0, v[98:99]
	global_load_dwordx4 v[72:75], v[66:67], off
	global_load_dwordx4 v[84:87], v[64:65], off
	v_add_u32_e32 v66, 0xb0, v172
	v_ashrrev_i32_e32 v67, 31, v66
	v_lshlrev_b64 v[68:69], 7, v[66:67]
	v_lshlrev_b64 v[96:97], 13, v[66:67]
	v_mul_f32_e32 v66, 0xbfb8aa3b, v60
	v_exp_f32_e32 v122, v66
	v_lshl_add_u64 v[68:69], s[12:13], 0, v[68:69]
	global_load_dwordx4 v[76:79], v[64:65], off offset:256
	global_load_dwordx4 v[80:83], v[68:69], off
	v_lshl_add_u64 v[64:65], v[174:175], 0, v[96:97]
	v_add_f32_e32 v122, 1.0, v122
	v_rcp_f32_e32 v122, v122
	global_load_dwordx4 v[68:71], v[64:65], off
	s_nop 0
	global_load_dwordx4 v[64:67], v[64:65], off offset:256
	v_lshl_add_u64 v[110:111], s[2:3], 0, v[110:111]
	v_lshl_add_u64 v[110:111], v[110:111], 0, v[170:171]
	v_mul_f32_e32 v60, v60, v122
	s_mov_b32 s13, s4
	s_mov_b32 s12, s6
	s_waitcnt vmcnt(0)
	v_lshlrev_b32_e32 v122, 16, v102
	v_mul_f32_e32 v60, v60, v122
	v_add_f32_e32 v122, 1.0, v124
	v_rcp_f32_e32 v122, v122
	v_and_b32_e32 v102, 0xffff0000, v102
	v_mul_f32_e32 v61, v61, v102
	v_lshlrev_b32_e32 v102, 16, v103
	v_mul_f32_e32 v62, v62, v122
	v_add_f32_e32 v122, 1.0, v123
	v_mul_f32_e32 v123, 0xbfb8aa3b, v56
	v_rcp_f32_e32 v122, v122
	v_exp_f32_e32 v123, v123
	v_mul_f32_e32 v62, v62, v102
	v_and_b32_e32 v102, 0xffff0000, v103
	v_mul_f32_e32 v63, v63, v122
	v_add_f32_e32 v103, 1.0, v123
	v_mul_f32_e32 v122, 0xbfb8aa3b, v57
	v_rcp_f32_e32 v103, v103
	v_exp_f32_e32 v122, v122
	v_mul_f32_e32 v63, v63, v102
	v_lshlrev_b32_e32 v102, 16, v104
	v_mul_f32_e32 v56, v56, v103
	v_add_f32_e32 v103, 1.0, v122
	v_mul_f32_e32 v122, 0xbfb8aa3b, v58
	v_rcp_f32_e32 v103, v103
	v_exp_f32_e32 v122, v122
	v_mul_f32_e32 v56, v56, v102
	v_and_b32_e32 v102, 0xffff0000, v104
	v_mul_f32_e32 v57, v57, v103
	v_add_f32_e32 v103, 1.0, v122
	v_mul_f32_e32 v104, 0xbfb8aa3b, v59
	v_rcp_f32_e32 v103, v103
	v_exp_f32_e32 v104, v104
	v_mul_f32_e32 v57, v57, v102
	v_lshlrev_b32_e32 v102, 16, v105
	v_mul_f32_e32 v58, v58, v103
	v_add_f32_e32 v103, 1.0, v104
	v_mul_f32_e32 v104, 0xbfb8aa3b, v52
	v_rcp_f32_e32 v103, v103
	v_exp_f32_e32 v104, v104
	v_mul_f32_e32 v58, v58, v102
	v_and_b32_e32 v102, 0xffff0000, v105
	v_mul_f32_e32 v59, v59, v103
	v_add_f32_e32 v103, 1.0, v104
	v_mul_f32_e32 v104, 0xbfb8aa3b, v53
	v_rcp_f32_e32 v103, v103
	v_exp_f32_e32 v104, v104
	v_mul_f32_e32 v59, v59, v102
	v_lshlrev_b32_e32 v102, 16, v114
	v_mul_f32_e32 v52, v52, v103
	v_add_f32_e32 v103, 1.0, v104
	v_mul_f32_e32 v104, 0xbfb8aa3b, v54
	v_rcp_f32_e32 v103, v103
	v_exp_f32_e32 v104, v104
	v_mul_f32_e32 v102, v52, v102
	v_mul_f32_e32 v52, v53, v103
	v_add_f32_e32 v103, 1.0, v104
	v_mul_f32_e32 v104, 0xbfb8aa3b, v55
	v_rcp_f32_e32 v103, v103
	v_exp_f32_e32 v104, v104
	v_and_b32_e32 v53, 0xffff0000, v114
	v_mul_f32_e32 v105, v52, v53
	v_mul_f32_e32 v52, v54, v103
	v_add_f32_e32 v54, 1.0, v104
	v_rcp_f32_e32 v54, v54
	v_mul_f32_e32 v103, 0xbfb8aa3b, v48
	v_exp_f32_e32 v103, v103
	v_lshlrev_b32_e32 v53, 16, v115
	v_mul_f32_e32 v104, v52, v53
	v_mul_f32_e32 v52, v55, v54
	v_mul_f32_e32 v55, 0xbfb8aa3b, v49
	v_add_f32_e32 v54, 1.0, v103
	v_exp_f32_e32 v55, v55
	v_rcp_f32_e32 v54, v54
	v_and_b32_e32 v53, 0xffff0000, v115
	v_mul_f32_e32 v103, v52, v53
	v_add_f32_e32 v53, 1.0, v55
	v_mul_f32_e32 v48, v48, v54
	v_rcp_f32_e32 v53, v53
	v_mul_f32_e32 v54, 0xbfb8aa3b, v50
	v_exp_f32_e32 v54, v54
	v_lshlrev_b32_e32 v52, 16, v116
	v_mul_f32_e32 v55, v48, v52
	v_mul_f32_e32 v48, v49, v53
	v_and_b32_e32 v49, 0xffff0000, v116
	v_add_f32_e32 v52, 1.0, v54
	v_mul_f32_e32 v54, v48, v49
	v_mul_f32_e32 v48, 0xbfb8aa3b, v51
	v_rcp_f32_e32 v52, v52
	v_exp_f32_e32 v48, v48
	v_mov_b32_e32 v53, v108
	v_mov_b32_e32 v108, v121
	v_mul_f32_e32 v49, v50, v52
	v_lshlrev_b32_e32 v50, 16, v117
	v_add_f32_e32 v48, 1.0, v48
	v_mul_f32_e32 v114, v49, v50
	v_rcp_f32_e32 v50, v48
	v_mov_b32_e32 v48, v118
	v_mov_b32_e32 v49, v106
	v_mov_b32_e32 v106, v119
	v_pk_add_f32 v[48:49], v[48:49], v[106:107]
	v_mov_b32_e32 v52, v120
	v_pk_add_f32 v[48:49], v[52:53], v[48:49]
	s_nop 0
	v_pk_add_f32 v[48:49], v[108:109], v[48:49]
	s_nop 0
	v_pk_fma_f32 v[52:53], v[48:49], s[14:15], v[112:113] op_sel_hi:[1,0,0]
	v_mul_f32_e32 v49, v51, v50
	v_mul_f32_e32 v48, 0x4b800000, v53
	v_cmp_gt_f32_e32 vcc, s5, v53
	v_and_b32_e32 v50, 0xffff0000, v117
	s_nop 0
	v_cndmask_b32_e32 v48, v53, v48, vcc
	v_rsq_f32_e32 v48, v48
	v_mul_f32_e32 v53, v49, v50
	v_mul_f32_e32 v49, 0x45800000, v48
	v_cndmask_b32_e32 v106, v48, v49, vcc
	v_mul_f32_e32 v48, v60, v106
	v_mul_f32_e32 v49, v61, v106
	v_cvt_pk_bf16_f32 v48, v48, v49
	v_mul_f32_e32 v49, v62, v106
	v_mul_f32_e32 v50, v63, v106
	v_cvt_pk_bf16_f32 v49, v49, v50
	v_mul_f32_e32 v50, v56, v106
	v_mul_f32_e32 v51, v57, v106
	v_cvt_pk_bf16_f32 v50, v50, v51
	v_mul_f32_e32 v51, v58, v106
	v_mul_f32_e32 v56, v59, v106
	v_cvt_pk_bf16_f32 v51, v51, v56
	global_store_dwordx4 v[110:111], v[48:51], off
	v_mul_f32_e32 v53, v53, v106
	v_cmp_gt_f32_e32 vcc, s5, v52
	v_mul_f32_e32 v48, v102, v106
	v_mul_f32_e32 v49, v105, v106
	v_cvt_pk_bf16_f32 v48, v48, v49
	v_mul_f32_e32 v49, v104, v106
	v_mul_f32_e32 v50, v103, v106
	v_cvt_pk_bf16_f32 v49, v49, v50
	v_mul_f32_e32 v50, v55, v106
	v_mul_f32_e32 v51, v54, v106
	v_cvt_pk_bf16_f32 v50, v50, v51
	v_mul_f32_e32 v51, v114, v106
	v_cvt_pk_bf16_f32 v51, v51, v53
	v_mul_f32_e32 v53, 0x4b800000, v52
	v_cndmask_b32_e32 v52, v52, v53, vcc
	global_store_dwordx4 v[110:111], v[48:51], off offset:256
	v_rsq_f32_e32 v52, v52
	s_nop 0
	v_mul_f32_e32 v48, 0xbfb8aa3b, v44
	v_exp_f32_e32 v50, v48
	v_mul_f32_e32 v48, 0x45800000, v52
	v_cndmask_b32_e32 v51, v52, v48, vcc
	v_mul_f32_e32 v52, 0xbfb8aa3b, v45
	v_add_f32_e32 v50, 1.0, v50
	v_rcp_f32_e32 v50, v50
	v_exp_f32_e32 v52, v52
	v_lshl_add_u64 v[48:49], s[2:3], 0, v[100:101]
	v_lshl_add_u64 v[48:49], v[48:49], 0, v[170:171]
	v_mul_f32_e32 v44, v44, v50
	v_lshlrev_b32_e32 v50, 16, v92
	v_mul_f32_e32 v44, v44, v50
	v_add_f32_e32 v50, 1.0, v52
	v_rcp_f32_e32 v50, v50
	v_mul_f32_e32 v52, 0xbfb8aa3b, v46
	v_exp_f32_e32 v52, v52
	v_mul_f32_e32 v44, v44, v51
	v_mul_f32_e32 v45, v45, v50
	v_and_b32_e32 v50, 0xffff0000, v92
	v_mul_f32_e32 v45, v45, v50
	v_add_f32_e32 v50, 1.0, v52
	v_mul_f32_e32 v52, 0xbfb8aa3b, v47
	v_rcp_f32_e32 v50, v50
	v_exp_f32_e32 v52, v52
	v_mul_f32_e32 v45, v45, v51
	v_cvt_pk_bf16_f32 v44, v44, v45
	v_mul_f32_e32 v45, v46, v50
	v_add_f32_e32 v46, 1.0, v52
	v_rcp_f32_e32 v46, v46
	v_lshlrev_b32_e32 v50, 16, v93
	v_mul_f32_e32 v45, v45, v50
	v_and_b32_e32 v50, 0xffff0000, v93
	v_mul_f32_e32 v46, v47, v46
	v_mul_f32_e32 v47, 0xbfb8aa3b, v40
	v_exp_f32_e32 v47, v47
	v_mul_f32_e32 v46, v46, v50
	v_mul_f32_e32 v45, v45, v51
	v_mul_f32_e32 v46, v46, v51
	v_add_f32_e32 v47, 1.0, v47
	v_cvt_pk_bf16_f32 v45, v45, v46
	v_mul_f32_e32 v46, 0xbfb8aa3b, v41
	v_rcp_f32_e32 v47, v47
	v_exp_f32_e32 v46, v46
	v_mul_f32_e32 v40, v40, v47
	v_lshlrev_b32_e32 v47, 16, v94
	v_add_f32_e32 v46, 1.0, v46
	v_mul_f32_e32 v40, v40, v47
	v_rcp_f32_e32 v46, v46
	v_mul_f32_e32 v47, 0xbfb8aa3b, v42
	v_exp_f32_e32 v47, v47
	v_mul_f32_e32 v40, v40, v51
	v_mul_f32_e32 v41, v41, v46
	v_and_b32_e32 v46, 0xffff0000, v94
	v_mul_f32_e32 v41, v41, v46
	v_add_f32_e32 v46, 1.0, v47
	v_rcp_f32_e32 v47, v46
	v_mul_f32_e32 v46, 0xbfb8aa3b, v43
	v_exp_f32_e32 v50, v46
	v_mul_f32_e32 v41, v41, v51
	v_cvt_pk_bf16_f32 v46, v40, v41
	v_mul_f32_e32 v40, v42, v47
	v_add_f32_e32 v41, 1.0, v50
	v_rcp_f32_e32 v41, v41
	v_lshlrev_b32_e32 v42, 16, v95
	v_mul_f32_e32 v40, v40, v42
	v_and_b32_e32 v42, 0xffff0000, v95
	v_mul_f32_e32 v41, v43, v41
	v_mul_f32_e32 v43, 0xbfb8aa3b, v36
	v_exp_f32_e32 v43, v43
	v_mul_f32_e32 v40, v40, v51
	v_mul_f32_e32 v41, v41, v42
	v_mul_f32_e32 v41, v41, v51
	v_cvt_pk_bf16_f32 v47, v40, v41
	v_add_f32_e32 v40, 1.0, v43
	v_rcp_f32_e32 v40, v40
	v_mul_f32_e32 v41, 0xbfb8aa3b, v37
	v_exp_f32_e32 v41, v41
	global_store_dwordx4 v[48:49], v[44:47], off
	v_mul_f32_e32 v36, v36, v40
	v_lshlrev_b32_e32 v40, 16, v88
	v_mul_f32_e32 v36, v36, v40
	v_add_f32_e32 v40, 1.0, v41
	v_rcp_f32_e32 v40, v40
	v_mul_f32_e32 v41, 0xbfb8aa3b, v38
	v_exp_f32_e32 v41, v41
	v_mul_f32_e32 v36, v36, v51
	v_mul_f32_e32 v37, v37, v40
	v_and_b32_e32 v40, 0xffff0000, v88
	v_mul_f32_e32 v37, v37, v40
	v_add_f32_e32 v40, 1.0, v41
	v_mul_f32_e32 v41, 0xbfb8aa3b, v39
	v_rcp_f32_e32 v40, v40
	v_exp_f32_e32 v41, v41
	v_mul_f32_e32 v37, v37, v51
	v_cvt_pk_bf16_f32 v36, v36, v37
	v_mul_f32_e32 v37, v38, v40
	v_add_f32_e32 v38, 1.0, v41
	v_rcp_f32_e32 v38, v38
	v_lshlrev_b32_e32 v40, 16, v89
	v_mul_f32_e32 v37, v37, v40
	v_and_b32_e32 v40, 0xffff0000, v89
	v_mul_f32_e32 v38, v39, v38
	v_mul_f32_e32 v39, 0xbfb8aa3b, v32
	v_exp_f32_e32 v39, v39
	v_mul_f32_e32 v38, v38, v40
	v_mul_f32_e32 v37, v37, v51
	v_mul_f32_e32 v38, v38, v51
	v_add_f32_e32 v39, 1.0, v39
	v_cvt_pk_bf16_f32 v37, v37, v38
	v_mul_f32_e32 v38, 0xbfb8aa3b, v33
	v_rcp_f32_e32 v39, v39
	v_exp_f32_e32 v38, v38
	v_mul_f32_e32 v32, v32, v39
	v_lshlrev_b32_e32 v39, 16, v90
	v_add_f32_e32 v38, 1.0, v38
	v_mul_f32_e32 v32, v32, v39
	v_rcp_f32_e32 v38, v38
	v_mul_f32_e32 v39, 0xbfb8aa3b, v34
	v_exp_f32_e32 v39, v39
	v_mul_f32_e32 v32, v32, v51
	v_mul_f32_e32 v33, v33, v38
	v_and_b32_e32 v38, 0xffff0000, v90
	v_mul_f32_e32 v33, v33, v38
	v_add_f32_e32 v38, 1.0, v39
	v_rcp_f32_e32 v39, v38
	v_mul_f32_e32 v38, 0xbfb8aa3b, v35
	v_exp_f32_e32 v40, v38
	v_mul_f32_e32 v33, v33, v51
	v_cvt_pk_bf16_f32 v38, v32, v33
	v_mul_f32_e32 v32, v34, v39
	v_add_f32_e32 v33, 1.0, v40
	v_rcp_f32_e32 v33, v33
	v_lshlrev_b32_e32 v34, 16, v91
	v_mul_f32_e32 v32, v32, v34
	v_and_b32_e32 v34, 0xffff0000, v91
	v_mul_f32_e32 v33, v35, v33
	v_mul_f32_e32 v35, 0xbfb8aa3b, v29
	v_exp_f32_e32 v35, v35
	v_mul_f32_e32 v33, v33, v34
	v_mul_f32_e32 v32, v32, v51
	v_mul_f32_e32 v33, v33, v51
	v_cvt_pk_bf16_f32 v39, v32, v33
	global_store_dwordx4 v[48:49], v[36:39], off offset:256
	v_add_f32_e32 v35, 1.0, v35
	v_rcp_f32_e32 v35, v35
	v_mul_f32_e32 v36, 0xbfb8aa3b, v30
	v_exp_f32_e32 v36, v36
	v_mul_f32_e32 v34, 0xbfb8aa3b, v28
	v_mul_f32_e32 v29, v29, v35
	v_exp_f32_e32 v34, v34
	v_add_f32_e32 v35, 1.0, v36
	v_mul_f32_e32 v36, 0xbfb8aa3b, v31
	v_rcp_f32_e32 v35, v35
	v_exp_f32_e32 v36, v36
	v_add_f32_e32 v34, 1.0, v34
	v_rcp_f32_e32 v34, v34
	v_mul_f32_e32 v30, v30, v35
	v_add_f32_e32 v35, 1.0, v36
	v_mul_f32_e32 v36, 0xbfb8aa3b, v24
	v_rcp_f32_e32 v35, v35
	v_exp_f32_e32 v36, v36
	v_mul_f32_e32 v28, v28, v34
	v_lshlrev_b32_e32 v34, 16, v84
	v_mul_f32_e32 v31, v31, v35
	v_add_f32_e32 v35, 1.0, v36
	v_mul_f32_e32 v36, 0xbfb8aa3b, v25
	v_rcp_f32_e32 v35, v35
	v_exp_f32_e32 v36, v36
	v_mul_f32_e32 v28, v28, v34
	v_and_b32_e32 v34, 0xffff0000, v84
	v_mul_f32_e32 v24, v24, v35
	v_add_f32_e32 v35, 1.0, v36
	v_mul_f32_e32 v36, 0xbfb8aa3b, v26
	v_rcp_f32_e32 v35, v35
	v_exp_f32_e32 v36, v36
	v_mul_f32_e32 v29, v29, v34
	v_lshlrev_b32_e32 v34, 16, v85
	v_mul_f32_e32 v25, v25, v35
	v_add_f32_e32 v35, 1.0, v36
	v_mul_f32_e32 v36, 0xbfb8aa3b, v27
	v_rcp_f32_e32 v35, v35
	v_exp_f32_e32 v36, v36
	v_mul_f32_e32 v30, v30, v34
	v_and_b32_e32 v34, 0xffff0000, v85
	v_mul_f32_e32 v26, v26, v35
	v_add_f32_e32 v35, 1.0, v36
	v_mul_f32_e32 v36, 0xbfb8aa3b, v20
	v_rcp_f32_e32 v35, v35
	v_exp_f32_e32 v36, v36
	v_mul_f32_e32 v31, v31, v34
	v_lshlrev_b32_e32 v34, 16, v86
	v_mul_f32_e32 v27, v27, v35
	v_add_f32_e32 v35, 1.0, v36
	v_mul_f32_e32 v36, 0xbfb8aa3b, v21
	v_rcp_f32_e32 v35, v35
	v_exp_f32_e32 v36, v36
	v_mul_f32_e32 v24, v24, v34
	v_and_b32_e32 v34, 0xffff0000, v86
	v_mul_f32_e32 v20, v20, v35
	v_add_f32_e32 v35, 1.0, v36
	v_mul_f32_e32 v36, 0xbfb8aa3b, v22
	v_rcp_f32_e32 v35, v35
	v_exp_f32_e32 v36, v36
	v_mul_f32_e32 v25, v25, v34
	v_lshlrev_b32_e32 v34, 16, v87
	v_mul_f32_e32 v26, v26, v34
	v_and_b32_e32 v34, 0xffff0000, v87
	v_mul_f32_e32 v27, v27, v34
	v_lshlrev_b32_e32 v34, 16, v76
	v_mul_f32_e32 v34, v20, v34
	v_mul_f32_e32 v20, v21, v35
	v_add_f32_e32 v35, 1.0, v36
	v_mul_f32_e32 v36, 0xbfb8aa3b, v23
	v_rcp_f32_e32 v35, v35
	v_exp_f32_e32 v36, v36
	v_and_b32_e32 v21, 0xffff0000, v76
	v_mul_f32_e32 v37, v20, v21
	v_mul_f32_e32 v20, v22, v35
	v_add_f32_e32 v22, 1.0, v36
	v_rcp_f32_e32 v22, v22
	v_mul_f32_e32 v35, 0xbfb8aa3b, v16
	v_exp_f32_e32 v35, v35
	v_lshlrev_b32_e32 v21, 16, v77
	v_mul_f32_e32 v36, v20, v21
	v_mul_f32_e32 v20, v23, v22
	v_mul_f32_e32 v23, 0xbfb8aa3b, v17
	v_add_f32_e32 v22, 1.0, v35
	v_exp_f32_e32 v23, v23
	v_rcp_f32_e32 v22, v22
	v_and_b32_e32 v21, 0xffff0000, v77
	v_mul_f32_e32 v35, v20, v21
	v_add_f32_e32 v21, 1.0, v23
	v_mul_f32_e32 v16, v16, v22
	v_rcp_f32_e32 v21, v21
	v_mul_f32_e32 v22, 0xbfb8aa3b, v18
	v_exp_f32_e32 v22, v22
	v_lshlrev_b32_e32 v20, 16, v78
	v_mul_f32_e32 v23, v16, v20
	v_mul_f32_e32 v16, v17, v21
	v_and_b32_e32 v17, 0xffff0000, v78
	v_add_f32_e32 v20, 1.0, v22
	v_mul_f32_e32 v22, v16, v17
	v_mul_f32_e32 v16, 0xbfb8aa3b, v19
	v_rcp_f32_e32 v20, v20
	v_exp_f32_e32 v16, v16
	v_mov_b32_e32 v21, v74
	v_mov_b32_e32 v74, v83
	v_mul_f32_e32 v17, v18, v20
	v_lshlrev_b32_e32 v18, 16, v79
	v_add_f32_e32 v16, 1.0, v16
	v_mul_f32_e32 v38, v17, v18
	v_rcp_f32_e32 v18, v16
	v_mov_b32_e32 v16, v80
	v_mov_b32_e32 v17, v72
	v_mov_b32_e32 v72, v81
	v_pk_add_f32 v[16:17], v[16:17], v[72:73]
	v_mov_b32_e32 v20, v82
	v_pk_add_f32 v[16:17], v[20:21], v[16:17]
	v_lshl_add_u64 v[32:33], s[2:3], 0, v[98:99]
	v_pk_add_f32 v[16:17], v[74:75], v[16:17]
	v_lshl_add_u64 v[32:33], v[32:33], 0, v[170:171]
	v_pk_fma_f32 v[20:21], v[16:17], s[14:15], v[112:113] op_sel_hi:[1,0,0]
	v_mul_f32_e32 v17, v19, v18
	v_mul_f32_e32 v16, 0x4b800000, v21
	v_cmp_gt_f32_e32 vcc, s5, v21
	v_and_b32_e32 v18, 0xffff0000, v79
	s_mov_b64 s[14:15], s[8:9]
	v_cndmask_b32_e32 v16, v21, v16, vcc
	v_rsq_f32_e32 v16, v16
	v_mul_f32_e32 v21, v17, v18
	v_mul_f32_e32 v17, 0x45800000, v16
	v_cndmask_b32_e32 v39, v16, v17, vcc
	v_mul_f32_e32 v16, v28, v39
	v_mul_f32_e32 v17, v29, v39
	v_cvt_pk_bf16_f32 v16, v16, v17
	v_mul_f32_e32 v17, v30, v39
	v_mul_f32_e32 v18, v31, v39
	v_cvt_pk_bf16_f32 v17, v17, v18
	v_mul_f32_e32 v18, v24, v39
	v_mul_f32_e32 v19, v25, v39
	v_cvt_pk_bf16_f32 v18, v18, v19
	v_mul_f32_e32 v19, v26, v39
	v_mul_f32_e32 v24, v27, v39
	v_cvt_pk_bf16_f32 v19, v19, v24
	global_store_dwordx4 v[32:33], v[16:19], off
	v_mul_f32_e32 v21, v21, v39
	v_cmp_gt_f32_e32 vcc, s5, v20
	v_mul_f32_e32 v16, v34, v39
	v_mul_f32_e32 v17, v37, v39
	v_cvt_pk_bf16_f32 v16, v16, v17
	v_mul_f32_e32 v17, v36, v39
	v_mul_f32_e32 v18, v35, v39
	v_cvt_pk_bf16_f32 v17, v17, v18
	v_mul_f32_e32 v18, v23, v39
	v_mul_f32_e32 v19, v22, v39
	v_cvt_pk_bf16_f32 v18, v18, v19
	v_mul_f32_e32 v19, v38, v39
	v_cvt_pk_bf16_f32 v19, v19, v21
	v_mul_f32_e32 v21, 0x4b800000, v20
	v_cndmask_b32_e32 v20, v20, v21, vcc
	global_store_dwordx4 v[32:33], v[16:19], off offset:256
	v_rsq_f32_e32 v20, v20
	s_nop 0
	v_mul_f32_e32 v16, 0xbfb8aa3b, v12
	v_exp_f32_e32 v18, v16
	v_mul_f32_e32 v16, 0x45800000, v20
	v_cndmask_b32_e32 v19, v20, v16, vcc
	v_mul_f32_e32 v20, 0xbfb8aa3b, v13
	v_add_f32_e32 v18, 1.0, v18
	v_rcp_f32_e32 v18, v18
	v_exp_f32_e32 v20, v20
	v_lshl_add_u64 v[16:17], s[2:3], 0, v[96:97]
	v_lshl_add_u64 v[16:17], v[16:17], 0, v[170:171]
	v_mul_f32_e32 v12, v12, v18
	v_lshlrev_b32_e32 v18, 16, v68
	v_mul_f32_e32 v12, v12, v18
	v_add_f32_e32 v18, 1.0, v20
	v_rcp_f32_e32 v18, v18
	v_mul_f32_e32 v20, 0xbfb8aa3b, v14
	v_exp_f32_e32 v20, v20
	v_mul_f32_e32 v12, v12, v19
	v_mul_f32_e32 v13, v13, v18
	v_and_b32_e32 v18, 0xffff0000, v68
	v_mul_f32_e32 v13, v13, v18
	v_add_f32_e32 v18, 1.0, v20
	v_mul_f32_e32 v20, 0xbfb8aa3b, v15
	v_rcp_f32_e32 v18, v18
	v_exp_f32_e32 v20, v20
	v_mul_f32_e32 v13, v13, v19
	v_cvt_pk_bf16_f32 v12, v12, v13
	v_mul_f32_e32 v13, v14, v18
	v_add_f32_e32 v14, 1.0, v20
	v_rcp_f32_e32 v14, v14
	v_lshlrev_b32_e32 v18, 16, v69
	v_mul_f32_e32 v13, v13, v18
	v_and_b32_e32 v18, 0xffff0000, v69
	v_mul_f32_e32 v14, v15, v14
	v_mul_f32_e32 v15, 0xbfb8aa3b, v8
	v_exp_f32_e32 v15, v15
	v_mul_f32_e32 v14, v14, v18
	v_mul_f32_e32 v13, v13, v19
	v_mul_f32_e32 v14, v14, v19
	v_add_f32_e32 v15, 1.0, v15
	v_cvt_pk_bf16_f32 v13, v13, v14
	v_mul_f32_e32 v14, 0xbfb8aa3b, v9
	v_rcp_f32_e32 v15, v15
	v_exp_f32_e32 v14, v14
	s_and_b64 vcc, exec, s[0:1]
	v_mul_f32_e32 v8, v8, v15
	v_lshlrev_b32_e32 v15, 16, v70
	v_add_f32_e32 v14, 1.0, v14
	v_mul_f32_e32 v8, v8, v15
	v_rcp_f32_e32 v14, v14
	v_mul_f32_e32 v15, 0xbfb8aa3b, v10
	v_exp_f32_e32 v15, v15
	v_mul_f32_e32 v8, v8, v19
	v_mul_f32_e32 v9, v9, v14
	v_and_b32_e32 v14, 0xffff0000, v70
	v_mul_f32_e32 v9, v9, v14
	v_add_f32_e32 v14, 1.0, v15
	v_rcp_f32_e32 v15, v14
	v_mul_f32_e32 v14, 0xbfb8aa3b, v11
	v_exp_f32_e32 v18, v14
	v_mul_f32_e32 v9, v9, v19
	v_cvt_pk_bf16_f32 v14, v8, v9
	v_mul_f32_e32 v8, v10, v15
	v_add_f32_e32 v9, 1.0, v18
	v_rcp_f32_e32 v9, v9
	v_lshlrev_b32_e32 v10, 16, v71
	v_mul_f32_e32 v8, v8, v10
	v_and_b32_e32 v10, 0xffff0000, v71
	v_mul_f32_e32 v9, v11, v9
	v_mul_f32_e32 v11, 0xbfb8aa3b, v4
	v_exp_f32_e32 v11, v11
	v_mul_f32_e32 v8, v8, v19
	v_mul_f32_e32 v9, v9, v10
	v_mul_f32_e32 v9, v9, v19
	v_cvt_pk_bf16_f32 v15, v8, v9
	v_add_f32_e32 v8, 1.0, v11
	v_rcp_f32_e32 v8, v8
	v_mul_f32_e32 v9, 0xbfb8aa3b, v5
	v_exp_f32_e32 v9, v9
	global_store_dwordx4 v[16:17], v[12:15], off
	v_mul_f32_e32 v4, v4, v8
	v_lshlrev_b32_e32 v8, 16, v64
	v_mul_f32_e32 v4, v4, v8
	v_add_f32_e32 v8, 1.0, v9
	v_rcp_f32_e32 v8, v8
	v_mul_f32_e32 v9, 0xbfb8aa3b, v6
	v_exp_f32_e32 v9, v9
	v_mul_f32_e32 v4, v4, v19
	v_mul_f32_e32 v5, v5, v8
	v_and_b32_e32 v8, 0xffff0000, v64
	v_mul_f32_e32 v5, v5, v8
	v_add_f32_e32 v8, 1.0, v9
	v_mul_f32_e32 v9, 0xbfb8aa3b, v7
	v_rcp_f32_e32 v8, v8
	v_exp_f32_e32 v9, v9
	v_mul_f32_e32 v5, v5, v19
	v_cvt_pk_bf16_f32 v4, v4, v5
	v_mul_f32_e32 v5, v6, v8
	v_add_f32_e32 v6, 1.0, v9
	v_rcp_f32_e32 v6, v6
	v_lshlrev_b32_e32 v8, 16, v65
	v_mul_f32_e32 v5, v5, v8
	v_and_b32_e32 v8, 0xffff0000, v65
	v_mul_f32_e32 v6, v7, v6
	v_mul_f32_e32 v7, 0xbfb8aa3b, v0
	v_exp_f32_e32 v7, v7
	v_mul_f32_e32 v6, v6, v8
	v_mul_f32_e32 v5, v5, v19
	v_mul_f32_e32 v6, v6, v19
	v_add_f32_e32 v7, 1.0, v7
	v_cvt_pk_bf16_f32 v5, v5, v6
	v_mul_f32_e32 v6, 0xbfb8aa3b, v1
	v_rcp_f32_e32 v7, v7
	v_exp_f32_e32 v6, v6
	v_mul_f32_e32 v0, v0, v7
	v_lshlrev_b32_e32 v7, 16, v66
	v_add_f32_e32 v6, 1.0, v6
	v_mul_f32_e32 v0, v0, v7
	v_rcp_f32_e32 v6, v6
	v_mul_f32_e32 v7, 0xbfb8aa3b, v2
	v_exp_f32_e32 v7, v7
	v_mul_f32_e32 v0, v0, v19
	v_mul_f32_e32 v1, v1, v6
	v_and_b32_e32 v6, 0xffff0000, v66
	v_mul_f32_e32 v1, v1, v6
	v_add_f32_e32 v6, 1.0, v7
	v_rcp_f32_e32 v7, v6
	v_mul_f32_e32 v6, 0xbfb8aa3b, v3
	v_exp_f32_e32 v8, v6
	v_mul_f32_e32 v1, v1, v19
	v_cvt_pk_bf16_f32 v6, v0, v1
	v_mul_f32_e32 v0, v2, v7
	v_add_f32_e32 v1, 1.0, v8
	v_rcp_f32_e32 v1, v1
	v_lshlrev_b32_e32 v2, 16, v67
	v_mul_f32_e32 v0, v0, v2
	v_and_b32_e32 v2, 0xffff0000, v67
	v_mul_f32_e32 v1, v3, v1
	v_mul_f32_e32 v1, v1, v2
	v_mul_f32_e32 v0, v0, v19
	v_mul_f32_e32 v1, v1, v19
	v_cvt_pk_bf16_f32 v7, v0, v1
	global_store_dwordx4 v[16:17], v[4:7], off offset:256
	s_cbranch_vccz .LBB0_80
	s_waitcnt vmcnt(0)
	s_cmpk_gt_u32 s21, 0xff
	s_cbranch_scc1 .LBB0_91
	s_barrier

.LBB0_199:
	v_mov_b64_e32 v[0:1], 0x1000
	s_ashr_i32 s9, s8, 31
	v_cmp_lt_i64_e32 vcc, s[10:11], v[0:1]
	s_lshl_b64 s[10:11], s[8:9], 20
	s_add_u32 s10, s23, s10
	s_addc_u32 s11, s24, s11
	s_and_b64 s[12:13], vcc, exec
	s_cselect_b32 s5, s11, s15
	s_cselect_b32 s9, s10, s14
	s_ashr_i32 s7, s6, 31
	s_lshl_b64 s[12:13], s[6:7], 20
	s_add_u32 s12, s25, s12
	s_addc_u32 s13, s26, s13
	s_and_b64 s[18:19], vcc, exec
	s_cselect_b32 s7, s13, s17
	s_cselect_b32 s37, s12, s16
	s_add_u32 s14, s14, 0x80080
	s_addc_u32 s15, s15, 0
	s_add_u32 s38, s16, 0x100
	s_addc_u32 s39, s17, 0
	s_mov_b32 s40, -2
	s_mov_b64 s[48:49], 0x80
	v_add_u32_e32 v222, 0x10000, v238
	s_add_u32 s16, s14, 0xfff80080
	s_addc_u32 s17, s15, -1
	s_add_i32 s41, 0, 0x10000
	ds_read_b128 v[128:131], v222 offset:0
	ds_read_b128 v[132:135], v222 offset:1024
	ds_read_b128 v[136:139], v222 offset:2048
	ds_read_b128 v[140:143], v222 offset:3072
	s_cmp_eq_u32 s40, 28
	s_cselect_b32 s19, s5, s17
	s_cselect_b32 s18, s9, s16
	s_cselect_b32 s17, s7, s39
	s_cselect_b32 s16, s37, s38
	s_add_i32 m0, s28, 0xc000
	ds_read_b128 v[144:147], v240
	ds_read_b128 v[148:151], v240 offset:1024
	ds_read_b128 v[152:155], v240 offset:2048
	ds_read_b128 v[156:159], v240 offset:3072
	ds_read_b128 v[160:163], v240 offset:4096
	ds_read_b128 v[164:167], v240 offset:5120
	ds_read_b128 v[168:171], v240 offset:6144
	ds_read_b128 v[172:175], v240 offset:7168
	global_load_lds_dwordx4 v218, s[14:15]
	s_add_i32 m0, s28, 0xe000
	s_nop 0
	global_load_lds_dwordx4 v220, s[14:15]
	s_waitcnt lgkmcnt(8)
	s_barrier
	s_waitcnt lgkmcnt(0)
	v_mfma_f32_16x16x32_bf16 v[124:127], v[128:131], v[144:147], 0
	v_mfma_f32_16x16x32_bf16 v[120:123], v[136:139], v[144:147], 0
	v_mfma_f32_16x16x32_bf16 v[116:119], v[128:131], v[152:155], 0
	v_mfma_f32_16x16x32_bf16 v[108:111], v[136:139], v[152:155], 0
	s_add_i32 s44, 0, 0x14000
	s_add_i32 s41, s41, s27
	v_mfma_f32_16x16x32_bf16 v[100:103], v[128:131], v[160:163], 0
	s_mov_b32 m0, s41
	v_mfma_f32_16x16x32_bf16 v[92:95], v[136:139], v[160:163], 0
	v_mfma_f32_16x16x32_bf16 v[84:87], v[128:131], v[168:171], 0
	v_mfma_f32_16x16x32_bf16 v[76:79], v[136:139], v[168:171], 0
	v_mfma_f32_16x16x32_bf16 v[124:127], v[132:135], v[148:151], v[124:127]
	v_mfma_f32_16x16x32_bf16 v[120:123], v[140:143], v[148:151], v[120:123]
	v_mfma_f32_16x16x32_bf16 v[116:119], v[132:135], v[156:159], v[116:119]
	v_mfma_f32_16x16x32_bf16 v[108:111], v[140:143], v[156:159], v[108:111]
	v_mfma_f32_16x16x32_bf16 v[100:103], v[132:135], v[164:167], v[100:103]
	v_mfma_f32_16x16x32_bf16 v[92:95], v[140:143], v[164:167], v[92:95]
	v_mfma_f32_16x16x32_bf16 v[84:87], v[132:135], v[172:175], v[84:87]
	v_mfma_f32_16x16x32_bf16 v[76:79], v[140:143], v[172:175], v[76:79]
	s_barrier
	ds_read_b128 v[176:179], v222 offset:16384
	ds_read_b128 v[180:183], v222 offset:17408
	ds_read_b128 v[184:187], v222 offset:18432
	ds_read_b128 v[188:191], v222 offset:19456
	global_load_lds_dwordx4 v206, s[16:17]
	s_add_i32 m0, s41, 0x2000
	s_nop 0
	global_load_lds_dwordx4 v210, s[16:17]
	s_barrier
	s_waitcnt lgkmcnt(0)
	v_mfma_f32_16x16x32_bf16 v[112:115], v[176:179], v[144:147], 0
	v_mfma_f32_16x16x32_bf16 v[104:107], v[184:187], v[144:147], 0
	v_mfma_f32_16x16x32_bf16 v[96:99], v[176:179], v[152:155], 0
	v_mfma_f32_16x16x32_bf16 v[88:91], v[184:187], v[152:155], 0
	s_mov_b32 m0, s28
	v_mfma_f32_16x16x32_bf16 v[80:83], v[176:179], v[160:163], 0
	s_add_u32 s48, s18, 0x80
	s_addc_u32 s49, s19, 0
	v_mfma_f32_16x16x32_bf16 v[72:75], v[184:187], v[160:163], 0
	v_mfma_f32_16x16x32_bf16 v[68:71], v[176:179], v[168:171], 0
	v_mfma_f32_16x16x32_bf16 v[64:67], v[184:187], v[168:171], 0
	v_mfma_f32_16x16x32_bf16 v[112:115], v[180:183], v[148:151], v[112:115]
	v_mfma_f32_16x16x32_bf16 v[104:107], v[188:191], v[148:151], v[104:107]
	v_mfma_f32_16x16x32_bf16 v[96:99], v[180:183], v[156:159], v[96:99]
	v_mfma_f32_16x16x32_bf16 v[88:91], v[188:191], v[156:159], v[88:91]
	v_mfma_f32_16x16x32_bf16 v[80:83], v[180:183], v[164:167], v[80:83]
	v_mfma_f32_16x16x32_bf16 v[72:75], v[188:191], v[164:167], v[72:75]
	v_mfma_f32_16x16x32_bf16 v[68:71], v[180:183], v[172:175], v[68:71]
	v_mfma_f32_16x16x32_bf16 v[64:67], v[188:191], v[172:175], v[64:67]
	s_barrier
	ds_read_b128 v[144:147], v240 offset:16384
	ds_read_b128 v[148:151], v240 offset:17408
	ds_read_b128 v[152:155], v240 offset:18432
	ds_read_b128 v[156:159], v240 offset:19456
	ds_read_b128 v[160:163], v240 offset:20480
	ds_read_b128 v[164:167], v240 offset:21504
	ds_read_b128 v[168:171], v240 offset:22528
	ds_read_b128 v[172:175], v240 offset:23552
	global_load_lds_dwordx4 v204, s[18:19]
	s_mov_b32 m0, s29
	s_nop 0
	global_load_lds_dwordx4 v208, s[18:19]
	s_waitcnt lgkmcnt(0)
	s_barrier
	v_mfma_f32_16x16x32_bf16 v[60:63], v[128:131], v[144:147], 0
	v_mfma_f32_16x16x32_bf16 v[56:59], v[136:139], v[144:147], 0
	v_mfma_f32_16x16x32_bf16 v[52:55], v[128:131], v[152:155], 0
	v_mfma_f32_16x16x32_bf16 v[44:47], v[136:139], v[152:155], 0
	s_add_u32 s42, s16, 0x80000
	s_addc_u32 s43, s17, 0
	v_mfma_f32_16x16x32_bf16 v[36:39], v[128:131], v[160:163], 0
	s_add_i32 s41, s44, s27
	s_mov_b32 m0, s41
	v_mfma_f32_16x16x32_bf16 v[28:31], v[136:139], v[160:163], 0
	v_mfma_f32_16x16x32_bf16 v[20:23], v[128:131], v[168:171], 0
	v_mfma_f32_16x16x32_bf16 v[12:15], v[136:139], v[168:171], 0
	v_mfma_f32_16x16x32_bf16 v[60:63], v[132:135], v[148:151], v[60:63]
	v_mfma_f32_16x16x32_bf16 v[56:59], v[140:143], v[148:151], v[56:59]
	v_mfma_f32_16x16x32_bf16 v[52:55], v[132:135], v[156:159], v[52:55]
	v_mfma_f32_16x16x32_bf16 v[44:47], v[140:143], v[156:159], v[44:47]
	v_mfma_f32_16x16x32_bf16 v[36:39], v[132:135], v[164:167], v[36:39]
	v_mfma_f32_16x16x32_bf16 v[28:31], v[140:143], v[164:167], v[28:31]
	v_mfma_f32_16x16x32_bf16 v[20:23], v[132:135], v[172:175], v[20:23]
	v_mfma_f32_16x16x32_bf16 v[12:15], v[140:143], v[172:175], v[12:15]
	s_barrier
	global_load_lds_dwordx4 v206, s[42:43]
	s_add_i32 m0, s41, 0x2000
	s_nop 0
	global_load_lds_dwordx4 v210, s[42:43]
	s_add_u32 s18, s18, 0x80000
	s_addc_u32 s19, s19, 0
	s_mov_b32 m0, s30
	s_nop 0
	global_load_lds_dwordx4 v204, s[18:19]
	s_mov_b32 m0, s31
	s_nop 0
	global_load_lds_dwordx4 v208, s[18:19]
	s_waitcnt vmcnt(8)
	s_barrier
	v_mfma_f32_16x16x32_bf16 v[48:51], v[176:179], v[144:147], 0
	v_mfma_f32_16x16x32_bf16 v[40:43], v[184:187], v[144:147], 0
	v_mfma_f32_16x16x32_bf16 v[32:35], v[176:179], v[152:155], 0
	v_mfma_f32_16x16x32_bf16 v[24:27], v[184:187], v[152:155], 0
	s_add_i32 s41, 0, 0x18000
	v_mfma_f32_16x16x32_bf16 v[16:19], v[176:179], v[160:163], 0
	v_mfma_f32_16x16x32_bf16 v[8:11], v[184:187], v[160:163], 0
	v_mfma_f32_16x16x32_bf16 v[4:7], v[176:179], v[168:171], 0
	v_mfma_f32_16x16x32_bf16 v[0:3], v[184:187], v[168:171], 0
	v_mfma_f32_16x16x32_bf16 v[48:51], v[180:183], v[148:151], v[48:51]
	v_mfma_f32_16x16x32_bf16 v[40:43], v[188:191], v[148:151], v[40:43]
	v_mfma_f32_16x16x32_bf16 v[32:35], v[180:183], v[156:159], v[32:35]
	v_mfma_f32_16x16x32_bf16 v[24:27], v[188:191], v[156:159], v[24:27]
	v_mfma_f32_16x16x32_bf16 v[16:19], v[180:183], v[164:167], v[16:19]
	v_mfma_f32_16x16x32_bf16 v[8:11], v[188:191], v[164:167], v[8:11]
	v_mfma_f32_16x16x32_bf16 v[4:7], v[180:183], v[172:175], v[4:7]
	v_mfma_f32_16x16x32_bf16 v[0:3], v[188:191], v[172:175], v[0:3]
	s_barrier
	ds_read_b128 v[128:131], v222 offset:32768
	ds_read_b128 v[132:135], v222 offset:33792
	ds_read_b128 v[136:139], v222 offset:34816
	ds_read_b128 v[140:143], v222 offset:35840
	ds_read_b128 v[144:147], v240 offset:32768
	ds_read_b128 v[148:151], v240 offset:33792
	ds_read_b128 v[152:155], v240 offset:34816
	ds_read_b128 v[156:159], v240 offset:35840
	ds_read_b128 v[160:163], v240 offset:36864
	ds_read_b128 v[164:167], v240 offset:37888
	ds_read_b128 v[168:171], v240 offset:38912
	ds_read_b128 v[172:175], v240 offset:39936
	s_waitcnt lgkmcnt(8)
	s_barrier
	s_waitcnt lgkmcnt(0)
	v_mfma_f32_16x16x32_bf16 v[124:127], v[128:131], v[144:147], v[124:127]
	v_mfma_f32_16x16x32_bf16 v[120:123], v[136:139], v[144:147], v[120:123]
	v_mfma_f32_16x16x32_bf16 v[116:119], v[128:131], v[152:155], v[116:119]
	v_mfma_f32_16x16x32_bf16 v[108:111], v[136:139], v[152:155], v[108:111]
	s_add_i32 s18, 0, 0x1c000
	s_add_i32 s19, s41, s27
	v_mfma_f32_16x16x32_bf16 v[100:103], v[128:131], v[160:163], v[100:103]
	s_add_i32 m0, s19, 0xffffff80
	v_mfma_f32_16x16x32_bf16 v[92:95], v[136:139], v[160:163], v[92:95]
	v_mfma_f32_16x16x32_bf16 v[84:87], v[128:131], v[168:171], v[84:87]
	v_mfma_f32_16x16x32_bf16 v[76:79], v[136:139], v[168:171], v[76:79]
	v_mfma_f32_16x16x32_bf16 v[124:127], v[132:135], v[148:151], v[124:127]
	v_mfma_f32_16x16x32_bf16 v[120:123], v[140:143], v[148:151], v[120:123]
	v_mfma_f32_16x16x32_bf16 v[116:119], v[132:135], v[156:159], v[116:119]
	v_mfma_f32_16x16x32_bf16 v[108:111], v[140:143], v[156:159], v[108:111]
	v_mfma_f32_16x16x32_bf16 v[100:103], v[132:135], v[164:167], v[100:103]
	v_mfma_f32_16x16x32_bf16 v[92:95], v[140:143], v[164:167], v[92:95]
	v_mfma_f32_16x16x32_bf16 v[84:87], v[132:135], v[172:175], v[84:87]
	v_mfma_f32_16x16x32_bf16 v[76:79], v[140:143], v[172:175], v[76:79]
	s_barrier
	ds_read_b128 v[176:179], v222 offset:49152
	ds_read_b128 v[180:183], v222 offset:50176
	ds_read_b128 v[184:187], v222 offset:51200
	ds_read_b128 v[188:191], v222 offset:52224
	global_load_lds_dwordx4 v206, s[16:17] offset:128
	s_add_i32 m0, s19, 0x1f80
	s_nop 0
	global_load_lds_dwordx4 v210, s[16:17] offset:128
	s_barrier
	s_waitcnt lgkmcnt(0)
	v_mfma_f32_16x16x32_bf16 v[112:115], v[176:179], v[144:147], v[112:115]
	v_mfma_f32_16x16x32_bf16 v[104:107], v[184:187], v[144:147], v[104:107]
	v_mfma_f32_16x16x32_bf16 v[96:99], v[176:179], v[152:155], v[96:99]
	v_mfma_f32_16x16x32_bf16 v[88:91], v[184:187], v[152:155], v[88:91]
	s_mov_b32 m0, s33
	v_mfma_f32_16x16x32_bf16 v[80:83], v[176:179], v[160:163], v[80:83]
	v_mfma_f32_16x16x32_bf16 v[72:75], v[184:187], v[160:163], v[72:75]
	v_mfma_f32_16x16x32_bf16 v[68:71], v[176:179], v[168:171], v[68:71]
	v_mfma_f32_16x16x32_bf16 v[64:67], v[184:187], v[168:171], v[64:67]
	v_mfma_f32_16x16x32_bf16 v[112:115], v[180:183], v[148:151], v[112:115]
	v_mfma_f32_16x16x32_bf16 v[104:107], v[188:191], v[148:151], v[104:107]
	v_mfma_f32_16x16x32_bf16 v[96:99], v[180:183], v[156:159], v[96:99]
	v_mfma_f32_16x16x32_bf16 v[88:91], v[188:191], v[156:159], v[88:91]
	v_mfma_f32_16x16x32_bf16 v[80:83], v[180:183], v[164:167], v[80:83]
	v_mfma_f32_16x16x32_bf16 v[72:75], v[188:191], v[164:167], v[72:75]
	v_mfma_f32_16x16x32_bf16 v[68:71], v[180:183], v[172:175], v[68:71]
	v_mfma_f32_16x16x32_bf16 v[64:67], v[188:191], v[172:175], v[64:67]
	s_barrier
	ds_read_b128 v[144:147], v240 offset:49152
	ds_read_b128 v[148:151], v240 offset:50176
	ds_read_b128 v[152:155], v240 offset:51200
	ds_read_b128 v[156:159], v240 offset:52224
	ds_read_b128 v[160:163], v240 offset:53248
	ds_read_b128 v[164:167], v240 offset:54272
	ds_read_b128 v[168:171], v240 offset:55296
	ds_read_b128 v[172:175], v240 offset:56320
	global_load_lds_dwordx4 v204, s[48:49]
	s_mov_b32 m0, s34
	s_nop 0
	global_load_lds_dwordx4 v208, s[48:49]
	s_barrier
	s_waitcnt lgkmcnt(0)
	v_mfma_f32_16x16x32_bf16 v[60:63], v[128:131], v[144:147], v[60:63]
	v_mfma_f32_16x16x32_bf16 v[56:59], v[136:139], v[144:147], v[56:59]
	v_mfma_f32_16x16x32_bf16 v[52:55], v[128:131], v[152:155], v[52:55]
	v_mfma_f32_16x16x32_bf16 v[44:47], v[136:139], v[152:155], v[44:47]
	s_add_u32 s16, s16, 0x80080
	s_addc_u32 s17, s17, 0
	v_mfma_f32_16x16x32_bf16 v[36:39], v[128:131], v[160:163], v[36:39]
	s_add_i32 s18, s18, s27
	s_mov_b32 m0, s18
	v_mfma_f32_16x16x32_bf16 v[28:31], v[136:139], v[160:163], v[28:31]
	v_mfma_f32_16x16x32_bf16 v[20:23], v[128:131], v[168:171], v[20:23]
	v_mfma_f32_16x16x32_bf16 v[12:15], v[136:139], v[168:171], v[12:15]
	v_mfma_f32_16x16x32_bf16 v[60:63], v[132:135], v[148:151], v[60:63]
	v_mfma_f32_16x16x32_bf16 v[56:59], v[140:143], v[148:151], v[56:59]
	v_mfma_f32_16x16x32_bf16 v[52:55], v[132:135], v[156:159], v[52:55]
	v_mfma_f32_16x16x32_bf16 v[44:47], v[140:143], v[156:159], v[44:47]
	v_mfma_f32_16x16x32_bf16 v[36:39], v[132:135], v[164:167], v[36:39]
	v_mfma_f32_16x16x32_bf16 v[28:31], v[140:143], v[164:167], v[28:31]
	v_mfma_f32_16x16x32_bf16 v[20:23], v[132:135], v[172:175], v[20:23]
	v_mfma_f32_16x16x32_bf16 v[12:15], v[140:143], v[172:175], v[12:15]
	s_barrier
	global_load_lds_dwordx4 v206, s[16:17]
	s_add_i32 m0, s18, 0x2000
	s_nop 0
	global_load_lds_dwordx4 v210, s[16:17]
	s_waitcnt vmcnt(6)
	s_barrier
	v_mfma_f32_16x16x32_bf16 v[48:51], v[176:179], v[144:147], v[48:51]
	v_mfma_f32_16x16x32_bf16 v[40:43], v[184:187], v[144:147], v[40:43]
	v_mfma_f32_16x16x32_bf16 v[32:35], v[176:179], v[152:155], v[32:35]
	v_mfma_f32_16x16x32_bf16 v[24:27], v[184:187], v[152:155], v[24:27]
	s_add_i32 s40, s40, 2
	v_mfma_f32_16x16x32_bf16 v[16:19], v[176:179], v[160:163], v[16:19]
	s_add_u32 s14, s14, 0x100
	s_addc_u32 s15, s15, 0
	v_mfma_f32_16x16x32_bf16 v[8:11], v[184:187], v[160:163], v[8:11]
	s_add_u32 s38, s38, 0x100
	s_addc_u32 s39, s39, 0
	v_mfma_f32_16x16x32_bf16 v[4:7], v[176:179], v[168:171], v[4:7]
	s_add_u32 s16, s14, 0xfff80080
	s_addc_u32 s17, s15, -1
	v_mfma_f32_16x16x32_bf16 v[0:3], v[184:187], v[168:171], v[0:3]
	s_add_i32 s41, 0, 0x10000
	s_cmp_eq_u32 s40, 28
	v_mfma_f32_16x16x32_bf16 v[48:51], v[180:183], v[148:151], v[48:51]
	s_cselect_b32 s19, s5, s17
	s_cselect_b32 s18, s9, s16
	v_mfma_f32_16x16x32_bf16 v[40:43], v[188:191], v[148:151], v[40:43]
	s_cselect_b32 s17, s7, s39
	s_cselect_b32 s16, s37, s38
	v_mfma_f32_16x16x32_bf16 v[32:35], v[180:183], v[156:159], v[32:35]
	s_add_i32 m0, s28, 0xc000
	v_mfma_f32_16x16x32_bf16 v[24:27], v[188:191], v[156:159], v[24:27]
	v_mfma_f32_16x16x32_bf16 v[16:19], v[180:183], v[164:167], v[16:19]
	v_mfma_f32_16x16x32_bf16 v[8:11], v[188:191], v[164:167], v[8:11]
	v_mfma_f32_16x16x32_bf16 v[4:7], v[180:183], v[172:175], v[4:7]
	v_mfma_f32_16x16x32_bf16 v[0:3], v[188:191], v[172:175], v[0:3]
	s_cmp_gt_u32 s40, 29
	s_barrier
.LBB0_200:
	ds_read_b128 v[128:131], v222 offset:0
	ds_read_b128 v[132:135], v222 offset:1024
	ds_read_b128 v[136:139], v222 offset:2048
	ds_read_b128 v[140:143], v222 offset:3072
	ds_read_b128 v[144:147], v240
	ds_read_b128 v[148:151], v240 offset:1024
	ds_read_b128 v[152:155], v240 offset:2048
	ds_read_b128 v[156:159], v240 offset:3072
	ds_read_b128 v[160:163], v240 offset:4096
	ds_read_b128 v[164:167], v240 offset:5120
	ds_read_b128 v[168:171], v240 offset:6144
	ds_read_b128 v[172:175], v240 offset:7168
	global_load_lds_dwordx4 v218, s[14:15]
	s_add_i32 m0, s28, 0xe000
	s_nop 0
	global_load_lds_dwordx4 v220, s[14:15]
	s_waitcnt lgkmcnt(8)
	s_barrier
	s_waitcnt lgkmcnt(0)
	v_mfma_f32_16x16x32_bf16 v[124:127], v[128:131], v[144:147], v[124:127]
	v_mfma_f32_16x16x32_bf16 v[120:123], v[136:139], v[144:147], v[120:123]
	v_mfma_f32_16x16x32_bf16 v[116:119], v[128:131], v[152:155], v[116:119]
	v_mfma_f32_16x16x32_bf16 v[108:111], v[136:139], v[152:155], v[108:111]
	s_add_i32 s44, 0, 0x14000
	s_add_i32 s41, s41, s27
	v_mfma_f32_16x16x32_bf16 v[100:103], v[128:131], v[160:163], v[100:103]
	s_mov_b32 m0, s41
	v_mfma_f32_16x16x32_bf16 v[92:95], v[136:139], v[160:163], v[92:95]
	v_mfma_f32_16x16x32_bf16 v[84:87], v[128:131], v[168:171], v[84:87]
	v_mfma_f32_16x16x32_bf16 v[76:79], v[136:139], v[168:171], v[76:79]
	v_mfma_f32_16x16x32_bf16 v[124:127], v[132:135], v[148:151], v[124:127]
	v_mfma_f32_16x16x32_bf16 v[120:123], v[140:143], v[148:151], v[120:123]
	v_mfma_f32_16x16x32_bf16 v[116:119], v[132:135], v[156:159], v[116:119]
	v_mfma_f32_16x16x32_bf16 v[108:111], v[140:143], v[156:159], v[108:111]
	v_mfma_f32_16x16x32_bf16 v[100:103], v[132:135], v[164:167], v[100:103]
	v_mfma_f32_16x16x32_bf16 v[92:95], v[140:143], v[164:167], v[92:95]
	v_mfma_f32_16x16x32_bf16 v[84:87], v[132:135], v[172:175], v[84:87]
	v_mfma_f32_16x16x32_bf16 v[76:79], v[140:143], v[172:175], v[76:79]
	s_barrier
	ds_read_b128 v[176:179], v222 offset:16384
	ds_read_b128 v[180:183], v222 offset:17408
	ds_read_b128 v[184:187], v222 offset:18432
	ds_read_b128 v[188:191], v222 offset:19456
	global_load_lds_dwordx4 v206, s[16:17]
	s_add_i32 m0, s41, 0x2000
	s_nop 0
	global_load_lds_dwordx4 v210, s[16:17]
	s_barrier
	s_waitcnt lgkmcnt(0)
	v_mfma_f32_16x16x32_bf16 v[112:115], v[176:179], v[144:147], v[112:115]
	v_mfma_f32_16x16x32_bf16 v[104:107], v[184:187], v[144:147], v[104:107]
	v_mfma_f32_16x16x32_bf16 v[96:99], v[176:179], v[152:155], v[96:99]
	v_mfma_f32_16x16x32_bf16 v[88:91], v[184:187], v[152:155], v[88:91]
	s_mov_b32 m0, s28
	v_mfma_f32_16x16x32_bf16 v[80:83], v[176:179], v[160:163], v[80:83]
	s_add_u32 s48, s18, 0x80
	s_addc_u32 s49, s19, 0
	v_mfma_f32_16x16x32_bf16 v[72:75], v[184:187], v[160:163], v[72:75]
	v_mfma_f32_16x16x32_bf16 v[68:71], v[176:179], v[168:171], v[68:71]
	v_mfma_f32_16x16x32_bf16 v[64:67], v[184:187], v[168:171], v[64:67]
	v_mfma_f32_16x16x32_bf16 v[112:115], v[180:183], v[148:151], v[112:115]
	v_mfma_f32_16x16x32_bf16 v[104:107], v[188:191], v[148:151], v[104:107]
	v_mfma_f32_16x16x32_bf16 v[96:99], v[180:183], v[156:159], v[96:99]
	v_mfma_f32_16x16x32_bf16 v[88:91], v[188:191], v[156:159], v[88:91]
	v_mfma_f32_16x16x32_bf16 v[80:83], v[180:183], v[164:167], v[80:83]
	v_mfma_f32_16x16x32_bf16 v[72:75], v[188:191], v[164:167], v[72:75]
	v_mfma_f32_16x16x32_bf16 v[68:71], v[180:183], v[172:175], v[68:71]
	v_mfma_f32_16x16x32_bf16 v[64:67], v[188:191], v[172:175], v[64:67]
	s_barrier
	ds_read_b128 v[144:147], v240 offset:16384
	ds_read_b128 v[148:151], v240 offset:17408
	ds_read_b128 v[152:155], v240 offset:18432
	ds_read_b128 v[156:159], v240 offset:19456
	ds_read_b128 v[160:163], v240 offset:20480
	ds_read_b128 v[164:167], v240 offset:21504
	ds_read_b128 v[168:171], v240 offset:22528
	ds_read_b128 v[172:175], v240 offset:23552
	global_load_lds_dwordx4 v204, s[18:19]
	s_mov_b32 m0, s29
	s_nop 0
	global_load_lds_dwordx4 v208, s[18:19]
	s_waitcnt lgkmcnt(0)
	s_barrier
	v_mfma_f32_16x16x32_bf16 v[60:63], v[128:131], v[144:147], v[60:63]
	v_mfma_f32_16x16x32_bf16 v[56:59], v[136:139], v[144:147], v[56:59]
	v_mfma_f32_16x16x32_bf16 v[52:55], v[128:131], v[152:155], v[52:55]
	v_mfma_f32_16x16x32_bf16 v[44:47], v[136:139], v[152:155], v[44:47]
	s_add_u32 s42, s16, 0x80000
	s_addc_u32 s43, s17, 0
	v_mfma_f32_16x16x32_bf16 v[36:39], v[128:131], v[160:163], v[36:39]
	s_add_i32 s41, s44, s27
	s_mov_b32 m0, s41
	v_mfma_f32_16x16x32_bf16 v[28:31], v[136:139], v[160:163], v[28:31]
	v_mfma_f32_16x16x32_bf16 v[20:23], v[128:131], v[168:171], v[20:23]
	v_mfma_f32_16x16x32_bf16 v[12:15], v[136:139], v[168:171], v[12:15]
	v_mfma_f32_16x16x32_bf16 v[60:63], v[132:135], v[148:151], v[60:63]
	v_mfma_f32_16x16x32_bf16 v[56:59], v[140:143], v[148:151], v[56:59]
	v_mfma_f32_16x16x32_bf16 v[52:55], v[132:135], v[156:159], v[52:55]
	v_mfma_f32_16x16x32_bf16 v[44:47], v[140:143], v[156:159], v[44:47]
	v_mfma_f32_16x16x32_bf16 v[36:39], v[132:135], v[164:167], v[36:39]
	v_mfma_f32_16x16x32_bf16 v[28:31], v[140:143], v[164:167], v[28:31]
	v_mfma_f32_16x16x32_bf16 v[20:23], v[132:135], v[172:175], v[20:23]
	v_mfma_f32_16x16x32_bf16 v[12:15], v[140:143], v[172:175], v[12:15]
	s_barrier
	global_load_lds_dwordx4 v206, s[42:43]
	s_add_i32 m0, s41, 0x2000
	s_nop 0
	global_load_lds_dwordx4 v210, s[42:43]
	s_add_u32 s18, s18, 0x80000
	s_addc_u32 s19, s19, 0
	s_mov_b32 m0, s30
	s_nop 0
	global_load_lds_dwordx4 v204, s[18:19]
	s_mov_b32 m0, s31
	s_nop 0
	global_load_lds_dwordx4 v208, s[18:19]
	s_waitcnt vmcnt(8)
	s_barrier
	v_mfma_f32_16x16x32_bf16 v[48:51], v[176:179], v[144:147], v[48:51]
	v_mfma_f32_16x16x32_bf16 v[40:43], v[184:187], v[144:147], v[40:43]
	v_mfma_f32_16x16x32_bf16 v[32:35], v[176:179], v[152:155], v[32:35]
	v_mfma_f32_16x16x32_bf16 v[24:27], v[184:187], v[152:155], v[24:27]
	s_add_i32 s41, 0, 0x18000
	v_mfma_f32_16x16x32_bf16 v[16:19], v[176:179], v[160:163], v[16:19]
	v_mfma_f32_16x16x32_bf16 v[8:11], v[184:187], v[160:163], v[8:11]
	v_mfma_f32_16x16x32_bf16 v[4:7], v[176:179], v[168:171], v[4:7]
	v_mfma_f32_16x16x32_bf16 v[0:3], v[184:187], v[168:171], v[0:3]
	v_mfma_f32_16x16x32_bf16 v[48:51], v[180:183], v[148:151], v[48:51]
	v_mfma_f32_16x16x32_bf16 v[40:43], v[188:191], v[148:151], v[40:43]
	v_mfma_f32_16x16x32_bf16 v[32:35], v[180:183], v[156:159], v[32:35]
	v_mfma_f32_16x16x32_bf16 v[24:27], v[188:191], v[156:159], v[24:27]
	v_mfma_f32_16x16x32_bf16 v[16:19], v[180:183], v[164:167], v[16:19]
	v_mfma_f32_16x16x32_bf16 v[8:11], v[188:191], v[164:167], v[8:11]
	v_mfma_f32_16x16x32_bf16 v[4:7], v[180:183], v[172:175], v[4:7]
	v_mfma_f32_16x16x32_bf16 v[0:3], v[188:191], v[172:175], v[0:3]
	s_barrier
	ds_read_b128 v[128:131], v222 offset:32768
	ds_read_b128 v[132:135], v222 offset:33792
	ds_read_b128 v[136:139], v222 offset:34816
	ds_read_b128 v[140:143], v222 offset:35840
	ds_read_b128 v[144:147], v240 offset:32768
	ds_read_b128 v[148:151], v240 offset:33792
	ds_read_b128 v[152:155], v240 offset:34816
	ds_read_b128 v[156:159], v240 offset:35840
	ds_read_b128 v[160:163], v240 offset:36864
	ds_read_b128 v[164:167], v240 offset:37888
	ds_read_b128 v[168:171], v240 offset:38912
	ds_read_b128 v[172:175], v240 offset:39936
	s_waitcnt lgkmcnt(8)
	s_barrier
	s_waitcnt lgkmcnt(0)
	v_mfma_f32_16x16x32_bf16 v[124:127], v[128:131], v[144:147], v[124:127]
	v_mfma_f32_16x16x32_bf16 v[120:123], v[136:139], v[144:147], v[120:123]
	v_mfma_f32_16x16x32_bf16 v[116:119], v[128:131], v[152:155], v[116:119]
	v_mfma_f32_16x16x32_bf16 v[108:111], v[136:139], v[152:155], v[108:111]
	s_add_i32 s18, 0, 0x1c000
	s_add_i32 s19, s41, s27
	v_mfma_f32_16x16x32_bf16 v[100:103], v[128:131], v[160:163], v[100:103]
	s_add_i32 m0, s19, 0xffffff80
	v_mfma_f32_16x16x32_bf16 v[92:95], v[136:139], v[160:163], v[92:95]
	v_mfma_f32_16x16x32_bf16 v[84:87], v[128:131], v[168:171], v[84:87]
	v_mfma_f32_16x16x32_bf16 v[76:79], v[136:139], v[168:171], v[76:79]
	v_mfma_f32_16x16x32_bf16 v[124:127], v[132:135], v[148:151], v[124:127]
	v_mfma_f32_16x16x32_bf16 v[120:123], v[140:143], v[148:151], v[120:123]
	v_mfma_f32_16x16x32_bf16 v[116:119], v[132:135], v[156:159], v[116:119]
	v_mfma_f32_16x16x32_bf16 v[108:111], v[140:143], v[156:159], v[108:111]
	v_mfma_f32_16x16x32_bf16 v[100:103], v[132:135], v[164:167], v[100:103]
	v_mfma_f32_16x16x32_bf16 v[92:95], v[140:143], v[164:167], v[92:95]
	v_mfma_f32_16x16x32_bf16 v[84:87], v[132:135], v[172:175], v[84:87]
	v_mfma_f32_16x16x32_bf16 v[76:79], v[140:143], v[172:175], v[76:79]
	s_barrier
	ds_read_b128 v[176:179], v222 offset:49152
	ds_read_b128 v[180:183], v222 offset:50176
	ds_read_b128 v[184:187], v222 offset:51200
	ds_read_b128 v[188:191], v222 offset:52224
	global_load_lds_dwordx4 v206, s[16:17] offset:128
	s_add_i32 m0, s19, 0x1f80
	s_nop 0
	global_load_lds_dwordx4 v210, s[16:17] offset:128
	s_barrier
	s_waitcnt lgkmcnt(0)
	v_mfma_f32_16x16x32_bf16 v[112:115], v[176:179], v[144:147], v[112:115]
	v_mfma_f32_16x16x32_bf16 v[104:107], v[184:187], v[144:147], v[104:107]
	v_mfma_f32_16x16x32_bf16 v[96:99], v[176:179], v[152:155], v[96:99]
	v_mfma_f32_16x16x32_bf16 v[88:91], v[184:187], v[152:155], v[88:91]
	s_mov_b32 m0, s33
	v_mfma_f32_16x16x32_bf16 v[80:83], v[176:179], v[160:163], v[80:83]
	v_mfma_f32_16x16x32_bf16 v[72:75], v[184:187], v[160:163], v[72:75]
	v_mfma_f32_16x16x32_bf16 v[68:71], v[176:179], v[168:171], v[68:71]
	v_mfma_f32_16x16x32_bf16 v[64:67], v[184:187], v[168:171], v[64:67]
	v_mfma_f32_16x16x32_bf16 v[112:115], v[180:183], v[148:151], v[112:115]
	v_mfma_f32_16x16x32_bf16 v[104:107], v[188:191], v[148:151], v[104:107]
	v_mfma_f32_16x16x32_bf16 v[96:99], v[180:183], v[156:159], v[96:99]
	v_mfma_f32_16x16x32_bf16 v[88:91], v[188:191], v[156:159], v[88:91]
	v_mfma_f32_16x16x32_bf16 v[80:83], v[180:183], v[164:167], v[80:83]
	v_mfma_f32_16x16x32_bf16 v[72:75], v[188:191], v[164:167], v[72:75]
	v_mfma_f32_16x16x32_bf16 v[68:71], v[180:183], v[172:175], v[68:71]
	v_mfma_f32_16x16x32_bf16 v[64:67], v[188:191], v[172:175], v[64:67]
	s_barrier
	ds_read_b128 v[144:147], v240 offset:49152
	ds_read_b128 v[148:151], v240 offset:50176
	ds_read_b128 v[152:155], v240 offset:51200
	ds_read_b128 v[156:159], v240 offset:52224
	ds_read_b128 v[160:163], v240 offset:53248
	ds_read_b128 v[164:167], v240 offset:54272
	ds_read_b128 v[168:171], v240 offset:55296
	ds_read_b128 v[172:175], v240 offset:56320
	global_load_lds_dwordx4 v204, s[48:49]
	s_mov_b32 m0, s34
	s_nop 0
	global_load_lds_dwordx4 v208, s[48:49]
	s_barrier
	s_waitcnt lgkmcnt(0)
	v_mfma_f32_16x16x32_bf16 v[60:63], v[128:131], v[144:147], v[60:63]
	v_mfma_f32_16x16x32_bf16 v[56:59], v[136:139], v[144:147], v[56:59]
	v_mfma_f32_16x16x32_bf16 v[52:55], v[128:131], v[152:155], v[52:55]
	v_mfma_f32_16x16x32_bf16 v[44:47], v[136:139], v[152:155], v[44:47]
	s_add_u32 s16, s16, 0x80080
	s_addc_u32 s17, s17, 0
	v_mfma_f32_16x16x32_bf16 v[36:39], v[128:131], v[160:163], v[36:39]
	s_add_i32 s18, s18, s27
	s_mov_b32 m0, s18
	v_mfma_f32_16x16x32_bf16 v[28:31], v[136:139], v[160:163], v[28:31]
	v_mfma_f32_16x16x32_bf16 v[20:23], v[128:131], v[168:171], v[20:23]
	v_mfma_f32_16x16x32_bf16 v[12:15], v[136:139], v[168:171], v[12:15]
	v_mfma_f32_16x16x32_bf16 v[60:63], v[132:135], v[148:151], v[60:63]
	v_mfma_f32_16x16x32_bf16 v[56:59], v[140:143], v[148:151], v[56:59]
	v_mfma_f32_16x16x32_bf16 v[52:55], v[132:135], v[156:159], v[52:55]
	v_mfma_f32_16x16x32_bf16 v[44:47], v[140:143], v[156:159], v[44:47]
	v_mfma_f32_16x16x32_bf16 v[36:39], v[132:135], v[164:167], v[36:39]
	v_mfma_f32_16x16x32_bf16 v[28:31], v[140:143], v[164:167], v[28:31]
	v_mfma_f32_16x16x32_bf16 v[20:23], v[132:135], v[172:175], v[20:23]
	v_mfma_f32_16x16x32_bf16 v[12:15], v[140:143], v[172:175], v[12:15]
	s_barrier
	global_load_lds_dwordx4 v206, s[16:17]
	s_add_i32 m0, s18, 0x2000
	s_nop 0
	global_load_lds_dwordx4 v210, s[16:17]
	s_waitcnt vmcnt(6)
	s_barrier
	v_mfma_f32_16x16x32_bf16 v[48:51], v[176:179], v[144:147], v[48:51]
	v_mfma_f32_16x16x32_bf16 v[40:43], v[184:187], v[144:147], v[40:43]
	v_mfma_f32_16x16x32_bf16 v[32:35], v[176:179], v[152:155], v[32:35]
	v_mfma_f32_16x16x32_bf16 v[24:27], v[184:187], v[152:155], v[24:27]
	s_add_i32 s40, s40, 2
	v_mfma_f32_16x16x32_bf16 v[16:19], v[176:179], v[160:163], v[16:19]
	s_add_u32 s14, s14, 0x100
	s_addc_u32 s15, s15, 0
	v_mfma_f32_16x16x32_bf16 v[8:11], v[184:187], v[160:163], v[8:11]
	s_add_u32 s38, s38, 0x100
	s_addc_u32 s39, s39, 0
	v_mfma_f32_16x16x32_bf16 v[4:7], v[176:179], v[168:171], v[4:7]
	s_add_u32 s16, s14, 0xfff80080
	s_addc_u32 s17, s15, -1
	v_mfma_f32_16x16x32_bf16 v[0:3], v[184:187], v[168:171], v[0:3]
	s_add_i32 s41, 0, 0x10000
	s_cmp_eq_u32 s40, 28
	v_mfma_f32_16x16x32_bf16 v[48:51], v[180:183], v[148:151], v[48:51]
	s_cselect_b32 s19, s5, s17
	s_cselect_b32 s18, s9, s16
	v_mfma_f32_16x16x32_bf16 v[40:43], v[188:191], v[148:151], v[40:43]
	s_cselect_b32 s17, s7, s39
	s_cselect_b32 s16, s37, s38
	v_mfma_f32_16x16x32_bf16 v[32:35], v[180:183], v[156:159], v[32:35]
	s_add_i32 m0, s28, 0xc000
	v_mfma_f32_16x16x32_bf16 v[24:27], v[188:191], v[156:159], v[24:27]
	v_mfma_f32_16x16x32_bf16 v[16:19], v[180:183], v[164:167], v[16:19]
	v_mfma_f32_16x16x32_bf16 v[8:11], v[188:191], v[164:167], v[8:11]
	v_mfma_f32_16x16x32_bf16 v[4:7], v[180:183], v[172:175], v[4:7]
	v_mfma_f32_16x16x32_bf16 v[0:3], v[188:191], v[172:175], v[0:3]
	s_cmp_gt_u32 s40, 29
	s_barrier
	s_cbranch_scc0 .LBB0_200
	v_lshl_add_u32 v228, s4, 8, v237
	v_or_b32_e32 v226, 16, v228
	s_mov_b64 s[4:5], -1
	s_cmp_lt_i32 s36, 16
	v_ashrrev_i32_e32 v229, 31, v228
	v_lshlrev_b32_e32 v192, 1, v212
	v_ashrrev_i32_e32 v227, 31, v226
	v_or_b32_e32 v224, 32, v228
	v_or_b32_e32 v222, 48, v228
	s_cbranch_scc0 .LBB0_203
	s_and_b32 s7, s36, 7
	s_cmp_gt_i32 s36, 7
	s_cselect_b64 vcc, -1, 0
	s_and_b64 s[4:5], vcc, exec
	s_mov_b32 s4, 0x15000000
	s_cselect_b32 s4, s4, 0xd000000
	s_add_u32 s4, s50, s4
	s_addc_u32 s5, s51, 0
	s_lshl_b32 s9, s7, 9
	s_add_u32 s4, s4, s9
	v_cvt_f32_ubyte0_e32 v128, s7
	s_addc_u32 s5, s5, 0
	v_sub_f32_e32 v128, 0xc0a00000, v128
	s_mov_b32 s7, 0xc2fc0000
	v_lshl_add_u64 v[230:231], s[4:5], 0, v[192:193]
	v_cmp_gt_f32_e64 s[4:5], s7, v128
	v_ashrrev_i32_e32 v225, 31, v224
	s_nop 0
	v_cndmask_b32_e64 v129, 0, v234, s[4:5]
	v_add_f32_e32 v128, v128, v129
	v_exp_f32_e32 v128, v128
	s_and_b64 s[4:5], s[4:5], exec
	s_cselect_b32 s4, 0xffffffc0, 0
	v_mov_b32_e32 v129, v193
	v_ldexp_f32 v128, v128, s4
	v_sub_f32_e32 v128, 1.0, v128
	v_log_f32_e32 v241, v128
	v_lshlrev_b32_e32 v128, 9, v228
	v_and_b32_e32 v128, 0x1f9e00, v128
	v_lshl_add_u64 v[130:131], v[214:215], 0, v[128:129]
	v_lshl_add_u64 v[132:133], v[216:217], 0, v[128:129]
	global_load_dwordx4 v[180:183], v[130:131], off offset:16
	global_load_dwordx4 v[188:191], v[130:131], off
	global_load_dwordx4 v[176:179], v[132:133], off offset:16
	global_load_dwordx4 v[184:187], v[132:133], off
	v_or_b32_e32 v130, 0x2000, v128
	v_mov_b32_e32 v131, v193
	v_lshl_add_u64 v[132:133], v[214:215], 0, v[130:131]
	v_lshl_add_u64 v[130:131], v[216:217], 0, v[130:131]
	global_load_dwordx4 v[164:167], v[132:133], off offset:16
	global_load_dwordx4 v[172:175], v[132:133], off
	global_load_dwordx4 v[160:163], v[130:131], off offset:16
	global_load_dwordx4 v[168:171], v[130:131], off
	v_mul_f32_e64 v196, v241, -v239
	v_cmp_gt_f32_e64 s[4:5], s7, v196
	v_or_b32_e32 v130, 0x4000, v128
	v_mov_b32_e32 v131, v193
	v_cndmask_b32_e64 v196, 0, v234, s[4:5]
	v_fma_f32 v196, v241, -v239, v196
	v_exp_f32_e32 v196, v196
	v_cndmask_b32_e64 v197, 0, v235, s[4:5]
	v_lshl_add_u64 v[132:133], v[214:215], 0, v[130:131]
	v_lshl_add_u64 v[130:131], v[216:217], 0, v[130:131]
	v_ldexp_f32 v196, v196, v197
	v_mul_f32_e32 v196, 0x3d800000, v196
	v_cndmask_b32_e32 v242, 1.0, v196, vcc
	v_mov_b32_e32 v196, v124
	v_mov_b32_e32 v197, v112
	global_load_dwordx4 v[148:151], v[132:133], off offset:16
	global_load_dwordx4 v[156:159], v[132:133], off
	global_load_dwordx4 v[144:147], v[130:131], off offset:16
	global_load_dwordx4 v[152:155], v[130:131], off
	v_or_b32_e32 v128, 0x6000, v128
	v_lshl_add_u64 v[130:131], v[214:215], 0, v[128:129]
	v_lshl_add_u64 v[136:137], v[216:217], 0, v[128:129]
	global_load_dwordx4 v[132:135], v[130:131], off offset:16
	global_load_dwordx4 v[140:143], v[130:131], off
	s_nop 0
	global_load_dwordx4 v[128:131], v[136:137], off offset:16
	s_nop 0
	global_load_dwordx4 v[136:139], v[136:137], off
	s_movk_i32 s4, 0x5f
	s_waitcnt vmcnt(0)
	v_mov_b32_e32 v198, v188
	v_mov_b32_e32 v199, v184
	v_pk_mul_f32 v[196:197], v[196:197], v[198:199]
	s_nop 0
	v_sub_f32_e32 v184, v196, v197
	v_mov_b32_e32 v196, v112
	v_mov_b32_e32 v197, v124
	v_pk_mul_f32 v[196:197], v[196:197], v[198:199]
	v_mul_f32_e32 v223, v242, v184
	v_add_f32_e32 v184, v196, v197
	v_mul_f32_e32 v198, v242, v184
	v_mov_b32_e32 v196, v125
	v_mov_b32_e32 v197, v113
	v_mov_b32_e32 v184, v189
	v_pk_mul_f32 v[188:189], v[196:197], v[184:185]
	s_nop 0
	v_sub_f32_e32 v188, v188, v189
	v_mul_f32_e32 v196, v242, v188
	v_mov_b32_e32 v188, v113
	v_mov_b32_e32 v189, v125
	v_pk_mul_f32 v[184:185], v[188:189], v[184:185]
	v_mov_b32_e32 v188, v190
	v_add_f32_e32 v184, v184, v185
	v_mul_f32_e32 v197, v242, v184
	v_mov_b32_e32 v184, v126
	v_mov_b32_e32 v185, v114
	v_mov_b32_e32 v189, v186
	v_pk_mul_f32 v[184:185], v[184:185], v[188:189]
	v_mov_b32_e32 v186, v191
	v_sub_f32_e32 v184, v184, v185
	v_mul_f32_e32 v190, v242, v184
	v_mov_b32_e32 v184, v114
	v_mov_b32_e32 v185, v126
	v_pk_mul_f32 v[184:185], v[184:185], v[188:189]
	s_nop 0
	v_add_f32_e32 v184, v184, v185
	v_mul_f32_e32 v188, v242, v184
	v_mov_b32_e32 v184, v127
	v_mov_b32_e32 v185, v115
	v_pk_mul_f32 v[184:185], v[184:185], v[186:187]
	s_nop 0
	v_sub_f32_e32 v184, v184, v185
	v_mul_f32_e32 v189, v242, v184
	v_mov_b32_e32 v184, v115
	v_mov_b32_e32 v185, v127
	v_pk_mul_f32 v[184:185], v[184:185], v[186:187]
	v_mov_b32_e32 v186, v180
	v_add_f32_e32 v184, v184, v185
	v_mul_f32_e32 v191, v242, v184
	v_mov_b32_e32 v184, v120
	v_mov_b32_e32 v185, v104
	v_mov_b32_e32 v187, v176
	v_pk_mul_f32 v[184:185], v[184:185], v[186:187]
	s_nop 0
	v_sub_f32_e32 v176, v184, v185
	v_mov_b32_e32 v184, v104
	v_mov_b32_e32 v185, v120
	v_pk_mul_f32 v[184:185], v[184:185], v[186:187]
	v_mul_f32_e32 v199, v242, v176
	v_add_f32_e32 v176, v184, v185
	v_mul_f32_e32 v186, v242, v176
	v_mov_b32_e32 v184, v121
	v_mov_b32_e32 v185, v105
	v_mov_b32_e32 v176, v181
	v_pk_mul_f32 v[180:181], v[184:185], v[176:177]
	s_nop 0
	v_sub_f32_e32 v180, v180, v181
	v_mul_f32_e32 v184, v242, v180
	v_mov_b32_e32 v180, v105
	v_mov_b32_e32 v181, v121
	v_pk_mul_f32 v[176:177], v[180:181], v[176:177]
	v_mov_b32_e32 v180, v182
	v_add_f32_e32 v176, v176, v177
	v_mul_f32_e32 v185, v242, v176
	v_mov_b32_e32 v176, v122
	v_mov_b32_e32 v177, v106
	v_mov_b32_e32 v181, v178
	v_pk_mul_f32 v[176:177], v[176:177], v[180:181]
	v_mov_b32_e32 v178, v183
	v_sub_f32_e32 v176, v176, v177
	v_mul_f32_e32 v182, v242, v176
	v_mov_b32_e32 v176, v106
	v_mov_b32_e32 v177, v122
	v_pk_mul_f32 v[176:177], v[176:177], v[180:181]
	s_nop 0
	v_add_f32_e32 v176, v176, v177
	v_mul_f32_e32 v187, v242, v176
	v_mov_b32_e32 v176, v123
	v_mov_b32_e32 v177, v107
	v_pk_mul_f32 v[176:177], v[176:177], v[178:179]
	s_nop 0
	v_sub_f32_e32 v176, v176, v177
	v_mul_f32_e32 v181, v242, v176
	v_mov_b32_e32 v176, v107
	v_mov_b32_e32 v177, v123
	v_pk_mul_f32 v[176:177], v[176:177], v[178:179]
	v_cvt_pk_bf16_f32 v178, v223, v196
	v_cvt_pk_bf16_f32 v179, v190, v189
	v_cvt_pk_bf16_f32 v180, v199, v184
	v_cvt_pk_bf16_f32 v181, v182, v181
	v_cvt_pk_bf16_f32 v182, v198, v197
	s_nop 0
	v_add_f32_e32 v176, v176, v177
	v_mul_f32_e32 v176, v242, v176
	v_cvt_pk_bf16_f32 v183, v188, v191
	v_cvt_pk_bf16_f32 v184, v186, v185
	v_cvt_pk_bf16_f32 v185, v187, v176
	v_lshlrev_b64 v[176:177], 12, v[228:229]
	v_lshl_add_u64 v[176:177], v[230:231], 0, v[176:177]
	global_store_dwordx4 v[176:177], v[178:181], off
	global_store_dwordx4 v[176:177], v[182:185], off offset:256
	v_ashrrev_i32_e32 v223, 31, v222
	v_bitop3_b32 v178, v228, s4, 16 bitop3:0xc8
	v_add_u32_e32 v178, 1, v178
	v_cvt_f32_ubyte0_e32 v178, v178
	v_mul_f32_e64 v179, v241, -v178
	v_cmp_gt_f32_e64 s[4:5], s7, v179
	v_mov_b32_e32 v181, v168
	v_mov_b32_e32 v190, v60
	v_cndmask_b32_e64 v180, 0, v234, s[4:5]
	v_fma_f32 v178, v241, -v178, v180
	v_exp_f32_e32 v178, v178
	v_cndmask_b32_e64 v179, 0, v235, s[4:5]
	v_mov_b32_e32 v180, v172
	s_movk_i32 s4, 0x6f
	v_ldexp_f32 v178, v178, v179
	v_mul_f32_e32 v178, 0x3d800000, v178
	v_cndmask_b32_e32 v182, 1.0, v178, vcc
	v_mov_b32_e32 v178, v116
	v_mov_b32_e32 v179, v96
	v_pk_mul_f32 v[178:179], v[178:179], v[180:181]
	v_mov_b32_e32 v191, v48
	v_sub_f32_e32 v168, v178, v179
	v_mov_b32_e32 v178, v96
	v_mov_b32_e32 v179, v116
	v_pk_mul_f32 v[178:179], v[178:179], v[180:181]
	v_mul_f32_e32 v183, v182, v168
	v_add_f32_e32 v168, v178, v179
	v_mul_f32_e32 v180, v182, v168
	v_mov_b32_e32 v178, v117
	v_mov_b32_e32 v179, v97
	v_mov_b32_e32 v168, v173
	v_pk_mul_f32 v[172:173], v[178:179], v[168:169]
	s_nop 0
	v_sub_f32_e32 v172, v172, v173
	v_mul_f32_e32 v178, v182, v172
	v_mov_b32_e32 v172, v97
	v_mov_b32_e32 v173, v117
	v_pk_mul_f32 v[168:169], v[172:173], v[168:169]
	v_mov_b32_e32 v172, v174
	v_add_f32_e32 v168, v168, v169
	v_mul_f32_e32 v179, v182, v168
	v_mov_b32_e32 v168, v118
	v_mov_b32_e32 v169, v98
	v_mov_b32_e32 v173, v170
	v_pk_mul_f32 v[168:169], v[168:169], v[172:173]
	v_mov_b32_e32 v170, v175
	v_sub_f32_e32 v168, v168, v169
	v_mul_f32_e32 v174, v182, v168
	v_mov_b32_e32 v168, v98
	v_mov_b32_e32 v169, v118
	v_pk_mul_f32 v[168:169], v[168:169], v[172:173]
	s_nop 0
	v_add_f32_e32 v168, v168, v169
	v_mul_f32_e32 v172, v182, v168
	v_mov_b32_e32 v168, v119
	v_mov_b32_e32 v169, v99
	v_pk_mul_f32 v[168:169], v[168:169], v[170:171]
	s_nop 0
	v_sub_f32_e32 v168, v168, v169
	v_mul_f32_e32 v173, v182, v168
	v_mov_b32_e32 v168, v99
	v_mov_b32_e32 v169, v119
	v_pk_mul_f32 v[168:169], v[168:169], v[170:171]
	v_mov_b32_e32 v170, v164
	v_add_f32_e32 v168, v168, v169
	v_mul_f32_e32 v175, v182, v168
	v_mov_b32_e32 v168, v108
	v_mov_b32_e32 v169, v88
	v_mov_b32_e32 v171, v160
	v_pk_mul_f32 v[168:169], v[168:169], v[170:171]
	s_nop 0
	v_sub_f32_e32 v160, v168, v169
	v_mov_b32_e32 v168, v88
	v_mov_b32_e32 v169, v108
	v_pk_mul_f32 v[168:169], v[168:169], v[170:171]
	v_mul_f32_e32 v181, v182, v160
	v_add_f32_e32 v160, v168, v169
	v_mul_f32_e32 v170, v182, v160
	v_mov_b32_e32 v168, v109
	v_mov_b32_e32 v169, v89
	v_mov_b32_e32 v160, v165
	v_pk_mul_f32 v[164:165], v[168:169], v[160:161]
	s_nop 0
	v_sub_f32_e32 v164, v164, v165
	v_mul_f32_e32 v168, v182, v164
	v_mov_b32_e32 v164, v89
	v_mov_b32_e32 v165, v109
	v_pk_mul_f32 v[160:161], v[164:165], v[160:161]
	v_mov_b32_e32 v164, v166
	v_add_f32_e32 v160, v160, v161
	v_mul_f32_e32 v169, v182, v160
	v_mov_b32_e32 v160, v110
	v_mov_b32_e32 v161, v90
	v_mov_b32_e32 v165, v162
	v_pk_mul_f32 v[160:161], v[160:161], v[164:165]
	v_mov_b32_e32 v162, v167
	v_sub_f32_e32 v160, v160, v161
	v_mul_f32_e32 v166, v182, v160
	v_mov_b32_e32 v160, v90
	v_mov_b32_e32 v161, v110
	v_pk_mul_f32 v[160:161], v[160:161], v[164:165]
	s_nop 0
	v_add_f32_e32 v160, v160, v161
	v_mul_f32_e32 v171, v182, v160
	v_mov_b32_e32 v160, v111
	v_mov_b32_e32 v161, v91
	v_pk_mul_f32 v[160:161], v[160:161], v[162:163]
	s_nop 0
	v_sub_f32_e32 v160, v160, v161
	v_mul_f32_e32 v164, v182, v160
	v_mov_b32_e32 v160, v91
	v_mov_b32_e32 v161, v111
	v_pk_mul_f32 v[160:161], v[160:161], v[162:163]
	s_nop 0
	v_add_f32_e32 v160, v160, v161
	v_mul_f32_e32 v167, v182, v160
	v_cvt_pk_bf16_f32 v160, v183, v178
	v_cvt_pk_bf16_f32 v161, v174, v173
	v_cvt_pk_bf16_f32 v162, v181, v168
	v_cvt_pk_bf16_f32 v163, v166, v164
	v_cvt_pk_bf16_f32 v164, v180, v179
	v_cvt_pk_bf16_f32 v165, v172, v175
	v_cvt_pk_bf16_f32 v166, v170, v169
	v_lshlrev_b64 v[168:169], 12, v[226:227]
	v_lshl_add_u64 v[168:169], v[230:231], 0, v[168:169]
	v_cvt_pk_bf16_f32 v167, v171, v167
	global_store_dwordx4 v[168:169], v[160:163], off
	global_store_dwordx4 v[168:169], v[164:167], off offset:256
	s_nop 0
	v_bitop3_b32 v160, v228, s4, 32 bitop3:0xc8
	v_add_u32_e32 v160, 1, v160
	v_cvt_f32_ubyte0_e32 v160, v160
	v_mul_f32_e64 v161, v241, -v160
	v_cmp_gt_f32_e64 s[4:5], s7, v161
	v_mov_b32_e32 v163, v152
	s_nop 0
	v_cndmask_b32_e64 v162, 0, v234, s[4:5]
	v_fma_f32 v160, v241, -v160, v162
	v_exp_f32_e32 v160, v160
	v_cndmask_b32_e64 v161, 0, v235, s[4:5]
	v_mov_b32_e32 v162, v156
	s_movk_i32 s4, 0x7f
	v_ldexp_f32 v160, v160, v161
	v_mul_f32_e32 v160, 0x3d800000, v160
	v_cndmask_b32_e32 v164, 1.0, v160, vcc
	v_mov_b32_e32 v160, v100
	v_mov_b32_e32 v161, v80
	v_pk_mul_f32 v[160:161], v[160:161], v[162:163]
	s_nop 0
	v_sub_f32_e32 v152, v160, v161
	v_mov_b32_e32 v160, v80
	v_mov_b32_e32 v161, v100
	v_pk_mul_f32 v[160:161], v[160:161], v[162:163]
	v_mul_f32_e32 v165, v164, v152
	v_add_f32_e32 v152, v160, v161
	v_mul_f32_e32 v162, v164, v152
	v_mov_b32_e32 v160, v101
	v_mov_b32_e32 v161, v81
	v_mov_b32_e32 v152, v157
	v_pk_mul_f32 v[156:157], v[160:161], v[152:153]
	s_nop 0
	v_sub_f32_e32 v156, v156, v157
	v_mul_f32_e32 v160, v164, v156
	v_mov_b32_e32 v156, v81
	v_mov_b32_e32 v157, v101
	v_pk_mul_f32 v[152:153], v[156:157], v[152:153]
	v_mov_b32_e32 v156, v158
	v_add_f32_e32 v152, v152, v153
	v_mul_f32_e32 v161, v164, v152
	v_mov_b32_e32 v152, v102
	v_mov_b32_e32 v153, v82
	v_mov_b32_e32 v157, v154
	v_pk_mul_f32 v[152:153], v[152:153], v[156:157]
	v_mov_b32_e32 v154, v159
	v_sub_f32_e32 v152, v152, v153
	v_mul_f32_e32 v158, v164, v152
	v_mov_b32_e32 v152, v82
	v_mov_b32_e32 v153, v102
	v_pk_mul_f32 v[152:153], v[152:153], v[156:157]
	s_nop 0
	v_add_f32_e32 v152, v152, v153
	v_mul_f32_e32 v156, v164, v152
	v_mov_b32_e32 v152, v103
	v_mov_b32_e32 v153, v83
	v_pk_mul_f32 v[152:153], v[152:153], v[154:155]
	s_nop 0
	v_sub_f32_e32 v152, v152, v153
	v_mul_f32_e32 v157, v164, v152
	v_mov_b32_e32 v152, v83
	v_mov_b32_e32 v153, v103
	v_pk_mul_f32 v[152:153], v[152:153], v[154:155]
	v_mov_b32_e32 v154, v148
	v_add_f32_e32 v152, v152, v153
	v_mul_f32_e32 v159, v164, v152
	v_mov_b32_e32 v152, v92
	v_mov_b32_e32 v153, v72
	v_mov_b32_e32 v155, v144
	v_pk_mul_f32 v[152:153], v[152:153], v[154:155]
	s_nop 0
	v_sub_f32_e32 v144, v152, v153
	v_mov_b32_e32 v152, v72
	v_mov_b32_e32 v153, v92
	v_pk_mul_f32 v[152:153], v[152:153], v[154:155]
	v_mul_f32_e32 v163, v164, v144
	v_add_f32_e32 v144, v152, v153
	v_mul_f32_e32 v154, v164, v144
	v_mov_b32_e32 v152, v93
	v_mov_b32_e32 v153, v73
	v_mov_b32_e32 v144, v149
	v_pk_mul_f32 v[148:149], v[152:153], v[144:145]
	s_nop 0
	v_sub_f32_e32 v148, v148, v149
	v_mul_f32_e32 v152, v164, v148
	v_mov_b32_e32 v148, v73
	v_mov_b32_e32 v149, v93
	v_pk_mul_f32 v[144:145], v[148:149], v[144:145]
	v_mov_b32_e32 v148, v150
	v_add_f32_e32 v144, v144, v145
	v_mul_f32_e32 v153, v164, v144
	v_mov_b32_e32 v144, v94
	v_mov_b32_e32 v145, v74
	v_mov_b32_e32 v149, v146
	v_pk_mul_f32 v[144:145], v[144:145], v[148:149]
	v_mov_b32_e32 v146, v151
	v_sub_f32_e32 v144, v144, v145
	v_mul_f32_e32 v150, v164, v144
	v_mov_b32_e32 v144, v74
	v_mov_b32_e32 v145, v94
	v_pk_mul_f32 v[144:145], v[144:145], v[148:149]
	s_nop 0
	v_add_f32_e32 v144, v144, v145
	v_mul_f32_e32 v155, v164, v144
	v_mov_b32_e32 v144, v95
	v_mov_b32_e32 v145, v75
	v_pk_mul_f32 v[144:145], v[144:145], v[146:147]
	s_nop 0
	v_sub_f32_e32 v144, v144, v145
	v_mul_f32_e32 v148, v164, v144
	v_mov_b32_e32 v144, v75
	v_mov_b32_e32 v145, v95
	v_pk_mul_f32 v[144:145], v[144:145], v[146:147]
	s_nop 0
	v_add_f32_e32 v144, v144, v145
	v_mul_f32_e32 v151, v164, v144
	v_cvt_pk_bf16_f32 v144, v165, v160
	v_cvt_pk_bf16_f32 v145, v158, v157
	v_cvt_pk_bf16_f32 v146, v163, v152
	v_cvt_pk_bf16_f32 v147, v150, v148
	v_cvt_pk_bf16_f32 v148, v162, v161
	v_cvt_pk_bf16_f32 v149, v156, v159
	v_cvt_pk_bf16_f32 v150, v154, v153
	v_lshlrev_b64 v[152:153], 12, v[224:225]
	v_lshl_add_u64 v[152:153], v[230:231], 0, v[152:153]
	v_cvt_pk_bf16_f32 v151, v155, v151
	global_store_dwordx4 v[152:153], v[144:147], off
	global_store_dwordx4 v[152:153], v[148:151], off offset:256
	s_nop 0
	v_bitop3_b32 v144, v228, s4, 48 bitop3:0xc8
	v_add_u32_e32 v144, 1, v144
	v_cvt_f32_ubyte0_e32 v144, v144
	v_mul_f32_e64 v145, v241, -v144
	v_cmp_gt_f32_e64 s[4:5], s7, v145
	v_mov_b32_e32 v147, v136
	s_nop 0
	v_cndmask_b32_e64 v146, 0, v234, s[4:5]
	v_fma_f32 v144, v241, -v144, v146
	v_exp_f32_e32 v144, v144
	v_cndmask_b32_e64 v145, 0, v235, s[4:5]
	v_mov_b32_e32 v146, v140
	s_mov_b64 s[4:5], 0x80000
	v_ldexp_f32 v144, v144, v145
	v_mul_f32_e32 v144, 0x3d800000, v144
	v_cndmask_b32_e32 v148, 1.0, v144, vcc
	v_mov_b32_e32 v144, v84
	v_mov_b32_e32 v145, v68
	v_pk_mul_f32 v[144:145], v[144:145], v[146:147]
	s_nop 0
	v_sub_f32_e32 v136, v144, v145
	v_mov_b32_e32 v144, v68
	v_mov_b32_e32 v145, v84
	v_pk_mul_f32 v[144:145], v[144:145], v[146:147]
	v_mul_f32_e32 v149, v148, v136
	v_add_f32_e32 v136, v144, v145
	v_mul_f32_e32 v146, v148, v136
	v_mov_b32_e32 v144, v85
	v_mov_b32_e32 v145, v69
	v_mov_b32_e32 v136, v141
	v_pk_mul_f32 v[140:141], v[144:145], v[136:137]
	s_nop 0
	v_sub_f32_e32 v140, v140, v141
	v_mul_f32_e32 v144, v148, v140
	v_mov_b32_e32 v140, v69
	v_mov_b32_e32 v141, v85
	v_pk_mul_f32 v[136:137], v[140:141], v[136:137]
	v_mov_b32_e32 v140, v142
	v_add_f32_e32 v136, v136, v137
	v_mul_f32_e32 v145, v148, v136
	v_mov_b32_e32 v136, v86
	v_mov_b32_e32 v137, v70
	v_mov_b32_e32 v141, v138
	v_pk_mul_f32 v[136:137], v[136:137], v[140:141]
	v_mov_b32_e32 v138, v143
	v_sub_f32_e32 v136, v136, v137
	v_mul_f32_e32 v142, v148, v136
	v_mov_b32_e32 v136, v70
	v_mov_b32_e32 v137, v86
	v_pk_mul_f32 v[136:137], v[136:137], v[140:141]
	s_nop 0
	v_add_f32_e32 v136, v136, v137
	v_mul_f32_e32 v140, v148, v136
	v_mov_b32_e32 v136, v87
	v_mov_b32_e32 v137, v71
	v_pk_mul_f32 v[136:137], v[136:137], v[138:139]
	s_nop 0
	v_sub_f32_e32 v136, v136, v137
	v_mul_f32_e32 v141, v148, v136
	v_mov_b32_e32 v136, v71
	v_mov_b32_e32 v137, v87
	v_pk_mul_f32 v[136:137], v[136:137], v[138:139]
	v_mov_b32_e32 v138, v132
	v_add_f32_e32 v136, v136, v137
	v_mul_f32_e32 v143, v148, v136
	v_mov_b32_e32 v136, v76
	v_mov_b32_e32 v137, v64
	v_mov_b32_e32 v139, v128
	v_pk_mul_f32 v[136:137], v[136:137], v[138:139]
	s_nop 0
	v_sub_f32_e32 v128, v136, v137
	v_mov_b32_e32 v136, v64
	v_mov_b32_e32 v137, v76
	v_pk_mul_f32 v[136:137], v[136:137], v[138:139]
	v_mul_f32_e32 v147, v148, v128
	v_add_f32_e32 v128, v136, v137
	v_mul_f32_e32 v138, v148, v128
	v_mov_b32_e32 v136, v77
	v_mov_b32_e32 v137, v65
	v_mov_b32_e32 v128, v133
	v_pk_mul_f32 v[132:133], v[136:137], v[128:129]
	s_nop 0
	v_sub_f32_e32 v132, v132, v133
	v_mul_f32_e32 v136, v148, v132
	v_mov_b32_e32 v132, v65
	v_mov_b32_e32 v133, v77
	v_pk_mul_f32 v[128:129], v[132:133], v[128:129]
	v_mov_b32_e32 v132, v134
	v_add_f32_e32 v128, v128, v129
	v_mul_f32_e32 v137, v148, v128
	v_mov_b32_e32 v128, v78
	v_mov_b32_e32 v129, v66
	v_mov_b32_e32 v133, v130
	v_pk_mul_f32 v[128:129], v[128:129], v[132:133]
	v_mov_b32_e32 v130, v135
	v_sub_f32_e32 v128, v128, v129
	v_mul_f32_e32 v134, v148, v128
	v_mov_b32_e32 v128, v66
	v_mov_b32_e32 v129, v78
	v_pk_mul_f32 v[128:129], v[128:129], v[132:133]
	s_nop 0
	v_add_f32_e32 v128, v128, v129
	v_mul_f32_e32 v139, v148, v128
	v_mov_b32_e32 v128, v79
	v_mov_b32_e32 v129, v67
	v_pk_mul_f32 v[128:129], v[128:129], v[130:131]
	s_nop 0
	v_sub_f32_e32 v128, v128, v129
	v_mul_f32_e32 v132, v148, v128
	v_mov_b32_e32 v128, v67
	v_mov_b32_e32 v129, v79
	v_pk_mul_f32 v[128:129], v[128:129], v[130:131]
	s_nop 0
	v_add_f32_e32 v128, v128, v129
	v_mul_f32_e32 v135, v148, v128
	v_cvt_pk_bf16_f32 v128, v149, v144
	v_cvt_pk_bf16_f32 v129, v142, v141
	v_cvt_pk_bf16_f32 v130, v147, v136
	v_cvt_pk_bf16_f32 v131, v134, v132
	v_cvt_pk_bf16_f32 v132, v146, v145
	v_cvt_pk_bf16_f32 v133, v140, v143
	v_cvt_pk_bf16_f32 v134, v138, v137
	v_lshlrev_b64 v[136:137], 12, v[222:223]
	v_lshl_add_u64 v[136:137], v[230:231], 0, v[136:137]
	v_cvt_pk_bf16_f32 v135, v139, v135
	global_store_dwordx4 v[136:137], v[128:131], off
	global_store_dwordx4 v[136:137], v[132:135], off offset:256
	s_nop 0
	v_mov_b32_e32 v128, 0x4000
	v_lshl_add_u32 v128, v228, 7, v128
	v_and_b32_e32 v128, 0x7e780, v128
	v_lshlrev_b32_e32 v128, 2, v128
	v_mov_b32_e32 v129, v193
	v_lshl_add_u64 v[130:131], v[214:215], 0, v[128:129]
	v_lshl_add_u64 v[132:133], v[216:217], 0, v[128:129]
	global_load_dwordx4 v[168:171], v[130:131], off offset:16
	global_load_dwordx4 v[172:175], v[130:131], off
	global_load_dwordx4 v[178:181], v[132:133], off offset:16
	global_load_dwordx4 v[182:185], v[132:133], off
	v_or_b32_e32 v130, 0x2000, v128
	v_mov_b32_e32 v131, v193
	v_lshl_add_u64 v[132:133], v[214:215], 0, v[130:131]
	v_lshl_add_u64 v[130:131], v[216:217], 0, v[130:131]
	global_load_dwordx4 v[164:167], v[132:133], off offset:16
	global_load_dwordx4 v[186:189], v[132:133], off
	global_load_dwordx4 v[160:163], v[130:131], off offset:16
	global_load_dwordx4 v[196:199], v[130:131], off
	v_or_b32_e32 v130, 0x4000, v128
	v_mov_b32_e32 v131, v193
	v_lshl_add_u64 v[132:133], v[214:215], 0, v[130:131]
	v_lshl_add_u64 v[130:131], v[216:217], 0, v[130:131]
	global_load_dwordx4 v[148:151], v[132:133], off offset:16
	global_load_dwordx4 v[156:159], v[132:133], off
	global_load_dwordx4 v[144:147], v[130:131], off offset:16
	global_load_dwordx4 v[152:155], v[130:131], off
	v_or_b32_e32 v128, 0x6000, v128
	v_lshl_add_u64 v[130:131], v[214:215], 0, v[128:129]
	v_lshl_add_u64 v[136:137], v[216:217], 0, v[128:129]
	global_load_dwordx4 v[132:135], v[130:131], off offset:16
	global_load_dwordx4 v[140:143], v[130:131], off
	s_nop 0
	global_load_dwordx4 v[128:131], v[136:137], off offset:16
	s_nop 0
	global_load_dwordx4 v[136:139], v[136:137], off
	s_waitcnt vmcnt(0)
	v_mov_b32_e32 v244, v172
	v_mov_b32_e32 v245, v182
	v_pk_mul_f32 v[190:191], v[190:191], v[244:245]
	v_mov_b32_e32 v182, v173
	v_sub_f32_e32 v172, v190, v191
	v_mov_b32_e32 v190, v48
	v_mov_b32_e32 v191, v60
	v_pk_mul_f32 v[190:191], v[190:191], v[244:245]
	v_mul_f32_e32 v223, v242, v172
	v_add_f32_e32 v172, v190, v191
	v_mov_b32_e32 v190, v61
	v_mov_b32_e32 v191, v49
	v_mul_f32_e32 v225, v242, v172
	v_pk_mul_f32 v[172:173], v[190:191], v[182:183]
	s_nop 0
	v_sub_f32_e32 v172, v172, v173
	v_mul_f32_e32 v190, v242, v172
	v_mov_b32_e32 v172, v49
	v_mov_b32_e32 v173, v61
	v_pk_mul_f32 v[172:173], v[172:173], v[182:183]
	v_mov_b32_e32 v182, v174
	v_add_f32_e32 v172, v172, v173
	v_mul_f32_e32 v191, v242, v172
	v_mov_b32_e32 v172, v62
	v_mov_b32_e32 v173, v50
	v_mov_b32_e32 v183, v184
	v_pk_mul_f32 v[172:173], v[172:173], v[182:183]
	v_mov_b32_e32 v184, v175
	v_sub_f32_e32 v172, v172, v173
	v_mul_f32_e32 v243, v242, v172
	v_mov_b32_e32 v172, v50
	v_mov_b32_e32 v173, v62
	v_pk_mul_f32 v[172:173], v[172:173], v[182:183]
	v_mov_b32_e32 v174, v168
	v_add_f32_e32 v172, v172, v173
	v_mul_f32_e32 v182, v242, v172
	v_mov_b32_e32 v172, v63
	v_mov_b32_e32 v173, v51
	v_pk_mul_f32 v[172:173], v[172:173], v[184:185]
	v_mov_b32_e32 v175, v178
	v_sub_f32_e32 v172, v172, v173
	v_mul_f32_e32 v183, v242, v172
	v_mov_b32_e32 v172, v51
	v_mov_b32_e32 v173, v63
	v_pk_mul_f32 v[172:173], v[172:173], v[184:185]
	v_mov_b32_e32 v178, v169
	v_add_f32_e32 v172, v172, v173
	v_mul_f32_e32 v184, v242, v172
	v_mov_b32_e32 v172, v56
	v_mov_b32_e32 v173, v40
	v_pk_mul_f32 v[172:173], v[172:173], v[174:175]
	s_nop 0
	v_sub_f32_e32 v168, v172, v173
	v_mov_b32_e32 v172, v40
	v_mov_b32_e32 v173, v56
	v_pk_mul_f32 v[172:173], v[172:173], v[174:175]
	v_mul_f32_e32 v185, v242, v168
	v_add_f32_e32 v168, v172, v173
	v_mov_b32_e32 v172, v57
	v_mov_b32_e32 v173, v41
	v_mul_f32_e32 v174, v242, v168
	v_pk_mul_f32 v[168:169], v[172:173], v[178:179]
	v_mov_b32_e32 v172, v170
	v_sub_f32_e32 v168, v168, v169
	v_mul_f32_e32 v175, v242, v168
	v_mov_b32_e32 v168, v41
	v_mov_b32_e32 v169, v57
	v_pk_mul_f32 v[168:169], v[168:169], v[178:179]
	v_mov_b32_e32 v173, v180
	v_add_f32_e32 v168, v168, v169
	v_mul_f32_e32 v178, v242, v168
	v_mov_b32_e32 v168, v58
	v_mov_b32_e32 v169, v42
	v_pk_mul_f32 v[168:169], v[168:169], v[172:173]
	v_mov_b32_e32 v180, v171
	v_sub_f32_e32 v168, v168, v169
	v_mul_f32_e32 v179, v242, v168
	v_mov_b32_e32 v168, v42
	v_mov_b32_e32 v169, v58
	v_pk_mul_f32 v[168:169], v[168:169], v[172:173]
	s_nop 0
	v_add_f32_e32 v168, v168, v169
	v_mul_f32_e32 v244, v242, v168
	v_mov_b32_e32 v168, v59
	v_mov_b32_e32 v169, v43
	v_pk_mul_f32 v[168:169], v[168:169], v[180:181]
	s_nop 0
	v_sub_f32_e32 v168, v168, v169
	v_mul_f32_e32 v171, v242, v168
	v_mov_b32_e32 v168, v43
	v_mov_b32_e32 v169, v59
	v_pk_mul_f32 v[168:169], v[168:169], v[180:181]
	s_nop 0
	v_add_f32_e32 v168, v168, v169
	v_mul_f32_e32 v180, v242, v168
	v_cvt_pk_bf16_f32 v168, v223, v190
	v_cvt_pk_bf16_f32 v169, v243, v183
	v_cvt_pk_bf16_f32 v170, v185, v175
	v_cvt_pk_bf16_f32 v171, v179, v171
	v_cvt_pk_bf16_f32 v172, v225, v191
	v_cvt_pk_bf16_f32 v173, v182, v184
	v_cvt_pk_bf16_f32 v174, v174, v178
	v_lshl_add_u64 v[178:179], v[176:177], 0, s[4:5]
	s_mov_b32 s4, 0x80000
	v_add_co_u32_e64 v176, s[4:5], s4, v176
	v_cvt_pk_bf16_f32 v175, v244, v180
	s_nop 1
	v_addc_co_u32_e64 v177, s[4:5], 0, v177, s[4:5]
	global_store_dwordx4 v[176:177], v[168:171], off
	global_store_dwordx4 v[178:179], v[172:175], off offset:256
	s_nop 0
	v_add_u32_e32 v168, 0x90, v228
	v_and_b32_e32 v169, 0x5f, v168
	v_add_u32_e32 v169, 1, v169
	v_cvt_f32_ubyte0_e32 v169, v169
	v_mul_f32_e64 v170, v241, -v169
	v_cmp_gt_f32_e64 s[4:5], s7, v170
	v_mov_b32_e32 v171, v32
	v_mov_b32_e32 v172, v186
	v_cndmask_b32_e64 v170, 0, v234, s[4:5]
	v_fma_f32 v169, v241, -v169, v170
	v_exp_f32_e32 v169, v169
	v_cndmask_b32_e64 v170, 0, v235, s[4:5]
	v_mov_b32_e32 v173, v196
	v_mov_b32_e32 v196, v187
	v_ldexp_f32 v169, v169, v170
	v_mov_b32_e32 v170, v52
	v_mul_f32_e32 v169, 0x3d800000, v169
	v_pk_mul_f32 v[170:171], v[170:171], v[172:173]
	v_cndmask_b32_e32 v169, 1.0, v169, vcc
	v_sub_f32_e32 v170, v170, v171
	v_mul_f32_e32 v174, v169, v170
	v_mov_b32_e32 v170, v32
	v_mov_b32_e32 v171, v52
	v_pk_mul_f32 v[170:171], v[170:171], v[172:173]
	v_mov_b32_e32 v172, v188
	v_add_f32_e32 v170, v170, v171
	v_mul_f32_e32 v175, v169, v170
	v_mov_b32_e32 v170, v53
	v_mov_b32_e32 v171, v33
	v_pk_mul_f32 v[170:171], v[170:171], v[196:197]
	v_mov_b32_e32 v173, v198
	v_sub_f32_e32 v170, v170, v171
	v_mul_f32_e32 v176, v169, v170
	v_mov_b32_e32 v170, v33
	v_mov_b32_e32 v171, v53
	v_pk_mul_f32 v[170:171], v[170:171], v[196:197]
	v_mov_b32_e32 v198, v189
	v_add_f32_e32 v170, v170, v171
	v_mul_f32_e32 v177, v169, v170
	v_mov_b32_e32 v170, v54
	v_mov_b32_e32 v171, v34
	v_pk_mul_f32 v[170:171], v[170:171], v[172:173]
	s_nop 0
	v_sub_f32_e32 v170, v170, v171
	v_mul_f32_e32 v178, v169, v170
	v_mov_b32_e32 v170, v34
	v_mov_b32_e32 v171, v54
	v_pk_mul_f32 v[170:171], v[170:171], v[172:173]
	v_mov_b32_e32 v172, v164
	v_add_f32_e32 v170, v170, v171
	v_mul_f32_e32 v179, v169, v170
	v_mov_b32_e32 v170, v55
	v_mov_b32_e32 v171, v35
	v_pk_mul_f32 v[170:171], v[170:171], v[198:199]
	v_mov_b32_e32 v173, v160
	v_sub_f32_e32 v170, v170, v171
	v_mul_f32_e32 v180, v169, v170
	v_mov_b32_e32 v170, v35
	v_mov_b32_e32 v171, v55
	v_pk_mul_f32 v[170:171], v[170:171], v[198:199]
	s_nop 0
	v_add_f32_e32 v170, v170, v171
	v_mul_f32_e32 v181, v169, v170
	v_mov_b32_e32 v170, v44
	v_mov_b32_e32 v171, v24
	v_pk_mul_f32 v[170:171], v[170:171], v[172:173]
	s_nop 0
	v_sub_f32_e32 v160, v170, v171
	v_mov_b32_e32 v170, v24
	v_mov_b32_e32 v171, v44
	v_pk_mul_f32 v[170:171], v[170:171], v[172:173]
	v_mul_f32_e32 v182, v169, v160
	v_add_f32_e32 v160, v170, v171
	v_mul_f32_e32 v172, v169, v160
	v_mov_b32_e32 v170, v45
	v_mov_b32_e32 v171, v25
	v_mov_b32_e32 v160, v165
	v_pk_mul_f32 v[164:165], v[170:171], v[160:161]
	s_nop 0
	v_sub_f32_e32 v164, v164, v165
	v_mul_f32_e32 v170, v169, v164
	v_mov_b32_e32 v164, v25
	v_mov_b32_e32 v165, v45
	v_pk_mul_f32 v[160:161], v[164:165], v[160:161]
	v_mov_b32_e32 v164, v166
	v_add_f32_e32 v160, v160, v161
	v_mul_f32_e32 v171, v169, v160
	v_mov_b32_e32 v160, v46
	v_mov_b32_e32 v161, v26
	v_mov_b32_e32 v165, v162
	v_pk_mul_f32 v[160:161], v[160:161], v[164:165]
	v_mov_b32_e32 v162, v167
	v_sub_f32_e32 v160, v160, v161
	v_mul_f32_e32 v166, v169, v160
	v_mov_b32_e32 v160, v26
	v_mov_b32_e32 v161, v46
	v_pk_mul_f32 v[160:161], v[160:161], v[164:165]
	s_nop 0
	v_add_f32_e32 v160, v160, v161
	v_mul_f32_e32 v173, v169, v160
	v_mov_b32_e32 v160, v47
	v_mov_b32_e32 v161, v27
	v_pk_mul_f32 v[160:161], v[160:161], v[162:163]
	s_nop 0
	v_sub_f32_e32 v160, v160, v161
	v_mul_f32_e32 v164, v169, v160
	v_mov_b32_e32 v160, v27
	v_mov_b32_e32 v161, v47
	v_pk_mul_f32 v[160:161], v[160:161], v[162:163]
	s_nop 0
	v_add_f32_e32 v160, v160, v161
	v_mul_f32_e32 v167, v169, v160
	v_ashrrev_i32_e32 v169, 31, v168
	v_lshlrev_b64 v[168:169], 12, v[168:169]
	v_cvt_pk_bf16_f32 v160, v174, v176
	v_cvt_pk_bf16_f32 v161, v178, v180
	v_cvt_pk_bf16_f32 v162, v182, v170
	v_cvt_pk_bf16_f32 v163, v166, v164
	v_lshl_add_u64 v[168:169], v[230:231], 0, v[168:169]
	v_cvt_pk_bf16_f32 v164, v175, v177
	v_cvt_pk_bf16_f32 v165, v179, v181
	v_cvt_pk_bf16_f32 v166, v172, v171
	v_cvt_pk_bf16_f32 v167, v173, v167
	global_store_dwordx4 v[168:169], v[160:163], off
	global_store_dwordx4 v[168:169], v[164:167], off offset:256
	s_nop 0
	v_add_u32_e32 v160, 0xa0, v228
	v_and_b32_e32 v161, 0x6f, v160
	v_add_u32_e32 v161, 1, v161
	v_cvt_f32_ubyte0_e32 v161, v161
	v_mul_f32_e64 v162, v241, -v161
	v_cmp_gt_f32_e64 s[4:5], s7, v162
	v_mov_b32_e32 v163, v16
	v_mov_b32_e32 v164, v156
	v_cndmask_b32_e64 v162, 0, v234, s[4:5]
	v_fma_f32 v161, v241, -v161, v162
	v_exp_f32_e32 v161, v161
	v_cndmask_b32_e64 v162, 0, v235, s[4:5]
	v_mov_b32_e32 v165, v152
	v_ldexp_f32 v161, v161, v162
	v_mov_b32_e32 v162, v36
	v_pk_mul_f32 v[162:163], v[162:163], v[164:165]
	v_mul_f32_e32 v161, 0x3d800000, v161
	v_sub_f32_e32 v152, v162, v163
	v_mov_b32_e32 v162, v16
	v_mov_b32_e32 v163, v36
	v_cndmask_b32_e32 v161, 1.0, v161, vcc
	v_pk_mul_f32 v[162:163], v[162:163], v[164:165]
	v_mul_f32_e32 v166, v161, v152
	v_add_f32_e32 v152, v162, v163
	v_mul_f32_e32 v164, v161, v152
	v_mov_b32_e32 v162, v37
	v_mov_b32_e32 v163, v17
	v_mov_b32_e32 v152, v157
	v_pk_mul_f32 v[156:157], v[162:163], v[152:153]
	s_nop 0
	v_sub_f32_e32 v156, v156, v157
	v_mul_f32_e32 v162, v161, v156
	v_mov_b32_e32 v156, v17
	v_mov_b32_e32 v157, v37
	v_pk_mul_f32 v[152:153], v[156:157], v[152:153]
	v_mov_b32_e32 v156, v158
	v_add_f32_e32 v152, v152, v153
	v_mul_f32_e32 v163, v161, v152
	v_mov_b32_e32 v152, v38
	v_mov_b32_e32 v153, v18
	v_mov_b32_e32 v157, v154
	v_pk_mul_f32 v[152:153], v[152:153], v[156:157]
	v_mov_b32_e32 v154, v159
	v_sub_f32_e32 v152, v152, v153
	v_mul_f32_e32 v158, v161, v152
	v_mov_b32_e32 v152, v18
	v_mov_b32_e32 v153, v38
	v_pk_mul_f32 v[152:153], v[152:153], v[156:157]
	s_nop 0
	v_add_f32_e32 v152, v152, v153
	v_mul_f32_e32 v156, v161, v152
	v_mov_b32_e32 v152, v39
	v_mov_b32_e32 v153, v19
	v_pk_mul_f32 v[152:153], v[152:153], v[154:155]
	s_nop 0
	v_sub_f32_e32 v152, v152, v153
	v_mul_f32_e32 v157, v161, v152
	v_mov_b32_e32 v152, v19
	v_mov_b32_e32 v153, v39
	v_pk_mul_f32 v[152:153], v[152:153], v[154:155]
	v_mov_b32_e32 v154, v148
	v_add_f32_e32 v152, v152, v153
	v_mul_f32_e32 v159, v161, v152
	v_mov_b32_e32 v152, v28
	v_mov_b32_e32 v153, v8
	v_mov_b32_e32 v155, v144
	v_pk_mul_f32 v[152:153], v[152:153], v[154:155]
	s_nop 0
	v_sub_f32_e32 v144, v152, v153
	v_mov_b32_e32 v152, v8
	v_mov_b32_e32 v153, v28
	v_pk_mul_f32 v[152:153], v[152:153], v[154:155]
	v_mul_f32_e32 v165, v161, v144
	v_add_f32_e32 v144, v152, v153
	v_mul_f32_e32 v154, v161, v144
	v_mov_b32_e32 v152, v29
	v_mov_b32_e32 v153, v9
	v_mov_b32_e32 v144, v149
	v_pk_mul_f32 v[148:149], v[152:153], v[144:145]
	s_nop 0
	v_sub_f32_e32 v148, v148, v149
	v_mul_f32_e32 v152, v161, v148
	v_mov_b32_e32 v148, v9
	v_mov_b32_e32 v149, v29
	v_pk_mul_f32 v[144:145], v[148:149], v[144:145]
	v_mov_b32_e32 v148, v150
	v_add_f32_e32 v144, v144, v145
	v_mul_f32_e32 v153, v161, v144
	v_mov_b32_e32 v144, v30
	v_mov_b32_e32 v145, v10
	v_mov_b32_e32 v149, v146
	v_pk_mul_f32 v[144:145], v[144:145], v[148:149]
	v_mov_b32_e32 v146, v151
	v_sub_f32_e32 v144, v144, v145
	v_mul_f32_e32 v150, v161, v144
	v_mov_b32_e32 v144, v10
	v_mov_b32_e32 v145, v30
	v_pk_mul_f32 v[144:145], v[144:145], v[148:149]
	s_nop 0
	v_add_f32_e32 v144, v144, v145
	v_mul_f32_e32 v155, v161, v144
	v_mov_b32_e32 v144, v31
	v_mov_b32_e32 v145, v11
	v_pk_mul_f32 v[144:145], v[144:145], v[146:147]
	s_nop 0
	v_sub_f32_e32 v144, v144, v145
	v_mul_f32_e32 v148, v161, v144
	v_mov_b32_e32 v144, v11
	v_mov_b32_e32 v145, v31
	v_pk_mul_f32 v[144:145], v[144:145], v[146:147]
	s_nop 0
	v_add_f32_e32 v144, v144, v145
	v_mul_f32_e32 v151, v161, v144
	v_ashrrev_i32_e32 v161, 31, v160
	v_cvt_pk_bf16_f32 v144, v166, v162
	v_cvt_pk_bf16_f32 v145, v158, v157
	v_cvt_pk_bf16_f32 v146, v165, v152
	v_cvt_pk_bf16_f32 v147, v150, v148
	v_cvt_pk_bf16_f32 v148, v164, v163
	v_cvt_pk_bf16_f32 v149, v156, v159
	v_cvt_pk_bf16_f32 v150, v154, v153
	v_lshlrev_b64 v[152:153], 12, v[160:161]
	v_lshl_add_u64 v[152:153], v[230:231], 0, v[152:153]
	v_cvt_pk_bf16_f32 v151, v155, v151
	global_store_dwordx4 v[152:153], v[144:147], off
	global_store_dwordx4 v[152:153], v[148:151], off offset:256
	s_nop 0
	v_add_u32_e32 v144, 0xb0, v228
	v_and_b32_e32 v145, 0x7f, v144
	v_add_u32_e32 v145, 1, v145
	v_cvt_f32_ubyte0_e32 v145, v145
	v_mul_f32_e64 v146, v241, -v145
	v_cmp_gt_f32_e64 s[4:5], s7, v146
	v_mov_b32_e32 v147, v4
	v_mov_b32_e32 v148, v140
	v_cndmask_b32_e64 v146, 0, v234, s[4:5]
	v_fma_f32 v145, v241, -v145, v146
	v_exp_f32_e32 v145, v145
	v_cndmask_b32_e64 v146, 0, v235, s[4:5]
	v_mov_b32_e32 v149, v136
	s_mov_b64 s[4:5], 0
	v_ldexp_f32 v145, v145, v146
	v_mov_b32_e32 v146, v20
	v_pk_mul_f32 v[146:147], v[146:147], v[148:149]
	v_mul_f32_e32 v145, 0x3d800000, v145
	v_sub_f32_e32 v136, v146, v147
	v_mov_b32_e32 v146, v4
	v_mov_b32_e32 v147, v20
	v_cndmask_b32_e32 v145, 1.0, v145, vcc
	v_pk_mul_f32 v[146:147], v[146:147], v[148:149]
	v_mul_f32_e32 v150, v145, v136
	v_add_f32_e32 v136, v146, v147
	v_mul_f32_e32 v148, v145, v136
	v_mov_b32_e32 v146, v21
	v_mov_b32_e32 v147, v5
	v_mov_b32_e32 v136, v141
	v_pk_mul_f32 v[140:141], v[146:147], v[136:137]
	s_nop 0
	v_sub_f32_e32 v140, v140, v141
	v_mul_f32_e32 v146, v145, v140
	v_mov_b32_e32 v140, v5
	v_mov_b32_e32 v141, v21
	v_pk_mul_f32 v[136:137], v[140:141], v[136:137]
	v_mov_b32_e32 v140, v142
	v_add_f32_e32 v136, v136, v137
	v_mul_f32_e32 v147, v145, v136
	v_mov_b32_e32 v136, v22
	v_mov_b32_e32 v137, v6
	v_mov_b32_e32 v141, v138
	v_pk_mul_f32 v[136:137], v[136:137], v[140:141]
	v_mov_b32_e32 v138, v143
	v_sub_f32_e32 v136, v136, v137
	v_mul_f32_e32 v142, v145, v136
	v_mov_b32_e32 v136, v6
	v_mov_b32_e32 v137, v22
	v_pk_mul_f32 v[136:137], v[136:137], v[140:141]
	s_nop 0
	v_add_f32_e32 v136, v136, v137
	v_mul_f32_e32 v140, v145, v136
	v_mov_b32_e32 v136, v23
	v_mov_b32_e32 v137, v7
	v_pk_mul_f32 v[136:137], v[136:137], v[138:139]
	s_nop 0
	v_sub_f32_e32 v136, v136, v137
	v_mul_f32_e32 v141, v145, v136
	v_mov_b32_e32 v136, v7
	v_mov_b32_e32 v137, v23
	v_pk_mul_f32 v[136:137], v[136:137], v[138:139]
	v_mov_b32_e32 v138, v132
	v_add_f32_e32 v136, v136, v137
	v_mul_f32_e32 v143, v145, v136
	v_mov_b32_e32 v136, v12
	v_mov_b32_e32 v137, v0
	v_mov_b32_e32 v139, v128
	v_pk_mul_f32 v[136:137], v[136:137], v[138:139]
	s_nop 0
	v_sub_f32_e32 v128, v136, v137
	v_mov_b32_e32 v136, v0
	v_mov_b32_e32 v137, v12
	v_pk_mul_f32 v[136:137], v[136:137], v[138:139]
	v_mul_f32_e32 v149, v145, v128
	v_add_f32_e32 v128, v136, v137
	v_mul_f32_e32 v138, v145, v128
	v_mov_b32_e32 v136, v13
	v_mov_b32_e32 v137, v1
	v_mov_b32_e32 v128, v133
	v_pk_mul_f32 v[132:133], v[136:137], v[128:129]
	s_nop 0
	v_sub_f32_e32 v132, v132, v133
	v_mul_f32_e32 v136, v145, v132
	v_mov_b32_e32 v132, v1
	v_mov_b32_e32 v133, v13
	v_pk_mul_f32 v[128:129], v[132:133], v[128:129]
	v_mov_b32_e32 v132, v134
	v_add_f32_e32 v128, v128, v129
	v_mul_f32_e32 v139, v145, v128
	v_mov_b32_e32 v128, v14
	v_mov_b32_e32 v129, v2
	v_mov_b32_e32 v133, v130
	v_pk_mul_f32 v[128:129], v[128:129], v[132:133]
	v_mov_b32_e32 v130, v135
	v_sub_f32_e32 v128, v128, v129
	v_mul_f32_e32 v137, v145, v128
	v_mov_b32_e32 v128, v2
	v_mov_b32_e32 v129, v14
	v_pk_mul_f32 v[128:129], v[128:129], v[132:133]
	v_cvt_pk_bf16_f32 v134, v150, v146
	v_cvt_pk_bf16_f32 v135, v142, v141
	v_cvt_pk_bf16_f32 v136, v149, v136
	s_nop 0
	v_add_f32_e32 v128, v128, v129
	v_mul_f32_e32 v132, v145, v128
	v_mov_b32_e32 v128, v15
	v_mov_b32_e32 v129, v3
	v_pk_mul_f32 v[128:129], v[128:129], v[130:131]
	s_nop 0
	v_sub_f32_e32 v128, v128, v129
	v_mul_f32_e32 v133, v145, v128
	v_mov_b32_e32 v128, v3
	v_mov_b32_e32 v129, v15
	v_pk_mul_f32 v[128:129], v[128:129], v[130:131]
	v_cvt_pk_bf16_f32 v137, v137, v133
	s_nop 0
	v_add_f32_e32 v128, v128, v129
	v_mul_f32_e32 v131, v145, v128
	v_ashrrev_i32_e32 v145, 31, v144
	v_cvt_pk_bf16_f32 v128, v148, v147
	v_cvt_pk_bf16_f32 v129, v140, v143
	v_cvt_pk_bf16_f32 v130, v138, v139
	v_cvt_pk_bf16_f32 v131, v132, v131
	v_lshlrev_b64 v[132:133], 12, v[144:145]
	v_lshl_add_u64 v[132:133], v[230:231], 0, v[132:133]
	global_store_dwordx4 v[132:133], v[134:137], off

.LBB0_216:
	v_mov_b64_e32 v[0:1], 0x1600
	s_ashr_i32 s7, s6, 31
	v_cmp_lt_i64_e32 vcc, s[8:9], v[0:1]
	s_lshl_b64 s[8:9], s[6:7], 20
	s_add_u32 s8, s22, s8
	s_addc_u32 s9, s23, s9
	s_and_b64 s[10:11], vcc, exec
	s_cselect_b32 s7, s9, s15
	s_cselect_b32 s36, s8, s14
	s_ashr_i32 s5, s4, 31
	s_lshl_b64 s[10:11], s[4:5], 20
	s_add_u32 s10, s24, s10
	s_addc_u32 s11, s25, s11
	s_and_b64 s[18:19], vcc, exec
	s_cselect_b32 s5, s11, s17
	s_cselect_b32 s37, s10, s16
	s_add_u32 s14, s14, 0x80080
	s_addc_u32 s15, s15, 0
	s_add_u32 s38, s16, 0x100
	s_addc_u32 s39, s17, 0
	s_mov_b32 s40, -2
	s_mov_b64 s[48:49], 0x80
	v_add_u32_e32 v220, 0x10000, v141
	s_add_u32 s16, s14, 0xfff80080
	s_addc_u32 s17, s15, -1
	s_add_i32 s41, 0, 0x10000
	ds_read_b128 v[144:147], v220 offset:0
	ds_read_b128 v[148:151], v220 offset:1024
	ds_read_b128 v[152:155], v220 offset:2048
	ds_read_b128 v[156:159], v220 offset:3072
	s_cmp_eq_u32 s40, 28
	s_cselect_b32 s19, s7, s17
	s_cselect_b32 s18, s36, s16
	s_cselect_b32 s17, s5, s39
	s_cselect_b32 s16, s37, s38
	s_add_i32 m0, s13, 0xc000
	ds_read_b128 v[160:163], v143
	ds_read_b128 v[164:167], v143 offset:1024
	ds_read_b128 v[168:171], v143 offset:2048
	ds_read_b128 v[172:175], v143 offset:3072
	ds_read_b128 v[176:179], v143 offset:4096
	ds_read_b128 v[180:183], v143 offset:5120
	ds_read_b128 v[184:187], v143 offset:6144
	ds_read_b128 v[188:191], v143 offset:7168
	global_load_lds_dwordx4 v134, s[14:15]
	s_add_i32 m0, s13, 0xe000
	s_nop 0
	global_load_lds_dwordx4 v136, s[14:15]
	s_waitcnt lgkmcnt(8)
	s_barrier
	s_waitcnt lgkmcnt(0)
	v_mfma_f32_16x16x32_bf16 v[124:127], v[144:147], v[160:163], 0
	v_mfma_f32_16x16x32_bf16 v[116:119], v[152:155], v[160:163], 0
	v_mfma_f32_16x16x32_bf16 v[108:111], v[144:147], v[168:171], 0
	v_mfma_f32_16x16x32_bf16 v[100:103], v[152:155], v[168:171], 0
	s_add_i32 s44, 0, 0x14000
	s_add_i32 s41, s41, s26
	v_mfma_f32_16x16x32_bf16 v[92:95], v[144:147], v[176:179], 0
	s_mov_b32 m0, s41
	v_mfma_f32_16x16x32_bf16 v[84:87], v[152:155], v[176:179], 0
	v_mfma_f32_16x16x32_bf16 v[76:79], v[144:147], v[184:187], 0
	v_mfma_f32_16x16x32_bf16 v[68:71], v[152:155], v[184:187], 0
	v_mfma_f32_16x16x32_bf16 v[124:127], v[148:151], v[164:167], v[124:127]
	v_mfma_f32_16x16x32_bf16 v[116:119], v[156:159], v[164:167], v[116:119]
	v_mfma_f32_16x16x32_bf16 v[108:111], v[148:151], v[172:175], v[108:111]
	v_mfma_f32_16x16x32_bf16 v[100:103], v[156:159], v[172:175], v[100:103]
	v_mfma_f32_16x16x32_bf16 v[92:95], v[148:151], v[180:183], v[92:95]
	v_mfma_f32_16x16x32_bf16 v[84:87], v[156:159], v[180:183], v[84:87]
	v_mfma_f32_16x16x32_bf16 v[76:79], v[148:151], v[188:191], v[76:79]
	v_mfma_f32_16x16x32_bf16 v[68:71], v[156:159], v[188:191], v[68:71]
	s_barrier
	ds_read_b128 v[196:199], v220 offset:16384
	ds_read_b128 v[204:207], v220 offset:17408
	ds_read_b128 v[208:211], v220 offset:18432
	ds_read_b128 v[214:217], v220 offset:19456
	global_load_lds_dwordx4 v192, s[16:17]
	s_add_i32 m0, s41, 0x2000
	s_nop 0
	global_load_lds_dwordx4 v128, s[16:17]
	s_barrier
	s_waitcnt lgkmcnt(0)
	v_mfma_f32_16x16x32_bf16 v[120:123], v[196:199], v[160:163], 0
	v_mfma_f32_16x16x32_bf16 v[112:115], v[208:211], v[160:163], 0
	v_mfma_f32_16x16x32_bf16 v[104:107], v[196:199], v[168:171], 0
	v_mfma_f32_16x16x32_bf16 v[96:99], v[208:211], v[168:171], 0
	s_mov_b32 m0, s13
	v_mfma_f32_16x16x32_bf16 v[88:91], v[196:199], v[176:179], 0
	s_add_u32 s48, s18, 0x80
	s_addc_u32 s49, s19, 0
	v_mfma_f32_16x16x32_bf16 v[80:83], v[208:211], v[176:179], 0
	v_mfma_f32_16x16x32_bf16 v[72:75], v[196:199], v[184:187], 0
	v_mfma_f32_16x16x32_bf16 v[64:67], v[208:211], v[184:187], 0
	v_mfma_f32_16x16x32_bf16 v[120:123], v[204:207], v[164:167], v[120:123]
	v_mfma_f32_16x16x32_bf16 v[112:115], v[214:217], v[164:167], v[112:115]
	v_mfma_f32_16x16x32_bf16 v[104:107], v[204:207], v[172:175], v[104:107]
	v_mfma_f32_16x16x32_bf16 v[96:99], v[214:217], v[172:175], v[96:99]
	v_mfma_f32_16x16x32_bf16 v[88:91], v[204:207], v[180:183], v[88:91]
	v_mfma_f32_16x16x32_bf16 v[80:83], v[214:217], v[180:183], v[80:83]
	v_mfma_f32_16x16x32_bf16 v[72:75], v[204:207], v[188:191], v[72:75]
	v_mfma_f32_16x16x32_bf16 v[64:67], v[214:217], v[188:191], v[64:67]
	s_barrier
	ds_read_b128 v[160:163], v143 offset:16384
	ds_read_b128 v[164:167], v143 offset:17408
	ds_read_b128 v[168:171], v143 offset:18432
	ds_read_b128 v[172:175], v143 offset:19456
	ds_read_b128 v[176:179], v143 offset:20480
	ds_read_b128 v[180:183], v143 offset:21504
	ds_read_b128 v[184:187], v143 offset:22528
	ds_read_b128 v[188:191], v143 offset:23552
	global_load_lds_dwordx4 v132, s[18:19]
	s_mov_b32 m0, s28
	s_nop 0
	global_load_lds_dwordx4 v130, s[18:19]
	s_waitcnt lgkmcnt(0)
	s_barrier
	v_mfma_f32_16x16x32_bf16 v[60:63], v[144:147], v[160:163], 0
	v_mfma_f32_16x16x32_bf16 v[52:55], v[152:155], v[160:163], 0
	v_mfma_f32_16x16x32_bf16 v[44:47], v[144:147], v[168:171], 0
	v_mfma_f32_16x16x32_bf16 v[36:39], v[152:155], v[168:171], 0
	s_add_u32 s42, s16, 0x80000
	s_addc_u32 s43, s17, 0
	v_mfma_f32_16x16x32_bf16 v[28:31], v[144:147], v[176:179], 0
	s_add_i32 s41, s44, s26
	s_mov_b32 m0, s41
	v_mfma_f32_16x16x32_bf16 v[20:23], v[152:155], v[176:179], 0
	v_mfma_f32_16x16x32_bf16 v[12:15], v[144:147], v[184:187], 0
	v_mfma_f32_16x16x32_bf16 v[4:7], v[152:155], v[184:187], 0
	v_mfma_f32_16x16x32_bf16 v[60:63], v[148:151], v[164:167], v[60:63]
	v_mfma_f32_16x16x32_bf16 v[52:55], v[156:159], v[164:167], v[52:55]
	v_mfma_f32_16x16x32_bf16 v[44:47], v[148:151], v[172:175], v[44:47]
	v_mfma_f32_16x16x32_bf16 v[36:39], v[156:159], v[172:175], v[36:39]
	v_mfma_f32_16x16x32_bf16 v[28:31], v[148:151], v[180:183], v[28:31]
	v_mfma_f32_16x16x32_bf16 v[20:23], v[156:159], v[180:183], v[20:23]
	v_mfma_f32_16x16x32_bf16 v[12:15], v[148:151], v[188:191], v[12:15]
	v_mfma_f32_16x16x32_bf16 v[4:7], v[156:159], v[188:191], v[4:7]
	s_barrier
	global_load_lds_dwordx4 v192, s[42:43]
	s_add_i32 m0, s41, 0x2000
	s_nop 0
	global_load_lds_dwordx4 v128, s[42:43]
	s_add_u32 s18, s18, 0x80000
	s_addc_u32 s19, s19, 0
	s_mov_b32 m0, s29
	s_nop 0
	global_load_lds_dwordx4 v132, s[18:19]
	s_mov_b32 m0, s30
	s_nop 0
	global_load_lds_dwordx4 v130, s[18:19]
	s_waitcnt vmcnt(8)
	s_barrier
	v_mfma_f32_16x16x32_bf16 v[56:59], v[196:199], v[160:163], 0
	v_mfma_f32_16x16x32_bf16 v[48:51], v[208:211], v[160:163], 0
	v_mfma_f32_16x16x32_bf16 v[40:43], v[196:199], v[168:171], 0
	v_mfma_f32_16x16x32_bf16 v[32:35], v[208:211], v[168:171], 0
	s_add_i32 s41, 0, 0x18000
	v_mfma_f32_16x16x32_bf16 v[24:27], v[196:199], v[176:179], 0
	v_mfma_f32_16x16x32_bf16 v[16:19], v[208:211], v[176:179], 0
	v_mfma_f32_16x16x32_bf16 v[8:11], v[196:199], v[184:187], 0
	v_mfma_f32_16x16x32_bf16 v[0:3], v[208:211], v[184:187], 0
	v_mfma_f32_16x16x32_bf16 v[56:59], v[204:207], v[164:167], v[56:59]
	v_mfma_f32_16x16x32_bf16 v[48:51], v[214:217], v[164:167], v[48:51]
	v_mfma_f32_16x16x32_bf16 v[40:43], v[204:207], v[172:175], v[40:43]
	v_mfma_f32_16x16x32_bf16 v[32:35], v[214:217], v[172:175], v[32:35]
	v_mfma_f32_16x16x32_bf16 v[24:27], v[204:207], v[180:183], v[24:27]
	v_mfma_f32_16x16x32_bf16 v[16:19], v[214:217], v[180:183], v[16:19]
	v_mfma_f32_16x16x32_bf16 v[8:11], v[204:207], v[188:191], v[8:11]
	v_mfma_f32_16x16x32_bf16 v[0:3], v[214:217], v[188:191], v[0:3]
	s_barrier
	ds_read_b128 v[144:147], v220 offset:32768
	ds_read_b128 v[148:151], v220 offset:33792
	ds_read_b128 v[152:155], v220 offset:34816
	ds_read_b128 v[156:159], v220 offset:35840
	ds_read_b128 v[160:163], v143 offset:32768
	ds_read_b128 v[164:167], v143 offset:33792
	ds_read_b128 v[168:171], v143 offset:34816
	ds_read_b128 v[172:175], v143 offset:35840
	ds_read_b128 v[176:179], v143 offset:36864
	ds_read_b128 v[180:183], v143 offset:37888
	ds_read_b128 v[184:187], v143 offset:38912
	ds_read_b128 v[188:191], v143 offset:39936
	s_waitcnt lgkmcnt(8)
	s_barrier
	s_waitcnt lgkmcnt(0)
	v_mfma_f32_16x16x32_bf16 v[124:127], v[144:147], v[160:163], v[124:127]
	v_mfma_f32_16x16x32_bf16 v[116:119], v[152:155], v[160:163], v[116:119]
	v_mfma_f32_16x16x32_bf16 v[108:111], v[144:147], v[168:171], v[108:111]
	v_mfma_f32_16x16x32_bf16 v[100:103], v[152:155], v[168:171], v[100:103]
	s_add_i32 s18, 0, 0x1c000
	s_add_i32 s19, s41, s26
	v_mfma_f32_16x16x32_bf16 v[92:95], v[144:147], v[176:179], v[92:95]
	s_add_i32 m0, s19, 0xffffff80
	v_mfma_f32_16x16x32_bf16 v[84:87], v[152:155], v[176:179], v[84:87]
	v_mfma_f32_16x16x32_bf16 v[76:79], v[144:147], v[184:187], v[76:79]
	v_mfma_f32_16x16x32_bf16 v[68:71], v[152:155], v[184:187], v[68:71]
	v_mfma_f32_16x16x32_bf16 v[124:127], v[148:151], v[164:167], v[124:127]
	v_mfma_f32_16x16x32_bf16 v[116:119], v[156:159], v[164:167], v[116:119]
	v_mfma_f32_16x16x32_bf16 v[108:111], v[148:151], v[172:175], v[108:111]
	v_mfma_f32_16x16x32_bf16 v[100:103], v[156:159], v[172:175], v[100:103]
	v_mfma_f32_16x16x32_bf16 v[92:95], v[148:151], v[180:183], v[92:95]
	v_mfma_f32_16x16x32_bf16 v[84:87], v[156:159], v[180:183], v[84:87]
	v_mfma_f32_16x16x32_bf16 v[76:79], v[148:151], v[188:191], v[76:79]
	v_mfma_f32_16x16x32_bf16 v[68:71], v[156:159], v[188:191], v[68:71]
	s_barrier
	ds_read_b128 v[196:199], v220 offset:49152
	ds_read_b128 v[204:207], v220 offset:50176
	ds_read_b128 v[208:211], v220 offset:51200
	ds_read_b128 v[214:217], v220 offset:52224
	global_load_lds_dwordx4 v192, s[16:17] offset:128
	s_add_i32 m0, s19, 0x1f80
	s_nop 0
	global_load_lds_dwordx4 v128, s[16:17] offset:128
	s_barrier
	s_waitcnt lgkmcnt(0)
	v_mfma_f32_16x16x32_bf16 v[120:123], v[196:199], v[160:163], v[120:123]
	v_mfma_f32_16x16x32_bf16 v[112:115], v[208:211], v[160:163], v[112:115]
	v_mfma_f32_16x16x32_bf16 v[104:107], v[196:199], v[168:171], v[104:107]
	v_mfma_f32_16x16x32_bf16 v[96:99], v[208:211], v[168:171], v[96:99]
	s_mov_b32 m0, s33
	v_mfma_f32_16x16x32_bf16 v[88:91], v[196:199], v[176:179], v[88:91]
	v_mfma_f32_16x16x32_bf16 v[80:83], v[208:211], v[176:179], v[80:83]
	v_mfma_f32_16x16x32_bf16 v[72:75], v[196:199], v[184:187], v[72:75]
	v_mfma_f32_16x16x32_bf16 v[64:67], v[208:211], v[184:187], v[64:67]
	v_mfma_f32_16x16x32_bf16 v[120:123], v[204:207], v[164:167], v[120:123]
	v_mfma_f32_16x16x32_bf16 v[112:115], v[214:217], v[164:167], v[112:115]
	v_mfma_f32_16x16x32_bf16 v[104:107], v[204:207], v[172:175], v[104:107]
	v_mfma_f32_16x16x32_bf16 v[96:99], v[214:217], v[172:175], v[96:99]
	v_mfma_f32_16x16x32_bf16 v[88:91], v[204:207], v[180:183], v[88:91]
	v_mfma_f32_16x16x32_bf16 v[80:83], v[214:217], v[180:183], v[80:83]
	v_mfma_f32_16x16x32_bf16 v[72:75], v[204:207], v[188:191], v[72:75]
	v_mfma_f32_16x16x32_bf16 v[64:67], v[214:217], v[188:191], v[64:67]
	s_barrier
	ds_read_b128 v[160:163], v143 offset:49152
	ds_read_b128 v[164:167], v143 offset:50176
	ds_read_b128 v[168:171], v143 offset:51200
	ds_read_b128 v[172:175], v143 offset:52224
	ds_read_b128 v[176:179], v143 offset:53248
	ds_read_b128 v[180:183], v143 offset:54272
	ds_read_b128 v[184:187], v143 offset:55296
	ds_read_b128 v[188:191], v143 offset:56320
	global_load_lds_dwordx4 v132, s[48:49]
	s_mov_b32 m0, s34
	s_nop 0
	global_load_lds_dwordx4 v130, s[48:49]
	s_barrier
	s_waitcnt lgkmcnt(0)
	v_mfma_f32_16x16x32_bf16 v[60:63], v[144:147], v[160:163], v[60:63]
	v_mfma_f32_16x16x32_bf16 v[52:55], v[152:155], v[160:163], v[52:55]
	v_mfma_f32_16x16x32_bf16 v[44:47], v[144:147], v[168:171], v[44:47]
	v_mfma_f32_16x16x32_bf16 v[36:39], v[152:155], v[168:171], v[36:39]
	s_add_u32 s16, s16, 0x80080
	s_addc_u32 s17, s17, 0
	v_mfma_f32_16x16x32_bf16 v[28:31], v[144:147], v[176:179], v[28:31]
	s_add_i32 s18, s18, s26
	s_mov_b32 m0, s18
	v_mfma_f32_16x16x32_bf16 v[20:23], v[152:155], v[176:179], v[20:23]
	v_mfma_f32_16x16x32_bf16 v[12:15], v[144:147], v[184:187], v[12:15]
	v_mfma_f32_16x16x32_bf16 v[4:7], v[152:155], v[184:187], v[4:7]
	v_mfma_f32_16x16x32_bf16 v[60:63], v[148:151], v[164:167], v[60:63]
	v_mfma_f32_16x16x32_bf16 v[52:55], v[156:159], v[164:167], v[52:55]
	v_mfma_f32_16x16x32_bf16 v[44:47], v[148:151], v[172:175], v[44:47]
	v_mfma_f32_16x16x32_bf16 v[36:39], v[156:159], v[172:175], v[36:39]
	v_mfma_f32_16x16x32_bf16 v[28:31], v[148:151], v[180:183], v[28:31]
	v_mfma_f32_16x16x32_bf16 v[20:23], v[156:159], v[180:183], v[20:23]
	v_mfma_f32_16x16x32_bf16 v[12:15], v[148:151], v[188:191], v[12:15]
	v_mfma_f32_16x16x32_bf16 v[4:7], v[156:159], v[188:191], v[4:7]
	s_barrier
	global_load_lds_dwordx4 v192, s[16:17]
	s_add_i32 m0, s18, 0x2000
	s_nop 0
	global_load_lds_dwordx4 v128, s[16:17]
	s_waitcnt vmcnt(6)
	s_barrier
	v_mfma_f32_16x16x32_bf16 v[56:59], v[196:199], v[160:163], v[56:59]
	v_mfma_f32_16x16x32_bf16 v[48:51], v[208:211], v[160:163], v[48:51]
	v_mfma_f32_16x16x32_bf16 v[40:43], v[196:199], v[168:171], v[40:43]
	v_mfma_f32_16x16x32_bf16 v[32:35], v[208:211], v[168:171], v[32:35]
	s_add_i32 s40, s40, 2
	v_mfma_f32_16x16x32_bf16 v[24:27], v[196:199], v[176:179], v[24:27]
	s_add_u32 s14, s14, 0x100
	s_addc_u32 s15, s15, 0
	v_mfma_f32_16x16x32_bf16 v[16:19], v[208:211], v[176:179], v[16:19]
	s_add_u32 s38, s38, 0x100
	s_addc_u32 s39, s39, 0
	v_mfma_f32_16x16x32_bf16 v[8:11], v[196:199], v[184:187], v[8:11]
	s_add_u32 s16, s14, 0xfff80080
	s_addc_u32 s17, s15, -1
	v_mfma_f32_16x16x32_bf16 v[0:3], v[208:211], v[184:187], v[0:3]
	s_add_i32 s41, 0, 0x10000
	s_cmp_eq_u32 s40, 28
	v_mfma_f32_16x16x32_bf16 v[56:59], v[204:207], v[164:167], v[56:59]
	s_cselect_b32 s19, s7, s17
	s_cselect_b32 s18, s36, s16
	v_mfma_f32_16x16x32_bf16 v[48:51], v[214:217], v[164:167], v[48:51]
	s_cselect_b32 s17, s5, s39
	s_cselect_b32 s16, s37, s38
	v_mfma_f32_16x16x32_bf16 v[40:43], v[204:207], v[172:175], v[40:43]
	s_add_i32 m0, s13, 0xc000
	v_mfma_f32_16x16x32_bf16 v[32:35], v[214:217], v[172:175], v[32:35]
	v_mfma_f32_16x16x32_bf16 v[24:27], v[204:207], v[180:183], v[24:27]
	v_mfma_f32_16x16x32_bf16 v[16:19], v[214:217], v[180:183], v[16:19]
	v_mfma_f32_16x16x32_bf16 v[8:11], v[204:207], v[188:191], v[8:11]
	v_mfma_f32_16x16x32_bf16 v[0:3], v[214:217], v[188:191], v[0:3]
	s_cmp_gt_u32 s40, 29
	s_barrier
.LBB0_217:
	ds_read_b128 v[144:147], v220 offset:0
	ds_read_b128 v[148:151], v220 offset:1024
	ds_read_b128 v[152:155], v220 offset:2048
	ds_read_b128 v[156:159], v220 offset:3072
	ds_read_b128 v[160:163], v143
	ds_read_b128 v[164:167], v143 offset:1024
	ds_read_b128 v[168:171], v143 offset:2048
	ds_read_b128 v[172:175], v143 offset:3072
	ds_read_b128 v[176:179], v143 offset:4096
	ds_read_b128 v[180:183], v143 offset:5120
	ds_read_b128 v[184:187], v143 offset:6144
	ds_read_b128 v[188:191], v143 offset:7168
	global_load_lds_dwordx4 v134, s[14:15]
	s_add_i32 m0, s13, 0xe000
	s_nop 0
	global_load_lds_dwordx4 v136, s[14:15]
	s_waitcnt lgkmcnt(8)
	s_barrier
	s_waitcnt lgkmcnt(0)
	v_mfma_f32_16x16x32_bf16 v[124:127], v[144:147], v[160:163], v[124:127]
	v_mfma_f32_16x16x32_bf16 v[116:119], v[152:155], v[160:163], v[116:119]
	v_mfma_f32_16x16x32_bf16 v[108:111], v[144:147], v[168:171], v[108:111]
	v_mfma_f32_16x16x32_bf16 v[100:103], v[152:155], v[168:171], v[100:103]
	s_add_i32 s44, 0, 0x14000
	s_add_i32 s41, s41, s26
	v_mfma_f32_16x16x32_bf16 v[92:95], v[144:147], v[176:179], v[92:95]
	s_mov_b32 m0, s41
	v_mfma_f32_16x16x32_bf16 v[84:87], v[152:155], v[176:179], v[84:87]
	v_mfma_f32_16x16x32_bf16 v[76:79], v[144:147], v[184:187], v[76:79]
	v_mfma_f32_16x16x32_bf16 v[68:71], v[152:155], v[184:187], v[68:71]
	v_mfma_f32_16x16x32_bf16 v[124:127], v[148:151], v[164:167], v[124:127]
	v_mfma_f32_16x16x32_bf16 v[116:119], v[156:159], v[164:167], v[116:119]
	v_mfma_f32_16x16x32_bf16 v[108:111], v[148:151], v[172:175], v[108:111]
	v_mfma_f32_16x16x32_bf16 v[100:103], v[156:159], v[172:175], v[100:103]
	v_mfma_f32_16x16x32_bf16 v[92:95], v[148:151], v[180:183], v[92:95]
	v_mfma_f32_16x16x32_bf16 v[84:87], v[156:159], v[180:183], v[84:87]
	v_mfma_f32_16x16x32_bf16 v[76:79], v[148:151], v[188:191], v[76:79]
	v_mfma_f32_16x16x32_bf16 v[68:71], v[156:159], v[188:191], v[68:71]
	s_barrier
	ds_read_b128 v[196:199], v220 offset:16384
	ds_read_b128 v[204:207], v220 offset:17408
	ds_read_b128 v[208:211], v220 offset:18432
	ds_read_b128 v[214:217], v220 offset:19456
	global_load_lds_dwordx4 v192, s[16:17]
	s_add_i32 m0, s41, 0x2000
	s_nop 0
	global_load_lds_dwordx4 v128, s[16:17]
	s_barrier
	s_waitcnt lgkmcnt(0)
	v_mfma_f32_16x16x32_bf16 v[120:123], v[196:199], v[160:163], v[120:123]
	v_mfma_f32_16x16x32_bf16 v[112:115], v[208:211], v[160:163], v[112:115]
	v_mfma_f32_16x16x32_bf16 v[104:107], v[196:199], v[168:171], v[104:107]
	v_mfma_f32_16x16x32_bf16 v[96:99], v[208:211], v[168:171], v[96:99]
	s_mov_b32 m0, s13
	v_mfma_f32_16x16x32_bf16 v[88:91], v[196:199], v[176:179], v[88:91]
	s_add_u32 s48, s18, 0x80
	s_addc_u32 s49, s19, 0
	v_mfma_f32_16x16x32_bf16 v[80:83], v[208:211], v[176:179], v[80:83]
	v_mfma_f32_16x16x32_bf16 v[72:75], v[196:199], v[184:187], v[72:75]
	v_mfma_f32_16x16x32_bf16 v[64:67], v[208:211], v[184:187], v[64:67]
	v_mfma_f32_16x16x32_bf16 v[120:123], v[204:207], v[164:167], v[120:123]
	v_mfma_f32_16x16x32_bf16 v[112:115], v[214:217], v[164:167], v[112:115]
	v_mfma_f32_16x16x32_bf16 v[104:107], v[204:207], v[172:175], v[104:107]
	v_mfma_f32_16x16x32_bf16 v[96:99], v[214:217], v[172:175], v[96:99]
	v_mfma_f32_16x16x32_bf16 v[88:91], v[204:207], v[180:183], v[88:91]
	v_mfma_f32_16x16x32_bf16 v[80:83], v[214:217], v[180:183], v[80:83]
	v_mfma_f32_16x16x32_bf16 v[72:75], v[204:207], v[188:191], v[72:75]
	v_mfma_f32_16x16x32_bf16 v[64:67], v[214:217], v[188:191], v[64:67]
	s_barrier
	ds_read_b128 v[160:163], v143 offset:16384
	ds_read_b128 v[164:167], v143 offset:17408
	ds_read_b128 v[168:171], v143 offset:18432
	ds_read_b128 v[172:175], v143 offset:19456
	ds_read_b128 v[176:179], v143 offset:20480
	ds_read_b128 v[180:183], v143 offset:21504
	ds_read_b128 v[184:187], v143 offset:22528
	ds_read_b128 v[188:191], v143 offset:23552
	global_load_lds_dwordx4 v132, s[18:19]
	s_mov_b32 m0, s28
	s_nop 0
	global_load_lds_dwordx4 v130, s[18:19]
	s_waitcnt lgkmcnt(0)
	s_barrier
	v_mfma_f32_16x16x32_bf16 v[60:63], v[144:147], v[160:163], v[60:63]
	v_mfma_f32_16x16x32_bf16 v[52:55], v[152:155], v[160:163], v[52:55]
	v_mfma_f32_16x16x32_bf16 v[44:47], v[144:147], v[168:171], v[44:47]
	v_mfma_f32_16x16x32_bf16 v[36:39], v[152:155], v[168:171], v[36:39]
	s_add_u32 s42, s16, 0x80000
	s_addc_u32 s43, s17, 0
	v_mfma_f32_16x16x32_bf16 v[28:31], v[144:147], v[176:179], v[28:31]
	s_add_i32 s41, s44, s26
	s_mov_b32 m0, s41
	v_mfma_f32_16x16x32_bf16 v[20:23], v[152:155], v[176:179], v[20:23]
	v_mfma_f32_16x16x32_bf16 v[12:15], v[144:147], v[184:187], v[12:15]
	v_mfma_f32_16x16x32_bf16 v[4:7], v[152:155], v[184:187], v[4:7]
	v_mfma_f32_16x16x32_bf16 v[60:63], v[148:151], v[164:167], v[60:63]
	v_mfma_f32_16x16x32_bf16 v[52:55], v[156:159], v[164:167], v[52:55]
	v_mfma_f32_16x16x32_bf16 v[44:47], v[148:151], v[172:175], v[44:47]
	v_mfma_f32_16x16x32_bf16 v[36:39], v[156:159], v[172:175], v[36:39]
	v_mfma_f32_16x16x32_bf16 v[28:31], v[148:151], v[180:183], v[28:31]
	v_mfma_f32_16x16x32_bf16 v[20:23], v[156:159], v[180:183], v[20:23]
	v_mfma_f32_16x16x32_bf16 v[12:15], v[148:151], v[188:191], v[12:15]
	v_mfma_f32_16x16x32_bf16 v[4:7], v[156:159], v[188:191], v[4:7]
	s_barrier
	global_load_lds_dwordx4 v192, s[42:43]
	s_add_i32 m0, s41, 0x2000
	s_nop 0
	global_load_lds_dwordx4 v128, s[42:43]
	s_add_u32 s18, s18, 0x80000
	s_addc_u32 s19, s19, 0
	s_mov_b32 m0, s29
	s_nop 0
	global_load_lds_dwordx4 v132, s[18:19]
	s_mov_b32 m0, s30
	s_nop 0
	global_load_lds_dwordx4 v130, s[18:19]
	s_waitcnt vmcnt(8)
	s_barrier
	v_mfma_f32_16x16x32_bf16 v[56:59], v[196:199], v[160:163], v[56:59]
	v_mfma_f32_16x16x32_bf16 v[48:51], v[208:211], v[160:163], v[48:51]
	v_mfma_f32_16x16x32_bf16 v[40:43], v[196:199], v[168:171], v[40:43]
	v_mfma_f32_16x16x32_bf16 v[32:35], v[208:211], v[168:171], v[32:35]
	s_add_i32 s41, 0, 0x18000
	v_mfma_f32_16x16x32_bf16 v[24:27], v[196:199], v[176:179], v[24:27]
	v_mfma_f32_16x16x32_bf16 v[16:19], v[208:211], v[176:179], v[16:19]
	v_mfma_f32_16x16x32_bf16 v[8:11], v[196:199], v[184:187], v[8:11]
	v_mfma_f32_16x16x32_bf16 v[0:3], v[208:211], v[184:187], v[0:3]
	v_mfma_f32_16x16x32_bf16 v[56:59], v[204:207], v[164:167], v[56:59]
	v_mfma_f32_16x16x32_bf16 v[48:51], v[214:217], v[164:167], v[48:51]
	v_mfma_f32_16x16x32_bf16 v[40:43], v[204:207], v[172:175], v[40:43]
	v_mfma_f32_16x16x32_bf16 v[32:35], v[214:217], v[172:175], v[32:35]
	v_mfma_f32_16x16x32_bf16 v[24:27], v[204:207], v[180:183], v[24:27]
	v_mfma_f32_16x16x32_bf16 v[16:19], v[214:217], v[180:183], v[16:19]
	v_mfma_f32_16x16x32_bf16 v[8:11], v[204:207], v[188:191], v[8:11]
	v_mfma_f32_16x16x32_bf16 v[0:3], v[214:217], v[188:191], v[0:3]
	s_barrier
	ds_read_b128 v[144:147], v220 offset:32768
	ds_read_b128 v[148:151], v220 offset:33792
	ds_read_b128 v[152:155], v220 offset:34816
	ds_read_b128 v[156:159], v220 offset:35840
	ds_read_b128 v[160:163], v143 offset:32768
	ds_read_b128 v[164:167], v143 offset:33792
	ds_read_b128 v[168:171], v143 offset:34816
	ds_read_b128 v[172:175], v143 offset:35840
	ds_read_b128 v[176:179], v143 offset:36864
	ds_read_b128 v[180:183], v143 offset:37888
	ds_read_b128 v[184:187], v143 offset:38912
	ds_read_b128 v[188:191], v143 offset:39936
	s_waitcnt lgkmcnt(8)
	s_barrier
	s_waitcnt lgkmcnt(0)
	v_mfma_f32_16x16x32_bf16 v[124:127], v[144:147], v[160:163], v[124:127]
	v_mfma_f32_16x16x32_bf16 v[116:119], v[152:155], v[160:163], v[116:119]
	v_mfma_f32_16x16x32_bf16 v[108:111], v[144:147], v[168:171], v[108:111]
	v_mfma_f32_16x16x32_bf16 v[100:103], v[152:155], v[168:171], v[100:103]
	s_add_i32 s18, 0, 0x1c000
	s_add_i32 s19, s41, s26
	v_mfma_f32_16x16x32_bf16 v[92:95], v[144:147], v[176:179], v[92:95]
	s_add_i32 m0, s19, 0xffffff80
	v_mfma_f32_16x16x32_bf16 v[84:87], v[152:155], v[176:179], v[84:87]
	v_mfma_f32_16x16x32_bf16 v[76:79], v[144:147], v[184:187], v[76:79]
	v_mfma_f32_16x16x32_bf16 v[68:71], v[152:155], v[184:187], v[68:71]
	v_mfma_f32_16x16x32_bf16 v[124:127], v[148:151], v[164:167], v[124:127]
	v_mfma_f32_16x16x32_bf16 v[116:119], v[156:159], v[164:167], v[116:119]
	v_mfma_f32_16x16x32_bf16 v[108:111], v[148:151], v[172:175], v[108:111]
	v_mfma_f32_16x16x32_bf16 v[100:103], v[156:159], v[172:175], v[100:103]
	v_mfma_f32_16x16x32_bf16 v[92:95], v[148:151], v[180:183], v[92:95]
	v_mfma_f32_16x16x32_bf16 v[84:87], v[156:159], v[180:183], v[84:87]
	v_mfma_f32_16x16x32_bf16 v[76:79], v[148:151], v[188:191], v[76:79]
	v_mfma_f32_16x16x32_bf16 v[68:71], v[156:159], v[188:191], v[68:71]
	s_barrier
	ds_read_b128 v[196:199], v220 offset:49152
	ds_read_b128 v[204:207], v220 offset:50176
	ds_read_b128 v[208:211], v220 offset:51200
	ds_read_b128 v[214:217], v220 offset:52224
	global_load_lds_dwordx4 v192, s[16:17] offset:128
	s_add_i32 m0, s19, 0x1f80
	s_nop 0
	global_load_lds_dwordx4 v128, s[16:17] offset:128
	s_barrier
	s_waitcnt lgkmcnt(0)
	v_mfma_f32_16x16x32_bf16 v[120:123], v[196:199], v[160:163], v[120:123]
	v_mfma_f32_16x16x32_bf16 v[112:115], v[208:211], v[160:163], v[112:115]
	v_mfma_f32_16x16x32_bf16 v[104:107], v[196:199], v[168:171], v[104:107]
	v_mfma_f32_16x16x32_bf16 v[96:99], v[208:211], v[168:171], v[96:99]
	s_mov_b32 m0, s33
	v_mfma_f32_16x16x32_bf16 v[88:91], v[196:199], v[176:179], v[88:91]
	v_mfma_f32_16x16x32_bf16 v[80:83], v[208:211], v[176:179], v[80:83]
	v_mfma_f32_16x16x32_bf16 v[72:75], v[196:199], v[184:187], v[72:75]
	v_mfma_f32_16x16x32_bf16 v[64:67], v[208:211], v[184:187], v[64:67]
	v_mfma_f32_16x16x32_bf16 v[120:123], v[204:207], v[164:167], v[120:123]
	v_mfma_f32_16x16x32_bf16 v[112:115], v[214:217], v[164:167], v[112:115]
	v_mfma_f32_16x16x32_bf16 v[104:107], v[204:207], v[172:175], v[104:107]
	v_mfma_f32_16x16x32_bf16 v[96:99], v[214:217], v[172:175], v[96:99]
	v_mfma_f32_16x16x32_bf16 v[88:91], v[204:207], v[180:183], v[88:91]
	v_mfma_f32_16x16x32_bf16 v[80:83], v[214:217], v[180:183], v[80:83]
	v_mfma_f32_16x16x32_bf16 v[72:75], v[204:207], v[188:191], v[72:75]
	v_mfma_f32_16x16x32_bf16 v[64:67], v[214:217], v[188:191], v[64:67]
	s_barrier
	ds_read_b128 v[160:163], v143 offset:49152
	ds_read_b128 v[164:167], v143 offset:50176
	ds_read_b128 v[168:171], v143 offset:51200
	ds_read_b128 v[172:175], v143 offset:52224
	ds_read_b128 v[176:179], v143 offset:53248
	ds_read_b128 v[180:183], v143 offset:54272
	ds_read_b128 v[184:187], v143 offset:55296
	ds_read_b128 v[188:191], v143 offset:56320
	global_load_lds_dwordx4 v132, s[48:49]
	s_mov_b32 m0, s34
	s_nop 0
	global_load_lds_dwordx4 v130, s[48:49]
	s_barrier
	s_waitcnt lgkmcnt(0)
	v_mfma_f32_16x16x32_bf16 v[60:63], v[144:147], v[160:163], v[60:63]
	v_mfma_f32_16x16x32_bf16 v[52:55], v[152:155], v[160:163], v[52:55]
	v_mfma_f32_16x16x32_bf16 v[44:47], v[144:147], v[168:171], v[44:47]
	v_mfma_f32_16x16x32_bf16 v[36:39], v[152:155], v[168:171], v[36:39]
	s_add_u32 s16, s16, 0x80080
	s_addc_u32 s17, s17, 0
	v_mfma_f32_16x16x32_bf16 v[28:31], v[144:147], v[176:179], v[28:31]
	s_add_i32 s18, s18, s26
	s_mov_b32 m0, s18
	v_mfma_f32_16x16x32_bf16 v[20:23], v[152:155], v[176:179], v[20:23]
	v_mfma_f32_16x16x32_bf16 v[12:15], v[144:147], v[184:187], v[12:15]
	v_mfma_f32_16x16x32_bf16 v[4:7], v[152:155], v[184:187], v[4:7]
	v_mfma_f32_16x16x32_bf16 v[60:63], v[148:151], v[164:167], v[60:63]
	v_mfma_f32_16x16x32_bf16 v[52:55], v[156:159], v[164:167], v[52:55]
	v_mfma_f32_16x16x32_bf16 v[44:47], v[148:151], v[172:175], v[44:47]
	v_mfma_f32_16x16x32_bf16 v[36:39], v[156:159], v[172:175], v[36:39]
	v_mfma_f32_16x16x32_bf16 v[28:31], v[148:151], v[180:183], v[28:31]
	v_mfma_f32_16x16x32_bf16 v[20:23], v[156:159], v[180:183], v[20:23]
	v_mfma_f32_16x16x32_bf16 v[12:15], v[148:151], v[188:191], v[12:15]
	v_mfma_f32_16x16x32_bf16 v[4:7], v[156:159], v[188:191], v[4:7]
	s_barrier
	global_load_lds_dwordx4 v192, s[16:17]
	s_add_i32 m0, s18, 0x2000
	s_nop 0
	global_load_lds_dwordx4 v128, s[16:17]
	s_waitcnt vmcnt(6)
	s_barrier
	v_mfma_f32_16x16x32_bf16 v[56:59], v[196:199], v[160:163], v[56:59]
	v_mfma_f32_16x16x32_bf16 v[48:51], v[208:211], v[160:163], v[48:51]
	v_mfma_f32_16x16x32_bf16 v[40:43], v[196:199], v[168:171], v[40:43]
	v_mfma_f32_16x16x32_bf16 v[32:35], v[208:211], v[168:171], v[32:35]
	s_add_i32 s40, s40, 2
	v_mfma_f32_16x16x32_bf16 v[24:27], v[196:199], v[176:179], v[24:27]
	s_add_u32 s14, s14, 0x100
	s_addc_u32 s15, s15, 0
	v_mfma_f32_16x16x32_bf16 v[16:19], v[208:211], v[176:179], v[16:19]
	s_add_u32 s38, s38, 0x100
	s_addc_u32 s39, s39, 0
	v_mfma_f32_16x16x32_bf16 v[8:11], v[196:199], v[184:187], v[8:11]
	s_add_u32 s16, s14, 0xfff80080
	s_addc_u32 s17, s15, -1
	v_mfma_f32_16x16x32_bf16 v[0:3], v[208:211], v[184:187], v[0:3]
	s_add_i32 s41, 0, 0x10000
	s_cmp_eq_u32 s40, 28
	v_mfma_f32_16x16x32_bf16 v[56:59], v[204:207], v[164:167], v[56:59]
	s_cselect_b32 s19, s7, s17
	s_cselect_b32 s18, s36, s16
	v_mfma_f32_16x16x32_bf16 v[48:51], v[214:217], v[164:167], v[48:51]
	s_cselect_b32 s17, s5, s39
	s_cselect_b32 s16, s37, s38
	v_mfma_f32_16x16x32_bf16 v[40:43], v[204:207], v[172:175], v[40:43]
	s_add_i32 m0, s13, 0xc000
	v_mfma_f32_16x16x32_bf16 v[32:35], v[214:217], v[172:175], v[32:35]
	v_mfma_f32_16x16x32_bf16 v[24:27], v[204:207], v[180:183], v[24:27]
	v_mfma_f32_16x16x32_bf16 v[16:19], v[214:217], v[180:183], v[16:19]
	v_mfma_f32_16x16x32_bf16 v[8:11], v[204:207], v[188:191], v[8:11]
	v_mfma_f32_16x16x32_bf16 v[0:3], v[214:217], v[188:191], v[0:3]
	s_cmp_gt_u32 s40, 29
	s_barrier
	s_cbranch_scc0 .LBB0_217
	v_mul_f32_e32 v145, 0xbfb8aa3b, v124
	v_exp_f32_e32 v145, v145
	v_lshl_or_b32 v146, s35, 7, v142
	v_lshl_add_u32 v144, s12, 8, v140
	v_ashrrev_i32_e32 v147, 31, v146
	v_add_f32_e32 v145, 1.0, v145
	v_rcp_f32_e32 v145, v145
	v_mov_b64_e32 v[138:139], s[2:3]
	s_movk_i32 s5, 0x2c00
	v_mad_i64_i32 v[148:149], s[14:15], v144, s5, v[138:139]
	v_mul_f32_e32 v124, v124, v145
	v_mul_f32_e32 v120, v124, v120
	v_mul_f32_e32 v124, 0xbfb8aa3b, v125
	v_exp_f32_e32 v124, v124
	s_and_b64 vcc, exec, s[0:1]
	s_mov_b32 s35, s4
	s_mov_b32 s12, s6
	v_add_f32_e32 v124, 1.0, v124
	v_rcp_f32_e32 v124, v124
	s_mov_b64 s[16:17], s[10:11]
	v_mul_f32_e32 v124, v125, v124
	v_mul_f32_e32 v121, v124, v121
	v_mul_f32_e32 v124, 0xbfb8aa3b, v126
	v_exp_f32_e32 v124, v124
	s_nop 0
	v_add_f32_e32 v124, 1.0, v124
	v_rcp_f32_e32 v124, v124
	s_nop 0
	v_mul_f32_e32 v124, v126, v124
	v_mul_f32_e32 v122, v124, v122
	v_mul_f32_e32 v124, 0xbfb8aa3b, v127
	v_exp_f32_e32 v124, v124
	s_nop 0
	v_add_f32_e32 v124, 1.0, v124
	v_rcp_f32_e32 v124, v124
	s_nop 0
	v_mul_f32_e32 v124, v127, v124
	v_mul_f32_e32 v123, v124, v123
	v_mul_f32_e32 v124, 0xbfb8aa3b, v116
	v_exp_f32_e32 v124, v124
	s_nop 0
	v_add_f32_e32 v124, 1.0, v124
	v_rcp_f32_e32 v124, v124
	s_nop 0
	v_mul_f32_e32 v116, v116, v124
	v_mul_f32_e32 v116, v116, v112
	v_mul_f32_e32 v112, 0xbfb8aa3b, v117
	v_exp_f32_e32 v112, v112
	s_nop 0
	v_add_f32_e32 v112, 1.0, v112
	v_rcp_f32_e32 v112, v112
	s_nop 0
	v_mul_f32_e32 v112, v117, v112
	v_mul_f32_e32 v117, v112, v113
	v_mul_f32_e32 v112, 0xbfb8aa3b, v118
	v_exp_f32_e32 v112, v112
	s_nop 0
	v_add_f32_e32 v112, 1.0, v112
	v_rcp_f32_e32 v112, v112
	s_nop 0
	v_mul_f32_e32 v112, v118, v112
	v_mul_f32_e32 v124, v112, v114
	v_mul_f32_e32 v112, 0xbfb8aa3b, v119
	v_exp_f32_e32 v112, v112
	v_cvt_pk_bf16_f32 v114, v120, v121
	s_nop 0
	v_add_f32_e32 v112, 1.0, v112
	v_rcp_f32_e32 v112, v112
	s_nop 0
	v_mul_f32_e32 v112, v119, v112
	v_mul_f32_e32 v125, v112, v115
	v_lshlrev_b64 v[112:113], 1, v[146:147]
	v_lshl_add_u64 v[118:119], v[148:149], 0, v[112:113]
	v_cvt_pk_bf16_f32 v115, v122, v123
	v_cvt_pk_bf16_f32 v116, v116, v117
	v_cvt_pk_bf16_f32 v117, v124, v125
	global_store_dwordx4 v[118:119], v[114:117], off
	s_nop 1
	v_mul_f32_e32 v116, 0xbfb8aa3b, v108
	v_exp_f32_e32 v116, v116
	v_or_b32_e32 v114, 16, v144
	v_mad_i64_i32 v[114:115], s[14:15], v114, s5, v[138:139]
	v_add_f32_e32 v116, 1.0, v116
	v_rcp_f32_e32 v116, v116
	s_nop 0
	v_mul_f32_e32 v108, v108, v116
	v_mul_f32_e32 v104, v108, v104
	v_mul_f32_e32 v108, 0xbfb8aa3b, v109
	v_exp_f32_e32 v108, v108
	s_nop 0
	v_add_f32_e32 v108, 1.0, v108
	v_rcp_f32_e32 v108, v108
	s_nop 0
	v_mul_f32_e32 v108, v109, v108
	v_mul_f32_e32 v105, v108, v105
	v_mul_f32_e32 v108, 0xbfb8aa3b, v110
	v_exp_f32_e32 v108, v108
	s_nop 0
	v_add_f32_e32 v108, 1.0, v108
	v_rcp_f32_e32 v108, v108
	s_nop 0
	v_mul_f32_e32 v108, v110, v108
	v_mul_f32_e32 v106, v108, v106
	v_mul_f32_e32 v108, 0xbfb8aa3b, v111
	v_exp_f32_e32 v108, v108
	s_nop 0
	v_add_f32_e32 v108, 1.0, v108
	v_rcp_f32_e32 v108, v108
	s_nop 0
	v_mul_f32_e32 v108, v111, v108
	v_mul_f32_e32 v107, v108, v107
	v_mul_f32_e32 v108, 0xbfb8aa3b, v100
	v_exp_f32_e32 v108, v108
	s_nop 0
	v_add_f32_e32 v108, 1.0, v108
	v_rcp_f32_e32 v108, v108
	s_nop 0
	v_mul_f32_e32 v100, v100, v108
	v_mul_f32_e32 v108, v100, v96
	v_mul_f32_e32 v96, 0xbfb8aa3b, v101
	v_exp_f32_e32 v96, v96
	s_nop 0
	v_add_f32_e32 v96, 1.0, v96
	v_rcp_f32_e32 v96, v96
	s_nop 0
	v_mul_f32_e32 v96, v101, v96
	v_mul_f32_e32 v109, v96, v97
	v_mul_f32_e32 v96, 0xbfb8aa3b, v102
	v_exp_f32_e32 v96, v96
	v_lshl_add_u64 v[100:101], v[114:115], 0, v[112:113]
	v_add_f32_e32 v96, 1.0, v96
	v_rcp_f32_e32 v96, v96
	s_nop 0
	v_mul_f32_e32 v96, v102, v96
	v_mul_f32_e32 v102, v96, v98
	v_mul_f32_e32 v96, 0xbfb8aa3b, v103
	v_exp_f32_e32 v96, v96
	s_nop 0
	v_add_f32_e32 v96, 1.0, v96
	v_rcp_f32_e32 v96, v96
	s_nop 0
	v_mul_f32_e32 v96, v103, v96
	v_mul_f32_e32 v99, v96, v99
	v_cvt_pk_bf16_f32 v96, v104, v105
	v_cvt_pk_bf16_f32 v97, v106, v107
	v_cvt_pk_bf16_f32 v98, v108, v109
	v_cvt_pk_bf16_f32 v99, v102, v99
	global_store_dwordx4 v[100:101], v[96:99], off
	s_nop 1
	v_mul_f32_e32 v98, 0xbfb8aa3b, v92
	v_exp_f32_e32 v98, v98
	v_or_b32_e32 v96, 32, v144
	v_mad_i64_i32 v[96:97], s[14:15], v96, s5, v[138:139]
	v_add_f32_e32 v98, 1.0, v98
	v_rcp_f32_e32 v98, v98
	s_nop 0
	v_mul_f32_e32 v92, v92, v98
	v_mul_f32_e32 v88, v92, v88
	v_mul_f32_e32 v92, 0xbfb8aa3b, v93
	v_exp_f32_e32 v92, v92
	s_nop 0
	v_add_f32_e32 v92, 1.0, v92
	v_rcp_f32_e32 v92, v92
	s_nop 0
	v_mul_f32_e32 v92, v93, v92
	v_mul_f32_e32 v89, v92, v89
	v_mul_f32_e32 v92, 0xbfb8aa3b, v94
	v_exp_f32_e32 v92, v92
	s_nop 0
	v_add_f32_e32 v92, 1.0, v92
	v_rcp_f32_e32 v92, v92
	s_nop 0
	v_mul_f32_e32 v92, v94, v92
	v_mul_f32_e32 v90, v92, v90
	v_mul_f32_e32 v92, 0xbfb8aa3b, v95
	v_exp_f32_e32 v92, v92
	s_nop 0
	v_add_f32_e32 v92, 1.0, v92
	v_rcp_f32_e32 v92, v92
	s_nop 0
	v_mul_f32_e32 v92, v95, v92
	v_mul_f32_e32 v91, v92, v91
	v_mul_f32_e32 v92, 0xbfb8aa3b, v84
	v_exp_f32_e32 v92, v92
	s_nop 0
	v_add_f32_e32 v92, 1.0, v92
	v_rcp_f32_e32 v92, v92
	s_nop 0
	v_mul_f32_e32 v84, v84, v92
	v_mul_f32_e32 v92, v84, v80
	v_mul_f32_e32 v80, 0xbfb8aa3b, v85
	v_exp_f32_e32 v80, v80
	s_nop 0
	v_add_f32_e32 v80, 1.0, v80
	v_rcp_f32_e32 v80, v80
	s_nop 0
	v_mul_f32_e32 v80, v85, v80
	v_mul_f32_e32 v93, v80, v81
	v_mul_f32_e32 v80, 0xbfb8aa3b, v86
	v_exp_f32_e32 v80, v80
	v_lshl_add_u64 v[84:85], v[96:97], 0, v[112:113]
	v_add_f32_e32 v80, 1.0, v80
	v_rcp_f32_e32 v80, v80
	s_nop 0
	v_mul_f32_e32 v80, v86, v80
	v_mul_f32_e32 v86, v80, v82
	v_mul_f32_e32 v80, 0xbfb8aa3b, v87
	v_exp_f32_e32 v80, v80
	s_nop 0
	v_add_f32_e32 v80, 1.0, v80
	v_rcp_f32_e32 v80, v80
	s_nop 0
	v_mul_f32_e32 v80, v87, v80
	v_mul_f32_e32 v83, v80, v83
	v_cvt_pk_bf16_f32 v80, v88, v89
	v_cvt_pk_bf16_f32 v81, v90, v91
	v_cvt_pk_bf16_f32 v82, v92, v93
	v_cvt_pk_bf16_f32 v83, v86, v83
	global_store_dwordx4 v[84:85], v[80:83], off
	s_nop 1
	v_mul_f32_e32 v82, 0xbfb8aa3b, v76
	v_exp_f32_e32 v82, v82
	v_or_b32_e32 v80, 48, v144
	v_mad_i64_i32 v[80:81], s[14:15], v80, s5, v[138:139]
	v_add_f32_e32 v82, 1.0, v82
	v_rcp_f32_e32 v82, v82
	s_nop 0
	v_mul_f32_e32 v76, v76, v82
	v_mul_f32_e32 v72, v76, v72
	v_mul_f32_e32 v76, 0xbfb8aa3b, v77
	v_exp_f32_e32 v76, v76
	s_nop 0
	v_add_f32_e32 v76, 1.0, v76
	v_rcp_f32_e32 v76, v76
	s_nop 0
	v_mul_f32_e32 v76, v77, v76
	v_mul_f32_e32 v73, v76, v73
	v_mul_f32_e32 v76, 0xbfb8aa3b, v78
	v_exp_f32_e32 v76, v76
	s_nop 0
	v_add_f32_e32 v76, 1.0, v76
	v_rcp_f32_e32 v76, v76
	s_nop 0
	v_mul_f32_e32 v76, v78, v76
	v_mul_f32_e32 v74, v76, v74
	v_mul_f32_e32 v76, 0xbfb8aa3b, v79
	v_exp_f32_e32 v76, v76
	s_nop 0
	v_add_f32_e32 v76, 1.0, v76
	v_rcp_f32_e32 v76, v76
	s_nop 0
	v_mul_f32_e32 v76, v79, v76
	v_mul_f32_e32 v75, v76, v75
	v_mul_f32_e32 v76, 0xbfb8aa3b, v68
	v_exp_f32_e32 v76, v76
	s_nop 0
	v_add_f32_e32 v76, 1.0, v76
	v_rcp_f32_e32 v76, v76
	s_nop 0
	v_mul_f32_e32 v68, v68, v76
	v_mul_f32_e32 v76, v68, v64
	v_mul_f32_e32 v64, 0xbfb8aa3b, v69
	v_exp_f32_e32 v64, v64
	s_nop 0
	v_add_f32_e32 v64, 1.0, v64
	v_rcp_f32_e32 v64, v64
	s_nop 0
	v_mul_f32_e32 v64, v69, v64
	v_mul_f32_e32 v77, v64, v65
	v_mul_f32_e32 v64, 0xbfb8aa3b, v70
	v_exp_f32_e32 v64, v64
	v_lshl_add_u64 v[68:69], v[80:81], 0, v[112:113]
	v_add_f32_e32 v64, 1.0, v64
	v_rcp_f32_e32 v64, v64
	s_nop 0
	v_mul_f32_e32 v64, v70, v64
	v_mul_f32_e32 v70, v64, v66
	v_mul_f32_e32 v64, 0xbfb8aa3b, v71
	v_exp_f32_e32 v64, v64
	s_nop 0
	v_add_f32_e32 v64, 1.0, v64
	v_rcp_f32_e32 v64, v64
	s_nop 0
	v_mul_f32_e32 v64, v71, v64
	v_mul_f32_e32 v67, v64, v67
	v_cvt_pk_bf16_f32 v64, v72, v73
	v_cvt_pk_bf16_f32 v65, v74, v75
	v_cvt_pk_bf16_f32 v66, v76, v77
	v_cvt_pk_bf16_f32 v67, v70, v67
	global_store_dwordx4 v[68:69], v[64:67], off
	s_nop 1
	v_mul_f32_e32 v66, 0xbfb8aa3b, v60
	v_exp_f32_e32 v66, v66
	v_add_u32_e32 v64, 0x80, v144
	v_mad_i64_i32 v[64:65], s[14:15], v64, s5, v[138:139]
	v_add_f32_e32 v66, 1.0, v66
	v_rcp_f32_e32 v66, v66
	s_nop 0
	v_mul_f32_e32 v60, v60, v66
	v_mul_f32_e32 v56, v60, v56
	v_mul_f32_e32 v60, 0xbfb8aa3b, v61
	v_exp_f32_e32 v60, v60
	s_nop 0
	v_add_f32_e32 v60, 1.0, v60
	v_rcp_f32_e32 v60, v60
	s_nop 0
	v_mul_f32_e32 v60, v61, v60
	v_mul_f32_e32 v57, v60, v57
	v_mul_f32_e32 v60, 0xbfb8aa3b, v62
	v_exp_f32_e32 v60, v60
	s_nop 0
	v_add_f32_e32 v60, 1.0, v60
	v_rcp_f32_e32 v60, v60
	s_nop 0
	v_mul_f32_e32 v60, v62, v60
	v_mul_f32_e32 v58, v60, v58
	v_mul_f32_e32 v60, 0xbfb8aa3b, v63
	v_exp_f32_e32 v60, v60
	s_nop 0
	v_add_f32_e32 v60, 1.0, v60
	v_rcp_f32_e32 v60, v60
	s_nop 0
	v_mul_f32_e32 v60, v63, v60
	v_mul_f32_e32 v59, v60, v59
	v_mul_f32_e32 v60, 0xbfb8aa3b, v52
	v_exp_f32_e32 v60, v60
	s_nop 0
	v_add_f32_e32 v60, 1.0, v60
	v_rcp_f32_e32 v60, v60
	s_nop 0
	v_mul_f32_e32 v52, v52, v60
	v_mul_f32_e32 v60, v52, v48
	v_mul_f32_e32 v48, 0xbfb8aa3b, v53
	v_exp_f32_e32 v48, v48
	s_nop 0
	v_add_f32_e32 v48, 1.0, v48
	v_rcp_f32_e32 v48, v48
	s_nop 0
	v_mul_f32_e32 v48, v53, v48
	v_mul_f32_e32 v61, v48, v49
	v_mul_f32_e32 v48, 0xbfb8aa3b, v54
	v_exp_f32_e32 v48, v48
	v_lshl_add_u64 v[52:53], v[64:65], 0, v[112:113]
	v_add_f32_e32 v48, 1.0, v48
	v_rcp_f32_e32 v48, v48
	s_nop 0
	v_mul_f32_e32 v48, v54, v48
	v_mul_f32_e32 v54, v48, v50
	v_mul_f32_e32 v48, 0xbfb8aa3b, v55
	v_exp_f32_e32 v48, v48
	s_nop 0
	v_add_f32_e32 v48, 1.0, v48
	v_rcp_f32_e32 v48, v48
	s_nop 0
	v_mul_f32_e32 v48, v55, v48
	v_mul_f32_e32 v51, v48, v51
	v_cvt_pk_bf16_f32 v48, v56, v57
	v_cvt_pk_bf16_f32 v49, v58, v59
	v_cvt_pk_bf16_f32 v50, v60, v61
	v_cvt_pk_bf16_f32 v51, v54, v51
	global_store_dwordx4 v[52:53], v[48:51], off
	s_nop 1
	v_mul_f32_e32 v50, 0xbfb8aa3b, v44
	v_exp_f32_e32 v50, v50
	v_add_u32_e32 v48, 0x90, v144
	v_mad_i64_i32 v[48:49], s[14:15], v48, s5, v[138:139]
	v_add_f32_e32 v50, 1.0, v50
	v_rcp_f32_e32 v50, v50
	s_nop 0
	v_mul_f32_e32 v44, v44, v50
	v_mul_f32_e32 v40, v44, v40
	v_mul_f32_e32 v44, 0xbfb8aa3b, v45
	v_exp_f32_e32 v44, v44
	s_nop 0
	v_add_f32_e32 v44, 1.0, v44
	v_rcp_f32_e32 v44, v44
	s_nop 0
	v_mul_f32_e32 v44, v45, v44
	v_mul_f32_e32 v41, v44, v41
	v_mul_f32_e32 v44, 0xbfb8aa3b, v46
	v_exp_f32_e32 v44, v44
	s_nop 0
	v_add_f32_e32 v44, 1.0, v44
	v_rcp_f32_e32 v44, v44
	s_nop 0
	v_mul_f32_e32 v44, v46, v44
	v_mul_f32_e32 v42, v44, v42
	v_mul_f32_e32 v44, 0xbfb8aa3b, v47
	v_exp_f32_e32 v44, v44
	s_nop 0
	v_add_f32_e32 v44, 1.0, v44
	v_rcp_f32_e32 v44, v44
	s_nop 0
	v_mul_f32_e32 v44, v47, v44
	v_mul_f32_e32 v43, v44, v43
	v_mul_f32_e32 v44, 0xbfb8aa3b, v36
	v_exp_f32_e32 v44, v44
	s_nop 0
	v_add_f32_e32 v44, 1.0, v44
	v_rcp_f32_e32 v44, v44
	s_nop 0
	v_mul_f32_e32 v36, v36, v44
	v_mul_f32_e32 v44, v36, v32
	v_mul_f32_e32 v32, 0xbfb8aa3b, v37
	v_exp_f32_e32 v32, v32
	s_nop 0
	v_add_f32_e32 v32, 1.0, v32
	v_rcp_f32_e32 v32, v32
	s_nop 0
	v_mul_f32_e32 v32, v37, v32
	v_mul_f32_e32 v45, v32, v33
	v_mul_f32_e32 v32, 0xbfb8aa3b, v38
	v_exp_f32_e32 v32, v32
	v_lshl_add_u64 v[36:37], v[48:49], 0, v[112:113]
	v_add_f32_e32 v32, 1.0, v32
	v_rcp_f32_e32 v32, v32
	s_nop 0
	v_mul_f32_e32 v32, v38, v32
	v_mul_f32_e32 v38, v32, v34
	v_mul_f32_e32 v32, 0xbfb8aa3b, v39
	v_exp_f32_e32 v32, v32
	s_nop 0
	v_add_f32_e32 v32, 1.0, v32
	v_rcp_f32_e32 v32, v32
	s_nop 0
	v_mul_f32_e32 v32, v39, v32
	v_mul_f32_e32 v35, v32, v35
	v_cvt_pk_bf16_f32 v32, v40, v41
	v_cvt_pk_bf16_f32 v33, v42, v43
	v_cvt_pk_bf16_f32 v34, v44, v45
	v_cvt_pk_bf16_f32 v35, v38, v35
	global_store_dwordx4 v[36:37], v[32:35], off
	s_nop 1
	v_mul_f32_e32 v34, 0xbfb8aa3b, v28
	v_exp_f32_e32 v34, v34
	v_add_u32_e32 v32, 0xa0, v144
	v_mad_i64_i32 v[32:33], s[14:15], v32, s5, v[138:139]
	v_add_f32_e32 v34, 1.0, v34
	v_rcp_f32_e32 v34, v34
	s_nop 0
	v_mul_f32_e32 v28, v28, v34
	v_mul_f32_e32 v24, v28, v24
	v_mul_f32_e32 v28, 0xbfb8aa3b, v29
	v_exp_f32_e32 v28, v28
	s_nop 0
	v_add_f32_e32 v28, 1.0, v28
	v_rcp_f32_e32 v28, v28
	s_nop 0
	v_mul_f32_e32 v28, v29, v28
	v_mul_f32_e32 v25, v28, v25
	v_mul_f32_e32 v28, 0xbfb8aa3b, v30
	v_exp_f32_e32 v28, v28
	s_nop 0
	v_add_f32_e32 v28, 1.0, v28
	v_rcp_f32_e32 v28, v28
	s_nop 0
	v_mul_f32_e32 v28, v30, v28
	v_mul_f32_e32 v26, v28, v26
	v_mul_f32_e32 v28, 0xbfb8aa3b, v31
	v_exp_f32_e32 v28, v28
	s_nop 0
	v_add_f32_e32 v28, 1.0, v28
	v_rcp_f32_e32 v28, v28
	s_nop 0
	v_mul_f32_e32 v28, v31, v28
	v_mul_f32_e32 v27, v28, v27
	v_mul_f32_e32 v28, 0xbfb8aa3b, v20
	v_exp_f32_e32 v28, v28
	s_nop 0
	v_add_f32_e32 v28, 1.0, v28
	v_rcp_f32_e32 v28, v28
	s_nop 0
	v_mul_f32_e32 v20, v20, v28
	v_mul_f32_e32 v28, v20, v16
	v_mul_f32_e32 v16, 0xbfb8aa3b, v21
	v_exp_f32_e32 v16, v16
	s_nop 0
	v_add_f32_e32 v16, 1.0, v16
	v_rcp_f32_e32 v16, v16
	s_nop 0
	v_mul_f32_e32 v16, v21, v16
	v_mul_f32_e32 v29, v16, v17
	v_mul_f32_e32 v16, 0xbfb8aa3b, v22
	v_exp_f32_e32 v16, v16
	v_lshl_add_u64 v[20:21], v[32:33], 0, v[112:113]
	v_add_f32_e32 v16, 1.0, v16
	v_rcp_f32_e32 v16, v16
	s_nop 0
	v_mul_f32_e32 v16, v22, v16
	v_mul_f32_e32 v22, v16, v18
	v_mul_f32_e32 v16, 0xbfb8aa3b, v23
	v_exp_f32_e32 v16, v16
	s_nop 0
	v_add_f32_e32 v16, 1.0, v16
	v_rcp_f32_e32 v16, v16
	s_nop 0
	v_mul_f32_e32 v16, v23, v16
	v_mul_f32_e32 v19, v16, v19
	v_cvt_pk_bf16_f32 v16, v24, v25
	v_cvt_pk_bf16_f32 v17, v26, v27
	v_cvt_pk_bf16_f32 v18, v28, v29
	v_cvt_pk_bf16_f32 v19, v22, v19
	global_store_dwordx4 v[20:21], v[16:19], off
	s_nop 1
	v_mul_f32_e32 v18, 0xbfb8aa3b, v12
	v_exp_f32_e32 v18, v18
	v_add_u32_e32 v16, 0xb0, v144
	v_mad_i64_i32 v[16:17], s[14:15], v16, s5, v[138:139]
	v_add_f32_e32 v18, 1.0, v18
	v_rcp_f32_e32 v18, v18
	s_mov_b64 s[14:15], s[8:9]
	v_mul_f32_e32 v12, v12, v18
	v_mul_f32_e32 v8, v12, v8
	v_mul_f32_e32 v12, 0xbfb8aa3b, v13
	v_exp_f32_e32 v12, v12
	s_nop 0
	v_add_f32_e32 v12, 1.0, v12
	v_rcp_f32_e32 v12, v12
	s_nop 0
	v_mul_f32_e32 v12, v13, v12
	v_mul_f32_e32 v9, v12, v9
	v_mul_f32_e32 v12, 0xbfb8aa3b, v14
	v_exp_f32_e32 v12, v12
	s_nop 0
	v_add_f32_e32 v12, 1.0, v12
	v_rcp_f32_e32 v12, v12
	s_nop 0
	v_mul_f32_e32 v12, v14, v12
	v_mul_f32_e32 v10, v12, v10
	v_mul_f32_e32 v12, 0xbfb8aa3b, v15
	v_exp_f32_e32 v12, v12
	s_nop 0
	v_add_f32_e32 v12, 1.0, v12
	v_rcp_f32_e32 v12, v12
	s_nop 0
	v_mul_f32_e32 v12, v15, v12
	v_mul_f32_e32 v11, v12, v11
	v_mul_f32_e32 v12, 0xbfb8aa3b, v4
	v_exp_f32_e32 v12, v12
	s_nop 0
	v_add_f32_e32 v12, 1.0, v12
	v_rcp_f32_e32 v12, v12
	s_nop 0
	v_mul_f32_e32 v4, v4, v12
	v_mul_f32_e32 v12, v4, v0
	v_mul_f32_e32 v0, 0xbfb8aa3b, v5
	v_exp_f32_e32 v0, v0
	s_nop 0
	v_add_f32_e32 v0, 1.0, v0
	v_rcp_f32_e32 v0, v0
	s_nop 0
	v_mul_f32_e32 v0, v5, v0
	v_mul_f32_e32 v13, v0, v1
	v_mul_f32_e32 v0, 0xbfb8aa3b, v6
	v_exp_f32_e32 v0, v0
	v_lshl_add_u64 v[4:5], v[16:17], 0, v[112:113]
	v_add_f32_e32 v0, 1.0, v0
	v_rcp_f32_e32 v0, v0
	s_nop 0
	v_mul_f32_e32 v0, v6, v0
	v_mul_f32_e32 v6, v0, v2
	v_mul_f32_e32 v0, 0xbfb8aa3b, v7
	v_exp_f32_e32 v0, v0
	s_nop 0
	v_add_f32_e32 v0, 1.0, v0
	v_rcp_f32_e32 v0, v0
	s_nop 0
	v_mul_f32_e32 v0, v7, v0
	v_mul_f32_e32 v3, v0, v3
	v_cvt_pk_bf16_f32 v0, v8, v9
	v_cvt_pk_bf16_f32 v1, v10, v11
	v_cvt_pk_bf16_f32 v2, v12, v13
	v_cvt_pk_bf16_f32 v3, v6, v3
	global_store_dwordx4 v[4:5], v[0:3], off
	s_cbranch_vccz .LBB0_214
	s_waitcnt vmcnt(0)
	v_readlane_b32 s34, v254, 18
	s_cmpk_gt_u32 s21, 0xff
	v_readlane_b32 s35, v254, 19
	v_readlane_b32 s31, v254, 20
	s_cbranch_scc1 .LBB0_221
	s_barrier

.LBB0_245:
	s_add_u32 s10, s10, 0x80
	s_addc_u32 s11, s11, 0
	s_add_u32 s42, s12, 0x100
	s_addc_u32 s43, s13, 0
	s_mov_b32 s12, 0
	s_mov_b64 s[48:49], 0x80
	v_readlane_b32 s52, v254, 14
	v_readlane_b32 s53, v254, 15
	v_readlane_b32 s54, v254, 16
	v_readlane_b32 s55, v254, 17
	v_add_u32_e32 v218, 0x10000, v191
	s_add_i32 s44, s12, 2
	s_add_u32 s14, s10, 0x80
	s_addc_u32 s13, s11, 0
	s_add_i32 s45, 0, 0x10000
	ds_read_b128 v[120:123], v218 offset:0
	ds_read_b128 v[124:127], v218 offset:1024
	ds_read_b128 v[128:131], v218 offset:2048
	ds_read_b128 v[132:135], v218 offset:3072
	s_cmp_eq_u32 s36, s12
	s_cselect_b32 s12, s4, s14
	s_cselect_b32 s13, s5, s13
	s_cselect_b32 s15, s7, s43
	s_cselect_b32 s14, s6, s42
	s_add_i32 m0, s26, 0xc000
	ds_read_b128 v[144:147], v205
	ds_read_b128 v[148:151], v205 offset:1024
	ds_read_b128 v[152:155], v205 offset:2048
	ds_read_b128 v[156:159], v205 offset:3072
	ds_read_b128 v[160:163], v205 offset:4096
	ds_read_b128 v[164:167], v205 offset:5120
	ds_read_b128 v[178:181], v205 offset:6144
	ds_read_b128 v[182:185], v205 offset:7168
	global_load_lds_dwordx4 v174, s[10:11]
	s_add_i32 m0, s26, 0xe000
	s_nop 0
	global_load_lds_dwordx4 v176, s[10:11]
	s_waitcnt lgkmcnt(8)
	s_barrier
	s_waitcnt lgkmcnt(0)
	v_mfma_f32_16x16x32_bf16 v[140:143], v[120:123], v[144:147], 0
	v_mfma_f32_16x16x32_bf16 v[136:139], v[128:131], v[144:147], 0
	v_mfma_f32_16x16x32_bf16 v[108:111], v[120:123], v[152:155], 0
	v_mfma_f32_16x16x32_bf16 v[104:107], v[128:131], v[152:155], 0
	s_add_i32 s46, 0, 0x14000
	s_add_i32 s45, s45, s25
	v_mfma_f32_16x16x32_bf16 v[92:95], v[120:123], v[160:163], 0
	s_add_u32 s68, s14, 0x80
	s_addc_u32 s69, s15, 0
	v_mfma_f32_16x16x32_bf16 v[88:91], v[128:131], v[160:163], 0
	s_mov_b32 m0, s45
	v_mfma_f32_16x16x32_bf16 v[76:79], v[120:123], v[178:181], 0
	v_mfma_f32_16x16x32_bf16 v[72:75], v[128:131], v[178:181], 0
	v_mfma_f32_16x16x32_bf16 v[140:143], v[124:127], v[148:151], v[140:143]
	v_mfma_f32_16x16x32_bf16 v[136:139], v[132:135], v[148:151], v[136:139]
	v_mfma_f32_16x16x32_bf16 v[108:111], v[124:127], v[156:159], v[108:111]
	v_mfma_f32_16x16x32_bf16 v[104:107], v[132:135], v[156:159], v[104:107]
	v_mfma_f32_16x16x32_bf16 v[92:95], v[124:127], v[164:167], v[92:95]
	v_mfma_f32_16x16x32_bf16 v[88:91], v[132:135], v[164:167], v[88:91]
	v_mfma_f32_16x16x32_bf16 v[76:79], v[124:127], v[182:185], v[76:79]
	v_mfma_f32_16x16x32_bf16 v[72:75], v[132:135], v[182:185], v[72:75]
	s_barrier
	ds_read_b128 v[186:189], v218 offset:16384
	ds_read_b128 v[196:199], v218 offset:17408
	ds_read_b128 v[206:209], v218 offset:18432
	ds_read_b128 v[214:217], v218 offset:19456
	global_load_lds_dwordx4 v192, s[14:15]
	s_add_i32 m0, s45, 0x2000
	s_nop 0
	global_load_lds_dwordx4 v172, s[14:15]
	s_barrier
	s_waitcnt lgkmcnt(0)
	v_mfma_f32_16x16x32_bf16 v[116:119], v[186:189], v[144:147], 0
	v_mfma_f32_16x16x32_bf16 v[112:115], v[206:209], v[144:147], 0
	v_mfma_f32_16x16x32_bf16 v[100:103], v[186:189], v[152:155], 0
	v_mfma_f32_16x16x32_bf16 v[96:99], v[206:209], v[152:155], 0
	s_mov_b32 m0, s26
	v_mfma_f32_16x16x32_bf16 v[84:87], v[186:189], v[160:163], 0
	s_add_u32 s70, s12, 0x80
	s_addc_u32 s71, s13, 0
	v_mfma_f32_16x16x32_bf16 v[80:83], v[206:209], v[160:163], 0
	v_mfma_f32_16x16x32_bf16 v[68:71], v[186:189], v[178:181], 0
	v_mfma_f32_16x16x32_bf16 v[64:67], v[206:209], v[178:181], 0
	v_mfma_f32_16x16x32_bf16 v[116:119], v[196:199], v[148:151], v[116:119]
	v_mfma_f32_16x16x32_bf16 v[112:115], v[214:217], v[148:151], v[112:115]
	v_mfma_f32_16x16x32_bf16 v[100:103], v[196:199], v[156:159], v[100:103]
	v_mfma_f32_16x16x32_bf16 v[96:99], v[214:217], v[156:159], v[96:99]
	v_mfma_f32_16x16x32_bf16 v[84:87], v[196:199], v[164:167], v[84:87]
	v_mfma_f32_16x16x32_bf16 v[80:83], v[214:217], v[164:167], v[80:83]
	v_mfma_f32_16x16x32_bf16 v[68:71], v[196:199], v[182:185], v[68:71]
	v_mfma_f32_16x16x32_bf16 v[64:67], v[214:217], v[182:185], v[64:67]
	s_barrier
	ds_read_b128 v[144:147], v205 offset:16384
	ds_read_b128 v[148:151], v205 offset:17408
	ds_read_b128 v[152:155], v205 offset:18432
	ds_read_b128 v[156:159], v205 offset:19456
	ds_read_b128 v[160:163], v205 offset:20480
	ds_read_b128 v[164:167], v205 offset:21504
	ds_read_b128 v[178:181], v205 offset:22528
	ds_read_b128 v[182:185], v205 offset:23552
	global_load_lds_dwordx4 v168, s[12:13]
	s_mov_b32 m0, s27
	s_nop 0
	global_load_lds_dwordx4 v170, s[12:13]
	s_waitcnt lgkmcnt(0)
	s_barrier
	v_mfma_f32_16x16x32_bf16 v[60:63], v[120:123], v[144:147], 0
	v_mfma_f32_16x16x32_bf16 v[56:59], v[128:131], v[144:147], 0
	v_mfma_f32_16x16x32_bf16 v[44:47], v[120:123], v[152:155], 0
	v_mfma_f32_16x16x32_bf16 v[40:43], v[128:131], v[152:155], 0
	s_add_u32 s14, s14, s52
	s_addc_u32 s15, s15, 0
	v_mfma_f32_16x16x32_bf16 v[28:31], v[120:123], v[160:163], 0
	s_add_i32 s45, s46, s25
	s_mov_b32 m0, s45
	v_mfma_f32_16x16x32_bf16 v[24:27], v[128:131], v[160:163], 0
	v_mfma_f32_16x16x32_bf16 v[12:15], v[120:123], v[178:181], 0
	v_mfma_f32_16x16x32_bf16 v[8:11], v[128:131], v[178:181], 0
	v_mfma_f32_16x16x32_bf16 v[60:63], v[124:127], v[148:151], v[60:63]
	v_mfma_f32_16x16x32_bf16 v[56:59], v[132:135], v[148:151], v[56:59]
	v_mfma_f32_16x16x32_bf16 v[44:47], v[124:127], v[156:159], v[44:47]
	v_mfma_f32_16x16x32_bf16 v[40:43], v[132:135], v[156:159], v[40:43]
	v_mfma_f32_16x16x32_bf16 v[28:31], v[124:127], v[164:167], v[28:31]
	v_mfma_f32_16x16x32_bf16 v[24:27], v[132:135], v[164:167], v[24:27]
	v_mfma_f32_16x16x32_bf16 v[12:15], v[124:127], v[182:185], v[12:15]
	v_mfma_f32_16x16x32_bf16 v[8:11], v[132:135], v[182:185], v[8:11]
	s_barrier
	global_load_lds_dwordx4 v192, s[14:15]
	s_add_i32 m0, s45, 0x2000
	s_nop 0
	global_load_lds_dwordx4 v172, s[14:15]
	s_add_u32 s12, s12, s52
	s_addc_u32 s13, s13, 0
	s_mov_b32 m0, s28
	s_nop 0
	global_load_lds_dwordx4 v168, s[12:13]
	s_mov_b32 m0, s29
	s_nop 0
	global_load_lds_dwordx4 v170, s[12:13]
	s_waitcnt vmcnt(8)
	s_barrier
	v_mfma_f32_16x16x32_bf16 v[52:55], v[186:189], v[144:147], 0
	v_mfma_f32_16x16x32_bf16 v[48:51], v[206:209], v[144:147], 0
	v_mfma_f32_16x16x32_bf16 v[36:39], v[186:189], v[152:155], 0
	v_mfma_f32_16x16x32_bf16 v[32:35], v[206:209], v[152:155], 0
	s_add_i32 s14, 0, 0x18000
	v_mfma_f32_16x16x32_bf16 v[20:23], v[186:189], v[160:163], 0
	v_mfma_f32_16x16x32_bf16 v[16:19], v[206:209], v[160:163], 0
	v_mfma_f32_16x16x32_bf16 v[4:7], v[186:189], v[178:181], 0
	v_mfma_f32_16x16x32_bf16 v[0:3], v[206:209], v[178:181], 0
	v_mfma_f32_16x16x32_bf16 v[52:55], v[196:199], v[148:151], v[52:55]
	v_mfma_f32_16x16x32_bf16 v[48:51], v[214:217], v[148:151], v[48:51]
	v_mfma_f32_16x16x32_bf16 v[36:39], v[196:199], v[156:159], v[36:39]
	v_mfma_f32_16x16x32_bf16 v[32:35], v[214:217], v[156:159], v[32:35]
	v_mfma_f32_16x16x32_bf16 v[20:23], v[196:199], v[164:167], v[20:23]
	v_mfma_f32_16x16x32_bf16 v[16:19], v[214:217], v[164:167], v[16:19]
	v_mfma_f32_16x16x32_bf16 v[4:7], v[196:199], v[182:185], v[4:7]
	v_mfma_f32_16x16x32_bf16 v[0:3], v[214:217], v[182:185], v[0:3]
	s_barrier
	ds_read_b128 v[120:123], v218 offset:32768
	ds_read_b128 v[124:127], v218 offset:33792
	ds_read_b128 v[128:131], v218 offset:34816
	ds_read_b128 v[132:135], v218 offset:35840
	ds_read_b128 v[144:147], v205 offset:32768
	ds_read_b128 v[148:151], v205 offset:33792
	ds_read_b128 v[152:155], v205 offset:34816
	ds_read_b128 v[156:159], v205 offset:35840
	ds_read_b128 v[160:163], v205 offset:36864
	ds_read_b128 v[164:167], v205 offset:37888
	ds_read_b128 v[178:181], v205 offset:38912
	ds_read_b128 v[182:185], v205 offset:39936
	s_waitcnt lgkmcnt(8)
	s_barrier
	s_waitcnt lgkmcnt(0)
	v_mfma_f32_16x16x32_bf16 v[140:143], v[120:123], v[144:147], v[140:143]
	v_mfma_f32_16x16x32_bf16 v[136:139], v[128:131], v[144:147], v[136:139]
	v_mfma_f32_16x16x32_bf16 v[108:111], v[120:123], v[152:155], v[108:111]
	v_mfma_f32_16x16x32_bf16 v[104:107], v[128:131], v[152:155], v[104:107]
	s_add_i32 s12, 0, 0x1c000
	s_add_i32 s13, s14, s25
	v_mfma_f32_16x16x32_bf16 v[92:95], v[120:123], v[160:163], v[92:95]
	s_mov_b32 m0, s13
	v_mfma_f32_16x16x32_bf16 v[88:91], v[128:131], v[160:163], v[88:91]
	v_mfma_f32_16x16x32_bf16 v[76:79], v[120:123], v[178:181], v[76:79]
	v_mfma_f32_16x16x32_bf16 v[72:75], v[128:131], v[178:181], v[72:75]
	v_mfma_f32_16x16x32_bf16 v[140:143], v[124:127], v[148:151], v[140:143]
	v_mfma_f32_16x16x32_bf16 v[136:139], v[132:135], v[148:151], v[136:139]
	v_mfma_f32_16x16x32_bf16 v[108:111], v[124:127], v[156:159], v[108:111]
	v_mfma_f32_16x16x32_bf16 v[104:107], v[132:135], v[156:159], v[104:107]
	v_mfma_f32_16x16x32_bf16 v[92:95], v[124:127], v[164:167], v[92:95]
	v_mfma_f32_16x16x32_bf16 v[88:91], v[132:135], v[164:167], v[88:91]
	v_mfma_f32_16x16x32_bf16 v[76:79], v[124:127], v[182:185], v[76:79]
	v_mfma_f32_16x16x32_bf16 v[72:75], v[132:135], v[182:185], v[72:75]
	s_barrier
	ds_read_b128 v[186:189], v218 offset:49152
	ds_read_b128 v[196:199], v218 offset:50176
	ds_read_b128 v[206:209], v218 offset:51200
	ds_read_b128 v[214:217], v218 offset:52224
	global_load_lds_dwordx4 v192, s[68:69]
	s_add_i32 m0, s13, 0x2000
	s_nop 0
	global_load_lds_dwordx4 v172, s[68:69]
	s_barrier
	s_waitcnt lgkmcnt(0)
	v_mfma_f32_16x16x32_bf16 v[116:119], v[186:189], v[144:147], v[116:119]
	v_mfma_f32_16x16x32_bf16 v[112:115], v[206:209], v[144:147], v[112:115]
	v_mfma_f32_16x16x32_bf16 v[100:103], v[186:189], v[152:155], v[100:103]
	v_mfma_f32_16x16x32_bf16 v[96:99], v[206:209], v[152:155], v[96:99]
	s_mov_b32 m0, s34
	v_mfma_f32_16x16x32_bf16 v[84:87], v[186:189], v[160:163], v[84:87]
	v_mfma_f32_16x16x32_bf16 v[80:83], v[206:209], v[160:163], v[80:83]
	v_mfma_f32_16x16x32_bf16 v[68:71], v[186:189], v[178:181], v[68:71]
	v_mfma_f32_16x16x32_bf16 v[64:67], v[206:209], v[178:181], v[64:67]
	v_mfma_f32_16x16x32_bf16 v[116:119], v[196:199], v[148:151], v[116:119]
	v_mfma_f32_16x16x32_bf16 v[112:115], v[214:217], v[148:151], v[112:115]
	v_mfma_f32_16x16x32_bf16 v[100:103], v[196:199], v[156:159], v[100:103]
	v_mfma_f32_16x16x32_bf16 v[96:99], v[214:217], v[156:159], v[96:99]
	v_mfma_f32_16x16x32_bf16 v[84:87], v[196:199], v[164:167], v[84:87]
	v_mfma_f32_16x16x32_bf16 v[80:83], v[214:217], v[164:167], v[80:83]
	v_mfma_f32_16x16x32_bf16 v[68:71], v[196:199], v[182:185], v[68:71]
	v_mfma_f32_16x16x32_bf16 v[64:67], v[214:217], v[182:185], v[64:67]
	s_barrier
	ds_read_b128 v[144:147], v205 offset:49152
	ds_read_b128 v[148:151], v205 offset:50176
	ds_read_b128 v[152:155], v205 offset:51200
	ds_read_b128 v[156:159], v205 offset:52224
	ds_read_b128 v[160:163], v205 offset:53248
	ds_read_b128 v[164:167], v205 offset:54272
	ds_read_b128 v[178:181], v205 offset:55296
	ds_read_b128 v[182:185], v205 offset:56320
	global_load_lds_dwordx4 v168, s[70:71]
	s_mov_b32 m0, s35
	s_nop 0
	global_load_lds_dwordx4 v170, s[70:71]
	s_barrier
	s_waitcnt lgkmcnt(0)
	v_mfma_f32_16x16x32_bf16 v[60:63], v[120:123], v[144:147], v[60:63]
	v_mfma_f32_16x16x32_bf16 v[56:59], v[128:131], v[144:147], v[56:59]
	v_mfma_f32_16x16x32_bf16 v[44:47], v[120:123], v[152:155], v[44:47]
	v_mfma_f32_16x16x32_bf16 v[40:43], v[128:131], v[152:155], v[40:43]
	s_add_i32 s12, s12, s25
	v_mfma_f32_16x16x32_bf16 v[28:31], v[120:123], v[160:163], v[28:31]
	s_add_u32 s68, s68, s52
	s_addc_u32 s69, s69, 0
	v_mfma_f32_16x16x32_bf16 v[24:27], v[128:131], v[160:163], v[24:27]
	s_mov_b32 m0, s12
	v_mfma_f32_16x16x32_bf16 v[12:15], v[120:123], v[178:181], v[12:15]
	v_mfma_f32_16x16x32_bf16 v[8:11], v[128:131], v[178:181], v[8:11]
	v_mfma_f32_16x16x32_bf16 v[60:63], v[124:127], v[148:151], v[60:63]
	v_mfma_f32_16x16x32_bf16 v[56:59], v[132:135], v[148:151], v[56:59]
	v_mfma_f32_16x16x32_bf16 v[44:47], v[124:127], v[156:159], v[44:47]
	v_mfma_f32_16x16x32_bf16 v[40:43], v[132:135], v[156:159], v[40:43]
	v_mfma_f32_16x16x32_bf16 v[28:31], v[124:127], v[164:167], v[28:31]
	v_mfma_f32_16x16x32_bf16 v[24:27], v[132:135], v[164:167], v[24:27]
	v_mfma_f32_16x16x32_bf16 v[12:15], v[124:127], v[182:185], v[12:15]
	v_mfma_f32_16x16x32_bf16 v[8:11], v[132:135], v[182:185], v[8:11]
	s_barrier
	global_load_lds_dwordx4 v192, s[68:69]
	s_add_i32 m0, s12, 0x2000
	s_nop 0
	global_load_lds_dwordx4 v172, s[68:69]
	s_waitcnt vmcnt(6)
	s_barrier
	v_mfma_f32_16x16x32_bf16 v[52:55], v[186:189], v[144:147], v[52:55]
	v_mfma_f32_16x16x32_bf16 v[48:51], v[206:209], v[144:147], v[48:51]
	v_mfma_f32_16x16x32_bf16 v[36:39], v[186:189], v[152:155], v[36:39]
	v_mfma_f32_16x16x32_bf16 v[32:35], v[206:209], v[152:155], v[32:35]
	s_add_u32 s10, s10, 0x100
	s_addc_u32 s11, s11, 0
	v_mfma_f32_16x16x32_bf16 v[20:23], v[186:189], v[160:163], v[20:23]
	s_add_u32 s42, s42, 0x100
	s_addc_u32 s43, s43, 0
	v_mfma_f32_16x16x32_bf16 v[16:19], v[206:209], v[160:163], v[16:19]
	s_mov_b32 s12, s44
	v_mfma_f32_16x16x32_bf16 v[4:7], v[186:189], v[178:181], v[4:7]
	v_mfma_f32_16x16x32_bf16 v[0:3], v[206:209], v[178:181], v[0:3]
	v_mfma_f32_16x16x32_bf16 v[52:55], v[196:199], v[148:151], v[52:55]
	v_mfma_f32_16x16x32_bf16 v[48:51], v[214:217], v[148:151], v[48:51]
	v_mfma_f32_16x16x32_bf16 v[36:39], v[196:199], v[156:159], v[36:39]
	v_mfma_f32_16x16x32_bf16 v[32:35], v[214:217], v[156:159], v[32:35]
	v_mfma_f32_16x16x32_bf16 v[20:23], v[196:199], v[164:167], v[20:23]
	v_mfma_f32_16x16x32_bf16 v[16:19], v[214:217], v[164:167], v[16:19]
	v_mfma_f32_16x16x32_bf16 v[4:7], v[196:199], v[182:185], v[4:7]
	v_mfma_f32_16x16x32_bf16 v[0:3], v[214:217], v[182:185], v[0:3]
	s_cmp_ge_u32 s44, s33
	s_barrier
.LBB0_246:
	s_add_i32 s44, s12, 2
	s_add_u32 s14, s10, 0x80
	s_addc_u32 s13, s11, 0
	s_add_i32 s45, 0, 0x10000
	ds_read_b128 v[120:123], v218 offset:0
	ds_read_b128 v[124:127], v218 offset:1024
	ds_read_b128 v[128:131], v218 offset:2048
	ds_read_b128 v[132:135], v218 offset:3072
	s_cmp_eq_u32 s36, s12
	s_cselect_b32 s12, s4, s14
	s_cselect_b32 s13, s5, s13
	s_cselect_b32 s15, s7, s43
	s_cselect_b32 s14, s6, s42
	s_add_i32 m0, s26, 0xc000
	ds_read_b128 v[144:147], v205
	ds_read_b128 v[148:151], v205 offset:1024
	ds_read_b128 v[152:155], v205 offset:2048
	ds_read_b128 v[156:159], v205 offset:3072
	ds_read_b128 v[160:163], v205 offset:4096
	ds_read_b128 v[164:167], v205 offset:5120
	ds_read_b128 v[178:181], v205 offset:6144
	ds_read_b128 v[182:185], v205 offset:7168
	global_load_lds_dwordx4 v174, s[10:11]
	s_add_i32 m0, s26, 0xe000
	s_nop 0
	global_load_lds_dwordx4 v176, s[10:11]
	s_waitcnt lgkmcnt(8)
	s_barrier
	s_waitcnt lgkmcnt(0)
	v_mfma_f32_16x16x32_bf16 v[140:143], v[120:123], v[144:147], v[140:143]
	v_mfma_f32_16x16x32_bf16 v[136:139], v[128:131], v[144:147], v[136:139]
	v_mfma_f32_16x16x32_bf16 v[108:111], v[120:123], v[152:155], v[108:111]
	v_mfma_f32_16x16x32_bf16 v[104:107], v[128:131], v[152:155], v[104:107]
	s_add_i32 s46, 0, 0x14000
	s_add_i32 s45, s45, s25
	v_mfma_f32_16x16x32_bf16 v[92:95], v[120:123], v[160:163], v[92:95]
	s_add_u32 s68, s14, 0x80
	s_addc_u32 s69, s15, 0
	v_mfma_f32_16x16x32_bf16 v[88:91], v[128:131], v[160:163], v[88:91]
	s_mov_b32 m0, s45
	v_mfma_f32_16x16x32_bf16 v[76:79], v[120:123], v[178:181], v[76:79]
	v_mfma_f32_16x16x32_bf16 v[72:75], v[128:131], v[178:181], v[72:75]
	v_mfma_f32_16x16x32_bf16 v[140:143], v[124:127], v[148:151], v[140:143]
	v_mfma_f32_16x16x32_bf16 v[136:139], v[132:135], v[148:151], v[136:139]
	v_mfma_f32_16x16x32_bf16 v[108:111], v[124:127], v[156:159], v[108:111]
	v_mfma_f32_16x16x32_bf16 v[104:107], v[132:135], v[156:159], v[104:107]
	v_mfma_f32_16x16x32_bf16 v[92:95], v[124:127], v[164:167], v[92:95]
	v_mfma_f32_16x16x32_bf16 v[88:91], v[132:135], v[164:167], v[88:91]
	v_mfma_f32_16x16x32_bf16 v[76:79], v[124:127], v[182:185], v[76:79]
	v_mfma_f32_16x16x32_bf16 v[72:75], v[132:135], v[182:185], v[72:75]
	s_barrier
	ds_read_b128 v[186:189], v218 offset:16384
	ds_read_b128 v[196:199], v218 offset:17408
	ds_read_b128 v[206:209], v218 offset:18432
	ds_read_b128 v[214:217], v218 offset:19456
	global_load_lds_dwordx4 v192, s[14:15]
	s_add_i32 m0, s45, 0x2000
	s_nop 0
	global_load_lds_dwordx4 v172, s[14:15]
	s_barrier
	s_waitcnt lgkmcnt(0)
	v_mfma_f32_16x16x32_bf16 v[116:119], v[186:189], v[144:147], v[116:119]
	v_mfma_f32_16x16x32_bf16 v[112:115], v[206:209], v[144:147], v[112:115]
	v_mfma_f32_16x16x32_bf16 v[100:103], v[186:189], v[152:155], v[100:103]
	v_mfma_f32_16x16x32_bf16 v[96:99], v[206:209], v[152:155], v[96:99]
	s_mov_b32 m0, s26
	v_mfma_f32_16x16x32_bf16 v[84:87], v[186:189], v[160:163], v[84:87]
	s_add_u32 s70, s12, 0x80
	s_addc_u32 s71, s13, 0
	v_mfma_f32_16x16x32_bf16 v[80:83], v[206:209], v[160:163], v[80:83]
	v_mfma_f32_16x16x32_bf16 v[68:71], v[186:189], v[178:181], v[68:71]
	v_mfma_f32_16x16x32_bf16 v[64:67], v[206:209], v[178:181], v[64:67]
	v_mfma_f32_16x16x32_bf16 v[116:119], v[196:199], v[148:151], v[116:119]
	v_mfma_f32_16x16x32_bf16 v[112:115], v[214:217], v[148:151], v[112:115]
	v_mfma_f32_16x16x32_bf16 v[100:103], v[196:199], v[156:159], v[100:103]
	v_mfma_f32_16x16x32_bf16 v[96:99], v[214:217], v[156:159], v[96:99]
	v_mfma_f32_16x16x32_bf16 v[84:87], v[196:199], v[164:167], v[84:87]
	v_mfma_f32_16x16x32_bf16 v[80:83], v[214:217], v[164:167], v[80:83]
	v_mfma_f32_16x16x32_bf16 v[68:71], v[196:199], v[182:185], v[68:71]
	v_mfma_f32_16x16x32_bf16 v[64:67], v[214:217], v[182:185], v[64:67]
	s_barrier
	ds_read_b128 v[144:147], v205 offset:16384
	ds_read_b128 v[148:151], v205 offset:17408
	ds_read_b128 v[152:155], v205 offset:18432
	ds_read_b128 v[156:159], v205 offset:19456
	ds_read_b128 v[160:163], v205 offset:20480
	ds_read_b128 v[164:167], v205 offset:21504
	ds_read_b128 v[178:181], v205 offset:22528
	ds_read_b128 v[182:185], v205 offset:23552
	global_load_lds_dwordx4 v168, s[12:13]
	s_mov_b32 m0, s27
	s_nop 0
	global_load_lds_dwordx4 v170, s[12:13]
	s_waitcnt lgkmcnt(0)
	s_barrier
	v_mfma_f32_16x16x32_bf16 v[60:63], v[120:123], v[144:147], v[60:63]
	v_mfma_f32_16x16x32_bf16 v[56:59], v[128:131], v[144:147], v[56:59]
	v_mfma_f32_16x16x32_bf16 v[44:47], v[120:123], v[152:155], v[44:47]
	v_mfma_f32_16x16x32_bf16 v[40:43], v[128:131], v[152:155], v[40:43]
	s_add_u32 s14, s14, s52
	s_addc_u32 s15, s15, 0
	v_mfma_f32_16x16x32_bf16 v[28:31], v[120:123], v[160:163], v[28:31]
	s_add_i32 s45, s46, s25
	s_mov_b32 m0, s45
	v_mfma_f32_16x16x32_bf16 v[24:27], v[128:131], v[160:163], v[24:27]
	v_mfma_f32_16x16x32_bf16 v[12:15], v[120:123], v[178:181], v[12:15]
	v_mfma_f32_16x16x32_bf16 v[8:11], v[128:131], v[178:181], v[8:11]
	v_mfma_f32_16x16x32_bf16 v[60:63], v[124:127], v[148:151], v[60:63]
	v_mfma_f32_16x16x32_bf16 v[56:59], v[132:135], v[148:151], v[56:59]
	v_mfma_f32_16x16x32_bf16 v[44:47], v[124:127], v[156:159], v[44:47]
	v_mfma_f32_16x16x32_bf16 v[40:43], v[132:135], v[156:159], v[40:43]
	v_mfma_f32_16x16x32_bf16 v[28:31], v[124:127], v[164:167], v[28:31]
	v_mfma_f32_16x16x32_bf16 v[24:27], v[132:135], v[164:167], v[24:27]
	v_mfma_f32_16x16x32_bf16 v[12:15], v[124:127], v[182:185], v[12:15]
	v_mfma_f32_16x16x32_bf16 v[8:11], v[132:135], v[182:185], v[8:11]
	s_barrier
	global_load_lds_dwordx4 v192, s[14:15]
	s_add_i32 m0, s45, 0x2000
	s_nop 0
	global_load_lds_dwordx4 v172, s[14:15]
	s_add_u32 s12, s12, s52
	s_addc_u32 s13, s13, 0
	s_mov_b32 m0, s28
	s_nop 0
	global_load_lds_dwordx4 v168, s[12:13]
	s_mov_b32 m0, s29
	s_nop 0
	global_load_lds_dwordx4 v170, s[12:13]
	s_waitcnt vmcnt(8)
	s_barrier
	v_mfma_f32_16x16x32_bf16 v[52:55], v[186:189], v[144:147], v[52:55]
	v_mfma_f32_16x16x32_bf16 v[48:51], v[206:209], v[144:147], v[48:51]
	v_mfma_f32_16x16x32_bf16 v[36:39], v[186:189], v[152:155], v[36:39]
	v_mfma_f32_16x16x32_bf16 v[32:35], v[206:209], v[152:155], v[32:35]
	s_add_i32 s14, 0, 0x18000
	v_mfma_f32_16x16x32_bf16 v[20:23], v[186:189], v[160:163], v[20:23]
	v_mfma_f32_16x16x32_bf16 v[16:19], v[206:209], v[160:163], v[16:19]
	v_mfma_f32_16x16x32_bf16 v[4:7], v[186:189], v[178:181], v[4:7]
	v_mfma_f32_16x16x32_bf16 v[0:3], v[206:209], v[178:181], v[0:3]
	v_mfma_f32_16x16x32_bf16 v[52:55], v[196:199], v[148:151], v[52:55]
	v_mfma_f32_16x16x32_bf16 v[48:51], v[214:217], v[148:151], v[48:51]
	v_mfma_f32_16x16x32_bf16 v[36:39], v[196:199], v[156:159], v[36:39]
	v_mfma_f32_16x16x32_bf16 v[32:35], v[214:217], v[156:159], v[32:35]
	v_mfma_f32_16x16x32_bf16 v[20:23], v[196:199], v[164:167], v[20:23]
	v_mfma_f32_16x16x32_bf16 v[16:19], v[214:217], v[164:167], v[16:19]
	v_mfma_f32_16x16x32_bf16 v[4:7], v[196:199], v[182:185], v[4:7]
	v_mfma_f32_16x16x32_bf16 v[0:3], v[214:217], v[182:185], v[0:3]
	s_barrier
	ds_read_b128 v[120:123], v218 offset:32768
	ds_read_b128 v[124:127], v218 offset:33792
	ds_read_b128 v[128:131], v218 offset:34816
	ds_read_b128 v[132:135], v218 offset:35840
	ds_read_b128 v[144:147], v205 offset:32768
	ds_read_b128 v[148:151], v205 offset:33792
	ds_read_b128 v[152:155], v205 offset:34816
	ds_read_b128 v[156:159], v205 offset:35840
	ds_read_b128 v[160:163], v205 offset:36864
	ds_read_b128 v[164:167], v205 offset:37888
	ds_read_b128 v[178:181], v205 offset:38912
	ds_read_b128 v[182:185], v205 offset:39936
	s_waitcnt lgkmcnt(8)
	s_barrier
	s_waitcnt lgkmcnt(0)
	v_mfma_f32_16x16x32_bf16 v[140:143], v[120:123], v[144:147], v[140:143]
	v_mfma_f32_16x16x32_bf16 v[136:139], v[128:131], v[144:147], v[136:139]
	v_mfma_f32_16x16x32_bf16 v[108:111], v[120:123], v[152:155], v[108:111]
	v_mfma_f32_16x16x32_bf16 v[104:107], v[128:131], v[152:155], v[104:107]
	s_add_i32 s12, 0, 0x1c000
	s_add_i32 s13, s14, s25
	v_mfma_f32_16x16x32_bf16 v[92:95], v[120:123], v[160:163], v[92:95]
	s_mov_b32 m0, s13
	v_mfma_f32_16x16x32_bf16 v[88:91], v[128:131], v[160:163], v[88:91]
	v_mfma_f32_16x16x32_bf16 v[76:79], v[120:123], v[178:181], v[76:79]
	v_mfma_f32_16x16x32_bf16 v[72:75], v[128:131], v[178:181], v[72:75]
	v_mfma_f32_16x16x32_bf16 v[140:143], v[124:127], v[148:151], v[140:143]
	v_mfma_f32_16x16x32_bf16 v[136:139], v[132:135], v[148:151], v[136:139]
	v_mfma_f32_16x16x32_bf16 v[108:111], v[124:127], v[156:159], v[108:111]
	v_mfma_f32_16x16x32_bf16 v[104:107], v[132:135], v[156:159], v[104:107]
	v_mfma_f32_16x16x32_bf16 v[92:95], v[124:127], v[164:167], v[92:95]
	v_mfma_f32_16x16x32_bf16 v[88:91], v[132:135], v[164:167], v[88:91]
	v_mfma_f32_16x16x32_bf16 v[76:79], v[124:127], v[182:185], v[76:79]
	v_mfma_f32_16x16x32_bf16 v[72:75], v[132:135], v[182:185], v[72:75]
	s_barrier
	ds_read_b128 v[186:189], v218 offset:49152
	ds_read_b128 v[196:199], v218 offset:50176
	ds_read_b128 v[206:209], v218 offset:51200
	ds_read_b128 v[214:217], v218 offset:52224
	global_load_lds_dwordx4 v192, s[68:69]
	s_add_i32 m0, s13, 0x2000
	s_nop 0
	global_load_lds_dwordx4 v172, s[68:69]
	s_barrier
	s_waitcnt lgkmcnt(0)
	v_mfma_f32_16x16x32_bf16 v[116:119], v[186:189], v[144:147], v[116:119]
	v_mfma_f32_16x16x32_bf16 v[112:115], v[206:209], v[144:147], v[112:115]
	v_mfma_f32_16x16x32_bf16 v[100:103], v[186:189], v[152:155], v[100:103]
	v_mfma_f32_16x16x32_bf16 v[96:99], v[206:209], v[152:155], v[96:99]
	s_mov_b32 m0, s34
	v_mfma_f32_16x16x32_bf16 v[84:87], v[186:189], v[160:163], v[84:87]
	v_mfma_f32_16x16x32_bf16 v[80:83], v[206:209], v[160:163], v[80:83]
	v_mfma_f32_16x16x32_bf16 v[68:71], v[186:189], v[178:181], v[68:71]
	v_mfma_f32_16x16x32_bf16 v[64:67], v[206:209], v[178:181], v[64:67]
	v_mfma_f32_16x16x32_bf16 v[116:119], v[196:199], v[148:151], v[116:119]
	v_mfma_f32_16x16x32_bf16 v[112:115], v[214:217], v[148:151], v[112:115]
	v_mfma_f32_16x16x32_bf16 v[100:103], v[196:199], v[156:159], v[100:103]
	v_mfma_f32_16x16x32_bf16 v[96:99], v[214:217], v[156:159], v[96:99]
	v_mfma_f32_16x16x32_bf16 v[84:87], v[196:199], v[164:167], v[84:87]
	v_mfma_f32_16x16x32_bf16 v[80:83], v[214:217], v[164:167], v[80:83]
	v_mfma_f32_16x16x32_bf16 v[68:71], v[196:199], v[182:185], v[68:71]
	v_mfma_f32_16x16x32_bf16 v[64:67], v[214:217], v[182:185], v[64:67]
	s_barrier
	ds_read_b128 v[144:147], v205 offset:49152
	ds_read_b128 v[148:151], v205 offset:50176
	ds_read_b128 v[152:155], v205 offset:51200
	ds_read_b128 v[156:159], v205 offset:52224
	ds_read_b128 v[160:163], v205 offset:53248
	ds_read_b128 v[164:167], v205 offset:54272
	ds_read_b128 v[178:181], v205 offset:55296
	ds_read_b128 v[182:185], v205 offset:56320
	global_load_lds_dwordx4 v168, s[70:71]
	s_mov_b32 m0, s35
	s_nop 0
	global_load_lds_dwordx4 v170, s[70:71]
	s_barrier
	s_waitcnt lgkmcnt(0)
	v_mfma_f32_16x16x32_bf16 v[60:63], v[120:123], v[144:147], v[60:63]
	v_mfma_f32_16x16x32_bf16 v[56:59], v[128:131], v[144:147], v[56:59]
	v_mfma_f32_16x16x32_bf16 v[44:47], v[120:123], v[152:155], v[44:47]
	v_mfma_f32_16x16x32_bf16 v[40:43], v[128:131], v[152:155], v[40:43]
	s_add_i32 s12, s12, s25
	v_mfma_f32_16x16x32_bf16 v[28:31], v[120:123], v[160:163], v[28:31]
	s_add_u32 s68, s68, s52
	s_addc_u32 s69, s69, 0
	v_mfma_f32_16x16x32_bf16 v[24:27], v[128:131], v[160:163], v[24:27]
	s_mov_b32 m0, s12
	v_mfma_f32_16x16x32_bf16 v[12:15], v[120:123], v[178:181], v[12:15]
	v_mfma_f32_16x16x32_bf16 v[8:11], v[128:131], v[178:181], v[8:11]
	v_mfma_f32_16x16x32_bf16 v[60:63], v[124:127], v[148:151], v[60:63]
	v_mfma_f32_16x16x32_bf16 v[56:59], v[132:135], v[148:151], v[56:59]
	v_mfma_f32_16x16x32_bf16 v[44:47], v[124:127], v[156:159], v[44:47]
	v_mfma_f32_16x16x32_bf16 v[40:43], v[132:135], v[156:159], v[40:43]
	v_mfma_f32_16x16x32_bf16 v[28:31], v[124:127], v[164:167], v[28:31]
	v_mfma_f32_16x16x32_bf16 v[24:27], v[132:135], v[164:167], v[24:27]
	v_mfma_f32_16x16x32_bf16 v[12:15], v[124:127], v[182:185], v[12:15]
	v_mfma_f32_16x16x32_bf16 v[8:11], v[132:135], v[182:185], v[8:11]
	s_barrier
	global_load_lds_dwordx4 v192, s[68:69]
	s_add_i32 m0, s12, 0x2000
	s_nop 0
	global_load_lds_dwordx4 v172, s[68:69]
	s_waitcnt vmcnt(6)
	s_barrier
	v_mfma_f32_16x16x32_bf16 v[52:55], v[186:189], v[144:147], v[52:55]
	v_mfma_f32_16x16x32_bf16 v[48:51], v[206:209], v[144:147], v[48:51]
	v_mfma_f32_16x16x32_bf16 v[36:39], v[186:189], v[152:155], v[36:39]
	v_mfma_f32_16x16x32_bf16 v[32:35], v[206:209], v[152:155], v[32:35]
	s_add_u32 s10, s10, 0x100
	s_addc_u32 s11, s11, 0
	v_mfma_f32_16x16x32_bf16 v[20:23], v[186:189], v[160:163], v[20:23]
	s_add_u32 s42, s42, 0x100
	s_addc_u32 s43, s43, 0
	v_mfma_f32_16x16x32_bf16 v[16:19], v[206:209], v[160:163], v[16:19]
	s_mov_b32 s12, s44
	v_mfma_f32_16x16x32_bf16 v[4:7], v[186:189], v[178:181], v[4:7]
	v_mfma_f32_16x16x32_bf16 v[0:3], v[206:209], v[178:181], v[0:3]
	v_mfma_f32_16x16x32_bf16 v[52:55], v[196:199], v[148:151], v[52:55]
	v_mfma_f32_16x16x32_bf16 v[48:51], v[214:217], v[148:151], v[48:51]
	v_mfma_f32_16x16x32_bf16 v[36:39], v[196:199], v[156:159], v[36:39]
	v_mfma_f32_16x16x32_bf16 v[32:35], v[214:217], v[156:159], v[32:35]
	v_mfma_f32_16x16x32_bf16 v[20:23], v[196:199], v[164:167], v[20:23]
	v_mfma_f32_16x16x32_bf16 v[16:19], v[214:217], v[164:167], v[16:19]
	v_mfma_f32_16x16x32_bf16 v[4:7], v[196:199], v[182:185], v[4:7]
	v_mfma_f32_16x16x32_bf16 v[0:3], v[214:217], v[182:185], v[0:3]
	s_cmp_ge_u32 s44, s33
	s_barrier
	s_cbranch_scc0 .LBB0_246
	v_lshl_or_b32 v144, s41, 8, v204
	s_ashr_i32 s10, s40, 4
	s_mul_hi_i32 s11, s10, 0xc000
	s_mul_i32 s10, s10, 0xc000
	v_ashrrev_i32_e32 v145, 31, v144
	v_lshl_add_u32 v146, s40, 8, v190
	s_add_u32 s10, s30, s10
	v_lshlrev_b64 v[178:179], 1, v[144:145]
	v_ashrrev_i32_e32 v147, 31, v146
	s_addc_u32 s11, s31, s11
	v_lshl_add_u64 v[180:181], s[2:3], 0, v[178:179]
	v_lshlrev_b64 v[182:183], 12, v[146:147]
	v_lshl_add_u64 v[124:125], v[144:145], 2, s[10:11]
	v_lshl_add_u64 v[144:145], v[180:181], 0, v[182:183]
	global_load_dwordx4 v[128:131], v[124:125], off offset:16
	global_load_dwordx4 v[132:135], v[124:125], off
	global_load_dwordx4 v[120:123], v[124:125], off offset:528
	s_nop 0
	global_load_dwordx4 v[124:127], v[124:125], off offset:512
	s_nop 0
	global_load_dwordx4 v[196:199], v[144:145], off
	global_load_dwordx4 v[206:209], v[144:145], off offset:256
	v_or_b32_e32 v144, 16, v146
	v_ashrrev_i32_e32 v145, 31, v144
	v_lshlrev_b64 v[188:189], 12, v[144:145]
	v_lshl_add_u64 v[144:145], v[180:181], 0, v[188:189]
	global_load_dwordx4 v[164:167], v[144:145], off
	global_load_dwordx4 v[160:163], v[144:145], off offset:256
	v_or_b32_e32 v144, 32, v146
	v_ashrrev_i32_e32 v145, 31, v144
	v_lshlrev_b64 v[186:187], 12, v[144:145]
	v_lshl_add_u64 v[144:145], v[180:181], 0, v[186:187]
	global_load_dwordx4 v[156:159], v[144:145], off
	global_load_dwordx4 v[152:155], v[144:145], off offset:256
	v_or_b32_e32 v144, 48, v146
	v_ashrrev_i32_e32 v145, 31, v144
	v_lshlrev_b64 v[184:185], 12, v[144:145]
	v_lshl_add_u64 v[144:145], v[180:181], 0, v[184:185]
	global_load_dwordx4 v[148:151], v[144:145], off
	s_nop 0
	global_load_dwordx4 v[144:147], v[144:145], off offset:256
	s_mov_b64 s[10:11], 0x80000
	s_and_b64 vcc, exec, s[0:1]
	s_mov_b32 s41, s38
	s_mov_b32 s40, s39
	s_mov_b64 s[12:13], s[6:7]
	v_readlane_b32 s14, v254, 21
	s_movk_i32 s15, 0x2000
	s_waitcnt vmcnt(0)
	v_lshlrev_b32_e32 v210, 16, v196
	v_and_b32_e32 v211, 0xffff0000, v196
	v_lshlrev_b32_e32 v196, 16, v197
	v_and_b32_e32 v197, 0xffff0000, v197
	v_lshlrev_b32_e32 v214, 16, v198
	v_and_b32_e32 v215, 0xffff0000, v198
	v_lshlrev_b32_e32 v198, 16, v199
	v_and_b32_e32 v199, 0xffff0000, v199
	v_pk_fma_f32 v[140:141], v[140:141], v[132:133], v[210:211]
	v_pk_fma_f32 v[142:143], v[142:143], v[134:135], v[196:197]
	v_pk_fma_f32 v[196:197], v[138:139], v[130:131], v[198:199]
	v_pk_fma_f32 v[138:139], v[136:137], v[128:129], v[214:215]
	v_cvt_pk_bf16_f32 v136, v140, v141
	v_lshl_add_u64 v[140:141], s[8:9], 0, v[182:183]
	v_cvt_pk_bf16_f32 v137, v142, v143
	v_cvt_pk_bf16_f32 v138, v138, v139
	v_cvt_pk_bf16_f32 v139, v196, v197
	v_lshl_add_u64 v[140:141], v[140:141], 0, v[178:179]
	global_store_dwordx4 v[140:141], v[136:139], off
	v_lshlrev_b32_e32 v142, 16, v208
	v_and_b32_e32 v143, 0xffff0000, v208
	v_lshlrev_b32_e32 v136, 16, v206
	v_and_b32_e32 v137, 0xffff0000, v206
	v_lshlrev_b32_e32 v138, 16, v207
	v_and_b32_e32 v139, 0xffff0000, v207
	v_lshlrev_b32_e32 v196, 16, v209
	v_and_b32_e32 v197, 0xffff0000, v209
	v_pk_fma_f32 v[118:119], v[118:119], v[126:127], v[138:139]
	v_pk_fma_f32 v[116:117], v[116:117], v[124:125], v[136:137]
	v_pk_fma_f32 v[136:137], v[114:115], v[122:123], v[196:197]
	v_pk_fma_f32 v[114:115], v[112:113], v[120:121], v[142:143]
	v_cvt_pk_bf16_f32 v112, v116, v117
	v_cvt_pk_bf16_f32 v113, v118, v119
	v_lshlrev_b32_e32 v116, 16, v166
	v_cvt_pk_bf16_f32 v114, v114, v115
	v_cvt_pk_bf16_f32 v115, v136, v137
	global_store_dwordx4 v[140:141], v[112:115], off offset:256
	v_and_b32_e32 v117, 0xffff0000, v166
	v_lshlrev_b32_e32 v118, 16, v167
	v_lshlrev_b32_e32 v112, 16, v164
	v_and_b32_e32 v113, 0xffff0000, v164
	v_and_b32_e32 v119, 0xffff0000, v167
	v_pk_fma_f32 v[108:109], v[108:109], v[132:133], v[112:113]
	v_lshlrev_b32_e32 v114, 16, v165
	v_and_b32_e32 v115, 0xffff0000, v165
	v_pk_fma_f32 v[112:113], v[106:107], v[130:131], v[118:119]
	v_pk_fma_f32 v[106:107], v[104:105], v[128:129], v[116:117]
	v_cvt_pk_bf16_f32 v104, v108, v109
	v_lshl_add_u64 v[108:109], s[8:9], 0, v[188:189]
	v_pk_fma_f32 v[110:111], v[110:111], v[134:135], v[114:115]
	v_lshl_add_u64 v[108:109], v[108:109], 0, v[178:179]
	v_cvt_pk_bf16_f32 v105, v110, v111
	v_cvt_pk_bf16_f32 v106, v106, v107
	v_cvt_pk_bf16_f32 v107, v112, v113
	global_store_dwordx4 v[108:109], v[104:107], off
	v_lshlrev_b32_e32 v110, 16, v162
	v_and_b32_e32 v111, 0xffff0000, v162
	v_lshlrev_b32_e32 v104, 16, v160
	v_and_b32_e32 v105, 0xffff0000, v160
	v_lshlrev_b32_e32 v106, 16, v161
	v_and_b32_e32 v107, 0xffff0000, v161
	v_lshlrev_b32_e32 v112, 16, v163
	v_and_b32_e32 v113, 0xffff0000, v163
	v_pk_fma_f32 v[102:103], v[102:103], v[126:127], v[106:107]
	v_pk_fma_f32 v[100:101], v[100:101], v[124:125], v[104:105]
	v_pk_fma_f32 v[104:105], v[98:99], v[122:123], v[112:113]
	v_pk_fma_f32 v[98:99], v[96:97], v[120:121], v[110:111]
	v_cvt_pk_bf16_f32 v96, v100, v101
	v_cvt_pk_bf16_f32 v97, v102, v103
	v_lshlrev_b32_e32 v100, 16, v158
	v_cvt_pk_bf16_f32 v98, v98, v99
	v_cvt_pk_bf16_f32 v99, v104, v105
	global_store_dwordx4 v[108:109], v[96:99], off offset:256
	v_and_b32_e32 v101, 0xffff0000, v158
	v_lshlrev_b32_e32 v102, 16, v159
	v_lshlrev_b32_e32 v96, 16, v156
	v_and_b32_e32 v97, 0xffff0000, v156
	v_and_b32_e32 v103, 0xffff0000, v159
	v_pk_fma_f32 v[92:93], v[92:93], v[132:133], v[96:97]
	v_lshlrev_b32_e32 v98, 16, v157
	v_and_b32_e32 v99, 0xffff0000, v157
	v_pk_fma_f32 v[96:97], v[90:91], v[130:131], v[102:103]
	v_pk_fma_f32 v[90:91], v[88:89], v[128:129], v[100:101]
	v_cvt_pk_bf16_f32 v88, v92, v93
	v_lshl_add_u64 v[92:93], s[8:9], 0, v[186:187]
	v_pk_fma_f32 v[94:95], v[94:95], v[134:135], v[98:99]
	v_lshl_add_u64 v[92:93], v[92:93], 0, v[178:179]
	v_cvt_pk_bf16_f32 v89, v94, v95
	v_cvt_pk_bf16_f32 v90, v90, v91
	v_cvt_pk_bf16_f32 v91, v96, v97
	global_store_dwordx4 v[92:93], v[88:91], off
	v_lshlrev_b32_e32 v94, 16, v154
	v_and_b32_e32 v95, 0xffff0000, v154
	v_lshlrev_b32_e32 v88, 16, v152
	v_and_b32_e32 v89, 0xffff0000, v152
	v_lshlrev_b32_e32 v90, 16, v153
	v_and_b32_e32 v91, 0xffff0000, v153
	v_lshlrev_b32_e32 v96, 16, v155
	v_and_b32_e32 v97, 0xffff0000, v155
	v_pk_fma_f32 v[86:87], v[86:87], v[126:127], v[90:91]
	v_pk_fma_f32 v[84:85], v[84:85], v[124:125], v[88:89]
	v_pk_fma_f32 v[88:89], v[82:83], v[122:123], v[96:97]
	v_pk_fma_f32 v[82:83], v[80:81], v[120:121], v[94:95]
	v_cvt_pk_bf16_f32 v80, v84, v85
	v_cvt_pk_bf16_f32 v81, v86, v87
	v_lshlrev_b32_e32 v84, 16, v150
	v_cvt_pk_bf16_f32 v82, v82, v83
	v_cvt_pk_bf16_f32 v83, v88, v89
	global_store_dwordx4 v[92:93], v[80:83], off offset:256
	v_and_b32_e32 v85, 0xffff0000, v150
	v_lshlrev_b32_e32 v86, 16, v151
	v_lshlrev_b32_e32 v80, 16, v148
	v_and_b32_e32 v81, 0xffff0000, v148
	v_and_b32_e32 v87, 0xffff0000, v151
	v_pk_fma_f32 v[76:77], v[76:77], v[132:133], v[80:81]
	v_lshlrev_b32_e32 v82, 16, v149
	v_and_b32_e32 v83, 0xffff0000, v149
	v_pk_fma_f32 v[80:81], v[74:75], v[130:131], v[86:87]
	v_pk_fma_f32 v[74:75], v[72:73], v[128:129], v[84:85]
	v_cvt_pk_bf16_f32 v72, v76, v77
	v_lshl_add_u64 v[76:77], s[8:9], 0, v[184:185]
	v_pk_fma_f32 v[78:79], v[78:79], v[134:135], v[82:83]
	v_lshl_add_u64 v[76:77], v[76:77], 0, v[178:179]
	v_cvt_pk_bf16_f32 v73, v78, v79
	v_cvt_pk_bf16_f32 v74, v74, v75
	v_cvt_pk_bf16_f32 v75, v80, v81
	global_store_dwordx4 v[76:77], v[72:75], off
	v_lshlrev_b32_e32 v78, 16, v146
	v_and_b32_e32 v79, 0xffff0000, v146
	v_lshlrev_b32_e32 v72, 16, v144
	v_and_b32_e32 v73, 0xffff0000, v144
	v_lshlrev_b32_e32 v74, 16, v145
	v_and_b32_e32 v75, 0xffff0000, v145
	v_lshlrev_b32_e32 v80, 16, v147
	v_and_b32_e32 v81, 0xffff0000, v147
	v_pk_fma_f32 v[70:71], v[70:71], v[126:127], v[74:75]
	v_pk_fma_f32 v[68:69], v[68:69], v[124:125], v[72:73]
	v_pk_fma_f32 v[72:73], v[66:67], v[122:123], v[80:81]
	v_pk_fma_f32 v[66:67], v[64:65], v[120:121], v[78:79]
	v_cvt_pk_bf16_f32 v64, v68, v69
	v_cvt_pk_bf16_f32 v65, v70, v71
	v_lshl_add_u64 v[98:99], v[182:183], 0, s[10:11]
	v_cvt_pk_bf16_f32 v66, v66, v67
	v_cvt_pk_bf16_f32 v67, v72, v73
	global_store_dwordx4 v[76:77], v[64:67], off offset:256
	s_mov_b64 s[10:11], 0x90000
	v_lshl_add_u64 v[100:101], v[182:183], 0, s[10:11]
	v_lshl_add_u64 v[64:65], v[180:181], 0, v[98:99]
	global_load_dwordx4 v[74:77], v[64:65], off
	global_load_dwordx4 v[78:81], v[64:65], off offset:256
	v_lshl_add_u64 v[64:65], v[180:181], 0, v[100:101]
	global_load_dwordx4 v[82:85], v[64:65], off
	global_load_dwordx4 v[86:89], v[64:65], off offset:256
	s_mov_b64 s[10:11], 0xa0000
	v_lshl_add_u64 v[102:103], v[182:183], 0, s[10:11]
	v_lshl_add_u64 v[64:65], v[180:181], 0, v[102:103]
	global_load_dwordx4 v[90:93], v[64:65], off
	global_load_dwordx4 v[94:97], v[64:65], off offset:256
	s_mov_b64 s[10:11], 0xb0000
	v_lshl_add_u64 v[72:73], v[182:183], 0, s[10:11]
	v_lshl_add_u64 v[64:65], v[180:181], 0, v[72:73]
	global_load_dwordx4 v[68:71], v[64:65], off
	s_nop 0
	global_load_dwordx4 v[64:67], v[64:65], off offset:256
	s_mov_b64 s[10:11], s[4:5]
	s_waitcnt vmcnt(0)
	v_lshlrev_b32_e32 v104, 16, v74
	v_and_b32_e32 v105, 0xffff0000, v74
	v_lshlrev_b32_e32 v74, 16, v75
	v_and_b32_e32 v75, 0xffff0000, v75
	v_lshlrev_b32_e32 v106, 16, v76
	v_and_b32_e32 v107, 0xffff0000, v76
	v_lshlrev_b32_e32 v76, 16, v77
	v_and_b32_e32 v77, 0xffff0000, v77
	v_pk_fma_f32 v[60:61], v[60:61], v[132:133], v[104:105]
	v_pk_fma_f32 v[62:63], v[62:63], v[134:135], v[74:75]
	v_pk_fma_f32 v[74:75], v[58:59], v[130:131], v[76:77]
	v_pk_fma_f32 v[58:59], v[56:57], v[128:129], v[106:107]
	v_cvt_pk_bf16_f32 v56, v60, v61
	v_lshl_add_u64 v[60:61], s[8:9], 0, v[98:99]
	v_cvt_pk_bf16_f32 v57, v62, v63
	v_cvt_pk_bf16_f32 v58, v58, v59
	v_cvt_pk_bf16_f32 v59, v74, v75
	v_lshl_add_u64 v[60:61], v[60:61], 0, v[178:179]
	global_store_dwordx4 v[60:61], v[56:59], off
	v_lshlrev_b32_e32 v62, 16, v80
	v_and_b32_e32 v63, 0xffff0000, v80
	v_lshlrev_b32_e32 v56, 16, v78
	v_and_b32_e32 v57, 0xffff0000, v78
	v_lshlrev_b32_e32 v58, 16, v79
	v_and_b32_e32 v59, 0xffff0000, v79
	v_lshlrev_b32_e32 v74, 16, v81
	v_and_b32_e32 v75, 0xffff0000, v81
	v_pk_fma_f32 v[54:55], v[54:55], v[126:127], v[58:59]
	v_pk_fma_f32 v[52:53], v[52:53], v[124:125], v[56:57]
	v_pk_fma_f32 v[56:57], v[50:51], v[122:123], v[74:75]
	v_pk_fma_f32 v[50:51], v[48:49], v[120:121], v[62:63]
	v_cvt_pk_bf16_f32 v48, v52, v53
	v_cvt_pk_bf16_f32 v49, v54, v55
	v_lshlrev_b32_e32 v52, 16, v84
	v_cvt_pk_bf16_f32 v50, v50, v51
	v_cvt_pk_bf16_f32 v51, v56, v57
	global_store_dwordx4 v[60:61], v[48:51], off offset:256
	v_and_b32_e32 v53, 0xffff0000, v84
	v_lshlrev_b32_e32 v54, 16, v85
	v_lshlrev_b32_e32 v48, 16, v82
	v_and_b32_e32 v49, 0xffff0000, v82
	v_and_b32_e32 v55, 0xffff0000, v85
	v_pk_fma_f32 v[44:45], v[44:45], v[132:133], v[48:49]
	v_lshlrev_b32_e32 v50, 16, v83
	v_and_b32_e32 v51, 0xffff0000, v83
	v_pk_fma_f32 v[48:49], v[42:43], v[130:131], v[54:55]
	v_pk_fma_f32 v[42:43], v[40:41], v[128:129], v[52:53]
	v_cvt_pk_bf16_f32 v40, v44, v45
	v_lshl_add_u64 v[44:45], s[8:9], 0, v[100:101]
	v_pk_fma_f32 v[46:47], v[46:47], v[134:135], v[50:51]
	v_lshl_add_u64 v[44:45], v[44:45], 0, v[178:179]
	v_cvt_pk_bf16_f32 v41, v46, v47
	v_cvt_pk_bf16_f32 v42, v42, v43
	v_cvt_pk_bf16_f32 v43, v48, v49
	global_store_dwordx4 v[44:45], v[40:43], off
	v_lshlrev_b32_e32 v46, 16, v88
	v_and_b32_e32 v47, 0xffff0000, v88
	v_lshlrev_b32_e32 v40, 16, v86
	v_and_b32_e32 v41, 0xffff0000, v86
	v_lshlrev_b32_e32 v42, 16, v87
	v_and_b32_e32 v43, 0xffff0000, v87
	v_lshlrev_b32_e32 v48, 16, v89
	v_and_b32_e32 v49, 0xffff0000, v89
	v_pk_fma_f32 v[38:39], v[38:39], v[126:127], v[42:43]
	v_pk_fma_f32 v[36:37], v[36:37], v[124:125], v[40:41]
	v_pk_fma_f32 v[40:41], v[34:35], v[122:123], v[48:49]
	v_pk_fma_f32 v[34:35], v[32:33], v[120:121], v[46:47]
	v_cvt_pk_bf16_f32 v32, v36, v37
	v_cvt_pk_bf16_f32 v33, v38, v39
	v_lshlrev_b32_e32 v36, 16, v92
	v_cvt_pk_bf16_f32 v34, v34, v35
	v_cvt_pk_bf16_f32 v35, v40, v41
	global_store_dwordx4 v[44:45], v[32:35], off offset:256
	v_and_b32_e32 v37, 0xffff0000, v92
	v_lshlrev_b32_e32 v38, 16, v93
	v_lshlrev_b32_e32 v32, 16, v90
	v_and_b32_e32 v33, 0xffff0000, v90
	v_and_b32_e32 v39, 0xffff0000, v93
	v_pk_fma_f32 v[28:29], v[28:29], v[132:133], v[32:33]
	v_lshlrev_b32_e32 v34, 16, v91
	v_and_b32_e32 v35, 0xffff0000, v91
	v_pk_fma_f32 v[32:33], v[26:27], v[130:131], v[38:39]
	v_pk_fma_f32 v[26:27], v[24:25], v[128:129], v[36:37]
	v_cvt_pk_bf16_f32 v24, v28, v29
	v_lshl_add_u64 v[28:29], s[8:9], 0, v[102:103]
	v_pk_fma_f32 v[30:31], v[30:31], v[134:135], v[34:35]
	v_lshl_add_u64 v[28:29], v[28:29], 0, v[178:179]
	v_cvt_pk_bf16_f32 v25, v30, v31
	v_cvt_pk_bf16_f32 v26, v26, v27
	v_cvt_pk_bf16_f32 v27, v32, v33
	global_store_dwordx4 v[28:29], v[24:27], off
	v_lshlrev_b32_e32 v30, 16, v96
	v_and_b32_e32 v31, 0xffff0000, v96
	v_lshlrev_b32_e32 v24, 16, v94
	v_and_b32_e32 v25, 0xffff0000, v94
	v_lshlrev_b32_e32 v26, 16, v95
	v_and_b32_e32 v27, 0xffff0000, v95
	v_lshlrev_b32_e32 v32, 16, v97
	v_and_b32_e32 v33, 0xffff0000, v97
	v_pk_fma_f32 v[22:23], v[22:23], v[126:127], v[26:27]
	v_pk_fma_f32 v[20:21], v[20:21], v[124:125], v[24:25]
	v_pk_fma_f32 v[24:25], v[18:19], v[122:123], v[32:33]
	v_pk_fma_f32 v[18:19], v[16:17], v[120:121], v[30:31]
	v_cvt_pk_bf16_f32 v16, v20, v21
	v_cvt_pk_bf16_f32 v17, v22, v23
	v_lshlrev_b32_e32 v20, 16, v70
	v_cvt_pk_bf16_f32 v18, v18, v19
	v_cvt_pk_bf16_f32 v19, v24, v25
	global_store_dwordx4 v[28:29], v[16:19], off offset:256
	v_and_b32_e32 v21, 0xffff0000, v70
	v_lshlrev_b32_e32 v22, 16, v71
	v_lshlrev_b32_e32 v16, 16, v68
	v_and_b32_e32 v17, 0xffff0000, v68
	v_and_b32_e32 v23, 0xffff0000, v71
	v_pk_fma_f32 v[12:13], v[12:13], v[132:133], v[16:17]
	v_lshlrev_b32_e32 v18, 16, v69
	v_and_b32_e32 v19, 0xffff0000, v69
	v_pk_fma_f32 v[16:17], v[10:11], v[130:131], v[22:23]
	v_pk_fma_f32 v[10:11], v[8:9], v[128:129], v[20:21]
	v_cvt_pk_bf16_f32 v8, v12, v13
	v_lshl_add_u64 v[12:13], s[8:9], 0, v[72:73]
	v_pk_fma_f32 v[14:15], v[14:15], v[134:135], v[18:19]
	v_lshl_add_u64 v[12:13], v[12:13], 0, v[178:179]
	v_cvt_pk_bf16_f32 v9, v14, v15
	v_cvt_pk_bf16_f32 v10, v10, v11
	v_cvt_pk_bf16_f32 v11, v16, v17
	global_store_dwordx4 v[12:13], v[8:11], off
	v_lshlrev_b32_e32 v14, 16, v66
	v_and_b32_e32 v15, 0xffff0000, v66
	v_lshlrev_b32_e32 v8, 16, v64
	v_and_b32_e32 v9, 0xffff0000, v64
	v_lshlrev_b32_e32 v16, 16, v67
	v_and_b32_e32 v17, 0xffff0000, v67
	v_lshlrev_b32_e32 v10, 16, v65
	v_and_b32_e32 v11, 0xffff0000, v65
	v_pk_fma_f32 v[4:5], v[4:5], v[124:125], v[8:9]
	v_pk_fma_f32 v[8:9], v[2:3], v[122:123], v[16:17]
	v_pk_fma_f32 v[2:3], v[0:1], v[120:121], v[14:15]
	v_pk_fma_f32 v[6:7], v[6:7], v[126:127], v[10:11]
	v_cvt_pk_bf16_f32 v0, v4, v5
	s_nop 0
	v_cvt_pk_bf16_f32 v1, v6, v7
	v_cvt_pk_bf16_f32 v2, v2, v3
	v_cvt_pk_bf16_f32 v3, v8, v9
	global_store_dwordx4 v[12:13], v[0:3], off offset:256
	s_cbranch_vccz .LBB0_235
	s_waitcnt vmcnt(0)
	s_cmpk_gt_u32 s16, 0xff
	s_cbranch_scc1 .LBB0_250
	s_barrier

.LBB0_271:
	s_add_u32 s39, s10, 0x100
	s_addc_u32 s40, s11, 0
	s_mov_b32 s41, -2
	s_mov_b64 s[44:45], 0x80
	v_add_u32_e32 v220, 0x10000, v187
	s_add_u32 s10, s8, 0x100
	s_addc_u32 s11, s9, 0
	s_add_i32 s42, 0, 0x10000
	ds_read_b128 v[108:111], v220 offset:0
	ds_read_b128 v[112:115], v220 offset:1024
	ds_read_b128 v[116:119], v220 offset:2048
	ds_read_b128 v[120:123], v220 offset:3072
	s_cmpk_eq_i32 s41, 0x54
	s_cselect_b32 s15, s5, s11
	s_cselect_b32 s14, s4, s10
	s_cselect_b32 s13, s7, s40
	s_cselect_b32 s12, s6, s39
	s_add_i32 m0, s25, 0xc000
	ds_read_b128 v[144:147], v189
	ds_read_b128 v[148:151], v189 offset:1024
	ds_read_b128 v[152:155], v189 offset:2048
	ds_read_b128 v[156:159], v189 offset:3072
	ds_read_b128 v[160:163], v189 offset:4096
	ds_read_b128 v[174:177], v189 offset:5120
	ds_read_b128 v[178:181], v189 offset:6144
	ds_read_b128 v[182:185], v189 offset:7168
	global_load_lds_dwordx4 v170, s[8:9]
	s_add_i32 m0, s25, 0xe000
	s_nop 0
	global_load_lds_dwordx4 v172, s[8:9]
	s_waitcnt lgkmcnt(8)
	s_barrier
	s_waitcnt lgkmcnt(0)
	v_mfma_f32_16x16x32_bf16 v[140:143], v[108:111], v[144:147], 0
	v_mfma_f32_16x16x32_bf16 v[136:139], v[116:119], v[144:147], 0
	v_mfma_f32_16x16x32_bf16 v[132:135], v[108:111], v[152:155], 0
	v_mfma_f32_16x16x32_bf16 v[104:107], v[116:119], v[152:155], 0
	s_add_i32 s43, 0, 0x14000
	s_add_i32 s8, s42, s19
	v_mfma_f32_16x16x32_bf16 v[96:99], v[108:111], v[160:163], 0
	s_mov_b32 m0, s8
	v_mfma_f32_16x16x32_bf16 v[88:91], v[116:119], v[160:163], 0
	v_mfma_f32_16x16x32_bf16 v[80:83], v[108:111], v[178:181], 0
	v_mfma_f32_16x16x32_bf16 v[72:75], v[116:119], v[178:181], 0
	v_mfma_f32_16x16x32_bf16 v[140:143], v[112:115], v[148:151], v[140:143]
	v_mfma_f32_16x16x32_bf16 v[136:139], v[120:123], v[148:151], v[136:139]
	v_mfma_f32_16x16x32_bf16 v[132:135], v[112:115], v[156:159], v[132:135]
	v_mfma_f32_16x16x32_bf16 v[104:107], v[120:123], v[156:159], v[104:107]
	v_mfma_f32_16x16x32_bf16 v[96:99], v[112:115], v[174:177], v[96:99]
	v_mfma_f32_16x16x32_bf16 v[88:91], v[120:123], v[174:177], v[88:91]
	v_mfma_f32_16x16x32_bf16 v[80:83], v[112:115], v[182:185], v[80:83]
	v_mfma_f32_16x16x32_bf16 v[72:75], v[120:123], v[182:185], v[72:75]
	s_barrier
	ds_read_b128 v[196:199], v220 offset:16384
	ds_read_b128 v[204:207], v220 offset:17408
	ds_read_b128 v[208:211], v220 offset:18432
	ds_read_b128 v[214:217], v220 offset:19456
	global_load_lds_dwordx4 v192, s[12:13]
	s_add_i32 m0, s8, 0x2000
	s_nop 0
	global_load_lds_dwordx4 v168, s[12:13]
	s_barrier
	s_waitcnt lgkmcnt(0)
	v_mfma_f32_16x16x32_bf16 v[128:131], v[196:199], v[144:147], 0
	v_mfma_f32_16x16x32_bf16 v[124:127], v[208:211], v[144:147], 0
	v_mfma_f32_16x16x32_bf16 v[100:103], v[196:199], v[152:155], 0
	v_mfma_f32_16x16x32_bf16 v[92:95], v[208:211], v[152:155], 0
	s_mov_b32 m0, s25
	v_mfma_f32_16x16x32_bf16 v[84:87], v[196:199], v[160:163], 0
	s_add_u32 s44, s14, 0x80
	s_addc_u32 s45, s15, 0
	v_mfma_f32_16x16x32_bf16 v[76:79], v[208:211], v[160:163], 0
	v_mfma_f32_16x16x32_bf16 v[68:71], v[196:199], v[178:181], 0
	v_mfma_f32_16x16x32_bf16 v[64:67], v[208:211], v[178:181], 0
	v_mfma_f32_16x16x32_bf16 v[128:131], v[204:207], v[148:151], v[128:131]
	v_mfma_f32_16x16x32_bf16 v[124:127], v[214:217], v[148:151], v[124:127]
	v_mfma_f32_16x16x32_bf16 v[100:103], v[204:207], v[156:159], v[100:103]
	v_mfma_f32_16x16x32_bf16 v[92:95], v[214:217], v[156:159], v[92:95]
	v_mfma_f32_16x16x32_bf16 v[84:87], v[204:207], v[174:177], v[84:87]
	v_mfma_f32_16x16x32_bf16 v[76:79], v[214:217], v[174:177], v[76:79]
	v_mfma_f32_16x16x32_bf16 v[68:71], v[204:207], v[182:185], v[68:71]
	v_mfma_f32_16x16x32_bf16 v[64:67], v[214:217], v[182:185], v[64:67]
	s_barrier
	ds_read_b128 v[144:147], v189 offset:16384
	ds_read_b128 v[148:151], v189 offset:17408
	ds_read_b128 v[152:155], v189 offset:18432
	ds_read_b128 v[156:159], v189 offset:19456
	ds_read_b128 v[160:163], v189 offset:20480
	ds_read_b128 v[174:177], v189 offset:21504
	ds_read_b128 v[178:181], v189 offset:22528
	ds_read_b128 v[182:185], v189 offset:23552
	global_load_lds_dwordx4 v164, s[14:15]
	s_mov_b32 m0, s26
	s_nop 0
	global_load_lds_dwordx4 v166, s[14:15]
	s_waitcnt lgkmcnt(0)
	s_barrier
	v_mfma_f32_16x16x32_bf16 v[60:63], v[108:111], v[144:147], 0
	v_mfma_f32_16x16x32_bf16 v[56:59], v[116:119], v[144:147], 0
	v_mfma_f32_16x16x32_bf16 v[48:51], v[108:111], v[152:155], 0
	v_mfma_f32_16x16x32_bf16 v[40:43], v[116:119], v[152:155], 0
	s_add_u32 s8, s12, 0x160000
	s_addc_u32 s9, s13, 0
	v_mfma_f32_16x16x32_bf16 v[32:35], v[108:111], v[160:163], 0
	s_add_i32 s42, s43, s19
	s_mov_b32 m0, s42
	v_mfma_f32_16x16x32_bf16 v[24:27], v[116:119], v[160:163], 0
	v_mfma_f32_16x16x32_bf16 v[16:19], v[108:111], v[178:181], 0
	v_mfma_f32_16x16x32_bf16 v[8:11], v[116:119], v[178:181], 0
	v_mfma_f32_16x16x32_bf16 v[60:63], v[112:115], v[148:151], v[60:63]
	v_mfma_f32_16x16x32_bf16 v[56:59], v[120:123], v[148:151], v[56:59]
	v_mfma_f32_16x16x32_bf16 v[48:51], v[112:115], v[156:159], v[48:51]
	v_mfma_f32_16x16x32_bf16 v[40:43], v[120:123], v[156:159], v[40:43]
	v_mfma_f32_16x16x32_bf16 v[32:35], v[112:115], v[174:177], v[32:35]
	v_mfma_f32_16x16x32_bf16 v[24:27], v[120:123], v[174:177], v[24:27]
	v_mfma_f32_16x16x32_bf16 v[16:19], v[112:115], v[182:185], v[16:19]
	v_mfma_f32_16x16x32_bf16 v[8:11], v[120:123], v[182:185], v[8:11]
	s_barrier
	global_load_lds_dwordx4 v192, s[8:9]
	s_add_i32 m0, s42, 0x2000
	s_nop 0
	global_load_lds_dwordx4 v168, s[8:9]
	s_add_u32 s8, s14, 0x160000
	s_addc_u32 s9, s15, 0
	s_mov_b32 m0, s27
	s_nop 0
	global_load_lds_dwordx4 v164, s[8:9]
	s_mov_b32 m0, s28
	s_nop 0
	global_load_lds_dwordx4 v166, s[8:9]
	s_waitcnt vmcnt(8)
	s_barrier
	v_mfma_f32_16x16x32_bf16 v[52:55], v[196:199], v[144:147], 0
	v_mfma_f32_16x16x32_bf16 v[44:47], v[208:211], v[144:147], 0
	v_mfma_f32_16x16x32_bf16 v[36:39], v[196:199], v[152:155], 0
	v_mfma_f32_16x16x32_bf16 v[28:31], v[208:211], v[152:155], 0
	s_add_i32 s42, 0, 0x18000
	v_mfma_f32_16x16x32_bf16 v[20:23], v[196:199], v[160:163], 0
	v_mfma_f32_16x16x32_bf16 v[12:15], v[208:211], v[160:163], 0
	v_mfma_f32_16x16x32_bf16 v[4:7], v[196:199], v[178:181], 0
	v_mfma_f32_16x16x32_bf16 v[0:3], v[208:211], v[178:181], 0
	v_mfma_f32_16x16x32_bf16 v[52:55], v[204:207], v[148:151], v[52:55]
	v_mfma_f32_16x16x32_bf16 v[44:47], v[214:217], v[148:151], v[44:47]
	v_mfma_f32_16x16x32_bf16 v[36:39], v[204:207], v[156:159], v[36:39]
	v_mfma_f32_16x16x32_bf16 v[28:31], v[214:217], v[156:159], v[28:31]
	v_mfma_f32_16x16x32_bf16 v[20:23], v[204:207], v[174:177], v[20:23]
	v_mfma_f32_16x16x32_bf16 v[12:15], v[214:217], v[174:177], v[12:15]
	v_mfma_f32_16x16x32_bf16 v[4:7], v[204:207], v[182:185], v[4:7]
	v_mfma_f32_16x16x32_bf16 v[0:3], v[214:217], v[182:185], v[0:3]
	s_barrier
	ds_read_b128 v[108:111], v220 offset:32768
	ds_read_b128 v[112:115], v220 offset:33792
	ds_read_b128 v[116:119], v220 offset:34816
	ds_read_b128 v[120:123], v220 offset:35840
	ds_read_b128 v[144:147], v189 offset:32768
	ds_read_b128 v[148:151], v189 offset:33792
	ds_read_b128 v[152:155], v189 offset:34816
	ds_read_b128 v[156:159], v189 offset:35840
	ds_read_b128 v[160:163], v189 offset:36864
	ds_read_b128 v[174:177], v189 offset:37888
	ds_read_b128 v[178:181], v189 offset:38912
	ds_read_b128 v[182:185], v189 offset:39936
	s_waitcnt lgkmcnt(8)
	s_barrier
	s_waitcnt lgkmcnt(0)
	v_mfma_f32_16x16x32_bf16 v[140:143], v[108:111], v[144:147], v[140:143]
	v_mfma_f32_16x16x32_bf16 v[136:139], v[116:119], v[144:147], v[136:139]
	v_mfma_f32_16x16x32_bf16 v[132:135], v[108:111], v[152:155], v[132:135]
	v_mfma_f32_16x16x32_bf16 v[104:107], v[116:119], v[152:155], v[104:107]
	s_add_i32 s14, 0, 0x1c000
	s_add_i32 s8, s42, s19
	v_mfma_f32_16x16x32_bf16 v[96:99], v[108:111], v[160:163], v[96:99]
	s_add_i32 m0, s8, 0xffffff80
	v_mfma_f32_16x16x32_bf16 v[88:91], v[116:119], v[160:163], v[88:91]
	v_mfma_f32_16x16x32_bf16 v[80:83], v[108:111], v[178:181], v[80:83]
	v_mfma_f32_16x16x32_bf16 v[72:75], v[116:119], v[178:181], v[72:75]
	v_mfma_f32_16x16x32_bf16 v[140:143], v[112:115], v[148:151], v[140:143]
	v_mfma_f32_16x16x32_bf16 v[136:139], v[120:123], v[148:151], v[136:139]
	v_mfma_f32_16x16x32_bf16 v[132:135], v[112:115], v[156:159], v[132:135]
	v_mfma_f32_16x16x32_bf16 v[104:107], v[120:123], v[156:159], v[104:107]
	v_mfma_f32_16x16x32_bf16 v[96:99], v[112:115], v[174:177], v[96:99]
	v_mfma_f32_16x16x32_bf16 v[88:91], v[120:123], v[174:177], v[88:91]
	v_mfma_f32_16x16x32_bf16 v[80:83], v[112:115], v[182:185], v[80:83]
	v_mfma_f32_16x16x32_bf16 v[72:75], v[120:123], v[182:185], v[72:75]
	s_barrier
	ds_read_b128 v[196:199], v220 offset:49152
	ds_read_b128 v[204:207], v220 offset:50176
	ds_read_b128 v[208:211], v220 offset:51200
	ds_read_b128 v[214:217], v220 offset:52224
	global_load_lds_dwordx4 v192, s[12:13] offset:128
	s_add_i32 m0, s8, 0x1f80
	s_nop 0
	global_load_lds_dwordx4 v168, s[12:13] offset:128
	s_barrier
	s_waitcnt lgkmcnt(0)
	v_mfma_f32_16x16x32_bf16 v[128:131], v[196:199], v[144:147], v[128:131]
	v_mfma_f32_16x16x32_bf16 v[124:127], v[208:211], v[144:147], v[124:127]
	v_mfma_f32_16x16x32_bf16 v[100:103], v[196:199], v[152:155], v[100:103]
	v_mfma_f32_16x16x32_bf16 v[92:95], v[208:211], v[152:155], v[92:95]
	s_mov_b32 m0, s31
	v_mfma_f32_16x16x32_bf16 v[84:87], v[196:199], v[160:163], v[84:87]
	v_mfma_f32_16x16x32_bf16 v[76:79], v[208:211], v[160:163], v[76:79]
	v_mfma_f32_16x16x32_bf16 v[68:71], v[196:199], v[178:181], v[68:71]
	v_mfma_f32_16x16x32_bf16 v[64:67], v[208:211], v[178:181], v[64:67]
	v_mfma_f32_16x16x32_bf16 v[128:131], v[204:207], v[148:151], v[128:131]
	v_mfma_f32_16x16x32_bf16 v[124:127], v[214:217], v[148:151], v[124:127]
	v_mfma_f32_16x16x32_bf16 v[100:103], v[204:207], v[156:159], v[100:103]
	v_mfma_f32_16x16x32_bf16 v[92:95], v[214:217], v[156:159], v[92:95]
	v_mfma_f32_16x16x32_bf16 v[84:87], v[204:207], v[174:177], v[84:87]
	v_mfma_f32_16x16x32_bf16 v[76:79], v[214:217], v[174:177], v[76:79]
	v_mfma_f32_16x16x32_bf16 v[68:71], v[204:207], v[182:185], v[68:71]
	v_mfma_f32_16x16x32_bf16 v[64:67], v[214:217], v[182:185], v[64:67]
	s_barrier
	ds_read_b128 v[144:147], v189 offset:49152
	ds_read_b128 v[148:151], v189 offset:50176
	ds_read_b128 v[152:155], v189 offset:51200
	ds_read_b128 v[156:159], v189 offset:52224
	ds_read_b128 v[160:163], v189 offset:53248
	ds_read_b128 v[174:177], v189 offset:54272
	ds_read_b128 v[178:181], v189 offset:55296
	ds_read_b128 v[182:185], v189 offset:56320
	global_load_lds_dwordx4 v164, s[44:45]
	s_mov_b32 m0, s33
	s_nop 0
	global_load_lds_dwordx4 v166, s[44:45]
	s_barrier
	s_waitcnt lgkmcnt(0)
	v_mfma_f32_16x16x32_bf16 v[60:63], v[108:111], v[144:147], v[60:63]
	v_mfma_f32_16x16x32_bf16 v[56:59], v[116:119], v[144:147], v[56:59]
	v_mfma_f32_16x16x32_bf16 v[48:51], v[108:111], v[152:155], v[48:51]
	v_mfma_f32_16x16x32_bf16 v[40:43], v[116:119], v[152:155], v[40:43]
	s_add_u32 s8, s12, 0x160080
	s_addc_u32 s9, s13, 0
	v_mfma_f32_16x16x32_bf16 v[32:35], v[108:111], v[160:163], v[32:35]
	s_add_i32 s12, s14, s19
	s_mov_b32 m0, s12
	v_mfma_f32_16x16x32_bf16 v[24:27], v[116:119], v[160:163], v[24:27]
	v_mfma_f32_16x16x32_bf16 v[16:19], v[108:111], v[178:181], v[16:19]
	v_mfma_f32_16x16x32_bf16 v[8:11], v[116:119], v[178:181], v[8:11]
	v_mfma_f32_16x16x32_bf16 v[60:63], v[112:115], v[148:151], v[60:63]
	v_mfma_f32_16x16x32_bf16 v[56:59], v[120:123], v[148:151], v[56:59]
	v_mfma_f32_16x16x32_bf16 v[48:51], v[112:115], v[156:159], v[48:51]
	v_mfma_f32_16x16x32_bf16 v[40:43], v[120:123], v[156:159], v[40:43]
	v_mfma_f32_16x16x32_bf16 v[32:35], v[112:115], v[174:177], v[32:35]
	v_mfma_f32_16x16x32_bf16 v[24:27], v[120:123], v[174:177], v[24:27]
	v_mfma_f32_16x16x32_bf16 v[16:19], v[112:115], v[182:185], v[16:19]
	v_mfma_f32_16x16x32_bf16 v[8:11], v[120:123], v[182:185], v[8:11]
	s_barrier
	global_load_lds_dwordx4 v192, s[8:9]
	s_add_i32 m0, s12, 0x2000
	s_nop 0
	global_load_lds_dwordx4 v168, s[8:9]
	s_waitcnt vmcnt(6)
	s_barrier
	v_mfma_f32_16x16x32_bf16 v[52:55], v[196:199], v[144:147], v[52:55]
	v_mfma_f32_16x16x32_bf16 v[44:47], v[208:211], v[144:147], v[44:47]
	v_mfma_f32_16x16x32_bf16 v[36:39], v[196:199], v[152:155], v[36:39]
	v_mfma_f32_16x16x32_bf16 v[28:31], v[208:211], v[152:155], v[28:31]
	s_add_i32 s41, s41, 2
	v_mfma_f32_16x16x32_bf16 v[20:23], v[196:199], v[160:163], v[20:23]
	s_add_u32 s39, s39, 0x100
	s_addc_u32 s40, s40, 0
	v_mfma_f32_16x16x32_bf16 v[12:15], v[208:211], v[160:163], v[12:15]
	s_mov_b64 s[8:9], s[10:11]
	v_mfma_f32_16x16x32_bf16 v[4:7], v[196:199], v[178:181], v[4:7]
	s_add_u32 s10, s8, 0x100
	s_addc_u32 s11, s9, 0
	v_mfma_f32_16x16x32_bf16 v[0:3], v[208:211], v[178:181], v[0:3]
	s_add_i32 s42, 0, 0x10000
	s_cmpk_eq_i32 s41, 0x54
	v_mfma_f32_16x16x32_bf16 v[52:55], v[204:207], v[148:151], v[52:55]
	s_cselect_b32 s15, s5, s11
	s_cselect_b32 s14, s4, s10
	v_mfma_f32_16x16x32_bf16 v[44:47], v[214:217], v[148:151], v[44:47]
	s_cselect_b32 s13, s7, s40
	s_cselect_b32 s12, s6, s39
	v_mfma_f32_16x16x32_bf16 v[36:39], v[204:207], v[156:159], v[36:39]
	s_add_i32 m0, s25, 0xc000
	v_mfma_f32_16x16x32_bf16 v[28:31], v[214:217], v[156:159], v[28:31]
	v_mfma_f32_16x16x32_bf16 v[20:23], v[204:207], v[174:177], v[20:23]
	v_mfma_f32_16x16x32_bf16 v[12:15], v[214:217], v[174:177], v[12:15]
	v_mfma_f32_16x16x32_bf16 v[4:7], v[204:207], v[182:185], v[4:7]
	v_mfma_f32_16x16x32_bf16 v[0:3], v[214:217], v[182:185], v[0:3]
	s_cmpk_gt_u32 s41, 0x55
	s_barrier
.LBB0_272:
	ds_read_b128 v[108:111], v220 offset:0
	ds_read_b128 v[112:115], v220 offset:1024
	ds_read_b128 v[116:119], v220 offset:2048
	ds_read_b128 v[120:123], v220 offset:3072
	ds_read_b128 v[144:147], v189
	ds_read_b128 v[148:151], v189 offset:1024
	ds_read_b128 v[152:155], v189 offset:2048
	ds_read_b128 v[156:159], v189 offset:3072
	ds_read_b128 v[160:163], v189 offset:4096
	ds_read_b128 v[174:177], v189 offset:5120
	ds_read_b128 v[178:181], v189 offset:6144
	ds_read_b128 v[182:185], v189 offset:7168
	global_load_lds_dwordx4 v170, s[8:9]
	s_add_i32 m0, s25, 0xe000
	s_nop 0
	global_load_lds_dwordx4 v172, s[8:9]
	s_waitcnt lgkmcnt(8)
	s_barrier
	s_waitcnt lgkmcnt(0)
	v_mfma_f32_16x16x32_bf16 v[140:143], v[108:111], v[144:147], v[140:143]
	v_mfma_f32_16x16x32_bf16 v[136:139], v[116:119], v[144:147], v[136:139]
	v_mfma_f32_16x16x32_bf16 v[132:135], v[108:111], v[152:155], v[132:135]
	v_mfma_f32_16x16x32_bf16 v[104:107], v[116:119], v[152:155], v[104:107]
	s_add_i32 s43, 0, 0x14000
	s_add_i32 s8, s42, s19
	v_mfma_f32_16x16x32_bf16 v[96:99], v[108:111], v[160:163], v[96:99]
	s_mov_b32 m0, s8
	v_mfma_f32_16x16x32_bf16 v[88:91], v[116:119], v[160:163], v[88:91]
	v_mfma_f32_16x16x32_bf16 v[80:83], v[108:111], v[178:181], v[80:83]
	v_mfma_f32_16x16x32_bf16 v[72:75], v[116:119], v[178:181], v[72:75]
	v_mfma_f32_16x16x32_bf16 v[140:143], v[112:115], v[148:151], v[140:143]
	v_mfma_f32_16x16x32_bf16 v[136:139], v[120:123], v[148:151], v[136:139]
	v_mfma_f32_16x16x32_bf16 v[132:135], v[112:115], v[156:159], v[132:135]
	v_mfma_f32_16x16x32_bf16 v[104:107], v[120:123], v[156:159], v[104:107]
	v_mfma_f32_16x16x32_bf16 v[96:99], v[112:115], v[174:177], v[96:99]
	v_mfma_f32_16x16x32_bf16 v[88:91], v[120:123], v[174:177], v[88:91]
	v_mfma_f32_16x16x32_bf16 v[80:83], v[112:115], v[182:185], v[80:83]
	v_mfma_f32_16x16x32_bf16 v[72:75], v[120:123], v[182:185], v[72:75]
	s_barrier
	ds_read_b128 v[196:199], v220 offset:16384
	ds_read_b128 v[204:207], v220 offset:17408
	ds_read_b128 v[208:211], v220 offset:18432
	ds_read_b128 v[214:217], v220 offset:19456
	global_load_lds_dwordx4 v192, s[12:13]
	s_add_i32 m0, s8, 0x2000
	s_nop 0
	global_load_lds_dwordx4 v168, s[12:13]
	s_barrier
	s_waitcnt lgkmcnt(0)
	v_mfma_f32_16x16x32_bf16 v[128:131], v[196:199], v[144:147], v[128:131]
	v_mfma_f32_16x16x32_bf16 v[124:127], v[208:211], v[144:147], v[124:127]
	v_mfma_f32_16x16x32_bf16 v[100:103], v[196:199], v[152:155], v[100:103]
	v_mfma_f32_16x16x32_bf16 v[92:95], v[208:211], v[152:155], v[92:95]
	s_mov_b32 m0, s25
	v_mfma_f32_16x16x32_bf16 v[84:87], v[196:199], v[160:163], v[84:87]
	s_add_u32 s44, s14, 0x80
	s_addc_u32 s45, s15, 0
	v_mfma_f32_16x16x32_bf16 v[76:79], v[208:211], v[160:163], v[76:79]
	v_mfma_f32_16x16x32_bf16 v[68:71], v[196:199], v[178:181], v[68:71]
	v_mfma_f32_16x16x32_bf16 v[64:67], v[208:211], v[178:181], v[64:67]
	v_mfma_f32_16x16x32_bf16 v[128:131], v[204:207], v[148:151], v[128:131]
	v_mfma_f32_16x16x32_bf16 v[124:127], v[214:217], v[148:151], v[124:127]
	v_mfma_f32_16x16x32_bf16 v[100:103], v[204:207], v[156:159], v[100:103]
	v_mfma_f32_16x16x32_bf16 v[92:95], v[214:217], v[156:159], v[92:95]
	v_mfma_f32_16x16x32_bf16 v[84:87], v[204:207], v[174:177], v[84:87]
	v_mfma_f32_16x16x32_bf16 v[76:79], v[214:217], v[174:177], v[76:79]
	v_mfma_f32_16x16x32_bf16 v[68:71], v[204:207], v[182:185], v[68:71]
	v_mfma_f32_16x16x32_bf16 v[64:67], v[214:217], v[182:185], v[64:67]
	s_barrier
	ds_read_b128 v[144:147], v189 offset:16384
	ds_read_b128 v[148:151], v189 offset:17408
	ds_read_b128 v[152:155], v189 offset:18432
	ds_read_b128 v[156:159], v189 offset:19456
	ds_read_b128 v[160:163], v189 offset:20480
	ds_read_b128 v[174:177], v189 offset:21504
	ds_read_b128 v[178:181], v189 offset:22528
	ds_read_b128 v[182:185], v189 offset:23552
	global_load_lds_dwordx4 v164, s[14:15]
	s_mov_b32 m0, s26
	s_nop 0
	global_load_lds_dwordx4 v166, s[14:15]
	s_waitcnt lgkmcnt(0)
	s_barrier
	v_mfma_f32_16x16x32_bf16 v[60:63], v[108:111], v[144:147], v[60:63]
	v_mfma_f32_16x16x32_bf16 v[56:59], v[116:119], v[144:147], v[56:59]
	v_mfma_f32_16x16x32_bf16 v[48:51], v[108:111], v[152:155], v[48:51]
	v_mfma_f32_16x16x32_bf16 v[40:43], v[116:119], v[152:155], v[40:43]
	s_add_u32 s8, s12, 0x160000
	s_addc_u32 s9, s13, 0
	v_mfma_f32_16x16x32_bf16 v[32:35], v[108:111], v[160:163], v[32:35]
	s_add_i32 s42, s43, s19
	s_mov_b32 m0, s42
	v_mfma_f32_16x16x32_bf16 v[24:27], v[116:119], v[160:163], v[24:27]
	v_mfma_f32_16x16x32_bf16 v[16:19], v[108:111], v[178:181], v[16:19]
	v_mfma_f32_16x16x32_bf16 v[8:11], v[116:119], v[178:181], v[8:11]
	v_mfma_f32_16x16x32_bf16 v[60:63], v[112:115], v[148:151], v[60:63]
	v_mfma_f32_16x16x32_bf16 v[56:59], v[120:123], v[148:151], v[56:59]
	v_mfma_f32_16x16x32_bf16 v[48:51], v[112:115], v[156:159], v[48:51]
	v_mfma_f32_16x16x32_bf16 v[40:43], v[120:123], v[156:159], v[40:43]
	v_mfma_f32_16x16x32_bf16 v[32:35], v[112:115], v[174:177], v[32:35]
	v_mfma_f32_16x16x32_bf16 v[24:27], v[120:123], v[174:177], v[24:27]
	v_mfma_f32_16x16x32_bf16 v[16:19], v[112:115], v[182:185], v[16:19]
	v_mfma_f32_16x16x32_bf16 v[8:11], v[120:123], v[182:185], v[8:11]
	s_barrier
	global_load_lds_dwordx4 v192, s[8:9]
	s_add_i32 m0, s42, 0x2000
	s_nop 0
	global_load_lds_dwordx4 v168, s[8:9]
	s_add_u32 s8, s14, 0x160000
	s_addc_u32 s9, s15, 0
	s_mov_b32 m0, s27
	s_nop 0
	global_load_lds_dwordx4 v164, s[8:9]
	s_mov_b32 m0, s28
	s_nop 0
	global_load_lds_dwordx4 v166, s[8:9]
	s_waitcnt vmcnt(8)
	s_barrier
	v_mfma_f32_16x16x32_bf16 v[52:55], v[196:199], v[144:147], v[52:55]
	v_mfma_f32_16x16x32_bf16 v[44:47], v[208:211], v[144:147], v[44:47]
	v_mfma_f32_16x16x32_bf16 v[36:39], v[196:199], v[152:155], v[36:39]
	v_mfma_f32_16x16x32_bf16 v[28:31], v[208:211], v[152:155], v[28:31]
	s_add_i32 s42, 0, 0x18000
	v_mfma_f32_16x16x32_bf16 v[20:23], v[196:199], v[160:163], v[20:23]
	v_mfma_f32_16x16x32_bf16 v[12:15], v[208:211], v[160:163], v[12:15]
	v_mfma_f32_16x16x32_bf16 v[4:7], v[196:199], v[178:181], v[4:7]
	v_mfma_f32_16x16x32_bf16 v[0:3], v[208:211], v[178:181], v[0:3]
	v_mfma_f32_16x16x32_bf16 v[52:55], v[204:207], v[148:151], v[52:55]
	v_mfma_f32_16x16x32_bf16 v[44:47], v[214:217], v[148:151], v[44:47]
	v_mfma_f32_16x16x32_bf16 v[36:39], v[204:207], v[156:159], v[36:39]
	v_mfma_f32_16x16x32_bf16 v[28:31], v[214:217], v[156:159], v[28:31]
	v_mfma_f32_16x16x32_bf16 v[20:23], v[204:207], v[174:177], v[20:23]
	v_mfma_f32_16x16x32_bf16 v[12:15], v[214:217], v[174:177], v[12:15]
	v_mfma_f32_16x16x32_bf16 v[4:7], v[204:207], v[182:185], v[4:7]
	v_mfma_f32_16x16x32_bf16 v[0:3], v[214:217], v[182:185], v[0:3]
	s_barrier
	ds_read_b128 v[108:111], v220 offset:32768
	ds_read_b128 v[112:115], v220 offset:33792
	ds_read_b128 v[116:119], v220 offset:34816
	ds_read_b128 v[120:123], v220 offset:35840
	ds_read_b128 v[144:147], v189 offset:32768
	ds_read_b128 v[148:151], v189 offset:33792
	ds_read_b128 v[152:155], v189 offset:34816
	ds_read_b128 v[156:159], v189 offset:35840
	ds_read_b128 v[160:163], v189 offset:36864
	ds_read_b128 v[174:177], v189 offset:37888
	ds_read_b128 v[178:181], v189 offset:38912
	ds_read_b128 v[182:185], v189 offset:39936
	s_waitcnt lgkmcnt(8)
	s_barrier
	s_waitcnt lgkmcnt(0)
	v_mfma_f32_16x16x32_bf16 v[140:143], v[108:111], v[144:147], v[140:143]
	v_mfma_f32_16x16x32_bf16 v[136:139], v[116:119], v[144:147], v[136:139]
	v_mfma_f32_16x16x32_bf16 v[132:135], v[108:111], v[152:155], v[132:135]
	v_mfma_f32_16x16x32_bf16 v[104:107], v[116:119], v[152:155], v[104:107]
	s_add_i32 s14, 0, 0x1c000
	s_add_i32 s8, s42, s19
	v_mfma_f32_16x16x32_bf16 v[96:99], v[108:111], v[160:163], v[96:99]
	s_add_i32 m0, s8, 0xffffff80
	v_mfma_f32_16x16x32_bf16 v[88:91], v[116:119], v[160:163], v[88:91]
	v_mfma_f32_16x16x32_bf16 v[80:83], v[108:111], v[178:181], v[80:83]
	v_mfma_f32_16x16x32_bf16 v[72:75], v[116:119], v[178:181], v[72:75]
	v_mfma_f32_16x16x32_bf16 v[140:143], v[112:115], v[148:151], v[140:143]
	v_mfma_f32_16x16x32_bf16 v[136:139], v[120:123], v[148:151], v[136:139]
	v_mfma_f32_16x16x32_bf16 v[132:135], v[112:115], v[156:159], v[132:135]
	v_mfma_f32_16x16x32_bf16 v[104:107], v[120:123], v[156:159], v[104:107]
	v_mfma_f32_16x16x32_bf16 v[96:99], v[112:115], v[174:177], v[96:99]
	v_mfma_f32_16x16x32_bf16 v[88:91], v[120:123], v[174:177], v[88:91]
	v_mfma_f32_16x16x32_bf16 v[80:83], v[112:115], v[182:185], v[80:83]
	v_mfma_f32_16x16x32_bf16 v[72:75], v[120:123], v[182:185], v[72:75]
	s_barrier
	ds_read_b128 v[196:199], v220 offset:49152
	ds_read_b128 v[204:207], v220 offset:50176
	ds_read_b128 v[208:211], v220 offset:51200
	ds_read_b128 v[214:217], v220 offset:52224
	global_load_lds_dwordx4 v192, s[12:13] offset:128
	s_add_i32 m0, s8, 0x1f80
	s_nop 0
	global_load_lds_dwordx4 v168, s[12:13] offset:128
	s_barrier
	s_waitcnt lgkmcnt(0)
	v_mfma_f32_16x16x32_bf16 v[128:131], v[196:199], v[144:147], v[128:131]
	v_mfma_f32_16x16x32_bf16 v[124:127], v[208:211], v[144:147], v[124:127]
	v_mfma_f32_16x16x32_bf16 v[100:103], v[196:199], v[152:155], v[100:103]
	v_mfma_f32_16x16x32_bf16 v[92:95], v[208:211], v[152:155], v[92:95]
	s_mov_b32 m0, s31
	v_mfma_f32_16x16x32_bf16 v[84:87], v[196:199], v[160:163], v[84:87]
	v_mfma_f32_16x16x32_bf16 v[76:79], v[208:211], v[160:163], v[76:79]
	v_mfma_f32_16x16x32_bf16 v[68:71], v[196:199], v[178:181], v[68:71]
	v_mfma_f32_16x16x32_bf16 v[64:67], v[208:211], v[178:181], v[64:67]
	v_mfma_f32_16x16x32_bf16 v[128:131], v[204:207], v[148:151], v[128:131]
	v_mfma_f32_16x16x32_bf16 v[124:127], v[214:217], v[148:151], v[124:127]
	v_mfma_f32_16x16x32_bf16 v[100:103], v[204:207], v[156:159], v[100:103]
	v_mfma_f32_16x16x32_bf16 v[92:95], v[214:217], v[156:159], v[92:95]
	v_mfma_f32_16x16x32_bf16 v[84:87], v[204:207], v[174:177], v[84:87]
	v_mfma_f32_16x16x32_bf16 v[76:79], v[214:217], v[174:177], v[76:79]
	v_mfma_f32_16x16x32_bf16 v[68:71], v[204:207], v[182:185], v[68:71]
	v_mfma_f32_16x16x32_bf16 v[64:67], v[214:217], v[182:185], v[64:67]
	s_barrier
	ds_read_b128 v[144:147], v189 offset:49152
	ds_read_b128 v[148:151], v189 offset:50176
	ds_read_b128 v[152:155], v189 offset:51200
	ds_read_b128 v[156:159], v189 offset:52224
	ds_read_b128 v[160:163], v189 offset:53248
	ds_read_b128 v[174:177], v189 offset:54272
	ds_read_b128 v[178:181], v189 offset:55296
	ds_read_b128 v[182:185], v189 offset:56320
	global_load_lds_dwordx4 v164, s[44:45]
	s_mov_b32 m0, s33
	s_nop 0
	global_load_lds_dwordx4 v166, s[44:45]
	s_barrier
	s_waitcnt lgkmcnt(0)
	v_mfma_f32_16x16x32_bf16 v[60:63], v[108:111], v[144:147], v[60:63]
	v_mfma_f32_16x16x32_bf16 v[56:59], v[116:119], v[144:147], v[56:59]
	v_mfma_f32_16x16x32_bf16 v[48:51], v[108:111], v[152:155], v[48:51]
	v_mfma_f32_16x16x32_bf16 v[40:43], v[116:119], v[152:155], v[40:43]
	s_add_u32 s8, s12, 0x160080
	s_addc_u32 s9, s13, 0
	v_mfma_f32_16x16x32_bf16 v[32:35], v[108:111], v[160:163], v[32:35]
	s_add_i32 s12, s14, s19
	s_mov_b32 m0, s12
	v_mfma_f32_16x16x32_bf16 v[24:27], v[116:119], v[160:163], v[24:27]
	v_mfma_f32_16x16x32_bf16 v[16:19], v[108:111], v[178:181], v[16:19]
	v_mfma_f32_16x16x32_bf16 v[8:11], v[116:119], v[178:181], v[8:11]
	v_mfma_f32_16x16x32_bf16 v[60:63], v[112:115], v[148:151], v[60:63]
	v_mfma_f32_16x16x32_bf16 v[56:59], v[120:123], v[148:151], v[56:59]
	v_mfma_f32_16x16x32_bf16 v[48:51], v[112:115], v[156:159], v[48:51]
	v_mfma_f32_16x16x32_bf16 v[40:43], v[120:123], v[156:159], v[40:43]
	v_mfma_f32_16x16x32_bf16 v[32:35], v[112:115], v[174:177], v[32:35]
	v_mfma_f32_16x16x32_bf16 v[24:27], v[120:123], v[174:177], v[24:27]
	v_mfma_f32_16x16x32_bf16 v[16:19], v[112:115], v[182:185], v[16:19]
	v_mfma_f32_16x16x32_bf16 v[8:11], v[120:123], v[182:185], v[8:11]
	s_barrier
	global_load_lds_dwordx4 v192, s[8:9]
	s_add_i32 m0, s12, 0x2000
	s_nop 0
	global_load_lds_dwordx4 v168, s[8:9]
	s_waitcnt vmcnt(6)
	s_barrier
	v_mfma_f32_16x16x32_bf16 v[52:55], v[196:199], v[144:147], v[52:55]
	v_mfma_f32_16x16x32_bf16 v[44:47], v[208:211], v[144:147], v[44:47]
	v_mfma_f32_16x16x32_bf16 v[36:39], v[196:199], v[152:155], v[36:39]
	v_mfma_f32_16x16x32_bf16 v[28:31], v[208:211], v[152:155], v[28:31]
	s_add_i32 s41, s41, 2
	v_mfma_f32_16x16x32_bf16 v[20:23], v[196:199], v[160:163], v[20:23]
	s_add_u32 s39, s39, 0x100
	s_addc_u32 s40, s40, 0
	v_mfma_f32_16x16x32_bf16 v[12:15], v[208:211], v[160:163], v[12:15]
	s_mov_b64 s[8:9], s[10:11]
	v_mfma_f32_16x16x32_bf16 v[4:7], v[196:199], v[178:181], v[4:7]
	s_add_u32 s10, s8, 0x100
	s_addc_u32 s11, s9, 0
	v_mfma_f32_16x16x32_bf16 v[0:3], v[208:211], v[178:181], v[0:3]
	s_add_i32 s42, 0, 0x10000
	s_cmpk_eq_i32 s41, 0x54
	v_mfma_f32_16x16x32_bf16 v[52:55], v[204:207], v[148:151], v[52:55]
	s_cselect_b32 s15, s5, s11
	s_cselect_b32 s14, s4, s10
	v_mfma_f32_16x16x32_bf16 v[44:47], v[214:217], v[148:151], v[44:47]
	s_cselect_b32 s13, s7, s40
	s_cselect_b32 s12, s6, s39
	v_mfma_f32_16x16x32_bf16 v[36:39], v[204:207], v[156:159], v[36:39]
	s_add_i32 m0, s25, 0xc000
	v_mfma_f32_16x16x32_bf16 v[28:31], v[214:217], v[156:159], v[28:31]
	v_mfma_f32_16x16x32_bf16 v[20:23], v[204:207], v[174:177], v[20:23]
	v_mfma_f32_16x16x32_bf16 v[12:15], v[214:217], v[174:177], v[12:15]
	v_mfma_f32_16x16x32_bf16 v[4:7], v[204:207], v[182:185], v[4:7]
	v_mfma_f32_16x16x32_bf16 v[0:3], v[214:217], v[182:185], v[0:3]
	s_cmpk_gt_u32 s41, 0x55
	s_barrier
	s_cbranch_scc0 .LBB0_272
	s_ashr_i32 s8, s37, 4
	v_lshl_or_b32 v144, s38, 8, v188
	s_mul_hi_i32 s9, s8, 0xc000
	s_mul_i32 s8, s8, 0xc000
	v_lshl_add_u32 v178, s37, 8, v186
	s_add_u32 s8, s29, s8
	v_ashrrev_i32_e32 v145, 31, v144
	v_ashrrev_i32_e32 v179, 31, v178
	s_addc_u32 s9, s30, s9
	v_lshlrev_b64 v[174:175], 2, v[144:145]
	v_lshl_add_u64 v[176:177], v[144:145], 1, s[2:3]
	v_lshlrev_b64 v[144:145], 12, v[178:179]
	v_lshl_add_u64 v[112:113], s[8:9], 0, v[174:175]
	v_lshl_add_u64 v[144:145], v[176:177], 0, v[144:145]
	global_load_dwordx4 v[116:119], v[112:113], off offset:16
	global_load_dwordx4 v[120:123], v[112:113], off
	global_load_dwordx4 v[108:111], v[112:113], off offset:528
	s_nop 0
	global_load_dwordx4 v[112:115], v[112:113], off offset:512
	s_nop 0
	global_load_dwordx4 v[196:199], v[144:145], off
	global_load_dwordx4 v[204:207], v[144:145], off offset:256
	v_or_b32_e32 v184, 16, v178
	v_ashrrev_i32_e32 v185, 31, v184
	v_lshlrev_b64 v[144:145], 12, v[184:185]
	v_lshl_add_u64 v[144:145], v[176:177], 0, v[144:145]
	global_load_dwordx4 v[208:211], v[144:145], off
	global_load_dwordx4 v[160:163], v[144:145], off offset:256
	v_or_b32_e32 v182, 32, v178
	v_ashrrev_i32_e32 v183, 31, v182
	v_lshlrev_b64 v[144:145], 12, v[182:183]
	v_lshl_add_u64 v[144:145], v[176:177], 0, v[144:145]
	global_load_dwordx4 v[156:159], v[144:145], off
	global_load_dwordx4 v[152:155], v[144:145], off offset:256
	v_or_b32_e32 v180, 48, v178
	v_ashrrev_i32_e32 v181, 31, v180
	v_lshlrev_b64 v[144:145], 12, v[180:181]
	v_lshl_add_u64 v[144:145], v[176:177], 0, v[144:145]
	global_load_dwordx4 v[148:151], v[144:145], off
	s_nop 0
	global_load_dwordx4 v[144:147], v[144:145], off offset:256
	v_readlane_b32 s52, v254, 39
	v_readlane_b32 s66, v254, 53
	v_readlane_b32 s67, v254, 54
	s_and_b64 vcc, exec, s[0:1]
	s_mov_b32 s38, s35
	s_mov_b32 s37, s36
	s_mov_b64 s[10:11], s[6:7]
	s_mov_b64 s[8:9], s[4:5]
	v_readlane_b32 s14, v254, 21
	s_movk_i32 s15, 0x2000
	v_readlane_b32 s53, v254, 40
	v_readlane_b32 s54, v254, 41
	v_readlane_b32 s55, v254, 42
	v_readlane_b32 s56, v254, 43
	v_readlane_b32 s57, v254, 44
	v_readlane_b32 s58, v254, 45
	v_readlane_b32 s59, v254, 46
	v_readlane_b32 s60, v254, 47
	v_readlane_b32 s61, v254, 48
	v_readlane_b32 s62, v254, 49
	v_readlane_b32 s63, v254, 50
	v_readlane_b32 s64, v254, 51
	v_readlane_b32 s65, v254, 52
	s_waitcnt vmcnt(0)
	v_lshlrev_b32_e32 v190, 16, v196
	v_and_b32_e32 v191, 0xffff0000, v196
	v_pk_fma_f32 v[140:141], v[140:141], v[120:121], v[190:191]
	v_lshlrev_b64 v[190:191], 13, v[178:179]
	v_lshlrev_b32_e32 v196, 16, v197
	v_and_b32_e32 v197, 0xffff0000, v197
	v_lshl_add_u64 v[190:191], s[66:67], 0, v[190:191]
	v_pk_fma_f32 v[142:143], v[142:143], v[122:123], v[196:197]
	v_lshl_add_u64 v[190:191], v[190:191], 0, v[174:175]
	global_store_dwordx4 v[190:191], v[140:143], off
	v_lshlrev_b32_e32 v214, 16, v198
	v_and_b32_e32 v215, 0xffff0000, v198
	v_lshlrev_b32_e32 v140, 16, v206
	v_and_b32_e32 v141, 0xffff0000, v206
	v_lshlrev_b32_e32 v142, 16, v207
	v_and_b32_e32 v143, 0xffff0000, v207
	v_pk_fma_f32 v[126:127], v[126:127], v[110:111], v[142:143]
	v_pk_fma_f32 v[124:125], v[124:125], v[108:109], v[140:141]
	global_store_dwordx4 v[190:191], v[124:127], off offset:528
	v_lshlrev_b32_e32 v198, 16, v199
	v_and_b32_e32 v199, 0xffff0000, v199
	v_lshlrev_b32_e32 v124, 16, v208
	v_and_b32_e32 v125, 0xffff0000, v208
	v_pk_fma_f32 v[124:125], v[132:133], v[120:121], v[124:125]
	v_lshlrev_b64 v[132:133], 13, v[184:185]
	v_lshlrev_b32_e32 v126, 16, v209
	v_and_b32_e32 v127, 0xffff0000, v209
	v_lshl_add_u64 v[132:133], s[66:67], 0, v[132:133]
	v_pk_fma_f32 v[126:127], v[134:135], v[122:123], v[126:127]
	v_lshl_add_u64 v[132:133], v[132:133], 0, v[174:175]
	v_pk_fma_f32 v[138:139], v[138:139], v[118:119], v[198:199]
	v_pk_fma_f32 v[136:137], v[136:137], v[116:117], v[214:215]
	global_store_dwordx4 v[132:133], v[124:127], off
	global_store_dwordx4 v[190:191], v[136:139], off offset:16
	s_nop 0
	v_lshlrev_b32_e32 v124, 16, v162
	v_and_b32_e32 v125, 0xffff0000, v162
	v_lshlrev_b32_e32 v126, 16, v163
	v_and_b32_e32 v127, 0xffff0000, v163
	v_lshlrev_b32_e32 v136, 16, v204
	v_and_b32_e32 v137, 0xffff0000, v204
	v_lshlrev_b32_e32 v138, 16, v205
	v_and_b32_e32 v139, 0xffff0000, v205
	v_pk_fma_f32 v[94:95], v[94:95], v[110:111], v[126:127]
	v_pk_fma_f32 v[92:93], v[92:93], v[108:109], v[124:125]
	v_pk_fma_f32 v[130:131], v[130:131], v[114:115], v[138:139]
	v_pk_fma_f32 v[128:129], v[128:129], v[112:113], v[136:137]
	global_store_dwordx4 v[132:133], v[92:95], off offset:528
	global_store_dwordx4 v[190:191], v[128:131], off offset:512
	s_nop 0
	v_lshlrev_b32_e32 v92, 16, v156
	v_and_b32_e32 v93, 0xffff0000, v156
	v_lshlrev_b32_e32 v128, 16, v210
	v_and_b32_e32 v129, 0xffff0000, v210
	v_lshlrev_b32_e32 v130, 16, v211
	v_and_b32_e32 v131, 0xffff0000, v211
	v_pk_fma_f32 v[92:93], v[96:97], v[120:121], v[92:93]
	v_lshlrev_b64 v[96:97], 13, v[182:183]
	v_pk_fma_f32 v[106:107], v[106:107], v[118:119], v[130:131]
	v_pk_fma_f32 v[104:105], v[104:105], v[116:117], v[128:129]
	v_lshlrev_b32_e32 v94, 16, v157
	v_and_b32_e32 v95, 0xffff0000, v157
	v_lshl_add_u64 v[96:97], s[66:67], 0, v[96:97]
	global_store_dwordx4 v[132:133], v[104:107], off offset:16
	v_pk_fma_f32 v[94:95], v[98:99], v[122:123], v[94:95]
	v_lshl_add_u64 v[96:97], v[96:97], 0, v[174:175]
	v_lshlrev_b32_e32 v104, 16, v160
	v_and_b32_e32 v105, 0xffff0000, v160
	v_lshlrev_b32_e32 v106, 16, v161
	v_and_b32_e32 v107, 0xffff0000, v161
	v_pk_fma_f32 v[102:103], v[102:103], v[114:115], v[106:107]
	v_pk_fma_f32 v[100:101], v[100:101], v[112:113], v[104:105]
	global_store_dwordx4 v[96:97], v[92:95], off
	global_store_dwordx4 v[132:133], v[100:103], off offset:512
	v_add_u32_e32 v98, 0x90, v178
	v_lshlrev_b32_e32 v92, 16, v154
	v_and_b32_e32 v93, 0xffff0000, v154
	v_lshlrev_b32_e32 v94, 16, v155
	v_and_b32_e32 v95, 0xffff0000, v155
	v_lshlrev_b32_e32 v100, 16, v158
	v_and_b32_e32 v101, 0xffff0000, v158
	v_lshlrev_b32_e32 v102, 16, v159
	v_and_b32_e32 v103, 0xffff0000, v159
	v_pk_fma_f32 v[78:79], v[78:79], v[110:111], v[94:95]
	v_pk_fma_f32 v[76:77], v[76:77], v[108:109], v[92:93]
	v_pk_fma_f32 v[90:91], v[90:91], v[118:119], v[102:103]
	v_pk_fma_f32 v[88:89], v[88:89], v[116:117], v[100:101]
	global_store_dwordx4 v[96:97], v[76:79], off offset:528
	global_store_dwordx4 v[96:97], v[88:91], off offset:16
	v_ashrrev_i32_e32 v99, 31, v98
	v_lshlrev_b32_e32 v76, 16, v148
	v_and_b32_e32 v77, 0xffff0000, v148
	v_lshlrev_b32_e32 v88, 16, v152
	v_and_b32_e32 v89, 0xffff0000, v152
	v_lshlrev_b32_e32 v90, 16, v153
	v_and_b32_e32 v91, 0xffff0000, v153
	v_pk_fma_f32 v[76:77], v[80:81], v[120:121], v[76:77]
	v_lshlrev_b64 v[80:81], 13, v[180:181]
	v_pk_fma_f32 v[86:87], v[86:87], v[114:115], v[90:91]
	v_pk_fma_f32 v[84:85], v[84:85], v[112:113], v[88:89]
	v_lshlrev_b32_e32 v78, 16, v149
	v_and_b32_e32 v79, 0xffff0000, v149
	v_lshl_add_u64 v[80:81], s[66:67], 0, v[80:81]
	global_store_dwordx4 v[96:97], v[84:87], off offset:512
	v_pk_fma_f32 v[78:79], v[82:83], v[122:123], v[78:79]
	v_lshl_add_u64 v[80:81], v[80:81], 0, v[174:175]
	v_lshlrev_b32_e32 v84, 16, v150
	v_and_b32_e32 v85, 0xffff0000, v150
	v_lshlrev_b32_e32 v86, 16, v151
	v_and_b32_e32 v87, 0xffff0000, v151
	global_store_dwordx4 v[80:81], v[76:79], off
	v_pk_fma_f32 v[74:75], v[74:75], v[118:119], v[86:87]
	v_pk_fma_f32 v[72:73], v[72:73], v[116:117], v[84:85]
	v_lshlrev_b32_e32 v76, 16, v146
	v_and_b32_e32 v77, 0xffff0000, v146
	v_lshlrev_b32_e32 v78, 16, v147
	v_and_b32_e32 v79, 0xffff0000, v147
	v_add_u32_e32 v96, 0x80, v178
	global_store_dwordx4 v[80:81], v[72:75], off offset:16
	v_pk_fma_f32 v[66:67], v[66:67], v[110:111], v[78:79]
	v_pk_fma_f32 v[64:65], v[64:65], v[108:109], v[76:77]
	v_lshlrev_b32_e32 v72, 16, v144
	v_and_b32_e32 v73, 0xffff0000, v144
	v_lshlrev_b32_e32 v74, 16, v145
	v_and_b32_e32 v75, 0xffff0000, v145
	v_ashrrev_i32_e32 v97, 31, v96
	v_pk_fma_f32 v[70:71], v[70:71], v[114:115], v[74:75]
	v_pk_fma_f32 v[68:69], v[68:69], v[112:113], v[72:73]
	global_store_dwordx4 v[80:81], v[64:67], off offset:528
	global_store_dwordx4 v[80:81], v[68:71], off offset:512
	v_add_u32_e32 v100, 0xa0, v178
	v_lshlrev_b64 v[64:65], 12, v[96:97]
	v_lshl_add_u64 v[64:65], v[176:177], 0, v[64:65]
	global_load_dwordx4 v[68:71], v[64:65], off
	global_load_dwordx4 v[72:75], v[64:65], off offset:256
	v_lshlrev_b64 v[64:65], 12, v[98:99]
	v_lshl_add_u64 v[64:65], v[176:177], 0, v[64:65]
	global_load_dwordx4 v[76:79], v[64:65], off
	global_load_dwordx4 v[80:83], v[64:65], off offset:256
	v_ashrrev_i32_e32 v101, 31, v100
	v_lshlrev_b64 v[64:65], 12, v[100:101]
	v_lshl_add_u64 v[64:65], v[176:177], 0, v[64:65]
	global_load_dwordx4 v[84:87], v[64:65], off
	global_load_dwordx4 v[88:91], v[64:65], off offset:256
	v_add_u32_e32 v102, 0xb0, v178
	v_ashrrev_i32_e32 v103, 31, v102
	v_lshlrev_b64 v[64:65], 12, v[102:103]
	v_lshl_add_u64 v[64:65], v[176:177], 0, v[64:65]
	global_load_dwordx4 v[92:95], v[64:65], off
	s_nop 0
	global_load_dwordx4 v[64:67], v[64:65], off offset:256
	s_waitcnt vmcnt(0)
	v_lshlrev_b32_e32 v104, 16, v68
	v_and_b32_e32 v105, 0xffff0000, v68
	v_lshlrev_b32_e32 v68, 16, v69
	v_and_b32_e32 v69, 0xffff0000, v69
	v_pk_fma_f32 v[62:63], v[62:63], v[122:123], v[68:69]
	v_lshlrev_b64 v[68:69], 13, v[96:97]
	v_lshl_add_u64 v[68:69], s[66:67], 0, v[68:69]
	v_pk_fma_f32 v[60:61], v[60:61], v[120:121], v[104:105]
	v_lshl_add_u64 v[68:69], v[68:69], 0, v[174:175]
	global_store_dwordx4 v[68:69], v[60:63], off
	v_lshlrev_b32_e32 v106, 16, v70
	v_and_b32_e32 v107, 0xffff0000, v70
	v_lshlrev_b32_e32 v60, 16, v74
	v_and_b32_e32 v61, 0xffff0000, v74
	v_lshlrev_b32_e32 v62, 16, v75
	v_and_b32_e32 v63, 0xffff0000, v75
	v_pk_fma_f32 v[46:47], v[46:47], v[110:111], v[62:63]
	v_pk_fma_f32 v[44:45], v[44:45], v[108:109], v[60:61]
	global_store_dwordx4 v[68:69], v[44:47], off offset:528
	v_lshlrev_b32_e32 v70, 16, v71
	v_and_b32_e32 v71, 0xffff0000, v71
	v_lshlrev_b32_e32 v44, 16, v76
	v_and_b32_e32 v45, 0xffff0000, v76
	v_pk_fma_f32 v[44:45], v[48:49], v[120:121], v[44:45]
	v_lshlrev_b64 v[48:49], 13, v[98:99]
	v_lshlrev_b32_e32 v46, 16, v77
	v_and_b32_e32 v47, 0xffff0000, v77
	v_lshl_add_u64 v[48:49], s[66:67], 0, v[48:49]
	v_pk_fma_f32 v[58:59], v[58:59], v[118:119], v[70:71]
	v_pk_fma_f32 v[56:57], v[56:57], v[116:117], v[106:107]
	v_pk_fma_f32 v[46:47], v[50:51], v[122:123], v[46:47]
	v_lshl_add_u64 v[48:49], v[48:49], 0, v[174:175]
	global_store_dwordx4 v[68:69], v[56:59], off offset:16
	global_store_dwordx4 v[48:49], v[44:47], off
	s_nop 0
	v_lshlrev_b32_e32 v56, 16, v72
	v_and_b32_e32 v57, 0xffff0000, v72
	v_lshlrev_b32_e32 v58, 16, v73
	v_and_b32_e32 v59, 0xffff0000, v73
	v_lshlrev_b32_e32 v44, 16, v82
	v_and_b32_e32 v45, 0xffff0000, v82
	v_lshlrev_b32_e32 v46, 16, v83
	v_and_b32_e32 v47, 0xffff0000, v83
	v_pk_fma_f32 v[54:55], v[54:55], v[114:115], v[58:59]
	v_pk_fma_f32 v[52:53], v[52:53], v[112:113], v[56:57]
	v_pk_fma_f32 v[30:31], v[30:31], v[110:111], v[46:47]
	v_pk_fma_f32 v[28:29], v[28:29], v[108:109], v[44:45]
	global_store_dwordx4 v[68:69], v[52:55], off offset:512
	global_store_dwordx4 v[48:49], v[28:31], off offset:528
	s_nop 0
	v_lshlrev_b32_e32 v52, 16, v78
	v_and_b32_e32 v53, 0xffff0000, v78
	v_lshlrev_b32_e32 v54, 16, v79
	v_and_b32_e32 v55, 0xffff0000, v79
	v_lshlrev_b32_e32 v28, 16, v84
	v_and_b32_e32 v29, 0xffff0000, v84
	v_pk_fma_f32 v[42:43], v[42:43], v[118:119], v[54:55]
	v_pk_fma_f32 v[40:41], v[40:41], v[116:117], v[52:53]
	v_pk_fma_f32 v[28:29], v[32:33], v[120:121], v[28:29]
	v_lshlrev_b64 v[32:33], 13, v[100:101]
	global_store_dwordx4 v[48:49], v[40:43], off offset:16
	v_lshlrev_b32_e32 v30, 16, v85
	v_and_b32_e32 v31, 0xffff0000, v85
	v_lshlrev_b32_e32 v40, 16, v80
	v_and_b32_e32 v41, 0xffff0000, v80
	v_lshlrev_b32_e32 v42, 16, v81
	v_and_b32_e32 v43, 0xffff0000, v81
	v_lshl_add_u64 v[32:33], s[66:67], 0, v[32:33]
	v_pk_fma_f32 v[38:39], v[38:39], v[114:115], v[42:43]
	v_pk_fma_f32 v[36:37], v[36:37], v[112:113], v[40:41]
	v_pk_fma_f32 v[30:31], v[34:35], v[122:123], v[30:31]
	v_lshl_add_u64 v[32:33], v[32:33], 0, v[174:175]
	global_store_dwordx4 v[48:49], v[36:39], off offset:512
	global_store_dwordx4 v[32:33], v[28:31], off
	s_nop 0
	v_lshlrev_b32_e32 v36, 16, v86
	v_and_b32_e32 v37, 0xffff0000, v86
	v_lshlrev_b32_e32 v38, 16, v87
	v_and_b32_e32 v39, 0xffff0000, v87
	v_lshlrev_b32_e32 v28, 16, v90
	v_and_b32_e32 v29, 0xffff0000, v90
	v_lshlrev_b32_e32 v30, 16, v91
	v_and_b32_e32 v31, 0xffff0000, v91
	v_pk_fma_f32 v[26:27], v[26:27], v[118:119], v[38:39]
	v_pk_fma_f32 v[24:25], v[24:25], v[116:117], v[36:37]
	v_pk_fma_f32 v[14:15], v[14:15], v[110:111], v[30:31]
	v_pk_fma_f32 v[12:13], v[12:13], v[108:109], v[28:29]
	global_store_dwordx4 v[32:33], v[24:27], off offset:16
	global_store_dwordx4 v[32:33], v[12:15], off offset:528
	s_nop 0
	v_lshlrev_b32_e32 v24, 16, v88
	v_and_b32_e32 v25, 0xffff0000, v88
	v_lshlrev_b32_e32 v26, 16, v89
	v_and_b32_e32 v27, 0xffff0000, v89
	v_lshlrev_b32_e32 v12, 16, v92
	v_and_b32_e32 v13, 0xffff0000, v92
	v_pk_fma_f32 v[22:23], v[22:23], v[114:115], v[26:27]
	v_pk_fma_f32 v[20:21], v[20:21], v[112:113], v[24:25]
	v_pk_fma_f32 v[12:13], v[16:17], v[120:121], v[12:13]
	v_lshlrev_b64 v[16:17], 13, v[102:103]
	global_store_dwordx4 v[32:33], v[20:23], off offset:512
	v_lshlrev_b32_e32 v14, 16, v93
	v_and_b32_e32 v15, 0xffff0000, v93
	v_lshlrev_b32_e32 v20, 16, v94
	v_and_b32_e32 v21, 0xffff0000, v94
	v_lshlrev_b32_e32 v22, 16, v95
	v_and_b32_e32 v23, 0xffff0000, v95
	v_lshl_add_u64 v[16:17], s[66:67], 0, v[16:17]
	v_pk_fma_f32 v[14:15], v[18:19], v[122:123], v[14:15]
	v_lshl_add_u64 v[16:17], v[16:17], 0, v[174:175]
	v_pk_fma_f32 v[10:11], v[10:11], v[118:119], v[22:23]
	v_pk_fma_f32 v[8:9], v[8:9], v[116:117], v[20:21]
	global_store_dwordx4 v[16:17], v[12:15], off
	global_store_dwordx4 v[16:17], v[8:11], off offset:16
	s_nop 0
	v_lshlrev_b32_e32 v12, 16, v66
	v_lshlrev_b32_e32 v8, 16, v64
	v_and_b32_e32 v9, 0xffff0000, v64
	v_lshlrev_b32_e32 v10, 16, v65
	v_and_b32_e32 v11, 0xffff0000, v65
	v_and_b32_e32 v13, 0xffff0000, v66
	v_lshlrev_b32_e32 v14, 16, v67
	v_and_b32_e32 v15, 0xffff0000, v67
	v_pk_fma_f32 v[6:7], v[6:7], v[114:115], v[10:11]
	v_pk_fma_f32 v[4:5], v[4:5], v[112:113], v[8:9]
	v_pk_fma_f32 v[2:3], v[2:3], v[110:111], v[14:15]
	v_pk_fma_f32 v[0:1], v[0:1], v[108:109], v[12:13]
	global_store_dwordx4 v[16:17], v[4:7], off offset:512
	global_store_dwordx4 v[16:17], v[0:3], off offset:528
	s_cbranch_vccz .LBB0_261
	s_waitcnt vmcnt(0)
	s_cmpk_gt_u32 s16, 0xff
	s_cbranch_scc1 .LBB0_276
	s_barrier

.LBB0_293:
	v_mov_b64_e32 v[0:1], 0x400
	s_ashr_i32 s7, s6, 31
	v_cmp_lt_i64_e32 vcc, s[8:9], v[0:1]
	s_lshl_b64 s[8:9], s[6:7], 20
	s_add_u32 s8, s20, s8
	s_addc_u32 s9, s21, s9
	s_and_b64 s[10:11], vcc, exec
	s_cselect_b32 s7, s9, s15
	s_cselect_b32 s38, s8, s14
	s_ashr_i32 s5, s4, 31
	s_lshl_b64 s[10:11], s[4:5], 20
	s_add_u32 s10, s22, s10
	s_addc_u32 s11, s23, s11
	s_and_b64 s[18:19], vcc, exec
	s_cselect_b32 s5, s11, s17
	s_cselect_b32 s39, s10, s16
	s_add_u32 s14, s14, 0x80080
	s_addc_u32 s15, s15, 0
	s_add_u32 s40, s16, 0x100
	s_addc_u32 s41, s17, 0
	s_mov_b32 s42, -2
	s_mov_b64 s[48:49], 0x80
	v_add_u32_e32 v220, 0x10000, v159
	s_add_u32 s16, s14, 0xfff80080
	s_addc_u32 s17, s15, -1
	s_add_i32 s43, 0, 0x10000
	ds_read_b128 v[64:67], v220 offset:0
	ds_read_b128 v[68:71], v220 offset:1024
	ds_read_b128 v[72:75], v220 offset:2048
	ds_read_b128 v[76:79], v220 offset:3072
	s_cmp_eq_u32 s42, 28
	s_cselect_b32 s19, s7, s17
	s_cselect_b32 s18, s38, s16
	s_cselect_b32 s17, s5, s41
	s_cselect_b32 s16, s39, s40
	s_add_i32 m0, s13, 0xc000
	ds_read_b128 v[154:157], v161
	ds_read_b128 v[162:165], v161 offset:1024
	ds_read_b128 v[166:169], v161 offset:2048
	ds_read_b128 v[170:173], v161 offset:3072
	ds_read_b128 v[174:177], v161 offset:4096
	ds_read_b128 v[178:181], v161 offset:5120
	ds_read_b128 v[182:185], v161 offset:6144
	ds_read_b128 v[186:189], v161 offset:7168
	global_load_lds_dwordx4 v150, s[14:15]
	s_add_i32 m0, s13, 0xe000
	s_nop 0
	global_load_lds_dwordx4 v152, s[14:15]
	s_waitcnt lgkmcnt(8)
	s_barrier
	s_waitcnt lgkmcnt(0)
	v_mfma_f32_16x16x32_bf16 v[140:143], v[64:67], v[154:157], 0
	v_mfma_f32_16x16x32_bf16 v[136:139], v[72:75], v[154:157], 0
	v_mfma_f32_16x16x32_bf16 v[132:135], v[64:67], v[166:169], 0
	v_mfma_f32_16x16x32_bf16 v[128:131], v[72:75], v[166:169], 0
	s_add_i32 s46, 0, 0x14000
	s_add_i32 s43, s43, s27
	v_mfma_f32_16x16x32_bf16 v[108:111], v[64:67], v[174:177], 0
	s_mov_b32 m0, s43
	v_mfma_f32_16x16x32_bf16 v[104:107], v[72:75], v[174:177], 0
	v_mfma_f32_16x16x32_bf16 v[100:103], v[64:67], v[182:185], 0
	v_mfma_f32_16x16x32_bf16 v[96:99], v[72:75], v[182:185], 0
	v_mfma_f32_16x16x32_bf16 v[140:143], v[68:71], v[162:165], v[140:143]
	v_mfma_f32_16x16x32_bf16 v[136:139], v[76:79], v[162:165], v[136:139]
	v_mfma_f32_16x16x32_bf16 v[132:135], v[68:71], v[170:173], v[132:135]
	v_mfma_f32_16x16x32_bf16 v[128:131], v[76:79], v[170:173], v[128:131]
	v_mfma_f32_16x16x32_bf16 v[108:111], v[68:71], v[178:181], v[108:111]
	v_mfma_f32_16x16x32_bf16 v[104:107], v[76:79], v[178:181], v[104:107]
	v_mfma_f32_16x16x32_bf16 v[100:103], v[68:71], v[186:189], v[100:103]
	v_mfma_f32_16x16x32_bf16 v[96:99], v[76:79], v[186:189], v[96:99]
	s_barrier
	ds_read_b128 v[196:199], v220 offset:16384
	ds_read_b128 v[204:207], v220 offset:17408
	ds_read_b128 v[208:211], v220 offset:18432
	ds_read_b128 v[214:217], v220 offset:19456
	global_load_lds_dwordx4 v192, s[16:17]
	s_add_i32 m0, s43, 0x2000
	s_nop 0
	global_load_lds_dwordx4 v148, s[16:17]
	s_barrier
	s_waitcnt lgkmcnt(0)
	v_mfma_f32_16x16x32_bf16 v[124:127], v[196:199], v[154:157], 0
	v_mfma_f32_16x16x32_bf16 v[120:123], v[208:211], v[154:157], 0
	v_mfma_f32_16x16x32_bf16 v[116:119], v[196:199], v[166:169], 0
	v_mfma_f32_16x16x32_bf16 v[112:115], v[208:211], v[166:169], 0
	s_mov_b32 m0, s13
	v_mfma_f32_16x16x32_bf16 v[92:95], v[196:199], v[174:177], 0
	s_add_u32 s48, s18, 0x80
	s_addc_u32 s49, s19, 0
	v_mfma_f32_16x16x32_bf16 v[88:91], v[208:211], v[174:177], 0
	v_mfma_f32_16x16x32_bf16 v[84:87], v[196:199], v[182:185], 0
	v_mfma_f32_16x16x32_bf16 v[80:83], v[208:211], v[182:185], 0
	v_mfma_f32_16x16x32_bf16 v[124:127], v[204:207], v[162:165], v[124:127]
	v_mfma_f32_16x16x32_bf16 v[120:123], v[214:217], v[162:165], v[120:123]
	v_mfma_f32_16x16x32_bf16 v[116:119], v[204:207], v[170:173], v[116:119]
	v_mfma_f32_16x16x32_bf16 v[112:115], v[214:217], v[170:173], v[112:115]
	v_mfma_f32_16x16x32_bf16 v[92:95], v[204:207], v[178:181], v[92:95]
	v_mfma_f32_16x16x32_bf16 v[88:91], v[214:217], v[178:181], v[88:91]
	v_mfma_f32_16x16x32_bf16 v[84:87], v[204:207], v[186:189], v[84:87]
	v_mfma_f32_16x16x32_bf16 v[80:83], v[214:217], v[186:189], v[80:83]
	s_barrier
	ds_read_b128 v[154:157], v161 offset:16384
	ds_read_b128 v[162:165], v161 offset:17408
	ds_read_b128 v[166:169], v161 offset:18432
	ds_read_b128 v[170:173], v161 offset:19456
	ds_read_b128 v[174:177], v161 offset:20480
	ds_read_b128 v[178:181], v161 offset:21504
	ds_read_b128 v[182:185], v161 offset:22528
	ds_read_b128 v[186:189], v161 offset:23552
	global_load_lds_dwordx4 v144, s[18:19]
	s_mov_b32 m0, s28
	s_nop 0
	global_load_lds_dwordx4 v146, s[18:19]
	s_waitcnt lgkmcnt(0)
	s_barrier
	v_mfma_f32_16x16x32_bf16 v[60:63], v[64:67], v[154:157], 0
	v_mfma_f32_16x16x32_bf16 v[56:59], v[72:75], v[154:157], 0
	v_mfma_f32_16x16x32_bf16 v[52:55], v[64:67], v[166:169], 0
	v_mfma_f32_16x16x32_bf16 v[48:51], v[72:75], v[166:169], 0
	s_add_u32 s44, s16, 0x80000
	s_addc_u32 s45, s17, 0
	v_mfma_f32_16x16x32_bf16 v[28:31], v[64:67], v[174:177], 0
	s_add_i32 s43, s46, s27
	s_mov_b32 m0, s43
	v_mfma_f32_16x16x32_bf16 v[24:27], v[72:75], v[174:177], 0
	v_mfma_f32_16x16x32_bf16 v[20:23], v[64:67], v[182:185], 0
	v_mfma_f32_16x16x32_bf16 v[16:19], v[72:75], v[182:185], 0
	v_mfma_f32_16x16x32_bf16 v[60:63], v[68:71], v[162:165], v[60:63]
	v_mfma_f32_16x16x32_bf16 v[56:59], v[76:79], v[162:165], v[56:59]
	v_mfma_f32_16x16x32_bf16 v[52:55], v[68:71], v[170:173], v[52:55]
	v_mfma_f32_16x16x32_bf16 v[48:51], v[76:79], v[170:173], v[48:51]
	v_mfma_f32_16x16x32_bf16 v[28:31], v[68:71], v[178:181], v[28:31]
	v_mfma_f32_16x16x32_bf16 v[24:27], v[76:79], v[178:181], v[24:27]
	v_mfma_f32_16x16x32_bf16 v[20:23], v[68:71], v[186:189], v[20:23]
	v_mfma_f32_16x16x32_bf16 v[16:19], v[76:79], v[186:189], v[16:19]
	s_barrier
	global_load_lds_dwordx4 v192, s[44:45]
	s_add_i32 m0, s43, 0x2000
	s_nop 0
	global_load_lds_dwordx4 v148, s[44:45]
	s_add_u32 s18, s18, 0x80000
	s_addc_u32 s19, s19, 0
	s_mov_b32 m0, s29
	s_nop 0
	global_load_lds_dwordx4 v144, s[18:19]
	s_mov_b32 m0, s30
	s_nop 0
	global_load_lds_dwordx4 v146, s[18:19]
	s_waitcnt vmcnt(8)
	s_barrier
	v_mfma_f32_16x16x32_bf16 v[44:47], v[196:199], v[154:157], 0
	v_mfma_f32_16x16x32_bf16 v[40:43], v[208:211], v[154:157], 0
	v_mfma_f32_16x16x32_bf16 v[36:39], v[196:199], v[166:169], 0
	v_mfma_f32_16x16x32_bf16 v[32:35], v[208:211], v[166:169], 0
	s_add_i32 s43, 0, 0x18000
	v_mfma_f32_16x16x32_bf16 v[12:15], v[196:199], v[174:177], 0
	v_mfma_f32_16x16x32_bf16 v[8:11], v[208:211], v[174:177], 0
	v_mfma_f32_16x16x32_bf16 v[4:7], v[196:199], v[182:185], 0
	v_mfma_f32_16x16x32_bf16 v[0:3], v[208:211], v[182:185], 0
	v_mfma_f32_16x16x32_bf16 v[44:47], v[204:207], v[162:165], v[44:47]
	v_mfma_f32_16x16x32_bf16 v[40:43], v[214:217], v[162:165], v[40:43]
	v_mfma_f32_16x16x32_bf16 v[36:39], v[204:207], v[170:173], v[36:39]
	v_mfma_f32_16x16x32_bf16 v[32:35], v[214:217], v[170:173], v[32:35]
	v_mfma_f32_16x16x32_bf16 v[12:15], v[204:207], v[178:181], v[12:15]
	v_mfma_f32_16x16x32_bf16 v[8:11], v[214:217], v[178:181], v[8:11]
	v_mfma_f32_16x16x32_bf16 v[4:7], v[204:207], v[186:189], v[4:7]
	v_mfma_f32_16x16x32_bf16 v[0:3], v[214:217], v[186:189], v[0:3]
	s_barrier
	ds_read_b128 v[64:67], v220 offset:32768
	ds_read_b128 v[68:71], v220 offset:33792
	ds_read_b128 v[72:75], v220 offset:34816
	ds_read_b128 v[76:79], v220 offset:35840
	ds_read_b128 v[154:157], v161 offset:32768
	ds_read_b128 v[162:165], v161 offset:33792
	ds_read_b128 v[166:169], v161 offset:34816
	ds_read_b128 v[170:173], v161 offset:35840
	ds_read_b128 v[174:177], v161 offset:36864
	ds_read_b128 v[178:181], v161 offset:37888
	ds_read_b128 v[182:185], v161 offset:38912
	ds_read_b128 v[186:189], v161 offset:39936
	s_waitcnt lgkmcnt(8)
	s_barrier
	s_waitcnt lgkmcnt(0)
	v_mfma_f32_16x16x32_bf16 v[140:143], v[64:67], v[154:157], v[140:143]
	v_mfma_f32_16x16x32_bf16 v[136:139], v[72:75], v[154:157], v[136:139]
	v_mfma_f32_16x16x32_bf16 v[132:135], v[64:67], v[166:169], v[132:135]
	v_mfma_f32_16x16x32_bf16 v[128:131], v[72:75], v[166:169], v[128:131]
	s_add_i32 s18, 0, 0x1c000
	s_add_i32 s19, s43, s27
	v_mfma_f32_16x16x32_bf16 v[108:111], v[64:67], v[174:177], v[108:111]
	s_add_i32 m0, s19, 0xffffff80
	v_mfma_f32_16x16x32_bf16 v[104:107], v[72:75], v[174:177], v[104:107]
	v_mfma_f32_16x16x32_bf16 v[100:103], v[64:67], v[182:185], v[100:103]
	v_mfma_f32_16x16x32_bf16 v[96:99], v[72:75], v[182:185], v[96:99]
	v_mfma_f32_16x16x32_bf16 v[140:143], v[68:71], v[162:165], v[140:143]
	v_mfma_f32_16x16x32_bf16 v[136:139], v[76:79], v[162:165], v[136:139]
	v_mfma_f32_16x16x32_bf16 v[132:135], v[68:71], v[170:173], v[132:135]
	v_mfma_f32_16x16x32_bf16 v[128:131], v[76:79], v[170:173], v[128:131]
	v_mfma_f32_16x16x32_bf16 v[108:111], v[68:71], v[178:181], v[108:111]
	v_mfma_f32_16x16x32_bf16 v[104:107], v[76:79], v[178:181], v[104:107]
	v_mfma_f32_16x16x32_bf16 v[100:103], v[68:71], v[186:189], v[100:103]
	v_mfma_f32_16x16x32_bf16 v[96:99], v[76:79], v[186:189], v[96:99]
	s_barrier
	ds_read_b128 v[196:199], v220 offset:49152
	ds_read_b128 v[204:207], v220 offset:50176
	ds_read_b128 v[208:211], v220 offset:51200
	ds_read_b128 v[214:217], v220 offset:52224
	global_load_lds_dwordx4 v192, s[16:17] offset:128
	s_add_i32 m0, s19, 0x1f80
	s_nop 0
	global_load_lds_dwordx4 v148, s[16:17] offset:128
	s_barrier
	s_waitcnt lgkmcnt(0)
	v_mfma_f32_16x16x32_bf16 v[124:127], v[196:199], v[154:157], v[124:127]
	v_mfma_f32_16x16x32_bf16 v[120:123], v[208:211], v[154:157], v[120:123]
	v_mfma_f32_16x16x32_bf16 v[116:119], v[196:199], v[166:169], v[116:119]
	v_mfma_f32_16x16x32_bf16 v[112:115], v[208:211], v[166:169], v[112:115]
	s_mov_b32 m0, s34
	v_mfma_f32_16x16x32_bf16 v[92:95], v[196:199], v[174:177], v[92:95]
	v_mfma_f32_16x16x32_bf16 v[88:91], v[208:211], v[174:177], v[88:91]
	v_mfma_f32_16x16x32_bf16 v[84:87], v[196:199], v[182:185], v[84:87]
	v_mfma_f32_16x16x32_bf16 v[80:83], v[208:211], v[182:185], v[80:83]
	v_mfma_f32_16x16x32_bf16 v[124:127], v[204:207], v[162:165], v[124:127]
	v_mfma_f32_16x16x32_bf16 v[120:123], v[214:217], v[162:165], v[120:123]
	v_mfma_f32_16x16x32_bf16 v[116:119], v[204:207], v[170:173], v[116:119]
	v_mfma_f32_16x16x32_bf16 v[112:115], v[214:217], v[170:173], v[112:115]
	v_mfma_f32_16x16x32_bf16 v[92:95], v[204:207], v[178:181], v[92:95]
	v_mfma_f32_16x16x32_bf16 v[88:91], v[214:217], v[178:181], v[88:91]
	v_mfma_f32_16x16x32_bf16 v[84:87], v[204:207], v[186:189], v[84:87]
	v_mfma_f32_16x16x32_bf16 v[80:83], v[214:217], v[186:189], v[80:83]
	s_barrier
	ds_read_b128 v[154:157], v161 offset:49152
	ds_read_b128 v[162:165], v161 offset:50176
	ds_read_b128 v[166:169], v161 offset:51200
	ds_read_b128 v[170:173], v161 offset:52224
	ds_read_b128 v[174:177], v161 offset:53248
	ds_read_b128 v[178:181], v161 offset:54272
	ds_read_b128 v[182:185], v161 offset:55296
	ds_read_b128 v[186:189], v161 offset:56320
	global_load_lds_dwordx4 v144, s[48:49]
	s_mov_b32 m0, s35
	s_nop 0
	global_load_lds_dwordx4 v146, s[48:49]
	s_barrier
	s_waitcnt lgkmcnt(0)
	v_mfma_f32_16x16x32_bf16 v[60:63], v[64:67], v[154:157], v[60:63]
	v_mfma_f32_16x16x32_bf16 v[56:59], v[72:75], v[154:157], v[56:59]
	v_mfma_f32_16x16x32_bf16 v[52:55], v[64:67], v[166:169], v[52:55]
	v_mfma_f32_16x16x32_bf16 v[48:51], v[72:75], v[166:169], v[48:51]
	s_add_u32 s16, s16, 0x80080
	s_addc_u32 s17, s17, 0
	v_mfma_f32_16x16x32_bf16 v[28:31], v[64:67], v[174:177], v[28:31]
	s_add_i32 s18, s18, s27
	s_mov_b32 m0, s18
	v_mfma_f32_16x16x32_bf16 v[24:27], v[72:75], v[174:177], v[24:27]
	v_mfma_f32_16x16x32_bf16 v[20:23], v[64:67], v[182:185], v[20:23]
	v_mfma_f32_16x16x32_bf16 v[16:19], v[72:75], v[182:185], v[16:19]
	v_mfma_f32_16x16x32_bf16 v[60:63], v[68:71], v[162:165], v[60:63]
	v_mfma_f32_16x16x32_bf16 v[56:59], v[76:79], v[162:165], v[56:59]
	v_mfma_f32_16x16x32_bf16 v[52:55], v[68:71], v[170:173], v[52:55]
	v_mfma_f32_16x16x32_bf16 v[48:51], v[76:79], v[170:173], v[48:51]
	v_mfma_f32_16x16x32_bf16 v[28:31], v[68:71], v[178:181], v[28:31]
	v_mfma_f32_16x16x32_bf16 v[24:27], v[76:79], v[178:181], v[24:27]
	v_mfma_f32_16x16x32_bf16 v[20:23], v[68:71], v[186:189], v[20:23]
	v_mfma_f32_16x16x32_bf16 v[16:19], v[76:79], v[186:189], v[16:19]
	s_barrier
	global_load_lds_dwordx4 v192, s[16:17]
	s_add_i32 m0, s18, 0x2000
	s_nop 0
	global_load_lds_dwordx4 v148, s[16:17]
	s_waitcnt vmcnt(6)
	s_barrier
	v_mfma_f32_16x16x32_bf16 v[44:47], v[196:199], v[154:157], v[44:47]
	v_mfma_f32_16x16x32_bf16 v[40:43], v[208:211], v[154:157], v[40:43]
	v_mfma_f32_16x16x32_bf16 v[36:39], v[196:199], v[166:169], v[36:39]
	v_mfma_f32_16x16x32_bf16 v[32:35], v[208:211], v[166:169], v[32:35]
	s_add_i32 s42, s42, 2
	v_mfma_f32_16x16x32_bf16 v[12:15], v[196:199], v[174:177], v[12:15]
	s_add_u32 s14, s14, 0x100
	s_addc_u32 s15, s15, 0
	v_mfma_f32_16x16x32_bf16 v[8:11], v[208:211], v[174:177], v[8:11]
	s_add_u32 s40, s40, 0x100
	s_addc_u32 s41, s41, 0
	v_mfma_f32_16x16x32_bf16 v[4:7], v[196:199], v[182:185], v[4:7]
	s_add_u32 s16, s14, 0xfff80080
	s_addc_u32 s17, s15, -1
	v_mfma_f32_16x16x32_bf16 v[0:3], v[208:211], v[182:185], v[0:3]
	s_add_i32 s43, 0, 0x10000
	s_cmp_eq_u32 s42, 28
	v_mfma_f32_16x16x32_bf16 v[44:47], v[204:207], v[162:165], v[44:47]
	s_cselect_b32 s19, s7, s17
	s_cselect_b32 s18, s38, s16
	v_mfma_f32_16x16x32_bf16 v[40:43], v[214:217], v[162:165], v[40:43]
	s_cselect_b32 s17, s5, s41
	s_cselect_b32 s16, s39, s40
	v_mfma_f32_16x16x32_bf16 v[36:39], v[204:207], v[170:173], v[36:39]
	s_add_i32 m0, s13, 0xc000
	v_mfma_f32_16x16x32_bf16 v[32:35], v[214:217], v[170:173], v[32:35]
	v_mfma_f32_16x16x32_bf16 v[12:15], v[204:207], v[178:181], v[12:15]
	v_mfma_f32_16x16x32_bf16 v[8:11], v[214:217], v[178:181], v[8:11]
	v_mfma_f32_16x16x32_bf16 v[4:7], v[204:207], v[186:189], v[4:7]
	v_mfma_f32_16x16x32_bf16 v[0:3], v[214:217], v[186:189], v[0:3]
	s_cmp_gt_u32 s42, 29
	s_barrier
.LBB0_294:
	ds_read_b128 v[64:67], v220 offset:0
	ds_read_b128 v[68:71], v220 offset:1024
	ds_read_b128 v[72:75], v220 offset:2048
	ds_read_b128 v[76:79], v220 offset:3072
	ds_read_b128 v[154:157], v161
	ds_read_b128 v[162:165], v161 offset:1024
	ds_read_b128 v[166:169], v161 offset:2048
	ds_read_b128 v[170:173], v161 offset:3072
	ds_read_b128 v[174:177], v161 offset:4096
	ds_read_b128 v[178:181], v161 offset:5120
	ds_read_b128 v[182:185], v161 offset:6144
	ds_read_b128 v[186:189], v161 offset:7168
	global_load_lds_dwordx4 v150, s[14:15]
	s_add_i32 m0, s13, 0xe000
	s_nop 0
	global_load_lds_dwordx4 v152, s[14:15]
	s_waitcnt lgkmcnt(8)
	s_barrier
	s_waitcnt lgkmcnt(0)
	v_mfma_f32_16x16x32_bf16 v[140:143], v[64:67], v[154:157], v[140:143]
	v_mfma_f32_16x16x32_bf16 v[136:139], v[72:75], v[154:157], v[136:139]
	v_mfma_f32_16x16x32_bf16 v[132:135], v[64:67], v[166:169], v[132:135]
	v_mfma_f32_16x16x32_bf16 v[128:131], v[72:75], v[166:169], v[128:131]
	s_add_i32 s46, 0, 0x14000
	s_add_i32 s43, s43, s27
	v_mfma_f32_16x16x32_bf16 v[108:111], v[64:67], v[174:177], v[108:111]
	s_mov_b32 m0, s43
	v_mfma_f32_16x16x32_bf16 v[104:107], v[72:75], v[174:177], v[104:107]
	v_mfma_f32_16x16x32_bf16 v[100:103], v[64:67], v[182:185], v[100:103]
	v_mfma_f32_16x16x32_bf16 v[96:99], v[72:75], v[182:185], v[96:99]
	v_mfma_f32_16x16x32_bf16 v[140:143], v[68:71], v[162:165], v[140:143]
	v_mfma_f32_16x16x32_bf16 v[136:139], v[76:79], v[162:165], v[136:139]
	v_mfma_f32_16x16x32_bf16 v[132:135], v[68:71], v[170:173], v[132:135]
	v_mfma_f32_16x16x32_bf16 v[128:131], v[76:79], v[170:173], v[128:131]
	v_mfma_f32_16x16x32_bf16 v[108:111], v[68:71], v[178:181], v[108:111]
	v_mfma_f32_16x16x32_bf16 v[104:107], v[76:79], v[178:181], v[104:107]
	v_mfma_f32_16x16x32_bf16 v[100:103], v[68:71], v[186:189], v[100:103]
	v_mfma_f32_16x16x32_bf16 v[96:99], v[76:79], v[186:189], v[96:99]
	s_barrier
	ds_read_b128 v[196:199], v220 offset:16384
	ds_read_b128 v[204:207], v220 offset:17408
	ds_read_b128 v[208:211], v220 offset:18432
	ds_read_b128 v[214:217], v220 offset:19456
	global_load_lds_dwordx4 v192, s[16:17]
	s_add_i32 m0, s43, 0x2000
	s_nop 0
	global_load_lds_dwordx4 v148, s[16:17]
	s_barrier
	s_waitcnt lgkmcnt(0)
	v_mfma_f32_16x16x32_bf16 v[124:127], v[196:199], v[154:157], v[124:127]
	v_mfma_f32_16x16x32_bf16 v[120:123], v[208:211], v[154:157], v[120:123]
	v_mfma_f32_16x16x32_bf16 v[116:119], v[196:199], v[166:169], v[116:119]
	v_mfma_f32_16x16x32_bf16 v[112:115], v[208:211], v[166:169], v[112:115]
	s_mov_b32 m0, s13
	v_mfma_f32_16x16x32_bf16 v[92:95], v[196:199], v[174:177], v[92:95]
	s_add_u32 s48, s18, 0x80
	s_addc_u32 s49, s19, 0
	v_mfma_f32_16x16x32_bf16 v[88:91], v[208:211], v[174:177], v[88:91]
	v_mfma_f32_16x16x32_bf16 v[84:87], v[196:199], v[182:185], v[84:87]
	v_mfma_f32_16x16x32_bf16 v[80:83], v[208:211], v[182:185], v[80:83]
	v_mfma_f32_16x16x32_bf16 v[124:127], v[204:207], v[162:165], v[124:127]
	v_mfma_f32_16x16x32_bf16 v[120:123], v[214:217], v[162:165], v[120:123]
	v_mfma_f32_16x16x32_bf16 v[116:119], v[204:207], v[170:173], v[116:119]
	v_mfma_f32_16x16x32_bf16 v[112:115], v[214:217], v[170:173], v[112:115]
	v_mfma_f32_16x16x32_bf16 v[92:95], v[204:207], v[178:181], v[92:95]
	v_mfma_f32_16x16x32_bf16 v[88:91], v[214:217], v[178:181], v[88:91]
	v_mfma_f32_16x16x32_bf16 v[84:87], v[204:207], v[186:189], v[84:87]
	v_mfma_f32_16x16x32_bf16 v[80:83], v[214:217], v[186:189], v[80:83]
	s_barrier
	ds_read_b128 v[154:157], v161 offset:16384
	ds_read_b128 v[162:165], v161 offset:17408
	ds_read_b128 v[166:169], v161 offset:18432
	ds_read_b128 v[170:173], v161 offset:19456
	ds_read_b128 v[174:177], v161 offset:20480
	ds_read_b128 v[178:181], v161 offset:21504
	ds_read_b128 v[182:185], v161 offset:22528
	ds_read_b128 v[186:189], v161 offset:23552
	global_load_lds_dwordx4 v144, s[18:19]
	s_mov_b32 m0, s28
	s_nop 0
	global_load_lds_dwordx4 v146, s[18:19]
	s_waitcnt lgkmcnt(0)
	s_barrier
	v_mfma_f32_16x16x32_bf16 v[60:63], v[64:67], v[154:157], v[60:63]
	v_mfma_f32_16x16x32_bf16 v[56:59], v[72:75], v[154:157], v[56:59]
	v_mfma_f32_16x16x32_bf16 v[52:55], v[64:67], v[166:169], v[52:55]
	v_mfma_f32_16x16x32_bf16 v[48:51], v[72:75], v[166:169], v[48:51]
	s_add_u32 s44, s16, 0x80000
	s_addc_u32 s45, s17, 0
	v_mfma_f32_16x16x32_bf16 v[28:31], v[64:67], v[174:177], v[28:31]
	s_add_i32 s43, s46, s27
	s_mov_b32 m0, s43
	v_mfma_f32_16x16x32_bf16 v[24:27], v[72:75], v[174:177], v[24:27]
	v_mfma_f32_16x16x32_bf16 v[20:23], v[64:67], v[182:185], v[20:23]
	v_mfma_f32_16x16x32_bf16 v[16:19], v[72:75], v[182:185], v[16:19]
	v_mfma_f32_16x16x32_bf16 v[60:63], v[68:71], v[162:165], v[60:63]
	v_mfma_f32_16x16x32_bf16 v[56:59], v[76:79], v[162:165], v[56:59]
	v_mfma_f32_16x16x32_bf16 v[52:55], v[68:71], v[170:173], v[52:55]
	v_mfma_f32_16x16x32_bf16 v[48:51], v[76:79], v[170:173], v[48:51]
	v_mfma_f32_16x16x32_bf16 v[28:31], v[68:71], v[178:181], v[28:31]
	v_mfma_f32_16x16x32_bf16 v[24:27], v[76:79], v[178:181], v[24:27]
	v_mfma_f32_16x16x32_bf16 v[20:23], v[68:71], v[186:189], v[20:23]
	v_mfma_f32_16x16x32_bf16 v[16:19], v[76:79], v[186:189], v[16:19]
	s_barrier
	global_load_lds_dwordx4 v192, s[44:45]
	s_add_i32 m0, s43, 0x2000
	s_nop 0
	global_load_lds_dwordx4 v148, s[44:45]
	s_add_u32 s18, s18, 0x80000
	s_addc_u32 s19, s19, 0
	s_mov_b32 m0, s29
	s_nop 0
	global_load_lds_dwordx4 v144, s[18:19]
	s_mov_b32 m0, s30
	s_nop 0
	global_load_lds_dwordx4 v146, s[18:19]
	s_waitcnt vmcnt(8)
	s_barrier
	v_mfma_f32_16x16x32_bf16 v[44:47], v[196:199], v[154:157], v[44:47]
	v_mfma_f32_16x16x32_bf16 v[40:43], v[208:211], v[154:157], v[40:43]
	v_mfma_f32_16x16x32_bf16 v[36:39], v[196:199], v[166:169], v[36:39]
	v_mfma_f32_16x16x32_bf16 v[32:35], v[208:211], v[166:169], v[32:35]
	s_add_i32 s43, 0, 0x18000
	v_mfma_f32_16x16x32_bf16 v[12:15], v[196:199], v[174:177], v[12:15]
	v_mfma_f32_16x16x32_bf16 v[8:11], v[208:211], v[174:177], v[8:11]
	v_mfma_f32_16x16x32_bf16 v[4:7], v[196:199], v[182:185], v[4:7]
	v_mfma_f32_16x16x32_bf16 v[0:3], v[208:211], v[182:185], v[0:3]
	v_mfma_f32_16x16x32_bf16 v[44:47], v[204:207], v[162:165], v[44:47]
	v_mfma_f32_16x16x32_bf16 v[40:43], v[214:217], v[162:165], v[40:43]
	v_mfma_f32_16x16x32_bf16 v[36:39], v[204:207], v[170:173], v[36:39]
	v_mfma_f32_16x16x32_bf16 v[32:35], v[214:217], v[170:173], v[32:35]
	v_mfma_f32_16x16x32_bf16 v[12:15], v[204:207], v[178:181], v[12:15]
	v_mfma_f32_16x16x32_bf16 v[8:11], v[214:217], v[178:181], v[8:11]
	v_mfma_f32_16x16x32_bf16 v[4:7], v[204:207], v[186:189], v[4:7]
	v_mfma_f32_16x16x32_bf16 v[0:3], v[214:217], v[186:189], v[0:3]
	s_barrier
	ds_read_b128 v[64:67], v220 offset:32768
	ds_read_b128 v[68:71], v220 offset:33792
	ds_read_b128 v[72:75], v220 offset:34816
	ds_read_b128 v[76:79], v220 offset:35840
	ds_read_b128 v[154:157], v161 offset:32768
	ds_read_b128 v[162:165], v161 offset:33792
	ds_read_b128 v[166:169], v161 offset:34816
	ds_read_b128 v[170:173], v161 offset:35840
	ds_read_b128 v[174:177], v161 offset:36864
	ds_read_b128 v[178:181], v161 offset:37888
	ds_read_b128 v[182:185], v161 offset:38912
	ds_read_b128 v[186:189], v161 offset:39936
	s_waitcnt lgkmcnt(8)
	s_barrier
	s_waitcnt lgkmcnt(0)
	v_mfma_f32_16x16x32_bf16 v[140:143], v[64:67], v[154:157], v[140:143]
	v_mfma_f32_16x16x32_bf16 v[136:139], v[72:75], v[154:157], v[136:139]
	v_mfma_f32_16x16x32_bf16 v[132:135], v[64:67], v[166:169], v[132:135]
	v_mfma_f32_16x16x32_bf16 v[128:131], v[72:75], v[166:169], v[128:131]
	s_add_i32 s18, 0, 0x1c000
	s_add_i32 s19, s43, s27
	v_mfma_f32_16x16x32_bf16 v[108:111], v[64:67], v[174:177], v[108:111]
	s_add_i32 m0, s19, 0xffffff80
	v_mfma_f32_16x16x32_bf16 v[104:107], v[72:75], v[174:177], v[104:107]
	v_mfma_f32_16x16x32_bf16 v[100:103], v[64:67], v[182:185], v[100:103]
	v_mfma_f32_16x16x32_bf16 v[96:99], v[72:75], v[182:185], v[96:99]
	v_mfma_f32_16x16x32_bf16 v[140:143], v[68:71], v[162:165], v[140:143]
	v_mfma_f32_16x16x32_bf16 v[136:139], v[76:79], v[162:165], v[136:139]
	v_mfma_f32_16x16x32_bf16 v[132:135], v[68:71], v[170:173], v[132:135]
	v_mfma_f32_16x16x32_bf16 v[128:131], v[76:79], v[170:173], v[128:131]
	v_mfma_f32_16x16x32_bf16 v[108:111], v[68:71], v[178:181], v[108:111]
	v_mfma_f32_16x16x32_bf16 v[104:107], v[76:79], v[178:181], v[104:107]
	v_mfma_f32_16x16x32_bf16 v[100:103], v[68:71], v[186:189], v[100:103]
	v_mfma_f32_16x16x32_bf16 v[96:99], v[76:79], v[186:189], v[96:99]
	s_barrier
	ds_read_b128 v[196:199], v220 offset:49152
	ds_read_b128 v[204:207], v220 offset:50176
	ds_read_b128 v[208:211], v220 offset:51200
	ds_read_b128 v[214:217], v220 offset:52224
	global_load_lds_dwordx4 v192, s[16:17] offset:128
	s_add_i32 m0, s19, 0x1f80
	s_nop 0
	global_load_lds_dwordx4 v148, s[16:17] offset:128
	s_barrier
	s_waitcnt lgkmcnt(0)
	v_mfma_f32_16x16x32_bf16 v[124:127], v[196:199], v[154:157], v[124:127]
	v_mfma_f32_16x16x32_bf16 v[120:123], v[208:211], v[154:157], v[120:123]
	v_mfma_f32_16x16x32_bf16 v[116:119], v[196:199], v[166:169], v[116:119]
	v_mfma_f32_16x16x32_bf16 v[112:115], v[208:211], v[166:169], v[112:115]
	s_mov_b32 m0, s34
	v_mfma_f32_16x16x32_bf16 v[92:95], v[196:199], v[174:177], v[92:95]
	v_mfma_f32_16x16x32_bf16 v[88:91], v[208:211], v[174:177], v[88:91]
	v_mfma_f32_16x16x32_bf16 v[84:87], v[196:199], v[182:185], v[84:87]
	v_mfma_f32_16x16x32_bf16 v[80:83], v[208:211], v[182:185], v[80:83]
	v_mfma_f32_16x16x32_bf16 v[124:127], v[204:207], v[162:165], v[124:127]
	v_mfma_f32_16x16x32_bf16 v[120:123], v[214:217], v[162:165], v[120:123]
	v_mfma_f32_16x16x32_bf16 v[116:119], v[204:207], v[170:173], v[116:119]
	v_mfma_f32_16x16x32_bf16 v[112:115], v[214:217], v[170:173], v[112:115]
	v_mfma_f32_16x16x32_bf16 v[92:95], v[204:207], v[178:181], v[92:95]
	v_mfma_f32_16x16x32_bf16 v[88:91], v[214:217], v[178:181], v[88:91]
	v_mfma_f32_16x16x32_bf16 v[84:87], v[204:207], v[186:189], v[84:87]
	v_mfma_f32_16x16x32_bf16 v[80:83], v[214:217], v[186:189], v[80:83]
	s_barrier
	ds_read_b128 v[154:157], v161 offset:49152
	ds_read_b128 v[162:165], v161 offset:50176
	ds_read_b128 v[166:169], v161 offset:51200
	ds_read_b128 v[170:173], v161 offset:52224
	ds_read_b128 v[174:177], v161 offset:53248
	ds_read_b128 v[178:181], v161 offset:54272
	ds_read_b128 v[182:185], v161 offset:55296
	ds_read_b128 v[186:189], v161 offset:56320
	global_load_lds_dwordx4 v144, s[48:49]
	s_mov_b32 m0, s35
	s_nop 0
	global_load_lds_dwordx4 v146, s[48:49]
	s_barrier
	s_waitcnt lgkmcnt(0)
	v_mfma_f32_16x16x32_bf16 v[60:63], v[64:67], v[154:157], v[60:63]
	v_mfma_f32_16x16x32_bf16 v[56:59], v[72:75], v[154:157], v[56:59]
	v_mfma_f32_16x16x32_bf16 v[52:55], v[64:67], v[166:169], v[52:55]
	v_mfma_f32_16x16x32_bf16 v[48:51], v[72:75], v[166:169], v[48:51]
	s_add_u32 s16, s16, 0x80080
	s_addc_u32 s17, s17, 0
	v_mfma_f32_16x16x32_bf16 v[28:31], v[64:67], v[174:177], v[28:31]
	s_add_i32 s18, s18, s27
	s_mov_b32 m0, s18
	v_mfma_f32_16x16x32_bf16 v[24:27], v[72:75], v[174:177], v[24:27]
	v_mfma_f32_16x16x32_bf16 v[20:23], v[64:67], v[182:185], v[20:23]
	v_mfma_f32_16x16x32_bf16 v[16:19], v[72:75], v[182:185], v[16:19]
	v_mfma_f32_16x16x32_bf16 v[60:63], v[68:71], v[162:165], v[60:63]
	v_mfma_f32_16x16x32_bf16 v[56:59], v[76:79], v[162:165], v[56:59]
	v_mfma_f32_16x16x32_bf16 v[52:55], v[68:71], v[170:173], v[52:55]
	v_mfma_f32_16x16x32_bf16 v[48:51], v[76:79], v[170:173], v[48:51]
	v_mfma_f32_16x16x32_bf16 v[28:31], v[68:71], v[178:181], v[28:31]
	v_mfma_f32_16x16x32_bf16 v[24:27], v[76:79], v[178:181], v[24:27]
	v_mfma_f32_16x16x32_bf16 v[20:23], v[68:71], v[186:189], v[20:23]
	v_mfma_f32_16x16x32_bf16 v[16:19], v[76:79], v[186:189], v[16:19]
	s_barrier
	global_load_lds_dwordx4 v192, s[16:17]
	s_add_i32 m0, s18, 0x2000
	s_nop 0
	global_load_lds_dwordx4 v148, s[16:17]
	s_waitcnt vmcnt(6)
	s_barrier
	v_mfma_f32_16x16x32_bf16 v[44:47], v[196:199], v[154:157], v[44:47]
	v_mfma_f32_16x16x32_bf16 v[40:43], v[208:211], v[154:157], v[40:43]
	v_mfma_f32_16x16x32_bf16 v[36:39], v[196:199], v[166:169], v[36:39]
	v_mfma_f32_16x16x32_bf16 v[32:35], v[208:211], v[166:169], v[32:35]
	s_add_i32 s42, s42, 2
	v_mfma_f32_16x16x32_bf16 v[12:15], v[196:199], v[174:177], v[12:15]
	s_add_u32 s14, s14, 0x100
	s_addc_u32 s15, s15, 0
	v_mfma_f32_16x16x32_bf16 v[8:11], v[208:211], v[174:177], v[8:11]
	s_add_u32 s40, s40, 0x100
	s_addc_u32 s41, s41, 0
	v_mfma_f32_16x16x32_bf16 v[4:7], v[196:199], v[182:185], v[4:7]
	s_add_u32 s16, s14, 0xfff80080
	s_addc_u32 s17, s15, -1
	v_mfma_f32_16x16x32_bf16 v[0:3], v[208:211], v[182:185], v[0:3]
	s_add_i32 s43, 0, 0x10000
	s_cmp_eq_u32 s42, 28
	v_mfma_f32_16x16x32_bf16 v[44:47], v[204:207], v[162:165], v[44:47]
	s_cselect_b32 s19, s7, s17
	s_cselect_b32 s18, s38, s16
	v_mfma_f32_16x16x32_bf16 v[40:43], v[214:217], v[162:165], v[40:43]
	s_cselect_b32 s17, s5, s41
	s_cselect_b32 s16, s39, s40
	v_mfma_f32_16x16x32_bf16 v[36:39], v[204:207], v[170:173], v[36:39]
	s_add_i32 m0, s13, 0xc000
	v_mfma_f32_16x16x32_bf16 v[32:35], v[214:217], v[170:173], v[32:35]
	v_mfma_f32_16x16x32_bf16 v[12:15], v[204:207], v[178:181], v[12:15]
	v_mfma_f32_16x16x32_bf16 v[8:11], v[214:217], v[178:181], v[8:11]
	v_mfma_f32_16x16x32_bf16 v[4:7], v[204:207], v[186:189], v[4:7]
	v_mfma_f32_16x16x32_bf16 v[0:3], v[214:217], v[186:189], v[0:3]
	s_cmp_gt_u32 s42, 29
	s_barrier
	s_cbranch_scc0 .LBB0_294
	s_ashr_i32 s5, s12, 4
	v_lshl_or_b32 v190, s37, 8, v160
	s_mul_hi_i32 s7, s5, 0xc000
	s_mul_i32 s5, s5, 0xc000
	s_add_u32 s14, s31, s5
	v_ashrrev_i32_e32 v191, 31, v190
	v_lshl_add_u32 v154, s12, 8, v158
	v_readlane_b32 s52, v254, 23
	s_addc_u32 s15, s33, s7
	v_lshlrev_b64 v[156:157], 2, v[190:191]
	v_readlane_b32 s53, v254, 24
	v_ashrrev_i32_e32 v155, 31, v154
	v_lshl_add_u64 v[68:69], s[14:15], 0, v[156:157]
	v_lshl_add_u64 v[156:157], s[52:53], 0, v[156:157]
	v_lshlrev_b64 v[162:163], 13, v[154:155]
	v_lshl_add_u64 v[174:175], v[156:157], 0, v[162:163]
	global_load_dwordx4 v[72:75], v[68:69], off offset:16
	global_load_dwordx4 v[76:79], v[68:69], off
	global_load_dwordx4 v[64:67], v[68:69], off offset:528
	s_nop 0
	global_load_dwordx4 v[68:71], v[68:69], off offset:512
	s_nop 0
	global_load_dwordx4 v[162:165], v[174:175], off offset:16
	global_load_dwordx4 v[166:169], v[174:175], off
	global_load_dwordx4 v[170:173], v[174:175], off offset:528
	s_nop 0
	global_load_dwordx4 v[174:177], v[174:175], off offset:512
	v_or_b32_e32 v204, 16, v154
	v_ashrrev_i32_e32 v205, 31, v204
	v_lshlrev_b64 v[178:179], 13, v[204:205]
	v_lshl_add_u64 v[196:197], v[156:157], 0, v[178:179]
	global_load_dwordx4 v[178:181], v[196:197], off offset:16
	global_load_dwordx4 v[182:185], v[196:197], off
	global_load_dwordx4 v[186:189], v[196:197], off offset:528
	s_nop 0
	global_load_dwordx4 v[196:199], v[196:197], off offset:512
	v_lshlrev_b64 v[206:207], 12, v[154:155]
	s_and_b64 vcc, exec, s[0:1]
	s_mov_b32 s37, s4
	s_mov_b32 s12, s6
	s_mov_b64 s[16:17], s[10:11]
	s_mov_b64 s[14:15], s[8:9]
	s_mov_b32 s11, 0xc000
	v_readlane_b32 s54, v254, 25
	v_readlane_b32 s55, v254, 26
	v_readlane_b32 s56, v254, 27
	v_readlane_b32 s57, v254, 28
	v_readlane_b32 s58, v254, 29
	v_readlane_b32 s59, v254, 30
	v_readlane_b32 s60, v254, 31
	v_readlane_b32 s61, v254, 32
	v_readlane_b32 s62, v254, 33
	v_readlane_b32 s63, v254, 34
	v_readlane_b32 s64, v254, 35
	v_readlane_b32 s65, v254, 36
	v_readlane_b32 s66, v254, 37
	v_readlane_b32 s67, v254, 38
	s_waitcnt vmcnt(0)
	v_pk_fma_f32 v[136:137], v[136:137], v[72:73], v[162:163]
	v_pk_fma_f32 v[142:143], v[142:143], v[78:79], v[168:169]
	v_pk_fma_f32 v[140:141], v[140:141], v[76:77], v[166:167]
	v_pk_fma_f32 v[164:165], v[138:139], v[74:75], v[164:165]
	v_cvt_pk_bf16_f32 v138, v140, v141
	v_cvt_pk_bf16_f32 v139, v142, v143
	v_cvt_pk_bf16_f32 v140, v136, v137
	v_lshl_add_u64 v[142:143], s[2:3], 0, v[206:207]
	v_lshlrev_b64 v[136:137], 1, v[190:191]
	v_lshl_add_u64 v[142:143], v[142:143], 0, v[136:137]
	v_pk_fma_f32 v[124:125], v[124:125], v[68:69], v[174:175]
	v_cvt_pk_bf16_f32 v141, v164, v165
	global_store_dwordx4 v[142:143], v[138:141], off
	v_pk_fma_f32 v[126:127], v[126:127], v[70:71], v[176:177]
	v_pk_fma_f32 v[128:129], v[128:129], v[72:73], v[178:179]
	v_pk_fma_f32 v[138:139], v[122:123], v[66:67], v[172:173]
	v_pk_fma_f32 v[122:123], v[120:121], v[64:65], v[170:171]
	v_cvt_pk_bf16_f32 v120, v124, v125
	v_cvt_pk_bf16_f32 v121, v126, v127
	v_lshlrev_b64 v[124:125], 12, v[204:205]
	v_cvt_pk_bf16_f32 v122, v122, v123
	v_cvt_pk_bf16_f32 v123, v138, v139
	global_store_dwordx4 v[142:143], v[120:123], off offset:256
	v_lshl_add_u64 v[124:125], s[2:3], 0, v[124:125]
	v_lshl_add_u64 v[124:125], v[124:125], 0, v[136:137]
	v_pk_fma_f32 v[120:121], v[132:133], v[76:77], v[182:183]
	v_pk_fma_f32 v[122:123], v[134:135], v[78:79], v[184:185]
	v_cvt_pk_bf16_f32 v120, v120, v121
	v_or_b32_e32 v142, 32, v154
	v_cvt_pk_bf16_f32 v121, v122, v123
	v_pk_fma_f32 v[126:127], v[130:131], v[74:75], v[180:181]
	v_cvt_pk_bf16_f32 v122, v128, v129
	v_pk_fma_f32 v[118:119], v[118:119], v[70:71], v[198:199]
	v_cvt_pk_bf16_f32 v123, v126, v127
	global_store_dwordx4 v[124:125], v[120:123], off
	v_pk_fma_f32 v[116:117], v[116:117], v[68:69], v[196:197]
	v_ashrrev_i32_e32 v143, 31, v142
	v_pk_fma_f32 v[120:121], v[114:115], v[66:67], v[188:189]
	v_pk_fma_f32 v[114:115], v[112:113], v[64:65], v[186:187]
	v_cvt_pk_bf16_f32 v112, v116, v117
	v_cvt_pk_bf16_f32 v113, v118, v119
	v_or_b32_e32 v166, 48, v154
	v_cvt_pk_bf16_f32 v114, v114, v115
	v_cvt_pk_bf16_f32 v115, v120, v121
	global_store_dwordx4 v[124:125], v[112:115], off offset:256
	v_ashrrev_i32_e32 v167, 31, v166
	v_lshlrev_b64 v[128:129], 13, v[166:167]
	v_lshlrev_b64 v[112:113], 13, v[142:143]
	v_lshl_add_u64 v[124:125], v[156:157], 0, v[112:113]
	global_load_dwordx4 v[112:115], v[124:125], off offset:16
	global_load_dwordx4 v[116:119], v[124:125], off
	global_load_dwordx4 v[120:123], v[124:125], off offset:528
	s_nop 0
	global_load_dwordx4 v[124:127], v[124:125], off offset:512
	v_lshl_add_u64 v[162:163], v[156:157], 0, v[128:129]
	global_load_dwordx4 v[128:131], v[162:163], off offset:16
	global_load_dwordx4 v[132:135], v[162:163], off
	global_load_dwordx4 v[138:141], v[162:163], off offset:528
	s_nop 0
	global_load_dwordx4 v[162:165], v[162:163], off offset:512
	v_lshlrev_b64 v[142:143], 12, v[142:143]
	s_waitcnt vmcnt(0)
	v_pk_fma_f32 v[114:115], v[106:107], v[74:75], v[114:115]
	v_pk_fma_f32 v[108:109], v[108:109], v[76:77], v[116:117]
	v_pk_fma_f32 v[106:107], v[104:105], v[72:73], v[112:113]
	v_cvt_pk_bf16_f32 v104, v108, v109
	v_lshl_add_u64 v[108:109], s[2:3], 0, v[142:143]
	v_pk_fma_f32 v[110:111], v[110:111], v[78:79], v[118:119]
	v_lshl_add_u64 v[108:109], v[108:109], 0, v[136:137]
	v_cvt_pk_bf16_f32 v105, v110, v111
	v_pk_fma_f32 v[92:93], v[92:93], v[68:69], v[124:125]
	v_cvt_pk_bf16_f32 v106, v106, v107
	v_cvt_pk_bf16_f32 v107, v114, v115
	global_store_dwordx4 v[108:109], v[104:107], off
	v_pk_fma_f32 v[94:95], v[94:95], v[70:71], v[126:127]
	v_add_u32_e32 v112, 0x80, v154
	v_pk_fma_f32 v[104:105], v[90:91], v[66:67], v[122:123]
	v_pk_fma_f32 v[90:91], v[88:89], v[64:65], v[120:121]
	v_cvt_pk_bf16_f32 v88, v92, v93
	v_cvt_pk_bf16_f32 v89, v94, v95
	v_lshlrev_b64 v[92:93], 12, v[166:167]
	v_cvt_pk_bf16_f32 v90, v90, v91
	v_cvt_pk_bf16_f32 v91, v104, v105
	global_store_dwordx4 v[108:109], v[88:91], off offset:256
	v_lshl_add_u64 v[92:93], s[2:3], 0, v[92:93]
	v_lshl_add_u64 v[92:93], v[92:93], 0, v[136:137]
	v_pk_fma_f32 v[88:89], v[100:101], v[76:77], v[132:133]
	v_pk_fma_f32 v[90:91], v[102:103], v[78:79], v[134:135]
	v_cvt_pk_bf16_f32 v88, v88, v89
	v_pk_fma_f32 v[94:95], v[98:99], v[74:75], v[130:131]
	v_cvt_pk_bf16_f32 v89, v90, v91
	v_pk_fma_f32 v[96:97], v[96:97], v[72:73], v[128:129]
	v_pk_fma_f32 v[86:87], v[86:87], v[70:71], v[164:165]
	v_cvt_pk_bf16_f32 v90, v96, v97
	v_cvt_pk_bf16_f32 v91, v94, v95
	global_store_dwordx4 v[92:93], v[88:91], off
	v_pk_fma_f32 v[84:85], v[84:85], v[68:69], v[162:163]
	v_ashrrev_i32_e32 v113, 31, v112
	v_pk_fma_f32 v[88:89], v[82:83], v[66:67], v[140:141]
	v_pk_fma_f32 v[82:83], v[80:81], v[64:65], v[138:139]
	v_cvt_pk_bf16_f32 v80, v84, v85
	v_cvt_pk_bf16_f32 v81, v86, v87
	v_add_u32_e32 v114, 0x90, v154
	v_cvt_pk_bf16_f32 v82, v82, v83
	v_cvt_pk_bf16_f32 v83, v88, v89
	global_store_dwordx4 v[92:93], v[80:83], off offset:256
	v_ashrrev_i32_e32 v115, 31, v114
	v_lshlrev_b64 v[96:97], 13, v[114:115]
	v_lshlrev_b64 v[80:81], 13, v[112:113]
	v_lshl_add_u64 v[92:93], v[156:157], 0, v[80:81]
	global_load_dwordx4 v[80:83], v[92:93], off offset:16
	global_load_dwordx4 v[84:87], v[92:93], off
	global_load_dwordx4 v[88:91], v[92:93], off offset:528
	s_nop 0
	global_load_dwordx4 v[92:95], v[92:93], off offset:512
	v_lshl_add_u64 v[108:109], v[156:157], 0, v[96:97]
	global_load_dwordx4 v[96:99], v[108:109], off offset:16
	global_load_dwordx4 v[100:103], v[108:109], off
	global_load_dwordx4 v[104:107], v[108:109], off offset:528
	s_nop 0
	global_load_dwordx4 v[108:111], v[108:109], off offset:512
	v_lshlrev_b64 v[112:113], 12, v[112:113]
	s_waitcnt vmcnt(0)
	v_pk_fma_f32 v[82:83], v[58:59], v[74:75], v[82:83]
	v_pk_fma_f32 v[60:61], v[60:61], v[76:77], v[84:85]
	v_pk_fma_f32 v[58:59], v[56:57], v[72:73], v[80:81]
	v_cvt_pk_bf16_f32 v56, v60, v61
	v_lshl_add_u64 v[60:61], s[2:3], 0, v[112:113]
	v_pk_fma_f32 v[62:63], v[62:63], v[78:79], v[86:87]
	v_lshl_add_u64 v[60:61], v[60:61], 0, v[136:137]
	v_cvt_pk_bf16_f32 v57, v62, v63
	v_pk_fma_f32 v[44:45], v[44:45], v[68:69], v[92:93]
	v_cvt_pk_bf16_f32 v58, v58, v59
	v_cvt_pk_bf16_f32 v59, v82, v83
	global_store_dwordx4 v[60:61], v[56:59], off
	v_pk_fma_f32 v[46:47], v[46:47], v[70:71], v[94:95]
	v_add_u32_e32 v80, 0xa0, v154
	v_pk_fma_f32 v[56:57], v[42:43], v[66:67], v[90:91]
	v_pk_fma_f32 v[42:43], v[40:41], v[64:65], v[88:89]
	v_cvt_pk_bf16_f32 v40, v44, v45
	v_cvt_pk_bf16_f32 v41, v46, v47
	v_lshlrev_b64 v[44:45], 12, v[114:115]
	v_cvt_pk_bf16_f32 v42, v42, v43
	v_cvt_pk_bf16_f32 v43, v56, v57
	global_store_dwordx4 v[60:61], v[40:43], off offset:256
	v_lshl_add_u64 v[44:45], s[2:3], 0, v[44:45]
	v_lshl_add_u64 v[44:45], v[44:45], 0, v[136:137]
	v_pk_fma_f32 v[40:41], v[52:53], v[76:77], v[100:101]
	v_pk_fma_f32 v[42:43], v[54:55], v[78:79], v[102:103]
	v_cvt_pk_bf16_f32 v40, v40, v41
	v_pk_fma_f32 v[46:47], v[50:51], v[74:75], v[98:99]
	v_cvt_pk_bf16_f32 v41, v42, v43
	v_pk_fma_f32 v[48:49], v[48:49], v[72:73], v[96:97]
	v_pk_fma_f32 v[38:39], v[38:39], v[70:71], v[110:111]
	v_cvt_pk_bf16_f32 v42, v48, v49
	v_cvt_pk_bf16_f32 v43, v46, v47
	global_store_dwordx4 v[44:45], v[40:43], off
	v_pk_fma_f32 v[36:37], v[36:37], v[68:69], v[108:109]
	v_ashrrev_i32_e32 v81, 31, v80
	v_pk_fma_f32 v[40:41], v[34:35], v[66:67], v[106:107]
	v_pk_fma_f32 v[34:35], v[32:33], v[64:65], v[104:105]
	v_cvt_pk_bf16_f32 v32, v36, v37
	v_cvt_pk_bf16_f32 v33, v38, v39
	v_add_u32_e32 v82, 0xb0, v154
	v_cvt_pk_bf16_f32 v34, v34, v35
	v_cvt_pk_bf16_f32 v35, v40, v41
	global_store_dwordx4 v[44:45], v[32:35], off offset:256
	v_ashrrev_i32_e32 v83, 31, v82
	v_lshlrev_b64 v[48:49], 13, v[82:83]
	v_lshlrev_b64 v[32:33], 13, v[80:81]
	v_lshl_add_u64 v[44:45], v[156:157], 0, v[32:33]
	global_load_dwordx4 v[32:35], v[44:45], off offset:16
	global_load_dwordx4 v[36:39], v[44:45], off
	global_load_dwordx4 v[40:43], v[44:45], off offset:528
	s_nop 0
	global_load_dwordx4 v[44:47], v[44:45], off offset:512
	v_lshl_add_u64 v[60:61], v[156:157], 0, v[48:49]
	global_load_dwordx4 v[48:51], v[60:61], off offset:16
	global_load_dwordx4 v[52:55], v[60:61], off
	global_load_dwordx4 v[56:59], v[60:61], off offset:528
	s_nop 0
	global_load_dwordx4 v[60:63], v[60:61], off offset:512
	v_lshlrev_b64 v[80:81], 12, v[80:81]
	s_waitcnt vmcnt(0)
	v_pk_fma_f32 v[34:35], v[26:27], v[74:75], v[34:35]
	v_pk_fma_f32 v[28:29], v[28:29], v[76:77], v[36:37]
	v_pk_fma_f32 v[26:27], v[24:25], v[72:73], v[32:33]
	v_cvt_pk_bf16_f32 v24, v28, v29
	v_lshl_add_u64 v[28:29], s[2:3], 0, v[80:81]
	v_pk_fma_f32 v[30:31], v[30:31], v[78:79], v[38:39]
	v_lshl_add_u64 v[28:29], v[28:29], 0, v[136:137]
	v_cvt_pk_bf16_f32 v25, v30, v31
	v_pk_fma_f32 v[12:13], v[12:13], v[68:69], v[44:45]
	v_cvt_pk_bf16_f32 v26, v26, v27
	v_cvt_pk_bf16_f32 v27, v34, v35
	global_store_dwordx4 v[28:29], v[24:27], off
	v_pk_fma_f32 v[14:15], v[14:15], v[70:71], v[46:47]
	v_pk_fma_f32 v[16:17], v[16:17], v[72:73], v[48:49]
	v_pk_fma_f32 v[24:25], v[10:11], v[66:67], v[42:43]
	v_pk_fma_f32 v[10:11], v[8:9], v[64:65], v[40:41]
	v_cvt_pk_bf16_f32 v8, v12, v13
	v_cvt_pk_bf16_f32 v9, v14, v15
	v_lshlrev_b64 v[12:13], 12, v[82:83]
	v_cvt_pk_bf16_f32 v10, v10, v11
	v_cvt_pk_bf16_f32 v11, v24, v25
	global_store_dwordx4 v[28:29], v[8:11], off offset:256
	v_lshl_add_u64 v[12:13], s[2:3], 0, v[12:13]
	v_lshl_add_u64 v[12:13], v[12:13], 0, v[136:137]
	v_pk_fma_f32 v[8:9], v[20:21], v[76:77], v[52:53]
	v_pk_fma_f32 v[10:11], v[22:23], v[78:79], v[54:55]
	v_cvt_pk_bf16_f32 v8, v8, v9
	v_pk_fma_f32 v[14:15], v[18:19], v[74:75], v[50:51]
	v_cvt_pk_bf16_f32 v9, v10, v11
	v_cvt_pk_bf16_f32 v10, v16, v17
	v_pk_fma_f32 v[6:7], v[6:7], v[70:71], v[62:63]
	v_cvt_pk_bf16_f32 v11, v14, v15
	global_store_dwordx4 v[12:13], v[8:11], off
	v_pk_fma_f32 v[4:5], v[4:5], v[68:69], v[60:61]
	s_nop 0
	v_pk_fma_f32 v[8:9], v[2:3], v[66:67], v[58:59]
	v_pk_fma_f32 v[2:3], v[0:1], v[64:65], v[56:57]
	v_cvt_pk_bf16_f32 v0, v4, v5
	v_cvt_pk_bf16_f32 v1, v6, v7
	s_nop 0
	v_cvt_pk_bf16_f32 v2, v2, v3
	v_cvt_pk_bf16_f32 v3, v8, v9
	global_store_dwordx4 v[12:13], v[0:3], off offset:256
	s_cbranch_vccz .LBB0_287
	s_waitcnt vmcnt(0)
	s_cmpk_gt_u32 s25, 0xff
	s_cbranch_scc1 .LBB0_298
	s_barrier

.LBB0_414:
	s_ashr_i32 s9, s8, 31
	v_cmp_lt_i64_e32 vcc, s[10:11], v[202:203]
	s_lshl_b64 s[10:11], s[8:9], 20
	s_add_u32 s10, s24, s10
	s_addc_u32 s11, s25, s11
	s_and_b64 s[12:13], vcc, exec
	s_cselect_b32 s9, s11, s17
	s_cselect_b32 s38, s10, s16
	s_ashr_i32 s7, s6, 31
	s_lshl_b64 s[12:13], s[6:7], 20
	s_add_u32 s12, s26, s12
	s_addc_u32 s13, s27, s13
	s_and_b64 s[20:21], vcc, exec
	s_cselect_b32 s7, s13, s19
	s_cselect_b32 s39, s12, s18
	s_add_u32 s16, s16, 0x80080
	s_addc_u32 s17, s17, 0
	s_add_u32 s40, s18, 0x100
	s_addc_u32 s41, s19, 0
	s_mov_b32 s42, -2
	s_mov_b64 s[48:49], 0x80
	v_add_u32_e32 v196, 0x10000, v143
	s_add_u32 s18, s16, 0xfff80080
	s_addc_u32 s19, s17, -1
	s_add_i32 s43, 0, 0x10000
	ds_read_b128 v[146:149], v196 offset:0
	ds_read_b128 v[150:153], v196 offset:1024
	ds_read_b128 v[154:157], v196 offset:2048
	ds_read_b128 v[158:161], v196 offset:3072
	s_cmp_eq_u32 s42, 28
	s_cselect_b32 s21, s9, s19
	s_cselect_b32 s20, s38, s18
	s_cselect_b32 s19, s7, s41
	s_cselect_b32 s18, s39, s40
	s_add_i32 m0, s30, 0xc000
	ds_read_b128 v[162:165], v145
	ds_read_b128 v[166:169], v145 offset:1024
	ds_read_b128 v[170:173], v145 offset:2048
	ds_read_b128 v[174:177], v145 offset:3072
	ds_read_b128 v[178:181], v145 offset:4096
	ds_read_b128 v[182:185], v145 offset:5120
	ds_read_b128 v[186:189], v145 offset:6144
	ds_read_b128 v[204:207], v145 offset:7168
	global_load_lds_dwordx4 v136, s[16:17]
	s_add_i32 m0, s30, 0xe000
	s_nop 0
	global_load_lds_dwordx4 v138, s[16:17]
	s_waitcnt lgkmcnt(8)
	s_barrier
	s_waitcnt lgkmcnt(0)
	v_mfma_f32_16x16x32_bf16 v[124:127], v[146:149], v[162:165], 0
	v_mfma_f32_16x16x32_bf16 v[120:123], v[154:157], v[162:165], 0
	v_mfma_f32_16x16x32_bf16 v[116:119], v[146:149], v[170:173], 0
	v_mfma_f32_16x16x32_bf16 v[108:111], v[154:157], v[170:173], 0
	s_add_i32 s46, 0, 0x14000
	s_add_i32 s43, s43, s28
	v_mfma_f32_16x16x32_bf16 v[100:103], v[146:149], v[178:181], 0
	s_mov_b32 m0, s43
	v_mfma_f32_16x16x32_bf16 v[92:95], v[154:157], v[178:181], 0
	v_mfma_f32_16x16x32_bf16 v[84:87], v[146:149], v[186:189], 0
	v_mfma_f32_16x16x32_bf16 v[76:79], v[154:157], v[186:189], 0
	v_mfma_f32_16x16x32_bf16 v[124:127], v[150:153], v[166:169], v[124:127]
	v_mfma_f32_16x16x32_bf16 v[120:123], v[158:161], v[166:169], v[120:123]
	v_mfma_f32_16x16x32_bf16 v[116:119], v[150:153], v[174:177], v[116:119]
	v_mfma_f32_16x16x32_bf16 v[108:111], v[158:161], v[174:177], v[108:111]
	v_mfma_f32_16x16x32_bf16 v[100:103], v[150:153], v[182:185], v[100:103]
	v_mfma_f32_16x16x32_bf16 v[92:95], v[158:161], v[182:185], v[92:95]
	v_mfma_f32_16x16x32_bf16 v[84:87], v[150:153], v[204:207], v[84:87]
	v_mfma_f32_16x16x32_bf16 v[76:79], v[158:161], v[204:207], v[76:79]
	s_barrier
	ds_read_b128 v[208:211], v196 offset:16384
	ds_read_b128 v[214:217], v196 offset:17408
	ds_read_b128 v[218:221], v196 offset:18432
	ds_read_b128 v[222:225], v196 offset:19456
	global_load_lds_dwordx4 v192, s[18:19]
	s_add_i32 m0, s43, 0x2000
	s_nop 0
	global_load_lds_dwordx4 v128, s[18:19]
	s_barrier
	s_waitcnt lgkmcnt(0)
	v_mfma_f32_16x16x32_bf16 v[112:115], v[208:211], v[162:165], 0
	v_mfma_f32_16x16x32_bf16 v[104:107], v[218:221], v[162:165], 0
	v_mfma_f32_16x16x32_bf16 v[96:99], v[208:211], v[170:173], 0
	v_mfma_f32_16x16x32_bf16 v[88:91], v[218:221], v[170:173], 0
	s_mov_b32 m0, s30
	v_mfma_f32_16x16x32_bf16 v[80:83], v[208:211], v[178:181], 0
	s_add_u32 s48, s20, 0x80
	s_addc_u32 s49, s21, 0
	v_mfma_f32_16x16x32_bf16 v[72:75], v[218:221], v[178:181], 0
	v_mfma_f32_16x16x32_bf16 v[68:71], v[208:211], v[186:189], 0
	v_mfma_f32_16x16x32_bf16 v[64:67], v[218:221], v[186:189], 0
	v_mfma_f32_16x16x32_bf16 v[112:115], v[214:217], v[166:169], v[112:115]
	v_mfma_f32_16x16x32_bf16 v[104:107], v[222:225], v[166:169], v[104:107]
	v_mfma_f32_16x16x32_bf16 v[96:99], v[214:217], v[174:177], v[96:99]
	v_mfma_f32_16x16x32_bf16 v[88:91], v[222:225], v[174:177], v[88:91]
	v_mfma_f32_16x16x32_bf16 v[80:83], v[214:217], v[182:185], v[80:83]
	v_mfma_f32_16x16x32_bf16 v[72:75], v[222:225], v[182:185], v[72:75]
	v_mfma_f32_16x16x32_bf16 v[68:71], v[214:217], v[204:207], v[68:71]
	v_mfma_f32_16x16x32_bf16 v[64:67], v[222:225], v[204:207], v[64:67]
	s_barrier
	ds_read_b128 v[162:165], v145 offset:16384
	ds_read_b128 v[166:169], v145 offset:17408
	ds_read_b128 v[170:173], v145 offset:18432
	ds_read_b128 v[174:177], v145 offset:19456
	ds_read_b128 v[178:181], v145 offset:20480
	ds_read_b128 v[182:185], v145 offset:21504
	ds_read_b128 v[186:189], v145 offset:22528
	ds_read_b128 v[204:207], v145 offset:23552
	global_load_lds_dwordx4 v132, s[20:21]
	s_mov_b32 m0, s31
	s_nop 0
	global_load_lds_dwordx4 v130, s[20:21]
	s_waitcnt lgkmcnt(0)
	s_barrier
	v_mfma_f32_16x16x32_bf16 v[60:63], v[146:149], v[162:165], 0
	v_mfma_f32_16x16x32_bf16 v[56:59], v[154:157], v[162:165], 0
	v_mfma_f32_16x16x32_bf16 v[52:55], v[146:149], v[170:173], 0
	v_mfma_f32_16x16x32_bf16 v[44:47], v[154:157], v[170:173], 0
	s_add_u32 s44, s18, 0x80000
	s_addc_u32 s45, s19, 0
	v_mfma_f32_16x16x32_bf16 v[36:39], v[146:149], v[178:181], 0
	s_add_i32 s43, s46, s28
	s_mov_b32 m0, s43
	v_mfma_f32_16x16x32_bf16 v[28:31], v[154:157], v[178:181], 0
	v_mfma_f32_16x16x32_bf16 v[20:23], v[146:149], v[186:189], 0
	v_mfma_f32_16x16x32_bf16 v[12:15], v[154:157], v[186:189], 0
	v_mfma_f32_16x16x32_bf16 v[60:63], v[150:153], v[166:169], v[60:63]
	v_mfma_f32_16x16x32_bf16 v[56:59], v[158:161], v[166:169], v[56:59]
	v_mfma_f32_16x16x32_bf16 v[52:55], v[150:153], v[174:177], v[52:55]
	v_mfma_f32_16x16x32_bf16 v[44:47], v[158:161], v[174:177], v[44:47]
	v_mfma_f32_16x16x32_bf16 v[36:39], v[150:153], v[182:185], v[36:39]
	v_mfma_f32_16x16x32_bf16 v[28:31], v[158:161], v[182:185], v[28:31]
	v_mfma_f32_16x16x32_bf16 v[20:23], v[150:153], v[204:207], v[20:23]
	v_mfma_f32_16x16x32_bf16 v[12:15], v[158:161], v[204:207], v[12:15]
	s_barrier
	global_load_lds_dwordx4 v192, s[44:45]
	s_add_i32 m0, s43, 0x2000
	s_nop 0
	global_load_lds_dwordx4 v128, s[44:45]
	s_add_u32 s20, s20, 0x80000
	s_addc_u32 s21, s21, 0
	s_mov_b32 m0, s33
	s_nop 0
	global_load_lds_dwordx4 v132, s[20:21]
	s_mov_b32 m0, s34
	s_nop 0
	global_load_lds_dwordx4 v130, s[20:21]
	s_waitcnt vmcnt(8)
	s_barrier
	v_mfma_f32_16x16x32_bf16 v[48:51], v[208:211], v[162:165], 0
	v_mfma_f32_16x16x32_bf16 v[40:43], v[218:221], v[162:165], 0
	v_mfma_f32_16x16x32_bf16 v[32:35], v[208:211], v[170:173], 0
	v_mfma_f32_16x16x32_bf16 v[24:27], v[218:221], v[170:173], 0
	s_add_i32 s43, 0, 0x18000
	v_mfma_f32_16x16x32_bf16 v[16:19], v[208:211], v[178:181], 0
	v_mfma_f32_16x16x32_bf16 v[8:11], v[218:221], v[178:181], 0
	v_mfma_f32_16x16x32_bf16 v[4:7], v[208:211], v[186:189], 0
	v_mfma_f32_16x16x32_bf16 v[0:3], v[218:221], v[186:189], 0
	v_mfma_f32_16x16x32_bf16 v[48:51], v[214:217], v[166:169], v[48:51]
	v_mfma_f32_16x16x32_bf16 v[40:43], v[222:225], v[166:169], v[40:43]
	v_mfma_f32_16x16x32_bf16 v[32:35], v[214:217], v[174:177], v[32:35]
	v_mfma_f32_16x16x32_bf16 v[24:27], v[222:225], v[174:177], v[24:27]
	v_mfma_f32_16x16x32_bf16 v[16:19], v[214:217], v[182:185], v[16:19]
	v_mfma_f32_16x16x32_bf16 v[8:11], v[222:225], v[182:185], v[8:11]
	v_mfma_f32_16x16x32_bf16 v[4:7], v[214:217], v[204:207], v[4:7]
	v_mfma_f32_16x16x32_bf16 v[0:3], v[222:225], v[204:207], v[0:3]
	s_barrier
	ds_read_b128 v[146:149], v196 offset:32768
	ds_read_b128 v[150:153], v196 offset:33792
	ds_read_b128 v[154:157], v196 offset:34816
	ds_read_b128 v[158:161], v196 offset:35840
	ds_read_b128 v[162:165], v145 offset:32768
	ds_read_b128 v[166:169], v145 offset:33792
	ds_read_b128 v[170:173], v145 offset:34816
	ds_read_b128 v[174:177], v145 offset:35840
	ds_read_b128 v[178:181], v145 offset:36864
	ds_read_b128 v[182:185], v145 offset:37888
	ds_read_b128 v[186:189], v145 offset:38912
	ds_read_b128 v[204:207], v145 offset:39936
	s_waitcnt lgkmcnt(8)
	s_barrier
	s_waitcnt lgkmcnt(0)
	v_mfma_f32_16x16x32_bf16 v[124:127], v[146:149], v[162:165], v[124:127]
	v_mfma_f32_16x16x32_bf16 v[120:123], v[154:157], v[162:165], v[120:123]
	v_mfma_f32_16x16x32_bf16 v[116:119], v[146:149], v[170:173], v[116:119]
	v_mfma_f32_16x16x32_bf16 v[108:111], v[154:157], v[170:173], v[108:111]
	s_add_i32 s20, 0, 0x1c000
	s_add_i32 s21, s43, s28
	v_mfma_f32_16x16x32_bf16 v[100:103], v[146:149], v[178:181], v[100:103]
	s_add_i32 m0, s21, 0xffffff80
	v_mfma_f32_16x16x32_bf16 v[92:95], v[154:157], v[178:181], v[92:95]
	v_mfma_f32_16x16x32_bf16 v[84:87], v[146:149], v[186:189], v[84:87]
	v_mfma_f32_16x16x32_bf16 v[76:79], v[154:157], v[186:189], v[76:79]
	v_mfma_f32_16x16x32_bf16 v[124:127], v[150:153], v[166:169], v[124:127]
	v_mfma_f32_16x16x32_bf16 v[120:123], v[158:161], v[166:169], v[120:123]
	v_mfma_f32_16x16x32_bf16 v[116:119], v[150:153], v[174:177], v[116:119]
	v_mfma_f32_16x16x32_bf16 v[108:111], v[158:161], v[174:177], v[108:111]
	v_mfma_f32_16x16x32_bf16 v[100:103], v[150:153], v[182:185], v[100:103]
	v_mfma_f32_16x16x32_bf16 v[92:95], v[158:161], v[182:185], v[92:95]
	v_mfma_f32_16x16x32_bf16 v[84:87], v[150:153], v[204:207], v[84:87]
	v_mfma_f32_16x16x32_bf16 v[76:79], v[158:161], v[204:207], v[76:79]
	s_barrier
	ds_read_b128 v[208:211], v196 offset:49152
	ds_read_b128 v[214:217], v196 offset:50176
	ds_read_b128 v[218:221], v196 offset:51200
	ds_read_b128 v[222:225], v196 offset:52224
	global_load_lds_dwordx4 v192, s[18:19] offset:128
	s_add_i32 m0, s21, 0x1f80
	s_nop 0
	global_load_lds_dwordx4 v128, s[18:19] offset:128
	s_barrier
	s_waitcnt lgkmcnt(0)
	v_mfma_f32_16x16x32_bf16 v[112:115], v[208:211], v[162:165], v[112:115]
	v_mfma_f32_16x16x32_bf16 v[104:107], v[218:221], v[162:165], v[104:107]
	v_mfma_f32_16x16x32_bf16 v[96:99], v[208:211], v[170:173], v[96:99]
	v_mfma_f32_16x16x32_bf16 v[88:91], v[218:221], v[170:173], v[88:91]
	s_mov_b32 m0, s35
	v_mfma_f32_16x16x32_bf16 v[80:83], v[208:211], v[178:181], v[80:83]
	v_mfma_f32_16x16x32_bf16 v[72:75], v[218:221], v[178:181], v[72:75]
	v_mfma_f32_16x16x32_bf16 v[68:71], v[208:211], v[186:189], v[68:71]
	v_mfma_f32_16x16x32_bf16 v[64:67], v[218:221], v[186:189], v[64:67]
	v_mfma_f32_16x16x32_bf16 v[112:115], v[214:217], v[166:169], v[112:115]
	v_mfma_f32_16x16x32_bf16 v[104:107], v[222:225], v[166:169], v[104:107]
	v_mfma_f32_16x16x32_bf16 v[96:99], v[214:217], v[174:177], v[96:99]
	v_mfma_f32_16x16x32_bf16 v[88:91], v[222:225], v[174:177], v[88:91]
	v_mfma_f32_16x16x32_bf16 v[80:83], v[214:217], v[182:185], v[80:83]
	v_mfma_f32_16x16x32_bf16 v[72:75], v[222:225], v[182:185], v[72:75]
	v_mfma_f32_16x16x32_bf16 v[68:71], v[214:217], v[204:207], v[68:71]
	v_mfma_f32_16x16x32_bf16 v[64:67], v[222:225], v[204:207], v[64:67]
	s_barrier
	ds_read_b128 v[162:165], v145 offset:49152
	ds_read_b128 v[166:169], v145 offset:50176
	ds_read_b128 v[170:173], v145 offset:51200
	ds_read_b128 v[174:177], v145 offset:52224
	ds_read_b128 v[178:181], v145 offset:53248
	ds_read_b128 v[182:185], v145 offset:54272
	ds_read_b128 v[186:189], v145 offset:55296
	ds_read_b128 v[204:207], v145 offset:56320
	global_load_lds_dwordx4 v132, s[48:49]
	s_mov_b32 m0, s36
	s_nop 0
	global_load_lds_dwordx4 v130, s[48:49]
	s_barrier
	s_waitcnt lgkmcnt(0)
	v_mfma_f32_16x16x32_bf16 v[60:63], v[146:149], v[162:165], v[60:63]
	v_mfma_f32_16x16x32_bf16 v[56:59], v[154:157], v[162:165], v[56:59]
	v_mfma_f32_16x16x32_bf16 v[52:55], v[146:149], v[170:173], v[52:55]
	v_mfma_f32_16x16x32_bf16 v[44:47], v[154:157], v[170:173], v[44:47]
	s_add_u32 s18, s18, 0x80080
	s_addc_u32 s19, s19, 0
	v_mfma_f32_16x16x32_bf16 v[36:39], v[146:149], v[178:181], v[36:39]
	s_add_i32 s20, s20, s28
	s_mov_b32 m0, s20
	v_mfma_f32_16x16x32_bf16 v[28:31], v[154:157], v[178:181], v[28:31]
	v_mfma_f32_16x16x32_bf16 v[20:23], v[146:149], v[186:189], v[20:23]
	v_mfma_f32_16x16x32_bf16 v[12:15], v[154:157], v[186:189], v[12:15]
	v_mfma_f32_16x16x32_bf16 v[60:63], v[150:153], v[166:169], v[60:63]
	v_mfma_f32_16x16x32_bf16 v[56:59], v[158:161], v[166:169], v[56:59]
	v_mfma_f32_16x16x32_bf16 v[52:55], v[150:153], v[174:177], v[52:55]
	v_mfma_f32_16x16x32_bf16 v[44:47], v[158:161], v[174:177], v[44:47]
	v_mfma_f32_16x16x32_bf16 v[36:39], v[150:153], v[182:185], v[36:39]
	v_mfma_f32_16x16x32_bf16 v[28:31], v[158:161], v[182:185], v[28:31]
	v_mfma_f32_16x16x32_bf16 v[20:23], v[150:153], v[204:207], v[20:23]
	v_mfma_f32_16x16x32_bf16 v[12:15], v[158:161], v[204:207], v[12:15]
	s_barrier
	global_load_lds_dwordx4 v192, s[18:19]
	s_add_i32 m0, s20, 0x2000
	s_nop 0
	global_load_lds_dwordx4 v128, s[18:19]
	s_waitcnt vmcnt(6)
	s_barrier
	v_mfma_f32_16x16x32_bf16 v[48:51], v[208:211], v[162:165], v[48:51]
	v_mfma_f32_16x16x32_bf16 v[40:43], v[218:221], v[162:165], v[40:43]
	v_mfma_f32_16x16x32_bf16 v[32:35], v[208:211], v[170:173], v[32:35]
	v_mfma_f32_16x16x32_bf16 v[24:27], v[218:221], v[170:173], v[24:27]
	s_add_i32 s42, s42, 2
	v_mfma_f32_16x16x32_bf16 v[16:19], v[208:211], v[178:181], v[16:19]
	s_add_u32 s16, s16, 0x100
	s_addc_u32 s17, s17, 0
	v_mfma_f32_16x16x32_bf16 v[8:11], v[218:221], v[178:181], v[8:11]
	s_add_u32 s40, s40, 0x100
	s_addc_u32 s41, s41, 0
	v_mfma_f32_16x16x32_bf16 v[4:7], v[208:211], v[186:189], v[4:7]
	s_add_u32 s18, s16, 0xfff80080
	s_addc_u32 s19, s17, -1
	v_mfma_f32_16x16x32_bf16 v[0:3], v[218:221], v[186:189], v[0:3]
	s_add_i32 s43, 0, 0x10000
	s_cmp_eq_u32 s42, 28
	v_mfma_f32_16x16x32_bf16 v[48:51], v[214:217], v[166:169], v[48:51]
	s_cselect_b32 s21, s9, s19
	s_cselect_b32 s20, s38, s18
	v_mfma_f32_16x16x32_bf16 v[40:43], v[222:225], v[166:169], v[40:43]
	s_cselect_b32 s19, s7, s41
	s_cselect_b32 s18, s39, s40
	v_mfma_f32_16x16x32_bf16 v[32:35], v[214:217], v[174:177], v[32:35]
	s_add_i32 m0, s30, 0xc000
	v_mfma_f32_16x16x32_bf16 v[24:27], v[222:225], v[174:177], v[24:27]
	v_mfma_f32_16x16x32_bf16 v[16:19], v[214:217], v[182:185], v[16:19]
	v_mfma_f32_16x16x32_bf16 v[8:11], v[222:225], v[182:185], v[8:11]
	v_mfma_f32_16x16x32_bf16 v[4:7], v[214:217], v[204:207], v[4:7]
	v_mfma_f32_16x16x32_bf16 v[0:3], v[222:225], v[204:207], v[0:3]
	s_cmp_gt_u32 s42, 29
	s_barrier
.LBB0_415:
	ds_read_b128 v[146:149], v196 offset:0
	ds_read_b128 v[150:153], v196 offset:1024
	ds_read_b128 v[154:157], v196 offset:2048
	ds_read_b128 v[158:161], v196 offset:3072
	ds_read_b128 v[162:165], v145
	ds_read_b128 v[166:169], v145 offset:1024
	ds_read_b128 v[170:173], v145 offset:2048
	ds_read_b128 v[174:177], v145 offset:3072
	ds_read_b128 v[178:181], v145 offset:4096
	ds_read_b128 v[182:185], v145 offset:5120
	ds_read_b128 v[186:189], v145 offset:6144
	ds_read_b128 v[204:207], v145 offset:7168
	global_load_lds_dwordx4 v136, s[16:17]
	s_add_i32 m0, s30, 0xe000
	s_nop 0
	global_load_lds_dwordx4 v138, s[16:17]
	s_waitcnt lgkmcnt(8)
	s_barrier
	s_waitcnt lgkmcnt(0)
	v_mfma_f32_16x16x32_bf16 v[124:127], v[146:149], v[162:165], v[124:127]
	v_mfma_f32_16x16x32_bf16 v[120:123], v[154:157], v[162:165], v[120:123]
	v_mfma_f32_16x16x32_bf16 v[116:119], v[146:149], v[170:173], v[116:119]
	v_mfma_f32_16x16x32_bf16 v[108:111], v[154:157], v[170:173], v[108:111]
	s_add_i32 s46, 0, 0x14000
	s_add_i32 s43, s43, s28
	v_mfma_f32_16x16x32_bf16 v[100:103], v[146:149], v[178:181], v[100:103]
	s_mov_b32 m0, s43
	v_mfma_f32_16x16x32_bf16 v[92:95], v[154:157], v[178:181], v[92:95]
	v_mfma_f32_16x16x32_bf16 v[84:87], v[146:149], v[186:189], v[84:87]
	v_mfma_f32_16x16x32_bf16 v[76:79], v[154:157], v[186:189], v[76:79]
	v_mfma_f32_16x16x32_bf16 v[124:127], v[150:153], v[166:169], v[124:127]
	v_mfma_f32_16x16x32_bf16 v[120:123], v[158:161], v[166:169], v[120:123]
	v_mfma_f32_16x16x32_bf16 v[116:119], v[150:153], v[174:177], v[116:119]
	v_mfma_f32_16x16x32_bf16 v[108:111], v[158:161], v[174:177], v[108:111]
	v_mfma_f32_16x16x32_bf16 v[100:103], v[150:153], v[182:185], v[100:103]
	v_mfma_f32_16x16x32_bf16 v[92:95], v[158:161], v[182:185], v[92:95]
	v_mfma_f32_16x16x32_bf16 v[84:87], v[150:153], v[204:207], v[84:87]
	v_mfma_f32_16x16x32_bf16 v[76:79], v[158:161], v[204:207], v[76:79]
	s_barrier
	ds_read_b128 v[208:211], v196 offset:16384
	ds_read_b128 v[214:217], v196 offset:17408
	ds_read_b128 v[218:221], v196 offset:18432
	ds_read_b128 v[222:225], v196 offset:19456
	global_load_lds_dwordx4 v192, s[18:19]
	s_add_i32 m0, s43, 0x2000
	s_nop 0
	global_load_lds_dwordx4 v128, s[18:19]
	s_barrier
	s_waitcnt lgkmcnt(0)
	v_mfma_f32_16x16x32_bf16 v[112:115], v[208:211], v[162:165], v[112:115]
	v_mfma_f32_16x16x32_bf16 v[104:107], v[218:221], v[162:165], v[104:107]
	v_mfma_f32_16x16x32_bf16 v[96:99], v[208:211], v[170:173], v[96:99]
	v_mfma_f32_16x16x32_bf16 v[88:91], v[218:221], v[170:173], v[88:91]
	s_mov_b32 m0, s30
	v_mfma_f32_16x16x32_bf16 v[80:83], v[208:211], v[178:181], v[80:83]
	s_add_u32 s48, s20, 0x80
	s_addc_u32 s49, s21, 0
	v_mfma_f32_16x16x32_bf16 v[72:75], v[218:221], v[178:181], v[72:75]
	v_mfma_f32_16x16x32_bf16 v[68:71], v[208:211], v[186:189], v[68:71]
	v_mfma_f32_16x16x32_bf16 v[64:67], v[218:221], v[186:189], v[64:67]
	v_mfma_f32_16x16x32_bf16 v[112:115], v[214:217], v[166:169], v[112:115]
	v_mfma_f32_16x16x32_bf16 v[104:107], v[222:225], v[166:169], v[104:107]
	v_mfma_f32_16x16x32_bf16 v[96:99], v[214:217], v[174:177], v[96:99]
	v_mfma_f32_16x16x32_bf16 v[88:91], v[222:225], v[174:177], v[88:91]
	v_mfma_f32_16x16x32_bf16 v[80:83], v[214:217], v[182:185], v[80:83]
	v_mfma_f32_16x16x32_bf16 v[72:75], v[222:225], v[182:185], v[72:75]
	v_mfma_f32_16x16x32_bf16 v[68:71], v[214:217], v[204:207], v[68:71]
	v_mfma_f32_16x16x32_bf16 v[64:67], v[222:225], v[204:207], v[64:67]
	s_barrier
	ds_read_b128 v[162:165], v145 offset:16384
	ds_read_b128 v[166:169], v145 offset:17408
	ds_read_b128 v[170:173], v145 offset:18432
	ds_read_b128 v[174:177], v145 offset:19456
	ds_read_b128 v[178:181], v145 offset:20480
	ds_read_b128 v[182:185], v145 offset:21504
	ds_read_b128 v[186:189], v145 offset:22528
	ds_read_b128 v[204:207], v145 offset:23552
	global_load_lds_dwordx4 v132, s[20:21]
	s_mov_b32 m0, s31
	s_nop 0
	global_load_lds_dwordx4 v130, s[20:21]
	s_waitcnt lgkmcnt(0)
	s_barrier
	v_mfma_f32_16x16x32_bf16 v[60:63], v[146:149], v[162:165], v[60:63]
	v_mfma_f32_16x16x32_bf16 v[56:59], v[154:157], v[162:165], v[56:59]
	v_mfma_f32_16x16x32_bf16 v[52:55], v[146:149], v[170:173], v[52:55]
	v_mfma_f32_16x16x32_bf16 v[44:47], v[154:157], v[170:173], v[44:47]
	s_add_u32 s44, s18, 0x80000
	s_addc_u32 s45, s19, 0
	v_mfma_f32_16x16x32_bf16 v[36:39], v[146:149], v[178:181], v[36:39]
	s_add_i32 s43, s46, s28
	s_mov_b32 m0, s43
	v_mfma_f32_16x16x32_bf16 v[28:31], v[154:157], v[178:181], v[28:31]
	v_mfma_f32_16x16x32_bf16 v[20:23], v[146:149], v[186:189], v[20:23]
	v_mfma_f32_16x16x32_bf16 v[12:15], v[154:157], v[186:189], v[12:15]
	v_mfma_f32_16x16x32_bf16 v[60:63], v[150:153], v[166:169], v[60:63]
	v_mfma_f32_16x16x32_bf16 v[56:59], v[158:161], v[166:169], v[56:59]
	v_mfma_f32_16x16x32_bf16 v[52:55], v[150:153], v[174:177], v[52:55]
	v_mfma_f32_16x16x32_bf16 v[44:47], v[158:161], v[174:177], v[44:47]
	v_mfma_f32_16x16x32_bf16 v[36:39], v[150:153], v[182:185], v[36:39]
	v_mfma_f32_16x16x32_bf16 v[28:31], v[158:161], v[182:185], v[28:31]
	v_mfma_f32_16x16x32_bf16 v[20:23], v[150:153], v[204:207], v[20:23]
	v_mfma_f32_16x16x32_bf16 v[12:15], v[158:161], v[204:207], v[12:15]
	s_barrier
	global_load_lds_dwordx4 v192, s[44:45]
	s_add_i32 m0, s43, 0x2000
	s_nop 0
	global_load_lds_dwordx4 v128, s[44:45]
	s_add_u32 s20, s20, 0x80000
	s_addc_u32 s21, s21, 0
	s_mov_b32 m0, s33
	s_nop 0
	global_load_lds_dwordx4 v132, s[20:21]
	s_mov_b32 m0, s34
	s_nop 0
	global_load_lds_dwordx4 v130, s[20:21]
	s_waitcnt vmcnt(8)
	s_barrier
	v_mfma_f32_16x16x32_bf16 v[48:51], v[208:211], v[162:165], v[48:51]
	v_mfma_f32_16x16x32_bf16 v[40:43], v[218:221], v[162:165], v[40:43]
	v_mfma_f32_16x16x32_bf16 v[32:35], v[208:211], v[170:173], v[32:35]
	v_mfma_f32_16x16x32_bf16 v[24:27], v[218:221], v[170:173], v[24:27]
	s_add_i32 s43, 0, 0x18000
	v_mfma_f32_16x16x32_bf16 v[16:19], v[208:211], v[178:181], v[16:19]
	v_mfma_f32_16x16x32_bf16 v[8:11], v[218:221], v[178:181], v[8:11]
	v_mfma_f32_16x16x32_bf16 v[4:7], v[208:211], v[186:189], v[4:7]
	v_mfma_f32_16x16x32_bf16 v[0:3], v[218:221], v[186:189], v[0:3]
	v_mfma_f32_16x16x32_bf16 v[48:51], v[214:217], v[166:169], v[48:51]
	v_mfma_f32_16x16x32_bf16 v[40:43], v[222:225], v[166:169], v[40:43]
	v_mfma_f32_16x16x32_bf16 v[32:35], v[214:217], v[174:177], v[32:35]
	v_mfma_f32_16x16x32_bf16 v[24:27], v[222:225], v[174:177], v[24:27]
	v_mfma_f32_16x16x32_bf16 v[16:19], v[214:217], v[182:185], v[16:19]
	v_mfma_f32_16x16x32_bf16 v[8:11], v[222:225], v[182:185], v[8:11]
	v_mfma_f32_16x16x32_bf16 v[4:7], v[214:217], v[204:207], v[4:7]
	v_mfma_f32_16x16x32_bf16 v[0:3], v[222:225], v[204:207], v[0:3]
	s_barrier
	ds_read_b128 v[146:149], v196 offset:32768
	ds_read_b128 v[150:153], v196 offset:33792
	ds_read_b128 v[154:157], v196 offset:34816
	ds_read_b128 v[158:161], v196 offset:35840
	ds_read_b128 v[162:165], v145 offset:32768
	ds_read_b128 v[166:169], v145 offset:33792
	ds_read_b128 v[170:173], v145 offset:34816
	ds_read_b128 v[174:177], v145 offset:35840
	ds_read_b128 v[178:181], v145 offset:36864
	ds_read_b128 v[182:185], v145 offset:37888
	ds_read_b128 v[186:189], v145 offset:38912
	ds_read_b128 v[204:207], v145 offset:39936
	s_waitcnt lgkmcnt(8)
	s_barrier
	s_waitcnt lgkmcnt(0)
	v_mfma_f32_16x16x32_bf16 v[124:127], v[146:149], v[162:165], v[124:127]
	v_mfma_f32_16x16x32_bf16 v[120:123], v[154:157], v[162:165], v[120:123]
	v_mfma_f32_16x16x32_bf16 v[116:119], v[146:149], v[170:173], v[116:119]
	v_mfma_f32_16x16x32_bf16 v[108:111], v[154:157], v[170:173], v[108:111]
	s_add_i32 s20, 0, 0x1c000
	s_add_i32 s21, s43, s28
	v_mfma_f32_16x16x32_bf16 v[100:103], v[146:149], v[178:181], v[100:103]
	s_add_i32 m0, s21, 0xffffff80
	v_mfma_f32_16x16x32_bf16 v[92:95], v[154:157], v[178:181], v[92:95]
	v_mfma_f32_16x16x32_bf16 v[84:87], v[146:149], v[186:189], v[84:87]
	v_mfma_f32_16x16x32_bf16 v[76:79], v[154:157], v[186:189], v[76:79]
	v_mfma_f32_16x16x32_bf16 v[124:127], v[150:153], v[166:169], v[124:127]
	v_mfma_f32_16x16x32_bf16 v[120:123], v[158:161], v[166:169], v[120:123]
	v_mfma_f32_16x16x32_bf16 v[116:119], v[150:153], v[174:177], v[116:119]
	v_mfma_f32_16x16x32_bf16 v[108:111], v[158:161], v[174:177], v[108:111]
	v_mfma_f32_16x16x32_bf16 v[100:103], v[150:153], v[182:185], v[100:103]
	v_mfma_f32_16x16x32_bf16 v[92:95], v[158:161], v[182:185], v[92:95]
	v_mfma_f32_16x16x32_bf16 v[84:87], v[150:153], v[204:207], v[84:87]
	v_mfma_f32_16x16x32_bf16 v[76:79], v[158:161], v[204:207], v[76:79]
	s_barrier
	ds_read_b128 v[208:211], v196 offset:49152
	ds_read_b128 v[214:217], v196 offset:50176
	ds_read_b128 v[218:221], v196 offset:51200
	ds_read_b128 v[222:225], v196 offset:52224
	global_load_lds_dwordx4 v192, s[18:19] offset:128
	s_add_i32 m0, s21, 0x1f80
	s_nop 0
	global_load_lds_dwordx4 v128, s[18:19] offset:128
	s_barrier
	s_waitcnt lgkmcnt(0)
	v_mfma_f32_16x16x32_bf16 v[112:115], v[208:211], v[162:165], v[112:115]
	v_mfma_f32_16x16x32_bf16 v[104:107], v[218:221], v[162:165], v[104:107]
	v_mfma_f32_16x16x32_bf16 v[96:99], v[208:211], v[170:173], v[96:99]
	v_mfma_f32_16x16x32_bf16 v[88:91], v[218:221], v[170:173], v[88:91]
	s_mov_b32 m0, s35
	v_mfma_f32_16x16x32_bf16 v[80:83], v[208:211], v[178:181], v[80:83]
	v_mfma_f32_16x16x32_bf16 v[72:75], v[218:221], v[178:181], v[72:75]
	v_mfma_f32_16x16x32_bf16 v[68:71], v[208:211], v[186:189], v[68:71]
	v_mfma_f32_16x16x32_bf16 v[64:67], v[218:221], v[186:189], v[64:67]
	v_mfma_f32_16x16x32_bf16 v[112:115], v[214:217], v[166:169], v[112:115]
	v_mfma_f32_16x16x32_bf16 v[104:107], v[222:225], v[166:169], v[104:107]
	v_mfma_f32_16x16x32_bf16 v[96:99], v[214:217], v[174:177], v[96:99]
	v_mfma_f32_16x16x32_bf16 v[88:91], v[222:225], v[174:177], v[88:91]
	v_mfma_f32_16x16x32_bf16 v[80:83], v[214:217], v[182:185], v[80:83]
	v_mfma_f32_16x16x32_bf16 v[72:75], v[222:225], v[182:185], v[72:75]
	v_mfma_f32_16x16x32_bf16 v[68:71], v[214:217], v[204:207], v[68:71]
	v_mfma_f32_16x16x32_bf16 v[64:67], v[222:225], v[204:207], v[64:67]
	s_barrier
	ds_read_b128 v[162:165], v145 offset:49152
	ds_read_b128 v[166:169], v145 offset:50176
	ds_read_b128 v[170:173], v145 offset:51200
	ds_read_b128 v[174:177], v145 offset:52224
	ds_read_b128 v[178:181], v145 offset:53248
	ds_read_b128 v[182:185], v145 offset:54272
	ds_read_b128 v[186:189], v145 offset:55296
	ds_read_b128 v[204:207], v145 offset:56320
	global_load_lds_dwordx4 v132, s[48:49]
	s_mov_b32 m0, s36
	s_nop 0
	global_load_lds_dwordx4 v130, s[48:49]
	s_barrier
	s_waitcnt lgkmcnt(0)
	v_mfma_f32_16x16x32_bf16 v[60:63], v[146:149], v[162:165], v[60:63]
	v_mfma_f32_16x16x32_bf16 v[56:59], v[154:157], v[162:165], v[56:59]
	v_mfma_f32_16x16x32_bf16 v[52:55], v[146:149], v[170:173], v[52:55]
	v_mfma_f32_16x16x32_bf16 v[44:47], v[154:157], v[170:173], v[44:47]
	s_add_u32 s18, s18, 0x80080
	s_addc_u32 s19, s19, 0
	v_mfma_f32_16x16x32_bf16 v[36:39], v[146:149], v[178:181], v[36:39]
	s_add_i32 s20, s20, s28
	s_mov_b32 m0, s20
	v_mfma_f32_16x16x32_bf16 v[28:31], v[154:157], v[178:181], v[28:31]
	v_mfma_f32_16x16x32_bf16 v[20:23], v[146:149], v[186:189], v[20:23]
	v_mfma_f32_16x16x32_bf16 v[12:15], v[154:157], v[186:189], v[12:15]
	v_mfma_f32_16x16x32_bf16 v[60:63], v[150:153], v[166:169], v[60:63]
	v_mfma_f32_16x16x32_bf16 v[56:59], v[158:161], v[166:169], v[56:59]
	v_mfma_f32_16x16x32_bf16 v[52:55], v[150:153], v[174:177], v[52:55]
	v_mfma_f32_16x16x32_bf16 v[44:47], v[158:161], v[174:177], v[44:47]
	v_mfma_f32_16x16x32_bf16 v[36:39], v[150:153], v[182:185], v[36:39]
	v_mfma_f32_16x16x32_bf16 v[28:31], v[158:161], v[182:185], v[28:31]
	v_mfma_f32_16x16x32_bf16 v[20:23], v[150:153], v[204:207], v[20:23]
	v_mfma_f32_16x16x32_bf16 v[12:15], v[158:161], v[204:207], v[12:15]
	s_barrier
	global_load_lds_dwordx4 v192, s[18:19]
	s_add_i32 m0, s20, 0x2000
	s_nop 0
	global_load_lds_dwordx4 v128, s[18:19]
	s_waitcnt vmcnt(6)
	s_barrier
	v_mfma_f32_16x16x32_bf16 v[48:51], v[208:211], v[162:165], v[48:51]
	v_mfma_f32_16x16x32_bf16 v[40:43], v[218:221], v[162:165], v[40:43]
	v_mfma_f32_16x16x32_bf16 v[32:35], v[208:211], v[170:173], v[32:35]
	v_mfma_f32_16x16x32_bf16 v[24:27], v[218:221], v[170:173], v[24:27]
	s_add_i32 s42, s42, 2
	v_mfma_f32_16x16x32_bf16 v[16:19], v[208:211], v[178:181], v[16:19]
	s_add_u32 s16, s16, 0x100
	s_addc_u32 s17, s17, 0
	v_mfma_f32_16x16x32_bf16 v[8:11], v[218:221], v[178:181], v[8:11]
	s_add_u32 s40, s40, 0x100
	s_addc_u32 s41, s41, 0
	v_mfma_f32_16x16x32_bf16 v[4:7], v[208:211], v[186:189], v[4:7]
	s_add_u32 s18, s16, 0xfff80080
	s_addc_u32 s19, s17, -1
	v_mfma_f32_16x16x32_bf16 v[0:3], v[218:221], v[186:189], v[0:3]
	s_add_i32 s43, 0, 0x10000
	s_cmp_eq_u32 s42, 28
	v_mfma_f32_16x16x32_bf16 v[48:51], v[214:217], v[166:169], v[48:51]
	s_cselect_b32 s21, s9, s19
	s_cselect_b32 s20, s38, s18
	v_mfma_f32_16x16x32_bf16 v[40:43], v[222:225], v[166:169], v[40:43]
	s_cselect_b32 s19, s7, s41
	s_cselect_b32 s18, s39, s40
	v_mfma_f32_16x16x32_bf16 v[32:35], v[214:217], v[174:177], v[32:35]
	s_add_i32 m0, s30, 0xc000
	v_mfma_f32_16x16x32_bf16 v[24:27], v[222:225], v[174:177], v[24:27]
	v_mfma_f32_16x16x32_bf16 v[16:19], v[214:217], v[182:185], v[16:19]
	v_mfma_f32_16x16x32_bf16 v[8:11], v[222:225], v[182:185], v[8:11]
	v_mfma_f32_16x16x32_bf16 v[4:7], v[214:217], v[204:207], v[4:7]
	v_mfma_f32_16x16x32_bf16 v[0:3], v[222:225], v[204:207], v[0:3]
	s_cmp_gt_u32 s42, 29
	s_barrier
	s_cbranch_scc0 .LBB0_415
	s_mul_hi_i32 s9, s15, 0x2aaaaaab
	v_lshl_add_u32 v153, s14, 8, v142
	s_lshr_b32 s14, s9, 31
	s_lshr_b32 s9, s9, 2
	s_add_i32 s9, s9, s14
	s_lshl_b32 s7, s15, 8
	s_mul_i32 s16, s9, 0x1800
	v_readlane_b32 s40, v254, 14
	v_readlane_b32 s41, v254, 15
	s_sub_i32 s40, s7, s16
	s_mov_b64 s[20:21], s[40:41]
	v_readlane_b32 s42, v254, 16
	v_readlane_b32 s43, v254, 17
	v_writelane_b32 v254, s20, 14
	s_mov_b64 s[14:15], -1
	s_cmpk_gt_i32 s40, 0xfff
	v_writelane_b32 v254, s21, 15
	v_writelane_b32 v254, s22, 16
	v_writelane_b32 v254, s23, 17
	v_or_b32_e32 v152, 16, v153
	v_or_b32_e32 v151, 32, v153
	v_or_b32_e32 v150, 48, v153
	v_add_u32_e32 v149, 0x80, v153
	v_add_u32_e32 v148, 0x90, v153
	v_add_u32_e32 v147, 0xa0, v153
	v_add_u32_e32 v146, 0xb0, v153
	s_cbranch_scc0 .LBB0_418
	v_mov_b32_e32 v156, v193
	v_mov_b32_e32 v157, v193
	s_ashr_i32 s17, s16, 31
	v_mov_b64_e32 v[140:141], s[2:3]
	s_mov_b32 s9, 0x9000
	v_cvt_pk_fp8_f32 v156, v124, v125
	v_cvt_pk_fp8_f32 v157, v120, v121
	s_lshl_b64 s[14:15], s[16:17], 1
	v_mad_i64_i32 v[154:155], s[16:17], v153, s9, v[140:141]
	s_add_u32 s14, s14, 0x2000
	v_readlane_b32 s16, v254, 14
	s_addc_u32 s15, s15, 0
	v_readlane_b32 s17, v254, 15
	v_lshl_add_u64 v[154:155], v[154:155], 0, s[14:15]
	s_mov_b64 s[20:21], s[16:17]
	v_cvt_pk_fp8_f32 v156, v126, v127 op_sel:[0,0,1]
	v_cvt_pk_fp8_f32 v157, v122, v123 op_sel:[0,0,1]
	v_lshl_add_u64 v[154:155], v[154:155], 0, s[20:21]
	v_lshl_add_u64 v[154:155], v[154:155], 0, s[4:5]
	v_lshl_add_u64 v[154:155], v[154:155], 0, v[134:135]
	global_store_dwordx2 v[154:155], v[156:157], off offset:-4096
	v_mov_b32_e32 v156, v193
	v_mov_b32_e32 v157, v193
	v_cvt_pk_fp8_f32 v156, v112, v113
	v_cvt_pk_fp8_f32 v157, v104, v105
	v_readlane_b32 s18, v254, 16
	v_readlane_b32 s19, v254, 17
	v_cvt_pk_fp8_f32 v156, v114, v115 op_sel:[0,0,1]
	v_cvt_pk_fp8_f32 v157, v106, v107 op_sel:[0,0,1]
	global_store_dwordx2 v[154:155], v[156:157], off offset:-3968
	v_mov_b32_e32 v156, v193
	v_mov_b32_e32 v157, v193
	v_cvt_pk_fp8_f32 v156, v116, v117
	v_cvt_pk_fp8_f32 v157, v108, v109
	v_mad_i64_i32 v[154:155], s[16:17], v152, s9, v[140:141]
	v_lshl_add_u64 v[154:155], v[154:155], 0, s[14:15]
	v_cvt_pk_fp8_f32 v156, v118, v119 op_sel:[0,0,1]
	v_cvt_pk_fp8_f32 v157, v110, v111 op_sel:[0,0,1]
	v_lshl_add_u64 v[154:155], v[154:155], 0, s[20:21]
	v_lshl_add_u64 v[154:155], v[154:155], 0, s[4:5]
	v_lshl_add_u64 v[154:155], v[154:155], 0, v[134:135]
	global_store_dwordx2 v[154:155], v[156:157], off offset:-4096
	v_mov_b32_e32 v156, v193
	v_mov_b32_e32 v157, v193
	v_cvt_pk_fp8_f32 v156, v96, v97
	v_cvt_pk_fp8_f32 v157, v88, v89
	v_cvt_pk_fp8_f32 v156, v98, v99 op_sel:[0,0,1]
	v_cvt_pk_fp8_f32 v157, v90, v91 op_sel:[0,0,1]
	global_store_dwordx2 v[154:155], v[156:157], off offset:-3968
	v_mov_b32_e32 v156, v193
	v_mov_b32_e32 v157, v193
	v_cvt_pk_fp8_f32 v156, v100, v101
	v_cvt_pk_fp8_f32 v157, v92, v93
	v_mad_i64_i32 v[154:155], s[16:17], v151, s9, v[140:141]
	v_lshl_add_u64 v[154:155], v[154:155], 0, s[14:15]
	v_cvt_pk_fp8_f32 v156, v102, v103 op_sel:[0,0,1]
	v_cvt_pk_fp8_f32 v157, v94, v95 op_sel:[0,0,1]
	v_lshl_add_u64 v[154:155], v[154:155], 0, s[20:21]
	v_lshl_add_u64 v[154:155], v[154:155], 0, s[4:5]
	v_lshl_add_u64 v[154:155], v[154:155], 0, v[134:135]
	global_store_dwordx2 v[154:155], v[156:157], off offset:-4096
	v_mov_b32_e32 v156, v193
	v_mov_b32_e32 v157, v193
	v_cvt_pk_fp8_f32 v156, v80, v81
	v_cvt_pk_fp8_f32 v157, v72, v73
	v_cvt_pk_fp8_f32 v156, v82, v83 op_sel:[0,0,1]
	v_cvt_pk_fp8_f32 v157, v74, v75 op_sel:[0,0,1]
	global_store_dwordx2 v[154:155], v[156:157], off offset:-3968
	v_mov_b32_e32 v156, v193
	v_mov_b32_e32 v157, v193
	v_cvt_pk_fp8_f32 v156, v84, v85
	v_cvt_pk_fp8_f32 v157, v76, v77
	v_mad_i64_i32 v[154:155], s[16:17], v150, s9, v[140:141]
	v_lshl_add_u64 v[154:155], v[154:155], 0, s[14:15]
	v_cvt_pk_fp8_f32 v156, v86, v87 op_sel:[0,0,1]
	v_cvt_pk_fp8_f32 v157, v78, v79 op_sel:[0,0,1]
	v_lshl_add_u64 v[154:155], v[154:155], 0, s[20:21]
	v_lshl_add_u64 v[154:155], v[154:155], 0, s[4:5]
	v_lshl_add_u64 v[154:155], v[154:155], 0, v[134:135]
	global_store_dwordx2 v[154:155], v[156:157], off offset:-4096
	v_mov_b32_e32 v156, v193
	v_mov_b32_e32 v157, v193
	v_cvt_pk_fp8_f32 v156, v68, v69
	v_cvt_pk_fp8_f32 v157, v64, v65
	v_cvt_pk_fp8_f32 v156, v70, v71 op_sel:[0,0,1]
	v_cvt_pk_fp8_f32 v157, v66, v67 op_sel:[0,0,1]
	global_store_dwordx2 v[154:155], v[156:157], off offset:-3968
	v_mov_b32_e32 v156, v193
	v_mov_b32_e32 v157, v193
	v_cvt_pk_fp8_f32 v156, v60, v61
	v_cvt_pk_fp8_f32 v157, v56, v57
	v_mad_i64_i32 v[154:155], s[16:17], v149, s9, v[140:141]
	v_lshl_add_u64 v[154:155], v[154:155], 0, s[14:15]
	v_cvt_pk_fp8_f32 v156, v62, v63 op_sel:[0,0,1]
	v_cvt_pk_fp8_f32 v157, v58, v59 op_sel:[0,0,1]
	v_lshl_add_u64 v[154:155], v[154:155], 0, s[20:21]
	v_lshl_add_u64 v[154:155], v[154:155], 0, s[4:5]
	v_lshl_add_u64 v[154:155], v[154:155], 0, v[134:135]
	global_store_dwordx2 v[154:155], v[156:157], off offset:-4096
	v_mov_b32_e32 v156, v193
	v_mov_b32_e32 v157, v193
	v_cvt_pk_fp8_f32 v156, v48, v49
	v_cvt_pk_fp8_f32 v157, v40, v41
	v_cvt_pk_fp8_f32 v156, v50, v51 op_sel:[0,0,1]
	v_cvt_pk_fp8_f32 v157, v42, v43 op_sel:[0,0,1]
	global_store_dwordx2 v[154:155], v[156:157], off offset:-3968
	v_mov_b32_e32 v156, v193
	v_mov_b32_e32 v157, v193
	v_cvt_pk_fp8_f32 v156, v52, v53
	v_cvt_pk_fp8_f32 v157, v44, v45
	v_mad_i64_i32 v[154:155], s[16:17], v148, s9, v[140:141]
	v_lshl_add_u64 v[154:155], v[154:155], 0, s[14:15]
	v_cvt_pk_fp8_f32 v156, v54, v55 op_sel:[0,0,1]
	v_cvt_pk_fp8_f32 v157, v46, v47 op_sel:[0,0,1]
	v_lshl_add_u64 v[154:155], v[154:155], 0, s[20:21]
	v_lshl_add_u64 v[154:155], v[154:155], 0, s[4:5]
	v_lshl_add_u64 v[154:155], v[154:155], 0, v[134:135]
	global_store_dwordx2 v[154:155], v[156:157], off offset:-4096
	v_mov_b32_e32 v156, v193
	v_mov_b32_e32 v157, v193
	v_cvt_pk_fp8_f32 v156, v32, v33
	v_cvt_pk_fp8_f32 v157, v24, v25
	v_cvt_pk_fp8_f32 v156, v34, v35 op_sel:[0,0,1]
	v_cvt_pk_fp8_f32 v157, v26, v27 op_sel:[0,0,1]
	global_store_dwordx2 v[154:155], v[156:157], off offset:-3968
	v_mov_b32_e32 v156, v193
	v_mov_b32_e32 v157, v193
	v_cvt_pk_fp8_f32 v156, v36, v37
	v_cvt_pk_fp8_f32 v157, v28, v29
	v_mad_i64_i32 v[154:155], s[16:17], v147, s9, v[140:141]
	v_lshl_add_u64 v[154:155], v[154:155], 0, s[14:15]
	v_cvt_pk_fp8_f32 v156, v38, v39 op_sel:[0,0,1]
	v_cvt_pk_fp8_f32 v157, v30, v31 op_sel:[0,0,1]
	v_lshl_add_u64 v[154:155], v[154:155], 0, s[20:21]
	v_lshl_add_u64 v[154:155], v[154:155], 0, s[4:5]
	v_lshl_add_u64 v[154:155], v[154:155], 0, v[134:135]
	global_store_dwordx2 v[154:155], v[156:157], off offset:-4096
	v_mov_b32_e32 v156, v193
	v_mov_b32_e32 v157, v193
	v_cvt_pk_fp8_f32 v156, v16, v17
	v_cvt_pk_fp8_f32 v157, v8, v9
	v_mad_i64_i32 v[140:141], s[16:17], v146, s9, v[140:141]
	v_cvt_pk_fp8_f32 v156, v18, v19 op_sel:[0,0,1]
	v_cvt_pk_fp8_f32 v157, v10, v11 op_sel:[0,0,1]
	v_lshl_add_u64 v[140:141], v[140:141], 0, s[14:15]
	v_lshl_add_u64 v[140:141], v[140:141], 0, s[20:21]
	v_lshl_add_u64 v[140:141], v[140:141], 0, s[4:5]
	global_store_dwordx2 v[154:155], v[156:157], off offset:-3968
	v_mov_b32_e32 v154, v193
	v_mov_b32_e32 v155, v193
	v_cvt_pk_fp8_f32 v154, v20, v21
	v_cvt_pk_fp8_f32 v155, v12, v13
	v_lshl_add_u64 v[140:141], v[140:141], 0, v[134:135]
	s_mov_b64 s[14:15], 0
	v_cvt_pk_fp8_f32 v154, v22, v23 op_sel:[0,0,1]
	v_cvt_pk_fp8_f32 v155, v14, v15 op_sel:[0,0,1]
	global_store_dwordx2 v[140:141], v[154:155], off offset:-4096
	v_mov_b32_e32 v154, v193
	v_mov_b32_e32 v155, v193
	v_cvt_pk_fp8_f32 v154, v4, v5
	v_cvt_pk_fp8_f32 v155, v0, v1
	v_cvt_pk_fp8_f32 v154, v6, v7 op_sel:[0,0,1]
	v_cvt_pk_fp8_f32 v155, v2, v3 op_sel:[0,0,1]
	global_store_dwordx2 v[140:141], v[154:155], off offset:-3968
